# write-through (sc1) on all wide epilogue/phase-output stores so the seam's L2 writeback has little left to flush
# baseline (speedup 1.0000x reference)
.LBB0_98:
	s_waitcnt lgkmcnt(0)
	global_load_dwordx4 v[16:19], v[8:9], off offset:-3072 nt
	global_load_dwordx4 v[20:23], v[8:9], off offset:-2048 nt
	global_load_dwordx4 v[24:27], v[8:9], off offset:-1024 nt
	global_load_dwordx4 v[28:31], v[8:9], off nt
	s_mov_b32 s4, 0xa645000
	s_waitcnt vmcnt(0)
	v_mul_f32_e32 v32, v17, v17
	v_mul_f32_e32 v33, v19, v19
	v_mul_f32_e32 v34, v21, v21
	v_mul_f32_e32 v35, v23, v23
	v_mul_f32_e32 v36, v25, v25
	v_mul_f32_e32 v37, v27, v27
	v_fmac_f32_e32 v32, v16, v16
	v_fmac_f32_e32 v33, v18, v18
	v_fmac_f32_e32 v34, v20, v20
	v_fmac_f32_e32 v35, v22, v22
	v_mul_f32_e32 v39, v29, v29
	v_mul_f32_e32 v40, v31, v31
	v_fmac_f32_e32 v36, v24, v24
	v_fmac_f32_e32 v37, v26, v26
	v_add_f32_e32 v32, v32, v33
	v_add_f32_e32 v33, v34, v35
	v_fmac_f32_e32 v39, v28, v28
	v_fmac_f32_e32 v40, v30, v30
	v_add_f32_e32 v34, v36, v37
	v_add_f32_e32 v32, v32, v33
	v_add_f32_e32 v35, v39, v40
	v_add_f32_e32 v32, v32, v34
	v_add_f32_e32 v32, v32, v35
	ds_bpermute_b32 v33, v10, v32
	v_cvt_pk_bf16_f32 v16, v16, v17
	v_cvt_pk_bf16_f32 v17, v18, v19
	v_cvt_pk_bf16_f32 v18, v20, v21
	v_cvt_pk_bf16_f32 v19, v22, v23
	s_waitcnt lgkmcnt(0)
	v_add_f32_e32 v32, v32, v33
	ds_bpermute_b32 v33, v11, v32
	v_cvt_pk_bf16_f32 v20, v24, v25
	s_waitcnt lgkmcnt(0)
	v_add_f32_e32 v34, v32, v33
	ds_bpermute_b32 v35, v12, v34
	v_lshl_add_u64 v[32:33], s[88:89], 0, v[6:7]
	v_add_co_u32_e64 v32, s[38:39], s4, v32
	s_waitcnt lgkmcnt(0)
	v_add_f32_e32 v34, v34, v35
	ds_bpermute_b32 v35, v13, v34
	v_addc_co_u32_e64 v33, s[38:39], 0, v33, s[38:39]
	global_store_dwordx2 v[32:33], v[16:17], off sc1
	global_store_dwordx2 v[32:33], v[18:19], off offset:512 sc1
	v_cvt_pk_bf16_f32 v18, v28, v29
	s_waitcnt lgkmcnt(0)
	v_add_f32_e32 v21, v34, v35
	ds_bpermute_b32 v34, v14, v21
	v_cvt_pk_bf16_f32 v19, v30, v31
	global_store_dwordx2 v[32:33], v[18:19], off offset:1536 sc1
	s_waitcnt lgkmcnt(0)
	v_add_f32_e32 v16, v21, v34
	ds_bpermute_b32 v17, v15, v16
	v_cvt_pk_bf16_f32 v21, v26, v27
	global_store_dwordx2 v[32:33], v[20:21], off offset:1024 sc1
	s_and_saveexec_b64 s[10:11], vcc
	s_cbranch_execz .LBB0_97
	s_waitcnt lgkmcnt(0)
	v_add_f32_e32 v16, v16, v17
	v_cndmask_b32_e64 v18, 0, v16, s[36:37]
	v_lshl_add_u64 v[16:17], s[88:89], 0, v[4:5]
	global_store_dword v[16:17], v18, off
	s_branch .LBB0_97

.LBB0_102:
	s_waitcnt lgkmcnt(0)
	global_load_dwordx4 v[16:19], v[8:9], off offset:-3072
	global_load_dwordx4 v[20:23], v[8:9], off offset:-2048
	global_load_dwordx4 v[24:27], v[8:9], off offset:-1024
	global_load_dwordx4 v[28:31], v[8:9], off
	global_load_dwordx4 v[32:35], v[4:5], off
	v_add_u32_e32 v0, s34, v0
	s_movk_i32 s4, 0x3ff
	v_lshl_add_u64 v[8:9], v[8:9], 0, s[46:47]
	s_waitcnt vmcnt(0)
	v_pk_mul_f32 v[36:37], v[18:19], v[18:19]
	v_pk_mul_f32 v[40:41], v[16:17], v[16:17]
	v_pk_mul_f32 v[42:43], v[22:23], v[22:23]
	v_pk_mul_f32 v[44:45], v[20:21], v[20:21]
	v_pk_mov_b32 v[50:51], v[40:41], v[36:37] op_sel:[1,0]
	v_mov_b32_e32 v41, v37
	v_pk_mov_b32 v[36:37], v[44:45], v[42:43] op_sel:[1,0]
	v_mov_b32_e32 v45, v43
	v_mul_f32_e32 v49, v31, v31
	v_mul_f32_e32 v46, v25, v25
	v_mul_f32_e32 v48, v27, v27
	v_pk_add_f32 v[40:41], v[50:51], v[40:41]
	v_pk_add_f32 v[36:37], v[36:37], v[44:45]
	v_mul_f32_e32 v1, v28, v28
	v_mul_f32_e32 v15, v29, v29
	v_mul_f32_e32 v39, v30, v30
	v_pk_fma_f32 v[42:43], v[24:25], v[24:25], v[46:47] op_sel_hi:[1,1,0]
	v_pk_fma_f32 v[46:47], v[26:27], v[26:27], v[48:49] op_sel_hi:[1,1,0]
	v_pk_add_f32 v[40:41], v[40:41], v[40:41] op_sel:[0,1] op_sel_hi:[1,0]
	v_pk_add_f32 v[36:37], v[36:37], v[36:37] op_sel:[0,1] op_sel_hi:[1,0]
	v_mov_b32_e32 v43, v39
	v_mov_b32_e32 v47, v49
	v_mov_b32_e32 v41, v1
	v_mov_b32_e32 v37, v15
	v_pk_add_f32 v[42:43], v[42:43], v[46:47]
	v_pk_add_f32 v[36:37], v[40:41], v[36:37]
	s_nop 0
	v_pk_add_f32 v[36:37], v[36:37], v[42:43]
	s_nop 0
	v_add_f32_e32 v1, v36, v37
	ds_bpermute_b32 v15, v3, v1
	s_waitcnt lgkmcnt(0)
	v_add_f32_e32 v1, v1, v15
	ds_bpermute_b32 v15, v10, v1
	s_waitcnt lgkmcnt(0)
	v_add_f32_e32 v1, v1, v15
	ds_bpermute_b32 v15, v11, v1
	s_waitcnt lgkmcnt(0)
	v_add_f32_e32 v1, v1, v15
	ds_bpermute_b32 v15, v12, v1
	s_waitcnt lgkmcnt(0)
	v_add_f32_e32 v1, v1, v15
	ds_bpermute_b32 v15, v13, v1
	s_waitcnt lgkmcnt(0)
	v_add_f32_e32 v1, v1, v15
	ds_bpermute_b32 v15, v14, v1
	s_waitcnt lgkmcnt(0)
	v_add_f32_e32 v1, v1, v15
	v_fmamk_f32 v1, v1, 0x3a800000, v216
	v_mul_f32_e32 v15, 0x4b800000, v1
	v_cmp_gt_f32_e32 vcc, s29, v1
	s_nop 1
	v_cndmask_b32_e32 v1, v1, v15, vcc
	v_rsq_f32_e32 v1, v1
	s_nop 0
	v_mul_f32_e32 v15, 0x45800000, v1
	v_cndmask_b32_e32 v36, v1, v15, vcc
	v_pk_mul_f32 v[16:17], v[16:17], v[36:37] op_sel_hi:[1,0]
	v_pk_mul_f32 v[18:19], v[18:19], v[36:37] op_sel_hi:[1,0]
	v_pk_mul_f32 v[16:17], v[32:33], v[16:17]
	v_pk_mul_f32 v[18:19], v[34:35], v[18:19]
	v_cvt_pk_bf16_f32 v16, v16, v17
	v_cvt_pk_bf16_f32 v17, v18, v19
	global_store_dwordx2 v[6:7], v[16:17], off sc1
	global_load_dwordx4 v[16:19], v[4:5], off offset:1024
	v_pk_mul_f32 v[20:21], v[20:21], v[36:37] op_sel_hi:[1,0]
	v_pk_mul_f32 v[22:23], v[22:23], v[36:37] op_sel_hi:[1,0]
	v_cmp_lt_i32_e32 vcc, s4, v0
	s_or_b64 s[8:9], vcc, s[8:9]
	s_waitcnt vmcnt(0)
	v_pk_mul_f32 v[18:19], v[18:19], v[22:23]
	v_pk_mul_f32 v[16:17], v[16:17], v[20:21]
	v_pk_mul_f32 v[20:21], v[24:25], v[36:37] op_sel_hi:[1,0]
	v_cvt_pk_bf16_f32 v16, v16, v17
	v_cvt_pk_bf16_f32 v17, v18, v19
	global_store_dwordx2 v[6:7], v[16:17], off offset:512 sc1
	global_load_dwordx4 v[16:19], v[4:5], off offset:2048
	v_pk_mul_f32 v[22:23], v[26:27], v[36:37] op_sel_hi:[1,0]
	s_waitcnt vmcnt(0)
	v_pk_mul_f32 v[16:17], v[16:17], v[20:21]
	v_pk_mul_f32 v[18:19], v[18:19], v[22:23]
	v_cvt_pk_bf16_f32 v16, v16, v17
	v_cvt_pk_bf16_f32 v17, v18, v19
	global_store_dwordx2 v[6:7], v[16:17], off offset:1024 sc1
	global_load_dwordx4 v[16:19], v[4:5], off offset:3072
	v_pk_mul_f32 v[20:21], v[28:29], v[36:37] op_sel_hi:[1,0]
	v_pk_mul_f32 v[22:23], v[30:31], v[36:37] op_sel_hi:[1,0]
	s_waitcnt vmcnt(0)
	v_pk_mul_f32 v[16:17], v[16:17], v[20:21]
	v_pk_mul_f32 v[18:19], v[18:19], v[22:23]
	v_cvt_pk_bf16_f32 v16, v16, v17
	v_cvt_pk_bf16_f32 v17, v18, v19
	global_store_dwordx2 v[6:7], v[16:17], off offset:1536 sc1
	v_lshl_add_u64 v[6:7], v[6:7], 0, s[66:67]
	s_andn2_b64 exec, exec, s[8:9]
	s_cbranch_execnz .LBB0_102

.LBB0_125:
	global_load_dwordx4 v[26:29], v[22:23], off offset:-8
	global_load_dwordx4 v[30:33], v[24:25], off offset:-8
	s_add_i32 s4, s4, 4
	v_lshl_add_u64 v[24:25], v[24:25], 0, 16
	v_lshl_add_u64 v[22:23], v[22:23], 0, 16
	s_cmp_gt_u32 s4, 13
	s_waitcnt vmcnt(1)
	v_pk_mul_f32 v[34:35], v[18:19], v[26:27]
	v_pk_mul_f32 v[26:27], v[16:17], v[26:27]
	v_pk_mul_f32 v[36:37], v[18:19], v[28:29]
	v_pk_mul_f32 v[28:29], v[16:17], v[28:29]
	s_waitcnt vmcnt(0)
	v_pk_fma_f32 v[34:35], v[16:17], v[30:31], v[34:35] neg_lo:[0,0,1] neg_hi:[0,0,1]
	v_pk_fma_f32 v[26:27], v[18:19], v[30:31], v[26:27]
	v_pk_fma_f32 v[30:31], v[16:17], v[32:33], v[36:37] neg_lo:[0,0,1] neg_hi:[0,0,1]
	v_pk_fma_f32 v[28:29], v[18:19], v[32:33], v[28:29]
	v_cvt_pk_bf16_f32 v32, v34, v35
	v_cvt_pk_bf16_f32 v33, v30, v31
	v_cvt_pk_bf16_f32 v26, v26, v27
	v_cvt_pk_bf16_f32 v27, v28, v29
	global_store_dwordx2 v[20:21], v[32:33], off offset:-2052 sc1
	global_store_dwordx2 v[20:21], v[26:27], off offset:-4 sc1
	v_lshl_add_u64 v[20:21], v[20:21], 0, 8
	s_cbranch_scc0 .LBB0_125
	v_lshl_add_u64 v[16:17], v[10:11], 0, v[14:15]
	v_lshl_add_u64 v[18:19], v[12:13], 0, v[14:15]
	v_lshl_add_u64 v[14:15], v[2:3], 0, v[14:15]
	s_mov_b64 s[10:11], 0

.LBB0_131:
	v_lshl_add_u64 v[30:31], v[2:3], 0, s[10:11]
	v_lshl_add_u64 v[38:39], v[6:7], 0, s[10:11]
	v_lshl_add_u64 v[26:27], v[8:9], 0, s[10:11]
	v_lshl_add_u64 v[34:35], v[4:5], 0, s[10:11]
	global_load_dwordx4 v[10:13], v[26:27], off
	s_waitcnt lgkmcnt(0)
	global_load_dwordx4 v[14:17], v[30:31], off
	global_load_dwordx4 v[18:21], v[34:35], off
	global_load_dwordx4 v[22:25], v[38:39], off
	s_nop 0
	global_load_dwordx4 v[26:29], v[26:27], off offset:16
	s_nop 0
	global_load_dwordx4 v[30:33], v[30:31], off offset:16
	s_nop 0
	global_load_dwordx4 v[34:37], v[34:35], off offset:16
	s_nop 0
	global_load_dwordx4 v[38:41], v[38:39], off offset:16
	s_add_u32 s10, s10, 32
	s_addc_u32 s11, s11, 0
	s_cmpk_eq_i32 s10, 0x100
	s_waitcnt vmcnt(0)
	v_mov_b32_e32 v42, v10
	v_mov_b32_e32 v43, v14
	v_mov_b32_e32 v44, v18
	v_mov_b32_e32 v45, v22
	v_mov_b32_e32 v14, v11
	v_mov_b32_e32 v22, v19
	v_pk_fma_f32 v[0:1], v[42:43], v[44:45], v[0:1]
	v_mov_b32_e32 v10, v12
	v_mov_b32_e32 v11, v16
	v_mov_b32_e32 v18, v20
	v_mov_b32_e32 v19, v24
	v_pk_fma_f32 v[0:1], v[14:15], v[22:23], v[0:1]
	v_mov_b32_e32 v16, v13
	v_mov_b32_e32 v24, v21
	v_pk_fma_f32 v[0:1], v[10:11], v[18:19], v[0:1]
	v_mov_b32_e32 v12, v26
	v_mov_b32_e32 v13, v30
	v_mov_b32_e32 v20, v34
	v_mov_b32_e32 v21, v38
	v_pk_fma_f32 v[0:1], v[16:17], v[24:25], v[0:1]
	v_mov_b32_e32 v30, v27
	v_mov_b32_e32 v38, v35
	v_pk_fma_f32 v[0:1], v[12:13], v[20:21], v[0:1]
	v_mov_b32_e32 v26, v28
	v_mov_b32_e32 v27, v32
	v_mov_b32_e32 v34, v36
	v_mov_b32_e32 v35, v40
	v_pk_fma_f32 v[0:1], v[30:31], v[38:39], v[0:1]
	v_mov_b32_e32 v32, v29
	v_mov_b32_e32 v40, v37
	v_pk_fma_f32 v[0:1], v[26:27], v[34:35], v[0:1]
	s_nop 0
	v_pk_fma_f32 v[0:1], v[32:33], v[40:41], v[0:1]
	s_cbranch_scc0 .LBB0_131
	v_add_u32_e32 v2, 2, v166
	v_cvt_f32_i32_e32 v2, v2
	s_mov_b32 s3, 0xc2ce8ed0
	s_mov_b32 s2, 0x42b17218
	v_readlane_b32 s20, v255, 17
	v_mul_f32_e32 v2, 0xbe99999a, v2
	v_mul_f32_e32 v3, 0x3fb8aa3b, v2
	v_fma_f32 v4, v2, s28, -v3
	v_rndne_f32_e32 v5, v3
	v_fmac_f32_e32 v4, 0x32a5705f, v2
	v_sub_f32_e32 v3, v3, v5
	v_add_f32_e32 v3, v3, v4
	v_cvt_i32_f32_e32 v5, v5
	v_exp_f32_e32 v3, v3
	v_mul_f32_e32 v4, 0x3fb8aa3b, v1
	v_rndne_f32_e32 v6, v4
	v_cmp_ngt_f32_e32 vcc, s3, v2
	v_ldexp_f32 v3, v3, v5
	v_sub_f32_e32 v5, v4, v6
	v_fma_f32 v4, v1, s28, -v4
	v_fmac_f32_e32 v4, 0x32a5705f, v1
	v_add_f32_e32 v4, v5, v4
	v_exp_f32_e32 v4, v4
	v_cvt_i32_f32_e32 v5, v6
	v_cndmask_b32_e32 v3, 0, v3, vcc
	v_cmp_nlt_f32_e32 vcc, s2, v2
	v_readlane_b32 s21, v255, 18
	s_nop 0
	v_cndmask_b32_e32 v2, v233, v3, vcc
	v_mov_b32_e32 v3, 0x3f4ccccd
	v_fmamk_f32 v6, v2, 0xbf19999a, v3
	v_mul_f32_e32 v3, 0x3fb8aa3b, v0
	v_ldexp_f32 v2, v4, v5
	v_rndne_f32_e32 v4, v3
	v_sub_f32_e32 v5, v3, v4
	v_fma_f32 v3, v0, s28, -v3
	v_fmac_f32_e32 v3, 0x32a5705f, v0
	v_add_f32_e32 v3, v5, v3
	v_exp_f32_e32 v3, v3
	v_cvt_i32_f32_e32 v4, v4
	v_cmp_ngt_f32_e32 vcc, s3, v1
	s_nop 1
	v_cndmask_b32_e32 v2, 0, v2, vcc
	v_cmp_nlt_f32_e32 vcc, s2, v1
	s_mov_b32 s2, 0xc2ce8ed0
	s_nop 0
	v_cndmask_b32_e32 v1, v233, v2, vcc
	v_ldexp_f32 v2, v3, v4
	v_cmp_ngt_f32_e32 vcc, s3, v0
	s_mov_b32 s3, 0x42b17218
	s_nop 0
	v_cndmask_b32_e32 v2, 0, v2, vcc
	v_cmp_nlt_f32_e32 vcc, s3, v0
	s_nop 1
	v_cndmask_b32_e32 v0, v233, v2, vcc
	v_lshlrev_b32_e32 v2, 1, v166
	v_sub_f32_e32 v0, v1, v0
	v_ashrrev_i32_e32 v3, 31, v2
	v_add_f32_e32 v0, v6, v0
	v_lshl_add_u64 v[2:3], v[2:3], 2, s[88:89]
	v_sub_f32_e32 v1, 1.0, v6
	global_store_dwordx2 v[2:3], v[0:1], off offset:64 sc1

.LBB0_168:
	v_lshl_or_b32 v138, s25, 8, v146
	v_lshl_add_u32 v140, s24, 8, v144
	v_mov_b64_e32 v[142:143], s[66:67]
	v_ashrrev_i32_e32 v139, 31, v138
	v_mad_i64_i32 v[148:149], s[14:15], v140, s35, v[142:143]
	v_lshlrev_b64 v[138:139], 1, v[138:139]
	v_lshl_add_u64 v[152:153], v[148:149], 0, v[138:139]
	global_load_dwordx4 v[148:151], v[152:153], off
	v_mul_f32_e32 v120, 0xbfb8aa3b, v120
	v_ashrrev_i32_e32 v141, 31, v140
	v_mul_f32_e32 v162, 0xbfb8aa3b, v112
	v_mul_f32_e32 v163, 0xbfb8aa3b, v113
	v_mul_f32_e32 v164, 0xbfb8aa3b, v118
	v_exp_f32_e32 v118, v120
	v_or_b32_e32 v120, 16, v140
	v_lshlrev_b64 v[112:113], 11, v[140:141]
	v_mul_f32_e32 v124, 0xbfb8aa3b, v124
	v_mul_f32_e32 v125, 0xbfb8aa3b, v125
	v_mul_f32_e32 v121, 0xbfb8aa3b, v121
	v_mul_f32_e32 v126, 0xbfb8aa3b, v126
	v_mul_f32_e32 v127, 0xbfb8aa3b, v127
	v_mul_f32_e32 v122, 0xbfb8aa3b, v122
	v_mul_f32_e32 v123, 0xbfb8aa3b, v123
	v_mul_f32_e32 v167, 0xbfb8aa3b, v114
	v_mul_f32_e32 v169, 0xbfb8aa3b, v115
	v_mad_i64_i32 v[114:115], s[14:15], v120, s35, v[142:143]
	v_lshl_add_u64 v[112:113], s[20:21], 0, v[112:113]
	v_mul_f32_e32 v158, 0xbfb8aa3b, v116
	v_mul_f32_e32 v159, 0xbfb8aa3b, v117
	v_mul_f32_e32 v165, 0xbfb8aa3b, v119
	v_exp_f32_e32 v116, v124
	v_exp_f32_e32 v117, v125
	v_exp_f32_e32 v119, v121
	v_exp_f32_e32 v121, v126
	v_exp_f32_e32 v126, v127
	v_exp_f32_e32 v127, v122
	v_exp_f32_e32 v154, v123
	v_lshl_add_u64 v[122:123], v[114:115], 0, v[138:139]
	v_lshl_add_u64 v[124:125], v[112:113], 0, v[138:139]
	global_load_dwordx4 v[112:115], v[152:153], off offset:256
	v_add_f32_e32 v116, 1.0, v116
	v_add_f32_e32 v117, 1.0, v117
	v_add_f32_e32 v118, 1.0, v118
	v_add_f32_e32 v119, 1.0, v119
	v_add_f32_e32 v121, 1.0, v121
	v_add_f32_e32 v141, 1.0, v126
	v_add_f32_e32 v152, 1.0, v127
	v_add_f32_e32 v153, 1.0, v154
	v_rcp_f32_e32 v116, v116
	v_rcp_f32_e32 v117, v117
	v_rcp_f32_e32 v118, v118
	v_rcp_f32_e32 v119, v119
	v_rcp_f32_e32 v126, v121
	v_rcp_f32_e32 v127, v141
	v_rcp_f32_e32 v152, v152
	v_rcp_f32_e32 v153, v153
	v_exp_f32_e32 v141, v159
	v_mul_f32_e32 v104, 0xbfb8aa3b, v104
	v_mul_f32_e32 v105, 0xbfb8aa3b, v105
	v_ashrrev_i32_e32 v121, 31, v120
	v_mul_f32_e32 v108, 0xbfb8aa3b, v108
	v_mul_f32_e32 v109, 0xbfb8aa3b, v109
	v_mul_f32_e32 v110, 0xbfb8aa3b, v110
	v_mul_f32_e32 v111, 0xbfb8aa3b, v111
	v_mul_f32_e32 v106, 0xbfb8aa3b, v106
	v_mul_f32_e32 v107, 0xbfb8aa3b, v107
	v_exp_f32_e32 v159, v111
	v_mul_f32_e32 v100, 0xbfb8aa3b, v100
	v_mul_f32_e32 v101, 0xbfb8aa3b, v101
	v_mul_f32_e32 v96, 0xbfb8aa3b, v96
	v_mul_f32_e32 v97, 0xbfb8aa3b, v97
	v_mul_f32_e32 v102, 0xbfb8aa3b, v102
	v_mul_f32_e32 v103, 0xbfb8aa3b, v103
	v_mul_f32_e32 v98, 0xbfb8aa3b, v98
	v_mul_f32_e32 v99, 0xbfb8aa3b, v99
	v_mul_f32_e32 v90, 0xbfb8aa3b, v90
	v_mul_f32_e32 v91, 0xbfb8aa3b, v91
	v_exp_f32_e32 v90, v90
	v_exp_f32_e32 v91, v91
	v_mul_f32_e32 v84, 0xbfb8aa3b, v84
	v_mul_f32_e32 v85, 0xbfb8aa3b, v85
	v_add_f32_e32 v90, 1.0, v90
	v_add_f32_e32 v91, 1.0, v91
	v_rcp_f32_e32 v90, v90
	v_rcp_f32_e32 v91, v91
	v_exp_f32_e32 v84, v84
	s_waitcnt vmcnt(0)
	v_lshlrev_b32_e32 v154, 16, v148
	v_and_b32_e32 v155, 0xffff0000, v148
	v_lshlrev_b32_e32 v156, 16, v150
	v_and_b32_e32 v157, 0xffff0000, v150
	v_lshlrev_b32_e32 v148, 16, v149
	v_and_b32_e32 v149, 0xffff0000, v149
	v_lshlrev_b32_e32 v150, 16, v151
	v_and_b32_e32 v151, 0xffff0000, v151
	v_pk_mul_f32 v[116:117], v[116:117], v[154:155]
	v_pk_mul_f32 v[118:119], v[118:119], v[156:157]
	v_pk_mul_f32 v[126:127], v[126:127], v[148:149]
	v_pk_mul_f32 v[148:149], v[152:153], v[150:151]
	v_cvt_pk_bf16_f32 v116, v116, v117
	v_cvt_pk_bf16_f32 v117, v126, v127
	v_cvt_pk_bf16_f32 v118, v118, v119
	v_cvt_pk_bf16_f32 v119, v148, v149
	global_store_dwordx4 v[124:125], v[116:119], off sc1
	global_load_dwordx4 v[116:119], v[122:123], off
	v_exp_f32_e32 v127, v158
	v_exp_f32_e32 v148, v162
	v_exp_f32_e32 v149, v163
	v_exp_f32_e32 v150, v164
	v_exp_f32_e32 v151, v165
	v_exp_f32_e32 v152, v167
	v_exp_f32_e32 v153, v169
	v_exp_f32_e32 v156, v104
	v_exp_f32_e32 v157, v105
	v_lshlrev_b64 v[104:105], 11, v[120:121]
	v_exp_f32_e32 v154, v108
	v_exp_f32_e32 v155, v109
	v_exp_f32_e32 v158, v110
	v_exp_f32_e32 v162, v106
	v_exp_f32_e32 v163, v107
	v_lshl_add_u64 v[108:109], s[20:21], 0, v[104:105]
	v_add_f32_e32 v104, 1.0, v127
	v_add_f32_e32 v105, 1.0, v141
	v_add_f32_e32 v106, 1.0, v148
	v_add_f32_e32 v107, 1.0, v149
	v_add_f32_e32 v110, 1.0, v150
	v_add_f32_e32 v111, 1.0, v151
	v_add_f32_e32 v120, 1.0, v152
	v_add_f32_e32 v121, 1.0, v153
	v_rcp_f32_e32 v104, v104
	v_rcp_f32_e32 v105, v105
	v_rcp_f32_e32 v106, v106
	v_rcp_f32_e32 v107, v107
	v_rcp_f32_e32 v110, v110
	v_rcp_f32_e32 v111, v111
	v_rcp_f32_e32 v120, v120
	v_rcp_f32_e32 v121, v121
	v_lshlrev_b32_e32 v148, 16, v112
	v_and_b32_e32 v149, 0xffff0000, v112
	v_lshlrev_b32_e32 v150, 16, v114
	v_and_b32_e32 v151, 0xffff0000, v114
	v_lshlrev_b32_e32 v112, 16, v113
	v_and_b32_e32 v113, 0xffff0000, v113
	v_lshlrev_b32_e32 v114, 16, v115
	v_and_b32_e32 v115, 0xffff0000, v115
	v_pk_mul_f32 v[104:105], v[104:105], v[148:149]
	v_pk_mul_f32 v[106:107], v[106:107], v[150:151]
	v_pk_mul_f32 v[110:111], v[110:111], v[112:113]
	v_pk_mul_f32 v[112:113], v[120:121], v[114:115]
	v_cvt_pk_bf16_f32 v104, v104, v105
	v_cvt_pk_bf16_f32 v105, v110, v111
	v_cvt_pk_bf16_f32 v106, v106, v107
	v_cvt_pk_bf16_f32 v107, v112, v113
	global_store_dwordx4 v[124:125], v[104:107], off offset:256 sc1
	global_load_dwordx4 v[104:107], v[122:123], off offset:256
	v_add_f32_e32 v127, 1.0, v154
	v_add_f32_e32 v141, 1.0, v155
	v_add_f32_e32 v152, 1.0, v156
	v_add_f32_e32 v153, 1.0, v157
	v_add_f32_e32 v114, 1.0, v158
	v_add_f32_e32 v115, 1.0, v159
	v_add_f32_e32 v120, 1.0, v162
	v_add_f32_e32 v121, 1.0, v163
	v_lshl_add_u64 v[112:113], v[108:109], 0, v[138:139]
	v_rcp_f32_e32 v108, v127
	v_rcp_f32_e32 v109, v141
	v_rcp_f32_e32 v110, v152
	v_rcp_f32_e32 v111, v153
	v_rcp_f32_e32 v114, v114
	v_rcp_f32_e32 v115, v115
	v_rcp_f32_e32 v120, v120
	v_rcp_f32_e32 v121, v121
	v_or_b32_e32 v126, 32, v140
	v_ashrrev_i32_e32 v127, 31, v126
	v_exp_f32_e32 v85, v85
	v_mul_f32_e32 v80, 0xbfb8aa3b, v80
	v_mul_f32_e32 v86, 0xbfb8aa3b, v86
	v_mul_f32_e32 v87, 0xbfb8aa3b, v87
	v_add_f32_e32 v84, 1.0, v84
	v_add_f32_e32 v85, 1.0, v85
	v_exp_f32_e32 v86, v86
	v_exp_f32_e32 v87, v87
	v_mul_f32_e32 v82, 0xbfb8aa3b, v82
	v_mul_f32_e32 v83, 0xbfb8aa3b, v83
	s_waitcnt vmcnt(2)
	v_lshlrev_b32_e32 v122, 16, v116
	v_and_b32_e32 v123, 0xffff0000, v116
	v_lshlrev_b32_e32 v124, 16, v118
	v_and_b32_e32 v125, 0xffff0000, v118
	v_lshlrev_b32_e32 v116, 16, v117
	v_and_b32_e32 v117, 0xffff0000, v117
	v_lshlrev_b32_e32 v118, 16, v119
	v_and_b32_e32 v119, 0xffff0000, v119
	v_pk_mul_f32 v[108:109], v[108:109], v[122:123]
	v_pk_mul_f32 v[110:111], v[110:111], v[124:125]
	v_pk_mul_f32 v[114:115], v[114:115], v[116:117]
	v_pk_mul_f32 v[116:117], v[120:121], v[118:119]
	v_cvt_pk_bf16_f32 v108, v108, v109
	v_cvt_pk_bf16_f32 v109, v114, v115
	v_cvt_pk_bf16_f32 v110, v110, v111
	v_cvt_pk_bf16_f32 v111, v116, v117
	global_store_dwordx4 v[112:113], v[108:111], off sc1
	v_mul_f32_e32 v116, 0xbfb8aa3b, v92
	v_mul_f32_e32 v117, 0xbfb8aa3b, v93
	v_mad_i64_i32 v[108:109], s[14:15], v126, s35, v[142:143]
	v_lshl_add_u64 v[114:115], v[108:109], 0, v[138:139]
	global_load_dwordx4 v[108:111], v[114:115], off
	v_mul_f32_e32 v118, 0xbfb8aa3b, v88
	v_mul_f32_e32 v119, 0xbfb8aa3b, v89
	v_mul_f32_e32 v120, 0xbfb8aa3b, v94
	v_mul_f32_e32 v121, 0xbfb8aa3b, v95
	v_exp_f32_e32 v88, v100
	v_exp_f32_e32 v89, v101
	v_exp_f32_e32 v92, v96
	v_exp_f32_e32 v93, v97
	v_exp_f32_e32 v94, v102
	v_exp_f32_e32 v95, v103
	v_exp_f32_e32 v96, v98
	v_exp_f32_e32 v97, v99
	v_add_f32_e32 v88, 1.0, v88
	v_add_f32_e32 v89, 1.0, v89
	v_add_f32_e32 v92, 1.0, v92
	v_add_f32_e32 v93, 1.0, v93
	v_add_f32_e32 v94, 1.0, v94
	v_add_f32_e32 v95, 1.0, v95
	v_add_f32_e32 v96, 1.0, v96
	v_add_f32_e32 v97, 1.0, v97
	v_rcp_f32_e32 v88, v88
	v_rcp_f32_e32 v89, v89
	v_rcp_f32_e32 v92, v92
	v_rcp_f32_e32 v93, v93
	v_rcp_f32_e32 v94, v94
	v_rcp_f32_e32 v95, v95
	v_rcp_f32_e32 v96, v96
	v_rcp_f32_e32 v97, v97
	s_waitcnt vmcnt(2)
	v_lshlrev_b32_e32 v98, 16, v104
	v_and_b32_e32 v99, 0xffff0000, v104
	v_lshlrev_b32_e32 v100, 16, v106
	v_and_b32_e32 v101, 0xffff0000, v106
	v_lshlrev_b32_e32 v102, 16, v105
	v_and_b32_e32 v103, 0xffff0000, v105
	v_lshlrev_b32_e32 v104, 16, v107
	v_and_b32_e32 v105, 0xffff0000, v107
	v_pk_mul_f32 v[88:89], v[88:89], v[98:99]
	v_pk_mul_f32 v[98:99], v[92:93], v[100:101]
	v_pk_mul_f32 v[94:95], v[94:95], v[102:103]
	v_pk_mul_f32 v[96:97], v[96:97], v[104:105]
	v_cvt_pk_bf16_f32 v92, v88, v89
	v_cvt_pk_bf16_f32 v93, v94, v95
	v_cvt_pk_bf16_f32 v94, v98, v99
	v_cvt_pk_bf16_f32 v95, v96, v97
	global_store_dwordx4 v[112:113], v[92:95], off offset:256 sc1
	global_load_dwordx4 v[92:95], v[114:115], off offset:256
	v_exp_f32_e32 v88, v116
	v_exp_f32_e32 v89, v117
	v_exp_f32_e32 v98, v118
	v_exp_f32_e32 v99, v119
	v_add_f32_e32 v88, 1.0, v88
	v_add_f32_e32 v89, 1.0, v89
	v_exp_f32_e32 v104, v120
	v_exp_f32_e32 v105, v121
	v_rcp_f32_e32 v88, v88
	v_rcp_f32_e32 v89, v89
	v_add_f32_e32 v98, 1.0, v98
	v_add_f32_e32 v99, 1.0, v99
	v_rcp_f32_e32 v98, v98
	v_rcp_f32_e32 v99, v99
	v_lshlrev_b64 v[96:97], 11, v[126:127]
	v_lshl_add_u64 v[96:97], s[20:21], 0, v[96:97]
	v_lshl_add_u64 v[96:97], v[96:97], 0, v[138:139]
	v_rcp_f32_e32 v84, v84
	v_rcp_f32_e32 v85, v85
	v_exp_f32_e32 v82, v82
	v_exp_f32_e32 v83, v83
	v_add_f32_e32 v86, 1.0, v86
	v_add_f32_e32 v87, 1.0, v87
	v_rcp_f32_e32 v86, v86
	v_rcp_f32_e32 v87, v87
	v_add_f32_e32 v82, 1.0, v82
	v_add_f32_e32 v83, 1.0, v83
	v_rcp_f32_e32 v82, v82
	v_rcp_f32_e32 v83, v83
	v_mul_f32_e32 v76, 0xbfb8aa3b, v76
	v_mul_f32_e32 v77, 0xbfb8aa3b, v77
	v_exp_f32_e32 v76, v76
	v_exp_f32_e32 v77, v77
	s_waitcnt vmcnt(2)
	v_lshlrev_b32_e32 v100, 16, v108
	v_and_b32_e32 v101, 0xffff0000, v108
	v_pk_mul_f32 v[88:89], v[88:89], v[100:101]
	v_add_f32_e32 v100, 1.0, v104
	v_add_f32_e32 v101, 1.0, v105
	v_rcp_f32_e32 v100, v100
	v_rcp_f32_e32 v101, v101
	v_lshlrev_b32_e32 v102, 16, v110
	v_and_b32_e32 v103, 0xffff0000, v110
	v_pk_mul_f32 v[98:99], v[98:99], v[102:103]
	v_lshlrev_b32_e32 v102, 16, v109
	v_and_b32_e32 v103, 0xffff0000, v109
	v_pk_mul_f32 v[100:101], v[100:101], v[102:103]
	v_lshlrev_b32_e32 v102, 16, v111
	v_and_b32_e32 v103, 0xffff0000, v111
	v_pk_mul_f32 v[102:103], v[90:91], v[102:103]
	v_cvt_pk_bf16_f32 v88, v88, v89
	v_cvt_pk_bf16_f32 v89, v100, v101
	v_cvt_pk_bf16_f32 v90, v98, v99
	v_cvt_pk_bf16_f32 v91, v102, v103
	v_or_b32_e32 v98, 48, v140
	global_store_dwordx4 v[96:97], v[88:91], off sc1
	v_mul_f32_e32 v72, 0xbfb8aa3b, v72
	v_add_f32_e32 v76, 1.0, v76
	v_mad_i64_i32 v[88:89], s[14:15], v98, s35, v[142:143]
	v_lshl_add_u64 v[100:101], v[88:89], 0, v[138:139]
	global_load_dwordx4 v[88:91], v[100:101], off
	v_add_f32_e32 v77, 1.0, v77
	v_rcp_f32_e32 v76, v76
	v_rcp_f32_e32 v77, v77
	v_mul_f32_e32 v78, 0xbfb8aa3b, v78
	v_mul_f32_e32 v79, 0xbfb8aa3b, v79
	v_exp_f32_e32 v78, v78
	v_exp_f32_e32 v79, v79
	v_mul_f32_e32 v74, 0xbfb8aa3b, v74
	v_mul_f32_e32 v75, 0xbfb8aa3b, v75
	v_exp_f32_e32 v74, v74
	v_exp_f32_e32 v75, v75
	v_add_f32_e32 v78, 1.0, v78
	v_add_f32_e32 v79, 1.0, v79
	v_rcp_f32_e32 v78, v78
	v_rcp_f32_e32 v79, v79
	v_add_f32_e32 v74, 1.0, v74
	v_add_f32_e32 v75, 1.0, v75
	v_rcp_f32_e32 v74, v74
	s_waitcnt vmcnt(2)
	v_lshlrev_b32_e32 v102, 16, v92
	v_and_b32_e32 v103, 0xffff0000, v92
	v_exp_f32_e32 v92, v80
	v_mul_f32_e32 v80, 0xbfb8aa3b, v81
	v_exp_f32_e32 v99, v80
	v_pk_mul_f32 v[80:81], v[84:85], v[102:103]
	v_add_f32_e32 v84, 1.0, v92
	v_rcp_f32_e32 v84, v84
	v_add_f32_e32 v85, 1.0, v99
	v_rcp_f32_e32 v85, v85
	v_lshlrev_b32_e32 v92, 16, v93
	v_and_b32_e32 v93, 0xffff0000, v93
	v_lshlrev_b32_e32 v102, 16, v94
	v_and_b32_e32 v103, 0xffff0000, v94
	v_pk_mul_f32 v[86:87], v[86:87], v[92:93]
	v_lshlrev_b32_e32 v92, 16, v95
	v_and_b32_e32 v93, 0xffff0000, v95
	v_pk_mul_f32 v[84:85], v[84:85], v[102:103]
	v_pk_mul_f32 v[92:93], v[82:83], v[92:93]
	v_cvt_pk_bf16_f32 v80, v80, v81
	v_cvt_pk_bf16_f32 v81, v86, v87
	v_cvt_pk_bf16_f32 v82, v84, v85
	v_cvt_pk_bf16_f32 v83, v92, v93
	global_store_dwordx4 v[96:97], v[80:83], off offset:256 sc1
	global_load_dwordx4 v[80:83], v[100:101], off offset:256
	v_rcp_f32_e32 v75, v75
	v_ashrrev_i32_e32 v99, 31, v98
	v_lshlrev_b64 v[84:85], 11, v[98:99]
	v_mul_f32_e32 v68, 0xbfb8aa3b, v68
	v_mul_f32_e32 v69, 0xbfb8aa3b, v69
	v_exp_f32_e32 v68, v68
	v_exp_f32_e32 v69, v69
	v_mul_f32_e32 v64, 0xbfb8aa3b, v64
	v_mul_f32_e32 v70, 0xbfb8aa3b, v70
	v_mul_f32_e32 v71, 0xbfb8aa3b, v71
	v_add_f32_e32 v68, 1.0, v68
	v_add_f32_e32 v69, 1.0, v69
	v_exp_f32_e32 v70, v70
	v_exp_f32_e32 v71, v71
	v_mul_f32_e32 v66, 0xbfb8aa3b, v66
	v_mul_f32_e32 v67, 0xbfb8aa3b, v67
	v_rcp_f32_e32 v68, v68
	v_rcp_f32_e32 v69, v69
	v_exp_f32_e32 v66, v66
	v_exp_f32_e32 v67, v67
	v_add_f32_e32 v70, 1.0, v70
	v_add_f32_e32 v71, 1.0, v71
	v_rcp_f32_e32 v70, v70
	v_rcp_f32_e32 v71, v71
	v_add_f32_e32 v66, 1.0, v66
	v_add_f32_e32 v67, 1.0, v67
	v_rcp_f32_e32 v66, v66
	v_rcp_f32_e32 v67, v67
	v_mul_f32_e32 v60, 0xbfb8aa3b, v60
	v_mul_f32_e32 v56, 0xbfb8aa3b, v56
	v_mul_f32_e32 v62, 0xbfb8aa3b, v62
	v_mul_f32_e32 v58, 0xbfb8aa3b, v58
	v_mul_f32_e32 v59, 0xbfb8aa3b, v59
	v_exp_f32_e32 v58, v58
	v_exp_f32_e32 v59, v59
	v_mul_f32_e32 v52, 0xbfb8aa3b, v52
	s_waitcnt vmcnt(2)
	v_lshlrev_b32_e32 v86, 16, v88
	v_and_b32_e32 v87, 0xffff0000, v88
	v_exp_f32_e32 v88, v72
	v_mul_f32_e32 v72, 0xbfb8aa3b, v73
	v_exp_f32_e32 v92, v72
	v_pk_mul_f32 v[72:73], v[76:77], v[86:87]
	v_add_f32_e32 v76, 1.0, v88
	v_rcp_f32_e32 v76, v76
	v_add_f32_e32 v77, 1.0, v92
	v_rcp_f32_e32 v77, v77
	v_lshlrev_b32_e32 v86, 16, v90
	v_and_b32_e32 v87, 0xffff0000, v90
	v_cvt_pk_bf16_f32 v72, v72, v73
	v_pk_mul_f32 v[76:77], v[76:77], v[86:87]
	v_lshlrev_b32_e32 v86, 16, v89
	v_and_b32_e32 v87, 0xffff0000, v89
	v_pk_mul_f32 v[78:79], v[78:79], v[86:87]
	v_lshlrev_b32_e32 v86, 16, v91
	v_and_b32_e32 v87, 0xffff0000, v91
	v_pk_mul_f32 v[86:87], v[74:75], v[86:87]
	v_cvt_pk_bf16_f32 v74, v76, v77
	v_lshl_add_u64 v[76:77], s[20:21], 0, v[84:85]
	v_cvt_pk_bf16_f32 v73, v78, v79
	v_cvt_pk_bf16_f32 v75, v86, v87
	v_lshl_add_u64 v[76:77], v[76:77], 0, v[138:139]
	v_add_u32_e32 v78, 0x80, v140
	global_store_dwordx4 v[76:77], v[72:75], off sc1
	v_exp_f32_e32 v79, v64
	v_mul_f32_e32 v64, 0xbfb8aa3b, v65
	v_mad_i64_i32 v[72:73], s[14:15], v78, s35, v[142:143]
	v_lshl_add_u64 v[84:85], v[72:73], 0, v[138:139]
	global_load_dwordx4 v[72:75], v[84:85], off
	v_add_f32_e32 v58, 1.0, v58
	v_add_f32_e32 v59, 1.0, v59
	v_rcp_f32_e32 v58, v58
	v_rcp_f32_e32 v59, v59
	v_mul_f32_e32 v53, 0xbfb8aa3b, v53
	v_exp_f32_e32 v52, v52
	v_exp_f32_e32 v53, v53
	v_mul_f32_e32 v48, 0xbfb8aa3b, v48
	v_mul_f32_e32 v54, 0xbfb8aa3b, v54
	v_mul_f32_e32 v55, 0xbfb8aa3b, v55
	s_waitcnt vmcnt(2)
	v_lshlrev_b32_e32 v86, 16, v80
	v_and_b32_e32 v87, 0xffff0000, v80
	v_exp_f32_e32 v80, v64
	v_pk_mul_f32 v[64:65], v[68:69], v[86:87]
	v_add_f32_e32 v68, 1.0, v79
	v_rcp_f32_e32 v68, v68
	v_add_f32_e32 v69, 1.0, v80
	v_rcp_f32_e32 v69, v69
	v_lshlrev_b32_e32 v80, 16, v81
	v_and_b32_e32 v81, 0xffff0000, v81
	v_lshlrev_b32_e32 v86, 16, v82
	v_and_b32_e32 v87, 0xffff0000, v82
	v_pk_mul_f32 v[70:71], v[70:71], v[80:81]
	v_lshlrev_b32_e32 v80, 16, v83
	v_and_b32_e32 v81, 0xffff0000, v83
	v_pk_mul_f32 v[68:69], v[68:69], v[86:87]
	v_pk_mul_f32 v[80:81], v[66:67], v[80:81]
	v_cvt_pk_bf16_f32 v64, v64, v65
	v_cvt_pk_bf16_f32 v65, v70, v71
	v_cvt_pk_bf16_f32 v66, v68, v69
	v_cvt_pk_bf16_f32 v67, v80, v81
	global_store_dwordx4 v[76:77], v[64:67], off offset:256 sc1
	global_load_dwordx4 v[64:67], v[84:85], off offset:256
	v_exp_f32_e32 v68, v60
	v_mul_f32_e32 v60, 0xbfb8aa3b, v61
	v_exp_f32_e32 v69, v60
	v_ashrrev_i32_e32 v79, 31, v78
	v_add_f32_e32 v68, 1.0, v68
	v_rcp_f32_e32 v68, v68
	v_add_f32_e32 v69, 1.0, v69
	v_rcp_f32_e32 v69, v69
	v_lshlrev_b64 v[60:61], 11, v[78:79]
	v_lshl_add_u64 v[60:61], s[20:21], 0, v[60:61]
	v_lshl_add_u64 v[60:61], v[60:61], 0, v[138:139]
	v_add_f32_e32 v52, 1.0, v52
	v_add_f32_e32 v53, 1.0, v53
	v_exp_f32_e32 v54, v54
	v_exp_f32_e32 v55, v55
	v_mul_f32_e32 v50, 0xbfb8aa3b, v50
	v_mul_f32_e32 v51, 0xbfb8aa3b, v51
	v_rcp_f32_e32 v52, v52
	v_rcp_f32_e32 v53, v53
	v_exp_f32_e32 v50, v50
	v_exp_f32_e32 v51, v51
	v_add_f32_e32 v54, 1.0, v54
	v_add_f32_e32 v55, 1.0, v55
	v_rcp_f32_e32 v54, v54
	v_rcp_f32_e32 v55, v55
	v_add_f32_e32 v50, 1.0, v50
	v_add_f32_e32 v51, 1.0, v51
	v_rcp_f32_e32 v50, v50
	v_rcp_f32_e32 v51, v51
	v_mul_f32_e32 v44, 0xbfb8aa3b, v44
	v_mul_f32_e32 v40, 0xbfb8aa3b, v40
	v_mul_f32_e32 v46, 0xbfb8aa3b, v46
	v_mul_f32_e32 v42, 0xbfb8aa3b, v42
	v_mul_f32_e32 v43, 0xbfb8aa3b, v43
	v_exp_f32_e32 v42, v42
	v_exp_f32_e32 v43, v43
	v_mul_f32_e32 v36, 0xbfb8aa3b, v36
	v_mul_f32_e32 v37, 0xbfb8aa3b, v37
	v_add_f32_e32 v42, 1.0, v42
	v_add_f32_e32 v43, 1.0, v43
	v_rcp_f32_e32 v42, v42
	v_rcp_f32_e32 v43, v43
	v_exp_f32_e32 v36, v36
	v_exp_f32_e32 v37, v37
	v_mul_f32_e32 v32, 0xbfb8aa3b, v32
	v_mul_f32_e32 v38, 0xbfb8aa3b, v38
	s_waitcnt vmcnt(2)
	v_lshlrev_b32_e32 v70, 16, v72
	v_and_b32_e32 v71, 0xffff0000, v72
	v_exp_f32_e32 v72, v56
	v_mul_f32_e32 v56, 0xbfb8aa3b, v57
	v_exp_f32_e32 v76, v56
	v_pk_mul_f32 v[56:57], v[68:69], v[70:71]
	v_add_f32_e32 v68, 1.0, v72
	v_exp_f32_e32 v72, v62
	v_add_f32_e32 v69, 1.0, v76
	v_mul_f32_e32 v62, 0xbfb8aa3b, v63
	v_rcp_f32_e32 v68, v68
	v_rcp_f32_e32 v69, v69
	v_lshlrev_b32_e32 v70, 16, v74
	v_and_b32_e32 v71, 0xffff0000, v74
	v_exp_f32_e32 v74, v62
	v_pk_mul_f32 v[62:63], v[68:69], v[70:71]
	v_add_f32_e32 v68, 1.0, v72
	v_rcp_f32_e32 v68, v68
	v_add_f32_e32 v69, 1.0, v74
	v_rcp_f32_e32 v69, v69
	v_lshlrev_b32_e32 v70, 16, v73
	v_and_b32_e32 v71, 0xffff0000, v73
	v_cvt_pk_bf16_f32 v56, v56, v57
	v_pk_mul_f32 v[68:69], v[68:69], v[70:71]
	v_lshlrev_b32_e32 v70, 16, v75
	v_and_b32_e32 v71, 0xffff0000, v75
	v_pk_mul_f32 v[70:71], v[58:59], v[70:71]
	v_cvt_pk_bf16_f32 v57, v68, v69
	v_cvt_pk_bf16_f32 v58, v62, v63
	v_cvt_pk_bf16_f32 v59, v70, v71
	v_add_u32_e32 v62, 0x90, v140
	global_store_dwordx4 v[60:61], v[56:59], off sc1
	v_exp_f32_e32 v63, v48
	v_mul_f32_e32 v48, 0xbfb8aa3b, v49
	v_mad_i64_i32 v[56:57], s[14:15], v62, s35, v[142:143]
	v_lshl_add_u64 v[68:69], v[56:57], 0, v[138:139]
	global_load_dwordx4 v[56:59], v[68:69], off
	s_waitcnt vmcnt(2)
	v_lshlrev_b32_e32 v70, 16, v64
	v_and_b32_e32 v71, 0xffff0000, v64
	v_exp_f32_e32 v64, v48
	v_pk_mul_f32 v[48:49], v[52:53], v[70:71]
	v_add_f32_e32 v52, 1.0, v63
	v_rcp_f32_e32 v52, v52
	v_add_f32_e32 v53, 1.0, v64
	v_rcp_f32_e32 v53, v53
	v_lshlrev_b32_e32 v64, 16, v65
	v_and_b32_e32 v65, 0xffff0000, v65
	v_lshlrev_b32_e32 v70, 16, v66
	v_and_b32_e32 v71, 0xffff0000, v66
	v_pk_mul_f32 v[54:55], v[54:55], v[64:65]
	v_lshlrev_b32_e32 v64, 16, v67
	v_and_b32_e32 v65, 0xffff0000, v67
	v_pk_mul_f32 v[52:53], v[52:53], v[70:71]
	v_pk_mul_f32 v[64:65], v[50:51], v[64:65]
	v_cvt_pk_bf16_f32 v48, v48, v49
	v_cvt_pk_bf16_f32 v49, v54, v55
	v_cvt_pk_bf16_f32 v50, v52, v53
	v_cvt_pk_bf16_f32 v51, v64, v65
	global_store_dwordx4 v[60:61], v[48:51], off offset:256 sc1
	global_load_dwordx4 v[48:51], v[68:69], off offset:256
	v_exp_f32_e32 v52, v44
	v_mul_f32_e32 v44, 0xbfb8aa3b, v45
	v_exp_f32_e32 v53, v44
	v_ashrrev_i32_e32 v63, 31, v62
	v_add_f32_e32 v52, 1.0, v52
	v_rcp_f32_e32 v52, v52
	v_add_f32_e32 v53, 1.0, v53
	v_rcp_f32_e32 v53, v53
	v_lshlrev_b64 v[44:45], 11, v[62:63]
	v_lshl_add_u64 v[44:45], s[20:21], 0, v[44:45]
	v_lshl_add_u64 v[44:45], v[44:45], 0, v[138:139]
	v_mul_f32_e32 v39, 0xbfb8aa3b, v39
	v_add_f32_e32 v36, 1.0, v36
	v_add_f32_e32 v37, 1.0, v37
	v_exp_f32_e32 v38, v38
	v_exp_f32_e32 v39, v39
	v_mul_f32_e32 v34, 0xbfb8aa3b, v34
	v_mul_f32_e32 v35, 0xbfb8aa3b, v35
	v_rcp_f32_e32 v36, v36
	v_rcp_f32_e32 v37, v37
	v_exp_f32_e32 v34, v34
	v_exp_f32_e32 v35, v35
	v_add_f32_e32 v38, 1.0, v38
	v_add_f32_e32 v39, 1.0, v39
	v_rcp_f32_e32 v38, v38
	v_rcp_f32_e32 v39, v39
	v_add_f32_e32 v34, 1.0, v34
	v_add_f32_e32 v35, 1.0, v35
	v_rcp_f32_e32 v34, v34
	v_rcp_f32_e32 v35, v35
	v_mul_f32_e32 v28, 0xbfb8aa3b, v28
	v_mul_f32_e32 v24, 0xbfb8aa3b, v24
	v_mul_f32_e32 v30, 0xbfb8aa3b, v30
	v_mul_f32_e32 v26, 0xbfb8aa3b, v26
	v_mul_f32_e32 v27, 0xbfb8aa3b, v27
	v_exp_f32_e32 v26, v26
	v_exp_f32_e32 v27, v27
	v_mul_f32_e32 v20, 0xbfb8aa3b, v20
	v_mul_f32_e32 v21, 0xbfb8aa3b, v21
	v_add_f32_e32 v26, 1.0, v26
	v_add_f32_e32 v27, 1.0, v27
	v_rcp_f32_e32 v26, v26
	v_rcp_f32_e32 v27, v27
	v_exp_f32_e32 v20, v20
	v_exp_f32_e32 v21, v21
	v_mul_f32_e32 v16, 0xbfb8aa3b, v16
	v_mul_f32_e32 v22, 0xbfb8aa3b, v22
	v_mul_f32_e32 v23, 0xbfb8aa3b, v23
	v_add_f32_e32 v20, 1.0, v20
	v_add_f32_e32 v21, 1.0, v21
	v_exp_f32_e32 v22, v22
	v_exp_f32_e32 v23, v23
	v_mul_f32_e32 v18, 0xbfb8aa3b, v18
	v_mul_f32_e32 v19, 0xbfb8aa3b, v19
	v_rcp_f32_e32 v20, v20
	v_rcp_f32_e32 v21, v21
	s_waitcnt vmcnt(2)
	v_lshlrev_b32_e32 v54, 16, v56
	v_and_b32_e32 v55, 0xffff0000, v56
	v_exp_f32_e32 v56, v40
	v_mul_f32_e32 v40, 0xbfb8aa3b, v41
	v_exp_f32_e32 v60, v40
	v_pk_mul_f32 v[40:41], v[52:53], v[54:55]
	v_add_f32_e32 v52, 1.0, v56
	v_exp_f32_e32 v56, v46
	v_add_f32_e32 v53, 1.0, v60
	v_mul_f32_e32 v46, 0xbfb8aa3b, v47
	v_rcp_f32_e32 v52, v52
	v_rcp_f32_e32 v53, v53
	v_lshlrev_b32_e32 v54, 16, v58
	v_and_b32_e32 v55, 0xffff0000, v58
	v_exp_f32_e32 v58, v46
	v_pk_mul_f32 v[46:47], v[52:53], v[54:55]
	v_add_f32_e32 v52, 1.0, v56
	v_rcp_f32_e32 v52, v52
	v_add_f32_e32 v53, 1.0, v58
	v_rcp_f32_e32 v53, v53
	v_lshlrev_b32_e32 v54, 16, v57
	v_and_b32_e32 v55, 0xffff0000, v57
	v_cvt_pk_bf16_f32 v40, v40, v41
	v_pk_mul_f32 v[52:53], v[52:53], v[54:55]
	v_lshlrev_b32_e32 v54, 16, v59
	v_and_b32_e32 v55, 0xffff0000, v59
	v_pk_mul_f32 v[54:55], v[42:43], v[54:55]
	v_cvt_pk_bf16_f32 v41, v52, v53
	v_cvt_pk_bf16_f32 v42, v46, v47
	v_cvt_pk_bf16_f32 v43, v54, v55
	v_add_u32_e32 v46, 0xa0, v140
	global_store_dwordx4 v[44:45], v[40:43], off sc1
	v_exp_f32_e32 v47, v32
	v_mul_f32_e32 v32, 0xbfb8aa3b, v33
	v_mad_i64_i32 v[40:41], s[14:15], v46, s35, v[142:143]
	v_lshl_add_u64 v[52:53], v[40:41], 0, v[138:139]
	global_load_dwordx4 v[40:43], v[52:53], off
	s_waitcnt vmcnt(2)
	v_lshlrev_b32_e32 v54, 16, v48
	v_and_b32_e32 v55, 0xffff0000, v48
	v_exp_f32_e32 v48, v32
	v_pk_mul_f32 v[32:33], v[36:37], v[54:55]
	v_add_f32_e32 v36, 1.0, v47
	v_rcp_f32_e32 v36, v36
	v_add_f32_e32 v37, 1.0, v48
	v_rcp_f32_e32 v37, v37
	v_lshlrev_b32_e32 v48, 16, v49
	v_and_b32_e32 v49, 0xffff0000, v49
	v_lshlrev_b32_e32 v54, 16, v50
	v_and_b32_e32 v55, 0xffff0000, v50
	v_pk_mul_f32 v[38:39], v[38:39], v[48:49]
	v_lshlrev_b32_e32 v48, 16, v51
	v_and_b32_e32 v49, 0xffff0000, v51
	v_pk_mul_f32 v[36:37], v[36:37], v[54:55]
	v_pk_mul_f32 v[48:49], v[34:35], v[48:49]
	v_cvt_pk_bf16_f32 v32, v32, v33
	v_cvt_pk_bf16_f32 v33, v38, v39
	v_cvt_pk_bf16_f32 v34, v36, v37
	v_cvt_pk_bf16_f32 v35, v48, v49
	global_store_dwordx4 v[44:45], v[32:35], off offset:256 sc1
	global_load_dwordx4 v[32:35], v[52:53], off offset:256
	v_exp_f32_e32 v36, v28
	v_mul_f32_e32 v28, 0xbfb8aa3b, v29
	v_exp_f32_e32 v37, v28
	v_ashrrev_i32_e32 v47, 31, v46
	v_add_f32_e32 v36, 1.0, v36
	v_rcp_f32_e32 v36, v36
	v_add_f32_e32 v37, 1.0, v37
	v_rcp_f32_e32 v37, v37
	v_lshlrev_b64 v[28:29], 11, v[46:47]
	v_lshl_add_u64 v[28:29], s[20:21], 0, v[28:29]
	v_lshl_add_u64 v[28:29], v[28:29], 0, v[138:139]
	v_exp_f32_e32 v18, v18
	v_exp_f32_e32 v19, v19
	v_add_f32_e32 v22, 1.0, v22
	v_add_f32_e32 v23, 1.0, v23
	v_rcp_f32_e32 v22, v22
	v_rcp_f32_e32 v23, v23
	v_add_f32_e32 v18, 1.0, v18
	v_add_f32_e32 v19, 1.0, v19
	v_rcp_f32_e32 v18, v18
	v_rcp_f32_e32 v19, v19
	v_mul_f32_e32 v12, 0xbfb8aa3b, v12
	v_mul_f32_e32 v8, 0xbfb8aa3b, v8
	v_mul_f32_e32 v14, 0xbfb8aa3b, v14
	v_mul_f32_e32 v10, 0xbfb8aa3b, v10
	v_mul_f32_e32 v11, 0xbfb8aa3b, v11
	v_exp_f32_e32 v10, v10
	v_exp_f32_e32 v11, v11
	v_mul_f32_e32 v4, 0xbfb8aa3b, v4
	v_mul_f32_e32 v5, 0xbfb8aa3b, v5
	v_add_f32_e32 v10, 1.0, v10
	v_add_f32_e32 v11, 1.0, v11
	v_rcp_f32_e32 v10, v10
	v_rcp_f32_e32 v11, v11
	v_exp_f32_e32 v4, v4
	v_exp_f32_e32 v5, v5
	v_mul_f32_e32 v0, 0xbfb8aa3b, v0
	v_mul_f32_e32 v6, 0xbfb8aa3b, v6
	v_add_f32_e32 v4, 1.0, v4
	v_add_f32_e32 v5, 1.0, v5
	v_rcp_f32_e32 v4, v4
	v_rcp_f32_e32 v5, v5
	v_mul_f32_e32 v7, 0xbfb8aa3b, v7
	v_exp_f32_e32 v6, v6
	v_exp_f32_e32 v7, v7
	v_mul_f32_e32 v2, 0xbfb8aa3b, v2
	v_mul_f32_e32 v3, 0xbfb8aa3b, v3
	v_exp_f32_e32 v2, v2
	v_exp_f32_e32 v3, v3
	v_add_f32_e32 v6, 1.0, v6
	v_add_f32_e32 v7, 1.0, v7
	v_rcp_f32_e32 v6, v6
	v_rcp_f32_e32 v7, v7
	v_add_f32_e32 v2, 1.0, v2
	v_add_f32_e32 v3, 1.0, v3
	v_rcp_f32_e32 v2, v2
	s_waitcnt vmcnt(2)
	v_lshlrev_b32_e32 v38, 16, v40
	v_and_b32_e32 v39, 0xffff0000, v40
	v_exp_f32_e32 v40, v24
	v_mul_f32_e32 v24, 0xbfb8aa3b, v25
	v_exp_f32_e32 v44, v24
	v_pk_mul_f32 v[24:25], v[36:37], v[38:39]
	v_add_f32_e32 v36, 1.0, v40
	v_exp_f32_e32 v40, v30
	v_add_f32_e32 v37, 1.0, v44
	v_mul_f32_e32 v30, 0xbfb8aa3b, v31
	v_rcp_f32_e32 v36, v36
	v_rcp_f32_e32 v37, v37
	v_lshlrev_b32_e32 v38, 16, v42
	v_and_b32_e32 v39, 0xffff0000, v42
	v_exp_f32_e32 v42, v30
	v_pk_mul_f32 v[30:31], v[36:37], v[38:39]
	v_add_f32_e32 v36, 1.0, v40
	v_rcp_f32_e32 v36, v36
	v_add_f32_e32 v37, 1.0, v42
	v_rcp_f32_e32 v37, v37
	v_lshlrev_b32_e32 v38, 16, v41
	v_and_b32_e32 v39, 0xffff0000, v41
	v_cvt_pk_bf16_f32 v24, v24, v25
	v_pk_mul_f32 v[36:37], v[36:37], v[38:39]
	v_lshlrev_b32_e32 v38, 16, v43
	v_and_b32_e32 v39, 0xffff0000, v43
	v_pk_mul_f32 v[38:39], v[26:27], v[38:39]
	v_cvt_pk_bf16_f32 v25, v36, v37
	v_cvt_pk_bf16_f32 v26, v30, v31
	v_cvt_pk_bf16_f32 v27, v38, v39
	v_add_u32_e32 v30, 0xb0, v140
	global_store_dwordx4 v[28:29], v[24:27], off sc1
	v_exp_f32_e32 v31, v16
	v_mul_f32_e32 v16, 0xbfb8aa3b, v17
	v_mad_i64_i32 v[24:25], s[14:15], v30, s35, v[142:143]
	v_lshl_add_u64 v[36:37], v[24:25], 0, v[138:139]
	global_load_dwordx4 v[24:27], v[36:37], off
	s_waitcnt vmcnt(2)
	v_lshlrev_b32_e32 v38, 16, v32
	v_and_b32_e32 v39, 0xffff0000, v32
	v_exp_f32_e32 v32, v16
	v_pk_mul_f32 v[16:17], v[20:21], v[38:39]
	v_add_f32_e32 v20, 1.0, v31
	v_rcp_f32_e32 v20, v20
	v_add_f32_e32 v21, 1.0, v32
	v_rcp_f32_e32 v21, v21
	v_lshlrev_b32_e32 v32, 16, v33
	v_and_b32_e32 v33, 0xffff0000, v33
	v_lshlrev_b32_e32 v38, 16, v34
	v_and_b32_e32 v39, 0xffff0000, v34
	v_pk_mul_f32 v[22:23], v[22:23], v[32:33]
	v_lshlrev_b32_e32 v32, 16, v35
	v_and_b32_e32 v33, 0xffff0000, v35
	v_pk_mul_f32 v[20:21], v[20:21], v[38:39]
	v_pk_mul_f32 v[32:33], v[18:19], v[32:33]
	v_cvt_pk_bf16_f32 v16, v16, v17
	v_cvt_pk_bf16_f32 v17, v22, v23
	v_cvt_pk_bf16_f32 v18, v20, v21
	v_cvt_pk_bf16_f32 v19, v32, v33
	global_store_dwordx4 v[28:29], v[16:19], off offset:256 sc1
	global_load_dwordx4 v[16:19], v[36:37], off offset:256
	v_exp_f32_e32 v20, v12
	v_mul_f32_e32 v12, 0xbfb8aa3b, v13
	v_exp_f32_e32 v21, v12
	v_ashrrev_i32_e32 v31, 31, v30
	v_add_f32_e32 v20, 1.0, v20
	v_rcp_f32_e32 v20, v20
	v_add_f32_e32 v21, 1.0, v21
	v_rcp_f32_e32 v21, v21
	v_lshlrev_b64 v[12:13], 11, v[30:31]
	v_lshl_add_u64 v[12:13], s[20:21], 0, v[12:13]
	v_lshl_add_u64 v[12:13], v[12:13], 0, v[138:139]
	v_rcp_f32_e32 v3, v3
	v_readlane_b32 s86, v255, 21
	s_and_b64 vcc, exec, s[36:37]
	s_mov_b64 s[14:15], -1
	v_readlane_b32 s87, v255, 22
	s_brev_b32 s50, 18
	s_mov_b32 s51, 0xfe5163ab
	s_waitcnt vmcnt(2)
	v_lshlrev_b32_e32 v22, 16, v24
	v_and_b32_e32 v23, 0xffff0000, v24
	v_exp_f32_e32 v24, v8
	v_mul_f32_e32 v8, 0xbfb8aa3b, v9
	v_exp_f32_e32 v28, v8
	v_pk_mul_f32 v[8:9], v[20:21], v[22:23]
	v_add_f32_e32 v20, 1.0, v24
	v_exp_f32_e32 v24, v14
	v_add_f32_e32 v21, 1.0, v28
	v_mul_f32_e32 v14, 0xbfb8aa3b, v15
	v_rcp_f32_e32 v20, v20
	v_rcp_f32_e32 v21, v21
	v_lshlrev_b32_e32 v22, 16, v26
	v_and_b32_e32 v23, 0xffff0000, v26
	v_exp_f32_e32 v26, v14
	v_pk_mul_f32 v[14:15], v[20:21], v[22:23]
	v_add_f32_e32 v20, 1.0, v24
	v_rcp_f32_e32 v20, v20
	v_add_f32_e32 v21, 1.0, v26
	v_rcp_f32_e32 v21, v21
	v_lshlrev_b32_e32 v22, 16, v25
	v_and_b32_e32 v23, 0xffff0000, v25
	v_cvt_pk_bf16_f32 v8, v8, v9
	v_pk_mul_f32 v[20:21], v[20:21], v[22:23]
	v_lshlrev_b32_e32 v22, 16, v27
	v_and_b32_e32 v23, 0xffff0000, v27
	v_pk_mul_f32 v[22:23], v[10:11], v[22:23]
	v_cvt_pk_bf16_f32 v9, v20, v21
	v_cvt_pk_bf16_f32 v10, v14, v15
	v_cvt_pk_bf16_f32 v11, v22, v23
	global_store_dwordx4 v[12:13], v[8:11], off sc1
	s_nop 1
	v_exp_f32_e32 v10, v0
	v_mul_f32_e32 v0, 0xbfb8aa3b, v1
	v_exp_f32_e32 v11, v0
	s_waitcnt vmcnt(1)
	v_lshlrev_b32_e32 v8, 16, v16
	v_and_b32_e32 v9, 0xffff0000, v16
	v_pk_mul_f32 v[0:1], v[4:5], v[8:9]
	v_add_f32_e32 v4, 1.0, v10
	v_add_f32_e32 v5, 1.0, v11
	v_rcp_f32_e32 v4, v4
	v_rcp_f32_e32 v5, v5
	v_lshlrev_b32_e32 v8, 16, v18
	v_and_b32_e32 v9, 0xffff0000, v18
	v_cvt_pk_bf16_f32 v0, v0, v1
	v_pk_mul_f32 v[4:5], v[4:5], v[8:9]
	v_lshlrev_b32_e32 v8, 16, v17
	v_and_b32_e32 v9, 0xffff0000, v17
	v_pk_mul_f32 v[6:7], v[6:7], v[8:9]
	v_lshlrev_b32_e32 v8, 16, v19
	v_and_b32_e32 v9, 0xffff0000, v19
	v_pk_mul_f32 v[8:9], v[2:3], v[8:9]
	v_cvt_pk_bf16_f32 v1, v6, v7
	v_cvt_pk_bf16_f32 v2, v4, v5
	v_cvt_pk_bf16_f32 v3, v8, v9
	global_store_dwordx4 v[12:13], v[0:3], off offset:256 sc1
	s_cbranch_vccnz .LBB0_157
	s_andn2_b64 vcc, exec, s[6:7]
	s_cbranch_vccnz .LBB0_156
	s_barrier
	s_branch .LBB0_156

.LBB0_176:
	s_ashr_i32 s11, s10, 6
	s_lshl_b32 s12, s11, 8
	s_ashr_i32 s13, s12, 31
	s_lshl_b64 s[12:13], s[12:13], 12
	s_add_u32 s12, s6, s12
	s_addc_u32 s13, s7, s13
	s_and_b32 s4, s8, 0xc0
	s_lshl_b32 s4, s4, 1
	s_add_u32 s12, s12, s4
	s_addc_u32 s13, s13, 0
	v_lshl_add_u64 v[4:5], s[12:13], 0, v[160:161]
	v_lshl_add_u64 v[6:7], v[4:5], 0, v[140:141]
	global_load_dwordx4 v[0:3], v[6:7], off offset:512
	v_lshl_add_u64 v[8:9], v[4:5], 0, v[142:143]
	v_lshl_add_u64 v[10:11], v[4:5], 0, v[144:145]
	v_lshl_add_u64 v[4:5], v[4:5], 0, v[146:147]
	s_lshl_b32 s11, s11, 12
	s_and_b32 s12, s9, 0xf00
	s_or_b32 s11, s11, s12
	v_mov_b32_e32 v149, v161
	v_add_u32_e32 v12, v159, v167
	s_add_i32 s10, s10, s33
	s_add_i32 s8, s8, s91
	s_add_i32 s9, s9, s92
	s_cmpk_lt_i32 s10, 0x100
	s_waitcnt vmcnt(0)
	ds_write_b16 v154, v0
	ds_write_b16_d16_hi v154, v0 offset:520
	ds_write_b16 v154, v1 offset:1040
	ds_write_b16_d16_hi v154, v1 offset:1560
	ds_write_b16 v154, v2 offset:2080
	ds_write_b16_d16_hi v154, v2 offset:2600
	ds_write_b16 v154, v3 offset:3120
	ds_write_b16_d16_hi v154, v3 offset:3640
	global_load_dwordx4 v[0:3], v[8:9], off offset:512
	s_waitcnt vmcnt(0)
	ds_write_b16 v155, v0
	ds_write_b16_d16_hi v155, v0 offset:520
	ds_write_b16 v155, v1 offset:1040
	ds_write_b16_d16_hi v155, v1 offset:1560
	ds_write_b16 v155, v2 offset:2080
	ds_write_b16_d16_hi v155, v2 offset:2600
	ds_write_b16 v155, v3 offset:3120
	ds_write_b16_d16_hi v155, v3 offset:3640
	global_load_dwordx4 v[0:3], v[10:11], off offset:512
	s_waitcnt vmcnt(0)
	ds_write_b16 v156, v0
	ds_write_b16_d16_hi v156, v0 offset:520
	ds_write_b16 v156, v1 offset:1040
	ds_write_b16_d16_hi v156, v1 offset:1560
	ds_write_b16 v156, v2 offset:2080
	ds_write_b16_d16_hi v156, v2 offset:2600
	ds_write_b16 v156, v3 offset:3120
	ds_write_b16_d16_hi v156, v3 offset:3640
	global_load_dwordx4 v[0:3], v[4:5], off offset:512
	s_waitcnt vmcnt(0)
	ds_write_b16 v157, v0
	ds_write_b16_d16_hi v157, v0 offset:520
	ds_write_b16 v157, v1 offset:1040
	ds_write_b16_d16_hi v157, v1 offset:1560
	ds_write_b16 v157, v2 offset:2080
	ds_write_b16_d16_hi v157, v2 offset:2600
	ds_write_b16 v157, v3 offset:3120
	ds_write_b16_d16_hi v157, v3 offset:3640
	global_load_dwordx4 v[0:3], v[6:7], off
	s_waitcnt vmcnt(0)
	ds_write_b128 v171, v[0:3] offset:33280
	global_load_dwordx4 v[0:3], v[8:9], off
	s_waitcnt vmcnt(0)
	ds_write_b128 v172, v[0:3] offset:33280
	global_load_dwordx4 v[0:3], v[10:11], off
	s_waitcnt vmcnt(0)
	ds_write_b128 v173, v[0:3] offset:33280
	global_load_dwordx4 v[0:3], v[4:5], off
	s_waitcnt vmcnt(0)
	ds_write_b128 v174, v[0:3] offset:33280
	v_add_u32_e32 v0, s11, v158
	v_ashrrev_i32_e32 v1, 31, v0
	v_lshlrev_b64 v[152:153], 11, v[0:1]
	v_lshl_add_u64 v[0:1], s[64:65], 0, v[152:153]
	v_lshl_add_u64 v[0:1], v[0:1], 0, s[4:5]
	v_lshl_add_u64 v[4:5], v[0:1], 0, v[148:149]
	s_waitcnt lgkmcnt(0)
	s_barrier
	global_load_dwordx4 v[0:3], v[4:5], off offset:1536
	global_load_dwordx4 v[136:139], v[4:5], off offset:1568
	global_load_dwordx4 v[132:135], v[4:5], off offset:1600
	global_load_dwordx4 v[128:131], v[4:5], off offset:1632
	ds_read_b128 v[4:7], v12 offset:33280
	ds_read_b128 v[8:11], v12 offset:33312
	s_waitcnt vmcnt(3) lgkmcnt(1)
	v_mfma_f32_32x32x16_bf16 v[112:127], v[4:7], v[0:3], 0
	ds_read_b128 v[4:7], v12 offset:33344
	s_waitcnt vmcnt(2) lgkmcnt(1)
	v_mfma_f32_32x32x16_bf16 v[112:127], v[8:11], v[136:139], v[112:127]
	s_waitcnt vmcnt(1) lgkmcnt(0)
	v_mfma_f32_32x32x16_bf16 v[112:127], v[4:7], v[132:135], v[112:127]
	ds_read_b128 v[4:7], v12 offset:33376
	s_waitcnt vmcnt(0) lgkmcnt(0)
	v_mfma_f32_32x32x16_bf16 v[112:127], v[4:7], v[128:131], v[112:127]
	ds_read_b128 v[4:7], v12 offset:37888
	s_waitcnt lgkmcnt(0)
	v_mfma_f32_32x32x16_bf16 v[96:111], v[4:7], v[0:3], 0
	ds_read_b128 v[4:7], v12 offset:37920
	s_waitcnt lgkmcnt(0)
	v_mfma_f32_32x32x16_bf16 v[96:111], v[4:7], v[136:139], v[96:111]
	ds_read_b128 v[4:7], v12 offset:37952
	s_waitcnt lgkmcnt(0)
	v_mfma_f32_32x32x16_bf16 v[96:111], v[4:7], v[132:135], v[96:111]
	ds_read_b128 v[4:7], v12 offset:37984
	s_waitcnt lgkmcnt(0)
	v_mfma_f32_32x32x16_bf16 v[96:111], v[4:7], v[128:131], v[96:111]
	ds_read_b128 v[4:7], v12 offset:42496
	s_waitcnt lgkmcnt(0)
	v_mfma_f32_32x32x16_bf16 v[80:95], v[4:7], v[0:3], 0
	ds_read_b128 v[4:7], v12 offset:42528
	s_waitcnt lgkmcnt(0)
	v_mfma_f32_32x32x16_bf16 v[80:95], v[4:7], v[136:139], v[80:95]
	ds_read_b128 v[4:7], v12 offset:42560
	s_waitcnt lgkmcnt(0)
	v_mfma_f32_32x32x16_bf16 v[80:95], v[4:7], v[132:135], v[80:95]
	ds_read_b128 v[4:7], v12 offset:42592
	s_waitcnt lgkmcnt(0)
	v_mfma_f32_32x32x16_bf16 v[80:95], v[4:7], v[128:131], v[80:95]
	ds_read_b128 v[4:7], v12 offset:47104
	s_waitcnt lgkmcnt(0)
	v_mfma_f32_32x32x16_bf16 v[64:79], v[4:7], v[0:3], 0
	ds_read_b128 v[4:7], v12 offset:47136
	s_waitcnt lgkmcnt(0)
	v_mfma_f32_32x32x16_bf16 v[64:79], v[4:7], v[136:139], v[64:79]
	ds_read_b128 v[4:7], v12 offset:47168
	s_waitcnt lgkmcnt(0)
	v_mfma_f32_32x32x16_bf16 v[64:79], v[4:7], v[132:135], v[64:79]
	ds_read_b128 v[4:7], v12 offset:47200
	s_waitcnt lgkmcnt(0)
	v_mfma_f32_32x32x16_bf16 v[64:79], v[4:7], v[128:131], v[64:79]
	ds_read_b128 v[4:7], v12 offset:51712
	s_waitcnt lgkmcnt(0)
	v_mfma_f32_32x32x16_bf16 v[48:63], v[4:7], v[0:3], 0
	ds_read_b128 v[4:7], v12 offset:51744
	s_waitcnt lgkmcnt(0)
	v_mfma_f32_32x32x16_bf16 v[48:63], v[4:7], v[136:139], v[48:63]
	ds_read_b128 v[4:7], v12 offset:51776
	s_waitcnt lgkmcnt(0)
	v_mfma_f32_32x32x16_bf16 v[48:63], v[4:7], v[132:135], v[48:63]
	ds_read_b128 v[4:7], v12 offset:51808
	s_waitcnt lgkmcnt(0)
	v_mfma_f32_32x32x16_bf16 v[48:63], v[4:7], v[128:131], v[48:63]
	ds_read_b128 v[4:7], v12 offset:56320
	s_waitcnt lgkmcnt(0)
	v_mfma_f32_32x32x16_bf16 v[32:47], v[4:7], v[0:3], 0
	ds_read_b128 v[4:7], v12 offset:56352
	s_waitcnt lgkmcnt(0)
	v_mfma_f32_32x32x16_bf16 v[32:47], v[4:7], v[136:139], v[32:47]
	ds_read_b128 v[4:7], v12 offset:56384
	s_waitcnt lgkmcnt(0)
	v_mfma_f32_32x32x16_bf16 v[32:47], v[4:7], v[132:135], v[32:47]
	ds_read_b128 v[4:7], v12 offset:56416
	s_waitcnt lgkmcnt(0)
	v_mfma_f32_32x32x16_bf16 v[32:47], v[4:7], v[128:131], v[32:47]
	ds_read_b128 v[4:7], v12 offset:60928
	s_waitcnt lgkmcnt(0)
	v_mfma_f32_32x32x16_bf16 v[16:31], v[4:7], v[0:3], 0
	ds_read_b128 v[4:7], v12 offset:60960
	s_waitcnt lgkmcnt(0)
	v_mfma_f32_32x32x16_bf16 v[16:31], v[4:7], v[136:139], v[16:31]
	ds_read_b128 v[4:7], v12 offset:60992
	s_waitcnt lgkmcnt(0)
	v_mfma_f32_32x32x16_bf16 v[16:31], v[4:7], v[132:135], v[16:31]
	ds_read_b128 v[4:7], v12 offset:61024
	s_waitcnt lgkmcnt(0)
	v_mfma_f32_32x32x16_bf16 v[16:31], v[4:7], v[128:131], v[16:31]
	ds_read_b128 v[4:7], v169 offset:32256
	ds_read_b128 v[176:179], v169 offset:32288
	s_waitcnt lgkmcnt(1)
	v_mfma_f32_32x32x16_bf16 v[0:15], v[4:7], v[0:3], 0
	s_waitcnt lgkmcnt(0)
	v_mfma_f32_32x32x16_bf16 v[0:15], v[176:179], v[136:139], v[0:15]
	ds_read_b128 v[136:139], v169 offset:32320
	s_waitcnt lgkmcnt(0)
	v_mfma_f32_32x32x16_bf16 v[0:15], v[136:139], v[132:135], v[0:15]
	ds_read_b128 v[132:135], v169 offset:32352
	s_waitcnt lgkmcnt(0)
	v_mfma_f32_32x32x16_bf16 v[0:15], v[132:135], v[128:131], v[0:15]
	v_max3_f32 v128, v112, s96, v113
	v_max3_f32 v128, v128, v114, v115
	v_max3_f32 v128, v128, v116, v117
	v_max3_f32 v128, v128, v118, v119
	v_max3_f32 v128, v128, v120, v121
	v_max3_f32 v128, v128, v122, v123
	v_max3_f32 v128, v128, v124, v125
	v_max3_f32 v128, v128, v126, v127
	v_max3_f32 v128, v128, v96, v97
	v_max3_f32 v128, v128, v98, v99
	v_max3_f32 v128, v128, v100, v101
	v_max3_f32 v128, v128, v102, v103
	v_max3_f32 v128, v128, v104, v105
	v_max3_f32 v128, v128, v106, v107
	v_max3_f32 v128, v128, v108, v109
	v_max3_f32 v128, v128, v110, v111
	v_max3_f32 v128, v128, v80, v81
	v_max3_f32 v128, v128, v82, v83
	v_max3_f32 v128, v128, v84, v85
	v_max3_f32 v128, v128, v86, v87
	v_max3_f32 v128, v128, v88, v89
	v_max3_f32 v128, v128, v90, v91
	v_max3_f32 v128, v128, v92, v93
	v_max3_f32 v128, v128, v94, v95
	v_max3_f32 v128, v128, v64, v65
	v_max3_f32 v128, v128, v66, v67
	v_max3_f32 v128, v128, v68, v69
	v_max3_f32 v128, v128, v70, v71
	v_max3_f32 v128, v128, v72, v73
	v_max3_f32 v128, v128, v74, v75
	v_max3_f32 v128, v128, v76, v77
	v_max3_f32 v128, v128, v78, v79
	v_max3_f32 v128, v128, v48, v49
	v_max3_f32 v128, v128, v50, v51
	v_max3_f32 v128, v128, v52, v53
	v_max3_f32 v128, v128, v54, v55
	v_max3_f32 v128, v128, v56, v57
	v_max3_f32 v128, v128, v58, v59
	v_max3_f32 v128, v128, v60, v61
	v_max3_f32 v128, v128, v62, v63
	v_max3_f32 v128, v128, v32, v33
	v_max3_f32 v128, v128, v34, v35
	v_max3_f32 v128, v128, v36, v37
	v_max3_f32 v128, v128, v38, v39
	v_max3_f32 v128, v128, v40, v41
	v_max3_f32 v128, v128, v42, v43
	v_max3_f32 v128, v128, v44, v45
	v_max3_f32 v128, v128, v46, v47
	v_max3_f32 v128, v128, v16, v17
	v_max3_f32 v128, v128, v18, v19
	v_max3_f32 v128, v128, v20, v21
	v_max3_f32 v128, v128, v22, v23
	v_max3_f32 v128, v128, v24, v25
	v_max3_f32 v128, v128, v26, v27
	v_max3_f32 v128, v128, v28, v29
	v_max3_f32 v128, v128, v30, v31
	v_max3_f32 v128, v128, v0, v1
	v_max3_f32 v128, v128, v2, v3
	v_max3_f32 v128, v128, v4, v5
	v_max3_f32 v128, v128, v6, v7
	v_max3_f32 v128, v128, v8, v9
	v_max3_f32 v128, v128, v10, v11
	v_max3_f32 v128, v128, v12, v13
	v_max3_f32 v128, v128, v14, v15
	ds_bpermute_b32 v129, v170, v128
	s_waitcnt lgkmcnt(0)
	v_max_f32_e32 v129, v129, v129
	v_max_f32_e32 v162, v128, v129
	v_sub_f32_e32 v112, v112, v162
	v_exp_f32_e32 v163, v112
	v_sub_f32_e32 v113, v113, v162
	v_exp_f32_e32 v164, v113
	v_sub_f32_e32 v113, v114, v162
	v_exp_f32_e32 v165, v113
	v_sub_f32_e32 v113, v115, v162
	v_exp_f32_e32 v192, v113
	v_sub_f32_e32 v113, v116, v162
	v_add_f32_e32 v112, 0, v163
	v_exp_f32_e32 v193, v113
	v_sub_f32_e32 v113, v117, v162
	v_add_f32_e32 v112, v164, v112
	v_exp_f32_e32 v194, v113
	v_sub_f32_e32 v113, v118, v162
	v_add_f32_e32 v112, v165, v112
	v_exp_f32_e32 v195, v113
	v_sub_f32_e32 v113, v119, v162
	v_add_f32_e32 v112, v192, v112
	v_exp_f32_e32 v196, v113
	v_add_f32_e32 v112, v193, v112
	v_add_f32_e32 v112, v194, v112
	v_add_f32_e32 v112, v195, v112
	v_add_f32_e32 v113, v196, v112
	v_sub_f32_e32 v112, v120, v162
	v_exp_f32_e32 v112, v112
	v_sub_f32_e32 v96, v96, v162
	v_exp_f32_e32 v96, v96
	v_sub_f32_e32 v97, v97, v162
	v_add_f32_e32 v114, v112, v113
	v_sub_f32_e32 v113, v121, v162
	v_exp_f32_e32 v113, v113
	v_exp_f32_e32 v97, v97
	v_sub_f32_e32 v98, v98, v162
	v_exp_f32_e32 v98, v98
	v_add_f32_e32 v115, v113, v114
	v_sub_f32_e32 v114, v122, v162
	v_exp_f32_e32 v114, v114
	v_sub_f32_e32 v99, v99, v162
	v_exp_f32_e32 v99, v99
	v_sub_f32_e32 v100, v100, v162
	v_add_f32_e32 v116, v114, v115
	v_sub_f32_e32 v115, v123, v162
	v_exp_f32_e32 v115, v115
	v_exp_f32_e32 v100, v100
	v_sub_f32_e32 v101, v101, v162
	v_exp_f32_e32 v101, v101
	v_add_f32_e32 v117, v115, v116
	v_sub_f32_e32 v116, v124, v162
	v_exp_f32_e32 v116, v116
	v_sub_f32_e32 v102, v102, v162
	v_exp_f32_e32 v102, v102
	v_sub_f32_e32 v103, v103, v162
	v_add_f32_e32 v118, v116, v117
	v_sub_f32_e32 v117, v125, v162
	v_exp_f32_e32 v117, v117
	v_sub_f32_e32 v80, v80, v162
	v_exp_f32_e32 v80, v80
	v_sub_f32_e32 v81, v81, v162
	v_add_f32_e32 v119, v117, v118
	v_sub_f32_e32 v118, v126, v162
	v_exp_f32_e32 v118, v118
	v_exp_f32_e32 v81, v81
	v_sub_f32_e32 v82, v82, v162
	v_exp_f32_e32 v82, v82
	v_add_f32_e32 v120, v118, v119
	v_sub_f32_e32 v119, v127, v162
	v_exp_f32_e32 v119, v119
	v_sub_f32_e32 v83, v83, v162
	v_exp_f32_e32 v83, v83
	v_sub_f32_e32 v84, v84, v162
	v_add_f32_e32 v120, v119, v120
	v_add_f32_e32 v120, v96, v120
	v_add_f32_e32 v120, v97, v120
	v_add_f32_e32 v120, v98, v120
	v_add_f32_e32 v120, v99, v120
	v_add_f32_e32 v120, v100, v120
	v_add_f32_e32 v120, v101, v120
	v_add_f32_e32 v121, v102, v120
	v_exp_f32_e32 v120, v103
	v_sub_f32_e32 v103, v104, v162
	v_exp_f32_e32 v103, v103
	v_sub_f32_e32 v104, v105, v162
	v_exp_f32_e32 v104, v104
	v_sub_f32_e32 v105, v106, v162
	v_exp_f32_e32 v105, v105
	v_sub_f32_e32 v106, v107, v162
	v_add_f32_e32 v121, v120, v121
	v_exp_f32_e32 v106, v106
	v_sub_f32_e32 v107, v108, v162
	v_add_f32_e32 v121, v103, v121
	v_exp_f32_e32 v107, v107
	v_sub_f32_e32 v108, v109, v162
	v_add_f32_e32 v121, v104, v121
	v_exp_f32_e32 v108, v108
	v_sub_f32_e32 v109, v110, v162
	v_add_f32_e32 v121, v105, v121
	v_exp_f32_e32 v109, v109
	v_sub_f32_e32 v110, v111, v162
	v_add_f32_e32 v121, v106, v121
	v_exp_f32_e32 v110, v110
	v_add_f32_e32 v121, v107, v121
	v_add_f32_e32 v121, v108, v121
	v_add_f32_e32 v121, v109, v121
	v_add_f32_e32 v111, v110, v121
	v_add_f32_e32 v111, v80, v111
	v_exp_f32_e32 v84, v84
	v_sub_f32_e32 v85, v85, v162
	v_add_f32_e32 v111, v81, v111
	v_exp_f32_e32 v85, v85
	v_sub_f32_e32 v86, v86, v162
	v_add_f32_e32 v111, v82, v111
	v_exp_f32_e32 v86, v86
	v_add_f32_e32 v111, v83, v111
	v_add_f32_e32 v111, v84, v111
	v_add_f32_e32 v111, v85, v111
	v_sub_f32_e32 v87, v87, v162
	v_add_f32_e32 v121, v86, v111
	v_exp_f32_e32 v111, v87
	v_sub_f32_e32 v87, v88, v162
	v_exp_f32_e32 v87, v87
	v_sub_f32_e32 v88, v89, v162
	v_exp_f32_e32 v88, v88
	v_sub_f32_e32 v89, v90, v162
	v_exp_f32_e32 v89, v89
	v_sub_f32_e32 v90, v91, v162
	v_add_f32_e32 v121, v111, v121
	v_exp_f32_e32 v90, v90
	v_sub_f32_e32 v91, v92, v162
	v_add_f32_e32 v121, v87, v121
	v_exp_f32_e32 v91, v91
	v_sub_f32_e32 v92, v93, v162
	v_add_f32_e32 v121, v88, v121
	v_exp_f32_e32 v92, v92
	v_sub_f32_e32 v93, v94, v162
	v_add_f32_e32 v121, v89, v121
	v_exp_f32_e32 v93, v93
	v_sub_f32_e32 v94, v95, v162
	v_add_f32_e32 v121, v90, v121
	v_exp_f32_e32 v94, v94
	v_sub_f32_e32 v64, v64, v162
	v_add_f32_e32 v121, v91, v121
	v_exp_f32_e32 v64, v64
	v_sub_f32_e32 v65, v65, v162
	v_add_f32_e32 v121, v92, v121
	v_exp_f32_e32 v65, v65
	v_sub_f32_e32 v66, v66, v162
	v_add_f32_e32 v121, v93, v121
	v_exp_f32_e32 v66, v66
	v_sub_f32_e32 v67, v67, v162
	v_add_f32_e32 v95, v94, v121
	v_exp_f32_e32 v67, v67
	v_sub_f32_e32 v68, v68, v162
	v_add_f32_e32 v95, v64, v95
	v_exp_f32_e32 v68, v68
	v_sub_f32_e32 v69, v69, v162
	v_add_f32_e32 v95, v65, v95
	v_exp_f32_e32 v69, v69
	v_sub_f32_e32 v70, v70, v162
	v_add_f32_e32 v95, v66, v95
	v_exp_f32_e32 v70, v70
	v_add_f32_e32 v95, v67, v95
	v_add_f32_e32 v95, v68, v95
	v_add_f32_e32 v95, v69, v95
	v_sub_f32_e32 v71, v71, v162
	v_add_f32_e32 v121, v70, v95
	v_exp_f32_e32 v95, v71
	v_sub_f32_e32 v71, v72, v162
	v_exp_f32_e32 v71, v71
	v_sub_f32_e32 v72, v73, v162
	v_exp_f32_e32 v72, v72
	v_sub_f32_e32 v73, v74, v162
	v_exp_f32_e32 v73, v73
	v_sub_f32_e32 v74, v75, v162
	v_add_f32_e32 v121, v95, v121
	v_exp_f32_e32 v74, v74
	v_sub_f32_e32 v75, v76, v162
	v_add_f32_e32 v121, v71, v121
	v_exp_f32_e32 v75, v75
	v_sub_f32_e32 v76, v77, v162
	v_add_f32_e32 v121, v72, v121
	v_exp_f32_e32 v76, v76
	v_sub_f32_e32 v77, v78, v162
	v_add_f32_e32 v121, v73, v121
	v_exp_f32_e32 v77, v77
	v_sub_f32_e32 v78, v79, v162
	v_add_f32_e32 v121, v74, v121
	v_exp_f32_e32 v78, v78
	v_sub_f32_e32 v48, v48, v162
	v_add_f32_e32 v121, v75, v121
	v_exp_f32_e32 v48, v48
	v_sub_f32_e32 v49, v49, v162
	v_add_f32_e32 v121, v76, v121
	v_exp_f32_e32 v49, v49
	v_sub_f32_e32 v50, v50, v162
	v_add_f32_e32 v121, v77, v121
	v_exp_f32_e32 v50, v50
	v_sub_f32_e32 v51, v51, v162
	v_add_f32_e32 v79, v78, v121
	v_exp_f32_e32 v51, v51
	v_sub_f32_e32 v52, v52, v162
	v_add_f32_e32 v79, v48, v79
	v_exp_f32_e32 v52, v52
	v_sub_f32_e32 v53, v53, v162
	v_add_f32_e32 v79, v49, v79
	v_exp_f32_e32 v53, v53
	v_sub_f32_e32 v54, v54, v162
	v_add_f32_e32 v79, v50, v79
	v_exp_f32_e32 v54, v54
	v_add_f32_e32 v79, v51, v79
	v_add_f32_e32 v79, v52, v79
	v_add_f32_e32 v79, v53, v79
	v_sub_f32_e32 v55, v55, v162
	v_add_f32_e32 v121, v54, v79
	v_exp_f32_e32 v79, v55
	v_sub_f32_e32 v55, v56, v162
	v_exp_f32_e32 v55, v55
	v_sub_f32_e32 v56, v57, v162
	v_exp_f32_e32 v56, v56
	v_sub_f32_e32 v57, v58, v162
	v_exp_f32_e32 v57, v57
	v_sub_f32_e32 v58, v59, v162
	v_add_f32_e32 v121, v79, v121
	v_exp_f32_e32 v58, v58
	v_sub_f32_e32 v59, v60, v162
	v_add_f32_e32 v121, v55, v121
	v_exp_f32_e32 v59, v59
	v_sub_f32_e32 v60, v61, v162
	v_add_f32_e32 v121, v56, v121
	v_exp_f32_e32 v60, v60
	v_sub_f32_e32 v61, v62, v162
	v_add_f32_e32 v121, v57, v121
	v_exp_f32_e32 v61, v61
	v_sub_f32_e32 v63, v63, v162
	v_add_f32_e32 v121, v58, v121
	v_exp_f32_e32 v63, v63
	v_add_f32_e32 v121, v59, v121
	v_add_f32_e32 v121, v60, v121
	v_add_f32_e32 v62, v61, v121
	v_sub_f32_e32 v32, v32, v162
	v_add_f32_e32 v121, v63, v62
	v_exp_f32_e32 v62, v32
	v_sub_f32_e32 v33, v33, v162
	v_sub_f32_e32 v16, v16, v162
	v_sub_f32_e32 v17, v17, v162
	v_add_f32_e32 v32, v62, v121
	v_exp_f32_e32 v121, v33
	v_sub_f32_e32 v33, v34, v162
	v_exp_f32_e32 v122, v33
	v_sub_f32_e32 v33, v35, v162
	v_exp_f32_e32 v123, v33
	v_sub_f32_e32 v33, v36, v162
	v_exp_f32_e32 v36, v33
	v_sub_f32_e32 v33, v37, v162
	v_add_f32_e32 v32, v121, v32
	v_exp_f32_e32 v37, v33
	v_sub_f32_e32 v33, v38, v162
	v_add_f32_e32 v32, v122, v32
	v_exp_f32_e32 v38, v33
	v_sub_f32_e32 v33, v39, v162
	v_add_f32_e32 v32, v123, v32
	v_exp_f32_e32 v124, v33
	v_sub_f32_e32 v33, v40, v162
	v_add_f32_e32 v32, v36, v32
	v_exp_f32_e32 v39, v33
	v_sub_f32_e32 v33, v41, v162
	v_add_f32_e32 v32, v37, v32
	v_exp_f32_e32 v40, v33
	v_sub_f32_e32 v33, v42, v162
	v_add_f32_e32 v32, v38, v32
	v_exp_f32_e32 v41, v33
	v_sub_f32_e32 v33, v43, v162
	v_add_f32_e32 v32, v124, v32
	v_exp_f32_e32 v42, v33
	v_sub_f32_e32 v33, v44, v162
	v_add_f32_e32 v32, v39, v32
	v_exp_f32_e32 v43, v33
	v_sub_f32_e32 v33, v45, v162
	v_add_f32_e32 v32, v40, v32
	v_exp_f32_e32 v44, v33
	v_sub_f32_e32 v33, v46, v162
	v_add_f32_e32 v32, v41, v32
	v_exp_f32_e32 v45, v33
	v_sub_f32_e32 v33, v47, v162
	v_add_f32_e32 v32, v42, v32
	v_exp_f32_e32 v47, v33
	v_add_f32_e32 v32, v43, v32
	v_exp_f32_e32 v46, v16
	v_add_f32_e32 v32, v44, v32
	v_exp_f32_e32 v125, v17
	v_sub_f32_e32 v17, v18, v162
	v_add_f32_e32 v32, v45, v32
	v_exp_f32_e32 v126, v17
	v_sub_f32_e32 v17, v19, v162
	v_add_f32_e32 v32, v47, v32
	v_exp_f32_e32 v127, v17
	v_sub_f32_e32 v17, v20, v162
	v_add_f32_e32 v16, v46, v32
	v_exp_f32_e32 v128, v17
	v_sub_f32_e32 v17, v21, v162
	v_add_f32_e32 v16, v125, v16
	v_exp_f32_e32 v129, v17
	v_sub_f32_e32 v17, v22, v162
	v_add_f32_e32 v16, v126, v16
	v_exp_f32_e32 v130, v17
	v_sub_f32_e32 v17, v23, v162
	v_add_f32_e32 v16, v127, v16
	v_exp_f32_e32 v132, v17
	v_sub_f32_e32 v17, v24, v162
	v_add_f32_e32 v16, v128, v16
	v_exp_f32_e32 v131, v17
	v_sub_f32_e32 v17, v25, v162
	v_add_f32_e32 v16, v129, v16
	v_exp_f32_e32 v133, v17
	v_sub_f32_e32 v17, v26, v162
	v_add_f32_e32 v16, v130, v16
	v_exp_f32_e32 v134, v17
	v_sub_f32_e32 v17, v27, v162
	v_add_f32_e32 v16, v132, v16
	v_exp_f32_e32 v135, v17
	v_sub_f32_e32 v17, v28, v162
	v_add_f32_e32 v16, v131, v16
	v_exp_f32_e32 v136, v17
	v_sub_f32_e32 v17, v29, v162
	v_add_f32_e32 v16, v133, v16
	v_exp_f32_e32 v137, v17
	v_sub_f32_e32 v17, v30, v162
	v_add_f32_e32 v16, v134, v16
	v_exp_f32_e32 v138, v17
	v_sub_f32_e32 v17, v31, v162
	v_add_f32_e32 v16, v135, v16
	v_exp_f32_e32 v149, v17
	v_sub_f32_e32 v0, v0, v162
	v_add_f32_e32 v16, v136, v16
	v_exp_f32_e32 v139, v0
	v_sub_f32_e32 v1, v1, v162
	v_add_f32_e32 v16, v137, v16
	v_exp_f32_e32 v151, v1
	v_sub_f32_e32 v1, v2, v162
	v_add_f32_e32 v16, v138, v16
	v_exp_f32_e32 v176, v1
	v_sub_f32_e32 v1, v3, v162
	v_add_f32_e32 v16, v149, v16
	v_exp_f32_e32 v177, v1
	v_sub_f32_e32 v1, v4, v162
	v_add_f32_e32 v0, v139, v16
	v_exp_f32_e32 v178, v1
	v_sub_f32_e32 v1, v5, v162
	v_add_f32_e32 v0, v151, v0
	v_exp_f32_e32 v179, v1
	v_sub_f32_e32 v1, v6, v162
	v_add_f32_e32 v0, v176, v0
	v_exp_f32_e32 v180, v1
	v_sub_f32_e32 v1, v7, v162
	v_add_f32_e32 v0, v177, v0
	v_exp_f32_e32 v182, v1
	v_sub_f32_e32 v1, v8, v162
	v_add_f32_e32 v0, v178, v0
	v_exp_f32_e32 v181, v1
	v_sub_f32_e32 v1, v9, v162
	v_add_f32_e32 v0, v179, v0
	v_exp_f32_e32 v183, v1
	v_sub_f32_e32 v1, v10, v162
	v_add_f32_e32 v0, v180, v0
	v_exp_f32_e32 v184, v1
	v_sub_f32_e32 v1, v11, v162
	v_add_f32_e32 v0, v182, v0
	v_exp_f32_e32 v185, v1
	v_sub_f32_e32 v1, v12, v162
	v_add_f32_e32 v0, v181, v0
	v_exp_f32_e32 v186, v1
	v_sub_f32_e32 v1, v13, v162
	v_add_f32_e32 v0, v183, v0
	v_exp_f32_e32 v187, v1
	v_sub_f32_e32 v1, v14, v162
	v_add_f32_e32 v0, v184, v0
	v_exp_f32_e32 v189, v1
	v_sub_f32_e32 v1, v15, v162
	v_add_f32_e32 v0, v185, v0
	v_exp_f32_e32 v191, v1
	v_add_f32_e32 v0, v186, v0
	v_add_f32_e32 v0, v187, v0
	v_add_f32_e32 v0, v189, v0
	v_add_f32_e32 v188, v191, v0
	ds_read2_b64 v[0:3], v175 offset1:2
	ds_read2_b64 v[32:35], v175 offset0:4 offset1:6
	v_cvt_pk_bf16_f32 v16, v163, v164
	v_cvt_pk_bf16_f32 v17, v165, v192
	v_cvt_pk_bf16_f32 v18, v193, v194
	v_cvt_pk_bf16_f32 v19, v195, v196
	v_add_u32_e32 v162, 0x4000, v175
	ds_read2_b64 v[20:23], v162 offset0:32 offset1:34
	s_waitcnt lgkmcnt(2)
	v_mfma_f32_32x32x16_bf16 v[0:15], v[0:3], v[16:19], 0
	v_cvt_pk_bf16_f32 v112, v112, v113
	v_cvt_pk_bf16_f32 v113, v114, v115
	v_cvt_pk_bf16_f32 v114, v116, v117
	v_cvt_pk_bf16_f32 v115, v118, v119
	ds_bpermute_b32 v190, v170, v188
	s_waitcnt lgkmcnt(2)
	v_mfma_f32_32x32x16_bf16 v[0:15], v[32:35], v[112:115], v[0:15]
	ds_read2_b64 v[32:35], v162 offset0:36 offset1:38
	s_waitcnt lgkmcnt(2)
	v_mfma_f32_32x32x16_bf16 v[16:31], v[20:23], v[16:19], 0
	s_waitcnt lgkmcnt(0)
	v_mfma_f32_32x32x16_bf16 v[16:31], v[32:35], v[112:115], v[16:31]
	v_cvt_pk_bf16_f32 v32, v96, v97
	v_cvt_pk_bf16_f32 v33, v98, v99
	ds_read2_b64 v[96:99], v175 offset0:8 offset1:10
	v_cvt_pk_bf16_f32 v34, v100, v101
	v_cvt_pk_bf16_f32 v35, v102, v120
	s_waitcnt lgkmcnt(0)
	s_nop 0
	v_mfma_f32_32x32x16_bf16 v[0:15], v[96:99], v[32:35], v[0:15]
	ds_read2_b64 v[96:99], v162 offset0:40 offset1:42
	s_waitcnt lgkmcnt(0)
	v_mfma_f32_32x32x16_bf16 v[16:31], v[96:99], v[32:35], v[16:31]
	ds_read2_b64 v[96:99], v175 offset0:12 offset1:14
	v_cvt_pk_bf16_f32 v32, v103, v104
	v_cvt_pk_bf16_f32 v33, v105, v106
	v_cvt_pk_bf16_f32 v34, v107, v108
	v_cvt_pk_bf16_f32 v35, v109, v110
	s_waitcnt lgkmcnt(0)
	s_nop 0
	v_mfma_f32_32x32x16_bf16 v[0:15], v[96:99], v[32:35], v[0:15]
	ds_read2_b64 v[96:99], v162 offset0:44 offset1:46
	s_waitcnt lgkmcnt(0)
	v_mfma_f32_32x32x16_bf16 v[16:31], v[96:99], v[32:35], v[16:31]
	v_cvt_pk_bf16_f32 v32, v80, v81
	v_cvt_pk_bf16_f32 v33, v82, v83
	ds_read2_b64 v[80:83], v175 offset0:16 offset1:18
	v_cvt_pk_bf16_f32 v34, v84, v85
	v_cvt_pk_bf16_f32 v35, v86, v111
	s_waitcnt lgkmcnt(0)
	s_nop 0
	v_mfma_f32_32x32x16_bf16 v[0:15], v[80:83], v[32:35], v[0:15]
	ds_read2_b64 v[80:83], v162 offset0:48 offset1:50
	s_waitcnt lgkmcnt(0)
	v_mfma_f32_32x32x16_bf16 v[16:31], v[80:83], v[32:35], v[16:31]
	ds_read2_b64 v[80:83], v175 offset0:20 offset1:22
	v_cvt_pk_bf16_f32 v32, v87, v88
	v_cvt_pk_bf16_f32 v33, v89, v90
	v_cvt_pk_bf16_f32 v34, v91, v92
	v_cvt_pk_bf16_f32 v35, v93, v94
	s_waitcnt lgkmcnt(0)
	s_nop 0
	v_mfma_f32_32x32x16_bf16 v[0:15], v[80:83], v[32:35], v[0:15]
	ds_read2_b64 v[80:83], v162 offset0:52 offset1:54
	s_waitcnt lgkmcnt(0)
	v_mfma_f32_32x32x16_bf16 v[16:31], v[80:83], v[32:35], v[16:31]
	v_cvt_pk_bf16_f32 v32, v64, v65
	v_cvt_pk_bf16_f32 v33, v66, v67
	ds_read2_b64 v[64:67], v175 offset0:24 offset1:26
	v_cvt_pk_bf16_f32 v34, v68, v69
	v_cvt_pk_bf16_f32 v35, v70, v95
	s_waitcnt lgkmcnt(0)
	s_nop 0
	v_mfma_f32_32x32x16_bf16 v[0:15], v[64:67], v[32:35], v[0:15]
	ds_read2_b64 v[64:67], v162 offset0:56 offset1:58
	s_waitcnt lgkmcnt(0)
	v_mfma_f32_32x32x16_bf16 v[16:31], v[64:67], v[32:35], v[16:31]
	ds_read2_b64 v[64:67], v175 offset0:28 offset1:30
	v_cvt_pk_bf16_f32 v32, v71, v72
	v_cvt_pk_bf16_f32 v33, v73, v74
	v_cvt_pk_bf16_f32 v34, v75, v76
	v_cvt_pk_bf16_f32 v35, v77, v78
	s_waitcnt lgkmcnt(0)
	s_nop 0
	v_mfma_f32_32x32x16_bf16 v[0:15], v[64:67], v[32:35], v[0:15]
	ds_read2_b64 v[64:67], v162 offset0:60 offset1:62
	s_waitcnt lgkmcnt(0)
	v_mfma_f32_32x32x16_bf16 v[16:31], v[64:67], v[32:35], v[16:31]
	v_cvt_pk_bf16_f32 v32, v48, v49
	v_cvt_pk_bf16_f32 v33, v50, v51
	ds_read2_b64 v[48:51], v175 offset0:32 offset1:34
	v_cvt_pk_bf16_f32 v34, v52, v53
	v_cvt_pk_bf16_f32 v35, v54, v79
	s_waitcnt lgkmcnt(0)
	s_nop 0
	v_mfma_f32_32x32x16_bf16 v[0:15], v[48:51], v[32:35], v[0:15]
	ds_read2_b64 v[48:51], v162 offset0:64 offset1:66
	s_waitcnt lgkmcnt(0)
	v_mfma_f32_32x32x16_bf16 v[16:31], v[48:51], v[32:35], v[16:31]
	ds_read2_b64 v[48:51], v175 offset0:36 offset1:38
	v_cvt_pk_bf16_f32 v32, v55, v56
	v_cvt_pk_bf16_f32 v33, v57, v58
	v_cvt_pk_bf16_f32 v34, v59, v60
	v_cvt_pk_bf16_f32 v35, v61, v63
	s_waitcnt lgkmcnt(0)
	s_nop 0
	v_mfma_f32_32x32x16_bf16 v[0:15], v[48:51], v[32:35], v[0:15]
	ds_read2_b64 v[48:51], v162 offset0:68 offset1:70
	s_waitcnt lgkmcnt(0)
	v_mfma_f32_32x32x16_bf16 v[16:31], v[48:51], v[32:35], v[16:31]
	ds_read2_b64 v[48:51], v175 offset0:40 offset1:42
	v_cvt_pk_bf16_f32 v32, v62, v121
	v_cvt_pk_bf16_f32 v33, v122, v123
	v_cvt_pk_bf16_f32 v34, v36, v37
	v_cvt_pk_bf16_f32 v35, v38, v124
	s_waitcnt lgkmcnt(0)
	s_nop 0
	v_mfma_f32_32x32x16_bf16 v[0:15], v[48:51], v[32:35], v[0:15]
	ds_read2_b64 v[48:51], v162 offset0:72 offset1:74
	s_waitcnt lgkmcnt(0)
	v_mfma_f32_32x32x16_bf16 v[16:31], v[48:51], v[32:35], v[16:31]
	v_cvt_pk_bf16_f32 v32, v39, v40
	ds_read2_b64 v[36:39], v175 offset0:44 offset1:46
	v_cvt_pk_bf16_f32 v33, v41, v42
	v_cvt_pk_bf16_f32 v34, v43, v44
	v_cvt_pk_bf16_f32 v35, v45, v47
	s_waitcnt lgkmcnt(0)
	s_nop 0
	v_mfma_f32_32x32x16_bf16 v[0:15], v[36:39], v[32:35], v[0:15]
	ds_read2_b64 v[36:39], v162 offset0:76 offset1:78
	s_waitcnt lgkmcnt(0)
	v_mfma_f32_32x32x16_bf16 v[16:31], v[36:39], v[32:35], v[16:31]
	ds_read2_b64 v[36:39], v175 offset0:48 offset1:50
	v_cvt_pk_bf16_f32 v32, v46, v125
	v_cvt_pk_bf16_f32 v33, v126, v127
	v_cvt_pk_bf16_f32 v34, v128, v129
	v_cvt_pk_bf16_f32 v35, v130, v132
	s_waitcnt lgkmcnt(0)
	s_nop 0
	v_mfma_f32_32x32x16_bf16 v[0:15], v[36:39], v[32:35], v[0:15]
	ds_read2_b64 v[36:39], v162 offset0:80 offset1:82
	s_waitcnt lgkmcnt(0)
	v_mfma_f32_32x32x16_bf16 v[16:31], v[36:39], v[32:35], v[16:31]
	ds_read2_b64 v[36:39], v175 offset0:52 offset1:54
	v_cvt_pk_bf16_f32 v32, v131, v133
	v_cvt_pk_bf16_f32 v33, v134, v135
	v_cvt_pk_bf16_f32 v34, v136, v137
	v_cvt_pk_bf16_f32 v35, v138, v149
	s_waitcnt lgkmcnt(0)
	s_nop 0
	v_mfma_f32_32x32x16_bf16 v[0:15], v[36:39], v[32:35], v[0:15]
	ds_read2_b64 v[36:39], v162 offset0:84 offset1:86
	s_waitcnt lgkmcnt(0)
	v_mfma_f32_32x32x16_bf16 v[16:31], v[36:39], v[32:35], v[16:31]
	ds_read2_b64 v[36:39], v175 offset0:56 offset1:58
	v_cvt_pk_bf16_f32 v32, v139, v151
	v_cvt_pk_bf16_f32 v33, v176, v177
	v_cvt_pk_bf16_f32 v34, v178, v179
	v_cvt_pk_bf16_f32 v35, v180, v182
	v_mov_b32_e32 v151, v161
	s_waitcnt lgkmcnt(0)
	v_mfma_f32_32x32x16_bf16 v[0:15], v[36:39], v[32:35], v[0:15]
	ds_read2_b64 v[36:39], v162 offset0:88 offset1:90
	s_waitcnt lgkmcnt(0)
	v_mfma_f32_32x32x16_bf16 v[16:31], v[36:39], v[32:35], v[16:31]
	ds_read2_b64 v[36:39], v175 offset0:60 offset1:62
	v_cvt_pk_bf16_f32 v32, v181, v183
	v_cvt_pk_bf16_f32 v33, v184, v185
	v_cvt_pk_bf16_f32 v34, v186, v187
	v_cvt_pk_bf16_f32 v35, v189, v191
	s_waitcnt lgkmcnt(0)
	s_nop 0
	v_mfma_f32_32x32x16_bf16 v[0:15], v[36:39], v[32:35], v[0:15]
	ds_read2_b64 v[36:39], v162 offset0:92 offset1:94
	s_waitcnt lgkmcnt(0)
	v_mfma_f32_32x32x16_bf16 v[16:31], v[36:39], v[32:35], v[16:31]
	v_add_f32_e32 v32, v188, v190
	v_div_scale_f32 v33, s[12:13], v32, v32, 1.0
	v_rcp_f32_e32 v34, v33
	s_nop 0
	v_fma_f32 v35, -v33, v34, 1.0
	v_fmac_f32_e32 v34, v35, v34
	v_div_scale_f32 v35, vcc, 1.0, v32, 1.0
	v_mul_f32_e32 v36, v35, v34
	v_fma_f32 v37, -v33, v36, v35
	v_fmac_f32_e32 v36, v37, v34
	v_fma_f32 v33, -v33, v36, v35
	v_div_fmas_f32 v33, v33, v34, v36
	v_div_fixup_f32 v32, v33, v32, 1.0
	v_lshl_add_u64 v[34:35], s[20:21], 0, v[152:153]
	v_lshl_add_u64 v[34:35], v[34:35], 0, s[4:5]
	v_pk_mul_f32 v[0:1], v[0:1], v[32:33] op_sel_hi:[1,0]
	v_pk_mul_f32 v[2:3], v[2:3], v[32:33] op_sel_hi:[1,0]
	v_lshl_add_u64 v[34:35], v[34:35], 0, v[150:151]
	v_cvt_pk_bf16_f32 v0, v0, v1
	v_cvt_pk_bf16_f32 v1, v2, v3
	global_store_dwordx2 v[34:35], v[0:1], off offset:1536 sc1
	v_pk_mul_f32 v[0:1], v[4:5], v[32:33] op_sel_hi:[1,0]
	v_pk_mul_f32 v[2:3], v[6:7], v[32:33] op_sel_hi:[1,0]
	v_cvt_pk_bf16_f32 v0, v0, v1
	v_cvt_pk_bf16_f32 v1, v2, v3
	global_store_dwordx2 v[34:35], v[0:1], off offset:1552 sc1
	v_pk_mul_f32 v[0:1], v[8:9], v[32:33] op_sel_hi:[1,0]
	v_pk_mul_f32 v[2:3], v[10:11], v[32:33] op_sel_hi:[1,0]
	v_cvt_pk_bf16_f32 v0, v0, v1
	v_cvt_pk_bf16_f32 v1, v2, v3
	global_store_dwordx2 v[34:35], v[0:1], off offset:1568 sc1
	v_pk_mul_f32 v[0:1], v[12:13], v[32:33] op_sel_hi:[1,0]
	v_pk_mul_f32 v[2:3], v[14:15], v[32:33] op_sel_hi:[1,0]
	v_cvt_pk_bf16_f32 v0, v0, v1
	v_cvt_pk_bf16_f32 v1, v2, v3
	global_store_dwordx2 v[34:35], v[0:1], off offset:1584 sc1
	v_pk_mul_f32 v[0:1], v[16:17], v[32:33] op_sel_hi:[1,0]
	v_pk_mul_f32 v[2:3], v[18:19], v[32:33] op_sel_hi:[1,0]
	v_cvt_pk_bf16_f32 v0, v0, v1
	v_cvt_pk_bf16_f32 v1, v2, v3
	global_store_dwordx2 v[34:35], v[0:1], off offset:1600 sc1
	v_pk_mul_f32 v[0:1], v[20:21], v[32:33] op_sel_hi:[1,0]
	v_pk_mul_f32 v[2:3], v[22:23], v[32:33] op_sel_hi:[1,0]
	v_cvt_pk_bf16_f32 v0, v0, v1
	v_cvt_pk_bf16_f32 v1, v2, v3
	global_store_dwordx2 v[34:35], v[0:1], off offset:1616 sc1
	v_pk_mul_f32 v[0:1], v[24:25], v[32:33] op_sel_hi:[1,0]
	v_pk_mul_f32 v[2:3], v[26:27], v[32:33] op_sel_hi:[1,0]
	v_cvt_pk_bf16_f32 v0, v0, v1
	v_cvt_pk_bf16_f32 v1, v2, v3
	global_store_dwordx2 v[34:35], v[0:1], off offset:1632 sc1
	v_pk_mul_f32 v[0:1], v[28:29], v[32:33] op_sel_hi:[1,0]
	v_pk_mul_f32 v[2:3], v[30:31], v[32:33] op_sel_hi:[1,0]
	v_cvt_pk_bf16_f32 v0, v0, v1
	v_cvt_pk_bf16_f32 v1, v2, v3
	global_store_dwordx2 v[34:35], v[0:1], off offset:1648 sc1
	s_barrier
	s_cbranch_scc1 .LBB0_176

.LBB0_185:
	v_or_b32_e32 v204, s11, v239
	v_cndmask_b32_e64 v0, 0, 1, s[6:7]
	v_ashrrev_i32_e32 v205, 31, v204
	v_cmp_ne_u32_e32 vcc, 1, v0
	v_lshlrev_b64 v[0:1], 11, v[204:205]
	v_or_b32_e32 v200, 16, v204
	v_lshl_add_u64 v[0:1], v[146:147], 0, v[0:1]
	v_ashrrev_i32_e32 v201, 31, v200
	global_load_dwordx2 v[206:207], v[0:1], off
	v_lshlrev_b64 v[0:1], 11, v[200:201]
	v_lshl_add_u64 v[0:1], v[146:147], 0, v[0:1]
	global_load_dwordx2 v[202:203], v[0:1], off
	s_waitcnt vmcnt(2)
	v_cndmask_b32_e64 v3, v107, v103, s[6:7]
	v_cndmask_b32_e64 v2, v106, v102, s[6:7]
	v_cndmask_b32_e64 v1, v105, v101, s[6:7]
	v_cndmask_b32_e64 v0, v104, v100, s[6:7]
	s_mov_b32 s11, 32
	s_and_b64 vcc, exec, vcc
	v_mfma_f32_32x32x16_bf16 v[32:47], v[0:3], v[72:75], 0
	v_mfma_f32_32x32x16_bf16 v[48:63], v[0:3], v[64:67], 0
	s_nop 10
	v_mul_f32_e64 v162, v190, v32
	v_mul_f32_e64 v163, v191, v32
	v_mov_b32_e32 v223, v34
	v_mfma_f32_32x32x16_bf16 v[16:31], v[0:3], v[68:71], 0
	v_fma_f32 v164, v126, v48, -v162
	v_fma_f32 v165, v127, v49, -v163
	v_fma_f32 v162, v126, v48, v162
	v_fma_f32 v163, v127, v48, v163
	v_mov_b32_e32 v222, v50
	v_mov_b32_e32 v165, v163
	v_mov_b32_e32 v162, v49
	v_mov_b32_e32 v163, v33
	v_pk_add_f32 v[162:163], v[162:163], v[164:165]
	v_mov_b32_e32 v34, v51
	v_mul_f32_e32 v208, v128, v162
	v_pk_fma_f32 v[210:211], v[128:129], v[162:163], v[208:209] op_sel_hi:[1,1,0]
	v_pk_mul_f32 v[208:209], v[190:191], v[36:37] op_sel_hi:[1,0]
	v_mul_f32_e32 v164, v127, v163
	v_pk_fma_f32 v[212:213], v[126:127], v[52:53], v[208:209] neg_lo:[0,0,1] neg_hi:[0,0,1]
	v_pk_fma_f32 v[208:209], v[126:127], v[52:53], v[208:209] op_sel_hi:[1,0,1]
	v_pk_fma_f32 v[164:165], v[126:127], v[162:163], v[164:165] op_sel_hi:[1,1,0] neg_lo:[0,0,1] neg_hi:[0,0,1]
	v_mov_b32_e32 v213, v209
	v_mov_b32_e32 v208, v53
	v_mov_b32_e32 v209, v37
	v_pk_add_f32 v[208:209], v[208:209], v[212:213]
	v_mov_b32_e32 v165, v211
	v_mul_f32_e32 v210, v127, v209
	v_pk_fma_f32 v[212:213], v[126:127], v[208:209], v[210:211] op_sel_hi:[1,1,0] neg_lo:[0,0,1] neg_hi:[0,0,1]
	v_mul_f32_e32 v210, v128, v208
	v_pk_add_f32 v[164:165], v[222:223], v[164:165]
	v_pk_fma_f32 v[214:215], v[128:129], v[208:209], v[210:211] op_sel_hi:[1,1,0]
	v_pk_mul_f32 v[210:211], v[158:159], v[164:165]
	v_mov_b32_e32 v49, v32
	v_pk_fma_f32 v[222:223], v[156:157], v[164:165], v[210:211] op_sel:[0,0,1] op_sel_hi:[1,1,0] neg_lo:[0,0,1] neg_hi:[0,0,1]
	v_pk_fma_f32 v[210:211], v[156:157], v[164:165], v[210:211] op_sel:[0,0,1] op_sel_hi:[1,1,0]
	v_mov_b32_e32 v213, v215
	v_mov_b32_e32 v223, v211
	v_pk_add_f32 v[34:35], v[34:35], v[222:223]
	ds_bpermute_b32 v37, v234, v34
	ds_bpermute_b32 v53, v234, v35
	v_pk_mul_f32 v[210:211], v[154:155], v[196:197] op_sel_hi:[1,0]
	v_mfma_f32_32x32x16_bf16 v[0:15], v[0:3], v[76:79], 0
	v_fma_f32 v222, v150, v198, -v210
	v_fma_f32 v223, v151, v199, -v211
	v_fma_f32 v210, v150, v198, v210
	v_fma_f32 v211, v151, v198, v211
	s_waitcnt lgkmcnt(0)
	v_cndmask_b32_e64 v51, v53, v35, s[36:37]
	v_cndmask_b32_e64 v50, v37, v34, s[36:37]
	v_mov_b32_e32 v223, v211
	v_pk_add_f32 v[50:51], v[222:223], v[50:51]
	s_nop 0
	v_cndmask_b32_e64 v199, v51, v196, s[36:37]
	v_cndmask_b32_e64 v198, v50, v198, s[36:37]
	v_pk_fma_f32 v[32:33], v[156:157], v[198:199], v[48:49]
	v_pk_mul_f32 v[48:49], v[158:159], v[198:199]
	s_nop 0
	v_pk_add_f32 v[210:211], v[32:33], v[48:49] op_sel:[0,1] op_sel_hi:[1,0] neg_lo:[0,1] neg_hi:[0,1]
	v_pk_add_f32 v[32:33], v[32:33], v[48:49] op_sel:[0,1] op_sel_hi:[1,0]
	v_pk_mul_f32 v[48:49], v[172:173], v[198:199]
	v_cvt_pk_bf16_f32 v245, v210, v33
	v_pk_fma_f32 v[32:33], v[170:171], v[198:199], v[162:163]
	s_nop 0
	v_pk_add_f32 v[162:163], v[32:33], v[48:49] op_sel:[0,1] op_sel_hi:[1,0] neg_lo:[0,1] neg_hi:[0,1]
	v_pk_add_f32 v[32:33], v[32:33], v[48:49] op_sel:[0,1] op_sel_hi:[1,0]
	v_pk_mul_f32 v[48:49], v[138:139], v[198:199]
	v_cvt_pk_bf16_f32 v244, v162, v33
	v_pk_fma_f32 v[32:33], v[136:137], v[198:199], v[164:165]
	s_nop 0
	v_pk_add_f32 v[162:163], v[32:33], v[48:49] op_sel:[0,1] op_sel_hi:[1,0] neg_lo:[0,1] neg_hi:[0,1]
	v_pk_add_f32 v[32:33], v[32:33], v[48:49] op_sel:[0,1] op_sel_hi:[1,0]
	v_pk_mul_f32 v[48:49], v[176:177], v[198:199]
	v_cvt_pk_bf16_f32 v243, v162, v33
	v_pk_fma_f32 v[32:33], v[174:175], v[198:199], v[34:35]
	v_cndmask_b32_e64 v35, v35, v53, s[36:37]
	v_pk_add_f32 v[162:163], v[32:33], v[48:49] op_sel:[0,1] op_sel_hi:[1,0] neg_lo:[0,1] neg_hi:[0,1]
	v_pk_add_f32 v[32:33], v[32:33], v[48:49] op_sel:[0,1] op_sel_hi:[1,0]
	v_cndmask_b32_e64 v34, v34, v37, s[36:37]
	v_cvt_pk_bf16_f32 v242, v162, v33
	v_mov_b32_e32 v32, v54
	v_mov_b32_e32 v33, v38
	v_pk_add_f32 v[32:33], v[32:33], v[212:213]
	v_mov_b32_e32 v38, v55
	v_pk_mul_f32 v[48:49], v[158:159], v[32:33]
	v_mov_b32_e32 v53, v36
	v_pk_fma_f32 v[162:163], v[156:157], v[32:33], v[48:49] op_sel:[0,0,1] op_sel_hi:[1,1,0] neg_lo:[0,0,1] neg_hi:[0,0,1]
	v_pk_fma_f32 v[48:49], v[156:157], v[32:33], v[48:49] op_sel:[0,0,1] op_sel_hi:[1,1,0]
	s_nop 0
	v_mov_b32_e32 v163, v49
	v_pk_add_f32 v[198:199], v[38:39], v[162:163]
	v_pk_mul_f32 v[48:49], v[176:177], v[50:51]
	ds_bpermute_b32 v246, v234, v198
	ds_bpermute_b32 v247, v234, v199
	v_pk_fma_f32 v[54:55], v[174:175], v[50:51], v[48:49] op_sel:[0,0,1] op_sel_hi:[1,1,0] neg_lo:[0,0,1] neg_hi:[0,0,1]
	v_pk_fma_f32 v[48:49], v[174:175], v[50:51], v[48:49] op_sel:[0,0,1] op_sel_hi:[1,1,0]
	s_waitcnt lgkmcnt(1)
	v_cndmask_b32_e64 v38, v246, v198, s[36:37]
	v_mov_b32_e32 v55, v49
	v_pk_add_f32 v[34:35], v[34:35], v[54:55]
	s_waitcnt lgkmcnt(0)
	v_cndmask_b32_e64 v39, v247, v199, s[36:37]
	v_pk_mul_f32 v[48:49], v[176:177], v[34:35]
	s_nop 0
	v_pk_fma_f32 v[50:51], v[174:175], v[34:35], v[48:49] op_sel:[0,0,1] op_sel_hi:[1,1,0] neg_lo:[0,0,1] neg_hi:[0,0,1]
	v_pk_fma_f32 v[48:49], v[174:175], v[34:35], v[48:49] op_sel:[0,0,1] op_sel_hi:[1,1,0]
	s_nop 0
	v_mov_b32_e32 v51, v49
	v_pk_add_f32 v[214:215], v[38:39], v[50:51]
	s_nop 0
	v_cndmask_b32_e64 v35, v215, v35, s[36:37]
	v_cndmask_b32_e64 v34, v214, v34, s[36:37]
	v_pk_fma_f32 v[36:37], v[156:157], v[34:35], v[52:53]
	v_pk_mul_f32 v[38:39], v[158:159], v[34:35]
	v_pk_fma_f32 v[32:33], v[136:137], v[34:35], v[32:33]
	v_pk_add_f32 v[48:49], v[36:37], v[38:39] op_sel:[0,1] op_sel_hi:[1,0] neg_lo:[0,1] neg_hi:[0,1]
	v_pk_add_f32 v[36:37], v[36:37], v[38:39] op_sel:[0,1] op_sel_hi:[1,0]
	v_pk_mul_f32 v[38:39], v[172:173], v[34:35]
	v_cvt_pk_bf16_f32 v241, v48, v37
	v_pk_fma_f32 v[36:37], v[170:171], v[34:35], v[208:209]
	v_pk_mul_f32 v[224:225], v[176:177], v[214:215]
	v_pk_add_f32 v[48:49], v[36:37], v[38:39] op_sel:[0,1] op_sel_hi:[1,0] neg_lo:[0,1] neg_hi:[0,1]
	v_pk_add_f32 v[36:37], v[36:37], v[38:39] op_sel:[0,1] op_sel_hi:[1,0]
	v_pk_fma_f32 v[226:227], v[174:175], v[214:215], v[224:225] op_sel:[0,0,1] op_sel_hi:[1,1,0] neg_lo:[0,0,1] neg_hi:[0,0,1]
	v_cvt_pk_bf16_f32 v240, v48, v37
	v_pk_mul_f32 v[36:37], v[138:139], v[34:35]
	v_pk_fma_f32 v[214:215], v[174:175], v[214:215], v[224:225] op_sel:[0,0,1] op_sel_hi:[1,1,0]
	v_pk_add_f32 v[38:39], v[32:33], v[36:37] op_sel:[0,1] op_sel_hi:[1,0] neg_lo:[0,1] neg_hi:[0,1]
	v_pk_add_f32 v[32:33], v[32:33], v[36:37] op_sel:[0,1] op_sel_hi:[1,0]
	v_mov_b32_e32 v227, v215
	v_cvt_pk_bf16_f32 v205, v38, v33
	v_pk_fma_f32 v[32:33], v[174:175], v[34:35], v[198:199]
	v_pk_mul_f32 v[34:35], v[176:177], v[34:35]
	v_cndmask_b32_e64 v199, v199, v247, s[36:37]
	v_pk_add_f32 v[36:37], v[32:33], v[34:35] op_sel:[0,1] op_sel_hi:[1,0] neg_lo:[0,1] neg_hi:[0,1]
	v_pk_add_f32 v[32:33], v[32:33], v[34:35] op_sel:[0,1] op_sel_hi:[1,0]
	v_cndmask_b32_e64 v198, v198, v246, s[36:37]
	v_cvt_pk_bf16_f32 v201, v36, v33
	v_pk_mul_f32 v[32:33], v[192:193], v[0:1] op_sel_hi:[1,0]
	v_pk_add_f32 v[198:199], v[198:199], v[226:227]
	v_pk_fma_f32 v[34:35], v[130:131], v[16:17], v[32:33]
	v_pk_fma_f32 v[32:33], v[130:131], v[16:17], v[32:33] op_sel_hi:[1,0,1] neg_lo:[0,0,1] neg_hi:[0,0,1]
	v_mov_b32_e32 v164, v199
	v_mov_b32_e32 v35, v33
	v_mov_b32_e32 v32, v1
	v_mov_b32_e32 v33, v17
	v_pk_add_f32 v[208:209], v[32:33], v[34:35]
	v_mov_b32_e32 v162, v198
	v_pk_mul_f32 v[32:33], v[182:183], v[208:209]
	s_nop 0
	v_pk_fma_f32 v[34:35], v[184:185], v[208:209], v[32:33] op_sel:[0,0,1] op_sel_hi:[1,1,0] neg_lo:[1,0,0] neg_hi:[1,0,0]
	v_pk_fma_f32 v[32:33], v[184:185], v[208:209], v[32:33] op_sel:[0,0,1] op_sel_hi:[1,1,0]
	s_nop 0
	v_mov_b32_e32 v35, v33
	v_mov_b32_e32 v32, v18
	v_mov_b32_e32 v33, v2
	v_pk_add_f32 v[210:211], v[32:33], v[34:35]
	v_mov_b32_e32 v2, v19
	v_pk_mul_f32 v[32:33], v[184:185], v[210:211]
	s_nop 0
	v_pk_fma_f32 v[34:35], v[182:183], v[210:211], v[32:33] op_sel:[0,0,1] op_sel_hi:[1,1,0] neg_lo:[0,0,1] neg_hi:[0,0,1]
	v_pk_fma_f32 v[32:33], v[182:183], v[210:211], v[32:33] op_sel:[0,0,1] op_sel_hi:[1,1,0]
	s_nop 0
	v_mov_b32_e32 v35, v33
	v_pk_add_f32 v[212:213], v[2:3], v[34:35]
	ds_bpermute_b32 v1, v234, v212
	ds_bpermute_b32 v2, v234, v213
	v_pk_mul_f32 v[32:33], v[186:187], v[196:197] op_sel:[0,1]
	s_waitcnt lgkmcnt(1)
	v_cndmask_b32_e64 v18, v1, v212, s[36:37]
	v_pk_fma_f32 v[34:35], v[152:153], v[160:161], v[32:33] neg_lo:[0,0,1] neg_hi:[0,0,1]
	v_pk_fma_f32 v[32:33], v[152:153], v[160:161], v[32:33] op_sel_hi:[1,0,1]
	s_waitcnt lgkmcnt(0)
	v_cndmask_b32_e64 v19, v2, v213, s[36:37]
	v_mov_b32_e32 v35, v33
	v_pk_add_f32 v[18:19], v[34:35], v[18:19]
	v_cndmask_b32_e64 v3, v213, v2, s[36:37]
	v_pk_mul_f32 v[32:33], v[188:189], v[18:19]
	v_cndmask_b32_e64 v248, v18, v160, s[36:37]
	v_cndmask_b32_e64 v249, v19, v197, s[36:37]
	v_pk_fma_f32 v[34:35], v[180:181], v[18:19], v[32:33] op_sel:[0,0,1] op_sel_hi:[1,1,0] neg_lo:[0,0,1] neg_hi:[0,0,1]
	v_pk_fma_f32 v[18:19], v[180:181], v[18:19], v[32:33] op_sel:[0,0,1] op_sel_hi:[1,1,0]
	v_cndmask_b32_e64 v2, v212, v1, s[36:37]
	v_mov_b32_e32 v35, v19
	v_pk_mul_f32 v[18:19], v[194:195], v[4:5] op_sel_hi:[1,0]
	v_pk_add_f32 v[2:3], v[2:3], v[34:35]
	v_pk_fma_f32 v[32:33], v[178:179], v[20:21], v[18:19] neg_lo:[0,0,1] neg_hi:[0,0,1]
	v_pk_fma_f32 v[18:19], v[178:179], v[20:21], v[18:19] op_sel_hi:[1,0,1]
	v_fma_f32 v16, v123, v248, v16
	v_mov_b32_e32 v33, v19
	v_mov_b32_e32 v18, v21
	v_mov_b32_e32 v19, v5
	v_pk_add_f32 v[50:51], v[18:19], v[32:33]
	v_fma_f32 v0, v123, v249, v0
	v_pk_mul_f32 v[18:19], v[184:185], v[50:51]
	v_fma_f32 v16, -v125, v249, v16
	v_pk_fma_f32 v[32:33], v[182:183], v[50:51], v[18:19] op_sel:[0,0,1] op_sel_hi:[1,1,0] neg_lo:[0,0,1] neg_hi:[0,0,1]
	v_pk_fma_f32 v[18:19], v[182:183], v[50:51], v[18:19] op_sel:[0,0,1] op_sel_hi:[1,1,0]
	v_fmac_f32_e32 v0, v125, v248
	v_mov_b32_e32 v33, v19
	v_mov_b32_e32 v18, v22
	v_mov_b32_e32 v19, v6
	v_pk_add_f32 v[52:53], v[18:19], v[32:33]
	v_mov_b32_e32 v6, v23
	v_pk_mul_f32 v[18:19], v[184:185], v[52:53]
	v_cvt_pk_bf16_f32 v0, v16, v0
	v_pk_fma_f32 v[32:33], v[182:183], v[52:53], v[18:19] op_sel:[0,0,1] op_sel_hi:[1,1,0] neg_lo:[0,0,1] neg_hi:[0,0,1]
	v_pk_fma_f32 v[18:19], v[182:183], v[52:53], v[18:19] op_sel:[0,0,1] op_sel_hi:[1,1,0]
	ds_write2_b32 v235, v245, v0 offset1:32
	v_mov_b32_e32 v33, v19
	v_pk_add_f32 v[54:55], v[6:7], v[32:33]
	ds_bpermute_b32 v1, v234, v54
	ds_bpermute_b32 v5, v234, v55
	v_pk_mul_f32 v[18:19], v[188:189], v[2:3]
	v_fma_f32 v0, v133, v248, v209
	v_pk_fma_f32 v[22:23], v[180:181], v[2:3], v[18:19] op_sel:[0,0,1] op_sel_hi:[1,1,0] neg_lo:[0,0,1] neg_hi:[0,0,1]
	v_pk_fma_f32 v[18:19], v[180:181], v[2:3], v[18:19] op_sel:[0,0,1] op_sel_hi:[1,1,0]
	s_waitcnt lgkmcnt(0)
	v_cndmask_b32_e64 v7, v5, v55, s[36:37]
	v_cndmask_b32_e64 v6, v1, v54, s[36:37]
	v_mov_b32_e32 v23, v19
	v_pk_add_f32 v[6:7], v[6:7], v[22:23]
	v_cndmask_b32_e64 v1, v54, v1, s[36:37]
	v_cndmask_b32_e64 v17, v6, v2, s[36:37]
	v_cndmask_b32_e64 v21, v7, v3, s[36:37]
	v_pk_mul_f32 v[2:3], v[152:153], v[6:7]
	v_mov_b32_e32 v22, v57
	v_sub_f32_e32 v2, v2, v3
	v_add_f32_e32 v163, v1, v2
	v_pk_mul_f32 v[2:3], v[186:187], v[6:7]
	v_mov_b32_e32 v6, v40
	v_mov_b32_e32 v7, v8
	v_add_f32_e32 v1, v2, v3
	v_mov_b32_e32 v2, v56
	v_mov_b32_e32 v3, v24
	v_pk_mul_f32 v[18:19], v[124:125], v[6:7]
	v_pk_mul_f32 v[6:7], v[122:123], v[6:7]
	v_pk_fma_f32 v[18:19], v[122:123], v[2:3], v[18:19] neg_lo:[0,0,1] neg_hi:[0,0,1]
	v_pk_fma_f32 v[2:3], v[124:125], v[2:3], v[6:7]
	v_mov_b32_e32 v6, v41
	v_mov_b32_e32 v7, v9
	v_mov_b32_e32 v23, v25
	v_pk_add_f32 v[34:35], v[6:7], v[2:3]
	v_pk_add_f32 v[32:33], v[22:23], v[18:19]
	v_pk_mul_f32 v[2:3], v[124:125], v[34:35]
	v_mov_b32_e32 v6, v58
	v_pk_fma_f32 v[2:3], v[122:123], v[32:33], v[2:3] neg_lo:[0,0,1] neg_hi:[0,0,1]
	v_mov_b32_e32 v7, v26
	v_pk_add_f32 v[36:37], v[6:7], v[2:3]
	v_pk_mul_f32 v[2:3], v[124:125], v[32:33]
	v_mov_b32_e32 v6, v42
	v_pk_fma_f32 v[2:3], v[122:123], v[34:35], v[2:3]
	v_mov_b32_e32 v7, v10
	v_pk_add_f32 v[38:39], v[6:7], v[2:3]
	v_mov_b32_e32 v26, v59
	v_pk_mul_f32 v[2:3], v[124:125], v[38:39]
	v_mov_b32_e32 v10, v43
	v_pk_fma_f32 v[2:3], v[122:123], v[36:37], v[2:3] neg_lo:[0,0,1] neg_hi:[0,0,1]
	v_mov_b32_e32 v6, v44
	v_pk_add_f32 v[48:49], v[26:27], v[2:3]
	v_pk_mul_f32 v[2:3], v[124:125], v[36:37]
	v_mov_b32_e32 v7, v12
	v_pk_fma_f32 v[2:3], v[122:123], v[38:39], v[2:3]
	v_cndmask_b32_e64 v5, v55, v5, s[36:37]
	v_pk_add_f32 v[42:43], v[10:11], v[2:3]
	v_mov_b32_e32 v2, v60
	v_mov_b32_e32 v3, v28
	v_pk_mul_f32 v[10:11], v[124:125], v[6:7]
	v_pk_mul_f32 v[6:7], v[122:123], v[6:7]
	v_pk_fma_f32 v[10:11], v[122:123], v[2:3], v[10:11] neg_lo:[0,0,1] neg_hi:[0,0,1]
	v_mov_b32_e32 v18, v61
	v_mov_b32_e32 v19, v29
	v_pk_fma_f32 v[2:3], v[124:125], v[2:3], v[6:7]
	v_mov_b32_e32 v6, v45
	v_mov_b32_e32 v7, v13
	v_add_f32_e32 v165, v5, v1
	ds_bpermute_b32 v1, v234, v48
	ds_bpermute_b32 v9, v234, v49
	v_pk_add_f32 v[10:11], v[18:19], v[10:11]
	v_pk_add_f32 v[18:19], v[6:7], v[2:3]
	ds_bpermute_b32 v5, v234, v42
	ds_bpermute_b32 v25, v234, v43
	v_pk_mul_f32 v[2:3], v[124:125], v[18:19]
	v_mov_b32_e32 v6, v62
	v_pk_fma_f32 v[2:3], v[122:123], v[10:11], v[2:3] neg_lo:[0,0,1] neg_hi:[0,0,1]
	v_mov_b32_e32 v7, v30
	v_pk_add_f32 v[22:23], v[6:7], v[2:3]
	v_pk_mul_f32 v[2:3], v[124:125], v[10:11]
	v_mov_b32_e32 v6, v46
	v_pk_fma_f32 v[2:3], v[122:123], v[18:19], v[2:3]
	v_mov_b32_e32 v7, v14
	v_pk_mul_f32 v[214:215], v[142:143], v[164:165]
	s_waitcnt lgkmcnt(2)
	v_cndmask_b32_e64 v59, v9, v49, s[36:37]
	v_cndmask_b32_e64 v58, v1, v48, s[36:37]
	v_pk_add_f32 v[26:27], v[6:7], v[2:3]
	v_pk_mul_f32 v[224:225], v[142:143], v[162:163]
	v_pk_fma_f32 v[214:215], v[140:141], v[162:163], v[214:215] neg_lo:[0,0,1] neg_hi:[0,0,1]
	s_waitcnt lgkmcnt(0)
	v_cndmask_b32_e64 v197, v25, v43, s[36:37]
	v_cndmask_b32_e64 v196, v5, v42, s[36:37]
	v_pk_mul_f32 v[2:3], v[124:125], v[26:27]
	v_pk_add_f32 v[58:59], v[58:59], v[214:215]
	v_pk_fma_f32 v[214:215], v[140:141], v[164:165], v[224:225]
	v_fmac_f32_e32 v208, v133, v249
	v_pk_fma_f32 v[2:3], v[122:123], v[22:23], v[2:3] neg_lo:[0,0,1] neg_hi:[0,0,1]
	v_mov_b32_e32 v30, v63
	v_pk_mul_f32 v[6:7], v[124:125], v[22:23]
	v_pk_add_f32 v[196:197], v[196:197], v[214:215]
	v_fma_f32 v0, -v135, v249, v0
	v_fmac_f32_e32 v208, v135, v248
	v_pk_add_f32 v[2:3], v[30:31], v[2:3]
	v_pk_fma_f32 v[6:7], v[122:123], v[26:27], v[6:7]
	v_mov_b32_e32 v14, v47
	v_cndmask_b32_e64 v215, v196, v199, s[36:37]
	v_cndmask_b32_e64 v214, v58, v198, s[36:37]
	v_pk_mul_f32 v[198:199], v[142:143], v[196:197]
	v_cvt_pk_bf16_f32 v0, v0, v208
	ds_bpermute_b32 v13, v234, v2
	v_pk_add_f32 v[6:7], v[14:15], v[6:7]
	ds_bpermute_b32 v45, v234, v3
	v_cndmask_b32_e64 v15, v49, v9, s[36:37]
	v_cndmask_b32_e64 v14, v48, v1, s[36:37]
	v_pk_fma_f32 v[198:199], v[140:141], v[58:59], v[198:199] neg_lo:[0,0,1] neg_hi:[0,0,1]
	ds_write2_b32 v235, v244, v0 offset0:68 offset1:100
	v_fma_f32 v0, v237, v248, v210
	v_fmac_f32_e32 v211, v237, v249
	v_pk_add_f32 v[198:199], v[14:15], v[198:199]
	v_pk_mul_f32 v[14:15], v[140:141], v[196:197]
	v_fma_f32 v0, -v238, v249, v0
	v_fmac_f32_e32 v211, v238, v248
	ds_bpermute_b32 v29, v234, v6
	v_cndmask_b32_e64 v31, v43, v25, s[36:37]
	v_cndmask_b32_e64 v30, v42, v5, s[36:37]
	ds_bpermute_b32 v1, v234, v7
	v_pk_fma_f32 v[14:15], v[142:143], v[58:59], v[14:15]
	v_cvt_pk_bf16_f32 v0, v0, v211
	v_pk_add_f32 v[30:31], v[30:31], v[14:15]
	ds_write2_b32 v235, v243, v0 offset0:136 offset1:168
	v_fma_f32 v0, v141, v248, v212
	v_fmac_f32_e32 v213, v141, v249
	v_pk_mul_f32 v[14:15], v[142:143], v[30:31]
	v_fma_f32 v0, -v143, v249, v0
	v_fmac_f32_e32 v213, v143, v248
	s_waitcnt lgkmcnt(4)
	v_cndmask_b32_e64 v47, v45, v3, s[36:37]
	v_cndmask_b32_e64 v46, v13, v2, s[36:37]
	v_pk_fma_f32 v[14:15], v[140:141], v[198:199], v[14:15] neg_lo:[0,0,1] neg_hi:[0,0,1]
	v_cvt_pk_bf16_f32 v0, v0, v213
	v_pk_add_f32 v[46:47], v[46:47], v[14:15]
	v_pk_mul_f32 v[14:15], v[142:143], v[198:199]
	ds_write2_b32 v235, v242, v0 offset0:204 offset1:236
	v_fma_f32 v0, v123, v17, v20
	v_fma_f32 v4, v123, v21, v4
	s_waitcnt lgkmcnt(2)
	v_cndmask_b32_e64 v63, v1, v7, s[36:37]
	v_cndmask_b32_e64 v62, v29, v6, s[36:37]
	v_pk_fma_f32 v[14:15], v[140:141], v[30:31], v[14:15]
	v_fma_f32 v0, -v125, v21, v0
	v_fmac_f32_e32 v4, v125, v17
	v_pk_add_f32 v[62:63], v[62:63], v[14:15]
	v_cvt_pk_bf16_f32 v0, v0, v4
	v_add_u32_e32 v4, 0x800, v235
	v_mov_b32_e32 v14, v46
	v_mov_b32_e32 v15, v62
	ds_write2_b32 v4, v241, v0 offset0:32 offset1:64
	v_fma_f32 v0, v133, v17, v50
	v_fmac_f32_e32 v51, v133, v21
	v_cndmask_b32_e64 v223, v7, v1, s[36:37]
	v_cndmask_b32_e64 v1, v46, v198, s[36:37]
	v_cndmask_b32_e64 v30, v62, v30, s[36:37]
	v_pk_mul_f32 v[14:15], v[150:151], v[14:15]
	v_fma_f32 v0, -v135, v21, v0
	v_fmac_f32_e32 v51, v135, v17
	v_cndmask_b32_e64 v41, v2, v13, s[36:37]
	v_sub_f32_e32 v5, v14, v15
	v_fmac_f32_e32 v60, v122, v1
	v_fmac_f32_e32 v44, v122, v30
	v_cvt_pk_bf16_f32 v0, v0, v51
	v_add_f32_e32 v198, v41, v5
	v_fma_f32 v5, -v124, v30, v60
	v_fmac_f32_e32 v44, v124, v1
	ds_write2_b32 v4, v240, v0 offset0:100 offset1:132
	v_fma_f32 v0, v237, v17, v52
	v_fmac_f32_e32 v53, v237, v21
	v_cvt_pk_bf16_f32 v13, v5, v44
	v_fma_f32 v5, v132, v1, v10
	v_fma_f32 v9, v132, v30, v18
	v_fma_f32 v0, -v238, v21, v0
	v_fmac_f32_e32 v53, v238, v17
	v_fma_f32 v5, -v134, v30, v5
	v_fmac_f32_e32 v9, v134, v1
	v_cvt_pk_bf16_f32 v0, v0, v53
	v_pk_mul_f32 v[14:15], v[140:141], v[62:63]
	v_mov_b32_e32 v57, v40
	v_cvt_pk_bf16_f32 v9, v5, v9
	v_fma_f32 v5, v136, v1, v22
	v_fma_f32 v10, v136, v30, v26
	ds_write2_b32 v4, v205, v0 offset0:168 offset1:200
	v_fma_f32 v0, v141, v17, v54
	v_fmac_f32_e32 v55, v141, v21
	v_pk_fma_f32 v[224:225], v[142:143], v[46:47], v[14:15]
	v_pk_fma_f32 v[14:15], v[156:157], v[214:215], v[56:57]
	v_pk_mul_f32 v[40:41], v[158:159], v[214:215]
	v_fma_f32 v5, -v138, v30, v5
	v_fmac_f32_e32 v10, v138, v1
	v_fma_f32 v0, -v143, v21, v0
	v_fmac_f32_e32 v55, v143, v17
	v_pk_add_f32 v[56:57], v[14:15], v[40:41] op_sel:[0,1] op_sel_hi:[1,0] neg_lo:[0,1] neg_hi:[0,1]
	v_pk_add_f32 v[14:15], v[14:15], v[40:41] op_sel:[0,1] op_sel_hi:[1,0]
	v_mov_b32_e32 v40, v32
	v_mov_b32_e32 v41, v34
	v_cvt_pk_bf16_f32 v5, v5, v10
	v_cndmask_b32_e64 v10, v59, v163, s[36:37]
	v_cndmask_b32_e64 v18, v197, v165, s[36:37]
	v_cvt_pk_bf16_f32 v0, v0, v55
	v_add_u32_e32 v4, 0xa00, v235
	v_cvt_pk_bf16_f32 v15, v56, v15
	v_pk_fma_f32 v[40:41], v[170:171], v[214:215], v[40:41]
	v_pk_mul_f32 v[56:57], v[172:173], v[214:215]
	ds_write2_b32 v4, v201, v0 offset0:108 offset1:140
	v_fma_f32 v0, v123, v10, v24
	v_fma_f32 v4, v123, v18, v8
	v_pk_add_f32 v[226:227], v[40:41], v[56:57] op_sel:[0,1] op_sel_hi:[1,0] neg_lo:[0,1] neg_hi:[0,1]
	v_pk_add_f32 v[40:41], v[40:41], v[56:57] op_sel:[0,1] op_sel_hi:[1,0]
	v_fma_f32 v0, -v125, v18, v0
	v_fmac_f32_e32 v4, v125, v10
	v_cvt_pk_bf16_f32 v25, v226, v41
	v_mov_b32_e32 v40, v36
	v_mov_b32_e32 v41, v38
	v_cvt_pk_bf16_f32 v0, v0, v4
	v_add_u32_e32 v4, 0x1000, v235
	v_fmac_f32_e32 v33, v133, v10
	v_fmac_f32_e32 v35, v133, v18
	v_pk_fma_f32 v[40:41], v[136:137], v[214:215], v[40:41]
	v_pk_mul_f32 v[56:57], v[138:139], v[214:215]
	ds_write2_b32 v4, v15, v0 offset0:64 offset1:96
	v_fma_f32 v0, -v135, v18, v33
	v_fmac_f32_e32 v35, v135, v10
	v_pk_add_f32 v[226:227], v[40:41], v[56:57] op_sel:[0,1] op_sel_hi:[1,0] neg_lo:[0,1] neg_hi:[0,1]
	v_pk_add_f32 v[40:41], v[40:41], v[56:57] op_sel:[0,1] op_sel_hi:[1,0]
	v_cvt_pk_bf16_f32 v0, v0, v35
	v_fmac_f32_e32 v37, v237, v10
	v_fmac_f32_e32 v39, v237, v18
	v_cndmask_b32_e64 v222, v6, v29, s[36:37]
	v_cvt_pk_bf16_f32 v29, v226, v41
	v_mov_b32_e32 v40, v48
	v_mov_b32_e32 v41, v42
	v_fma_f32 v2, v140, v1, v2
	v_fma_f32 v6, v140, v30, v6
	ds_write2_b32 v4, v25, v0 offset0:132 offset1:164
	v_fma_f32 v0, -v238, v18, v37
	v_fmac_f32_e32 v39, v238, v10
	v_pk_fma_f32 v[40:41], v[174:175], v[214:215], v[40:41]
	v_pk_mul_f32 v[56:57], v[176:177], v[214:215]
	v_fma_f32 v2, -v142, v30, v2
	v_fmac_f32_e32 v6, v142, v1
	v_cvt_pk_bf16_f32 v0, v0, v39
	v_fmac_f32_e32 v49, v141, v10
	v_fmac_f32_e32 v43, v141, v18
	v_pk_add_f32 v[214:215], v[40:41], v[56:57] op_sel:[0,1] op_sel_hi:[1,0] neg_lo:[0,1] neg_hi:[0,1]
	v_pk_add_f32 v[40:41], v[40:41], v[56:57] op_sel:[0,1] op_sel_hi:[1,0]
	v_cvt_pk_bf16_f32 v1, v2, v6
	v_cndmask_b32_e64 v2, v47, v199, s[36:37]
	v_cndmask_b32_e64 v6, v63, v31, s[36:37]
	ds_write2_b32 v4, v29, v0 offset0:200 offset1:232
	v_fma_f32 v0, -v143, v18, v49
	v_fmac_f32_e32 v43, v143, v10
	v_cvt_pk_bf16_f32 v14, v214, v41
	v_cvt_pk_bf16_f32 v0, v0, v43
	v_add_u32_e32 v4, 0x1400, v235
	v_fmac_f32_e32 v28, v123, v2
	v_fmac_f32_e32 v12, v123, v6
	ds_write2_b32 v4, v14, v0 offset0:12 offset1:44
	v_fma_f32 v0, -v125, v6, v28
	v_fmac_f32_e32 v12, v125, v2
	v_cvt_pk_bf16_f32 v0, v0, v12
	v_add_u32_e32 v4, 0x1800, v235
	v_fmac_f32_e32 v11, v133, v2
	v_fmac_f32_e32 v19, v133, v6
	ds_write2_b32 v4, v13, v0 offset0:96 offset1:128
	v_fma_f32 v0, -v135, v6, v11
	v_fmac_f32_e32 v19, v135, v2
	v_cvt_pk_bf16_f32 v0, v0, v19
	v_fmac_f32_e32 v23, v237, v2
	v_fmac_f32_e32 v27, v237, v6
	ds_write2_b32 v4, v9, v0 offset0:164 offset1:196
	v_fma_f32 v0, -v238, v6, v23
	v_fmac_f32_e32 v27, v238, v2
	v_cndmask_b32_e64 v22, v3, v45, s[36:37]
	v_cvt_pk_bf16_f32 v0, v0, v27
	v_add_u32_e32 v4, 0x1a00, v235
	v_fmac_f32_e32 v3, v141, v2
	v_fmac_f32_e32 v7, v141, v6
	ds_write2_b32 v4, v5, v0 offset0:104 offset1:136
	v_fma_f32 v0, -v143, v6, v3
	v_fmac_f32_e32 v7, v143, v2
	v_cvt_pk_bf16_f32 v0, v0, v7
	v_add_u32_e32 v2, 0x1c00, v235
	ds_write2_b32 v2, v1, v0 offset0:44 offset1:76
	s_waitcnt lgkmcnt(0)
	ds_read_b128 v[0:3], v236
	ds_read_b128 v[4:7], v236 offset:64
	s_waitcnt lgkmcnt(1)
	v_mfma_f32_16x16x32_bf16 v[0:3], v[80:83], v[0:3], 0
	v_mov_b32_e32 v62, v47
	v_pk_mul_f32 v[30:31], v[152:153], v[62:63]
	v_pk_add_f32 v[196:197], v[222:223], v[224:225]
	s_waitcnt lgkmcnt(0)
	v_mfma_f32_16x16x32_bf16 v[0:3], v[84:87], v[4:7], v[0:3]
	ds_read_b128 v[4:7], v236 offset:128
	v_sub_f32_e32 v26, v30, v31
	v_add_f32_e32 v160, v22, v26
	s_waitcnt lgkmcnt(0)
	v_mfma_f32_16x16x32_bf16 v[0:3], v[88:91], v[4:7], v[0:3]
	ds_read_b128 v[4:7], v236 offset:192
	s_waitcnt lgkmcnt(0)
	v_mfma_f32_16x16x32_bf16 v[0:3], v[92:95], v[4:7], v[0:3]
	s_waitcnt vmcnt(1)
	v_lshlrev_b32_e32 v4, 16, v206
	v_and_b32_e32 v5, 0xffff0000, v206
	s_nop 4
	v_pk_fma_f32 v[0:1], v[96:97], v[4:5], v[0:1]
	s_nop 0
	v_mul_f32_e32 v4, 0x3d372713, v0
	v_mul_f32_e32 v5, 0x3d372713, v1
	v_mul_f32_e32 v4, v0, v4
	v_mul_f32_e32 v5, v1, v5
	v_fma_f32 v4, v0, v4, v0
	v_fma_f32 v5, v1, v5, v1
	v_mul_f32_e32 v4, 0xbfcc422a, v4
	v_mul_f32_e32 v5, 0xbfcc422a, v5
	v_mul_f32_e32 v4, 0x3fb8aa3b, v4
	v_mul_f32_e32 v5, 0x3fb8aa3b, v5
	v_exp_f32_e32 v4, v4
	v_exp_f32_e32 v5, v5
	v_add_f32_e32 v4, 1.0, v4
	v_add_f32_e32 v5, 1.0, v5
	v_rcp_f32_e32 v4, v4
	v_rcp_f32_e32 v5, v5
	s_nop 0
	v_pk_mul_f32 v[0:1], v[0:1], v[4:5]
	v_lshlrev_b32_e32 v4, 16, v207
	v_and_b32_e32 v5, 0xffff0000, v207
	v_pk_fma_f32 v[2:3], v[98:99], v[4:5], v[2:3]
	v_cvt_pk_bf16_f32 v0, v0, v1
	v_mul_f32_e32 v4, 0x3d372713, v2
	v_mul_f32_e32 v5, 0x3d372713, v3
	v_mul_f32_e32 v4, v2, v4
	v_mul_f32_e32 v5, v3, v5
	v_fma_f32 v4, v2, v4, v2
	v_fma_f32 v5, v3, v5, v3
	v_mul_f32_e32 v4, 0xbfcc422a, v4
	v_mul_f32_e32 v5, 0xbfcc422a, v5
	v_mul_f32_e32 v4, 0x3fb8aa3b, v4
	v_mul_f32_e32 v5, 0x3fb8aa3b, v5
	v_exp_f32_e32 v4, v4
	v_exp_f32_e32 v5, v5
	v_add_f32_e32 v4, 1.0, v4
	v_add_f32_e32 v5, 1.0, v5
	v_rcp_f32_e32 v4, v4
	v_rcp_f32_e32 v5, v5
	s_nop 0
	v_pk_mul_f32 v[2:3], v[2:3], v[4:5]
	s_nop 0
	v_cvt_pk_bf16_f32 v1, v2, v3
	v_mad_i64_i32 v[2:3], s[6:7], v204, s35, v[148:149]
	global_store_dwordx2 v[2:3], v[0:1], off sc1
	ds_read_b128 v[0:3], v236 offset:4352
	ds_read_b128 v[4:7], v236 offset:4416
	s_waitcnt lgkmcnt(1)
	v_mfma_f32_16x16x32_bf16 v[0:3], v[80:83], v[0:3], 0
	s_waitcnt lgkmcnt(0)
	v_mfma_f32_16x16x32_bf16 v[0:3], v[84:87], v[4:7], v[0:3]
	ds_read_b128 v[4:7], v236 offset:4480
	s_waitcnt lgkmcnt(0)
	v_mfma_f32_16x16x32_bf16 v[0:3], v[88:91], v[4:7], v[0:3]
	ds_read_b128 v[4:7], v236 offset:4544
	s_waitcnt lgkmcnt(0)
	v_mfma_f32_16x16x32_bf16 v[0:3], v[92:95], v[4:7], v[0:3]
	s_waitcnt vmcnt(1)
	v_lshlrev_b32_e32 v4, 16, v202
	v_and_b32_e32 v5, 0xffff0000, v202
	s_nop 4
	v_pk_fma_f32 v[0:1], v[96:97], v[4:5], v[0:1]
	s_nop 0
	v_mul_f32_e32 v4, 0x3d372713, v0
	v_mul_f32_e32 v5, 0x3d372713, v1
	v_mul_f32_e32 v4, v0, v4
	v_mul_f32_e32 v5, v1, v5
	v_fma_f32 v4, v0, v4, v0
	v_fma_f32 v5, v1, v5, v1
	v_mul_f32_e32 v4, 0xbfcc422a, v4
	v_mul_f32_e32 v5, 0xbfcc422a, v5
	v_mul_f32_e32 v4, 0x3fb8aa3b, v4
	v_mul_f32_e32 v5, 0x3fb8aa3b, v5
	v_exp_f32_e32 v4, v4
	v_exp_f32_e32 v5, v5
	v_add_f32_e32 v4, 1.0, v4
	v_add_f32_e32 v5, 1.0, v5
	v_rcp_f32_e32 v4, v4
	v_rcp_f32_e32 v5, v5
	s_nop 0
	v_pk_mul_f32 v[0:1], v[0:1], v[4:5]
	v_lshlrev_b32_e32 v4, 16, v203
	v_and_b32_e32 v5, 0xffff0000, v203
	v_pk_fma_f32 v[2:3], v[98:99], v[4:5], v[2:3]
	v_cvt_pk_bf16_f32 v0, v0, v1
	v_mul_f32_e32 v4, 0x3d372713, v2
	v_mul_f32_e32 v5, 0x3d372713, v3
	v_mul_f32_e32 v4, v2, v4
	v_mul_f32_e32 v5, v3, v5
	v_fma_f32 v4, v2, v4, v2
	v_fma_f32 v5, v3, v5, v3
	v_mul_f32_e32 v4, 0xbfcc422a, v4
	v_mul_f32_e32 v5, 0xbfcc422a, v5
	v_mul_f32_e32 v4, 0x3fb8aa3b, v4
	v_mul_f32_e32 v5, 0x3fb8aa3b, v5
	v_exp_f32_e32 v4, v4
	v_exp_f32_e32 v5, v5
	v_add_f32_e32 v4, 1.0, v4
	v_add_f32_e32 v5, 1.0, v5
	v_rcp_f32_e32 v4, v4
	v_rcp_f32_e32 v5, v5
	s_nop 0
	v_pk_mul_f32 v[2:3], v[2:3], v[4:5]
	s_nop 0
	v_cvt_pk_bf16_f32 v1, v2, v3
	v_mad_i64_i32 v[2:3], s[6:7], v200, s35, v[148:149]
	global_store_dwordx2 v[2:3], v[0:1], off sc1
	s_waitcnt lgkmcnt(0)
	s_mov_b64 s[6:7], 0
	s_cbranch_vccz .LBB0_185
	s_add_i32 s10, s10, 1
	s_cmp_eq_u32 s10, 4
	s_cbranch_scc0 .LBB0_184
	s_add_i32 s4, s4, s34
	s_sub_i32 s8, s8, s34
	s_cmpk_gt_i32 s4, 0xbff
	s_cbranch_scc0 .LBB0_179

.LBB0_222:
	s_or_b64 exec, exec, s[6:7]
	s_waitcnt lgkmcnt(0)
	s_barrier
	s_and_saveexec_b64 s[6:7], s[40:41]
	s_cbranch_execz .LBB0_195
	ds_read2st64_b32 v[78:79], v206 offset1:1
	ds_read2st64_b32 v[82:83], v206 offset0:2 offset1:3
	ds_read2st64_b32 v[96:97], v206 offset0:4 offset1:5
	ds_read2st64_b32 v[86:87], v206 offset0:6 offset1:7
	ds_read2st64_b32 v[100:101], v206 offset0:8 offset1:9
	ds_read2st64_b32 v[118:119], v206 offset0:10 offset1:11
	ds_read2st64_b32 v[120:121], v206 offset0:12 offset1:13
	ds_read2st64_b32 v[122:123], v206 offset0:14 offset1:15
	ds_read2st64_b32 v[124:125], v206 offset0:16 offset1:17
	ds_read2st64_b32 v[126:127], v206 offset0:18 offset1:19
	ds_read2st64_b32 v[128:129], v206 offset0:20 offset1:21
	ds_read2st64_b32 v[130:131], v206 offset0:22 offset1:23
	ds_read2st64_b32 v[132:133], v206 offset0:24 offset1:25
	ds_read2st64_b32 v[134:135], v206 offset0:26 offset1:27
	ds_read2st64_b32 v[114:115], v206 offset0:28 offset1:29
	ds_read2st64_b32 v[136:137], v206 offset0:30 offset1:31
	ds_read2st64_b32 v[110:111], v206 offset0:32 offset1:33
	ds_read2st64_b32 v[116:117], v206 offset0:34 offset1:35
	ds_read2st64_b32 v[106:107], v206 offset0:36 offset1:37
	ds_read2st64_b32 v[112:113], v206 offset0:38 offset1:39
	ds_read2st64_b32 v[102:103], v206 offset0:40 offset1:41
	ds_read2st64_b32 v[108:109], v206 offset0:42 offset1:43
	ds_read2st64_b32 v[98:99], v206 offset0:44 offset1:45
	ds_read2st64_b32 v[104:105], v206 offset0:46 offset1:47
	ds_read2st64_b32 v[90:91], v206 offset0:48 offset1:49
	ds_read2st64_b32 v[94:95], v206 offset0:50 offset1:51
	ds_read2st64_b32 v[76:77], v206 offset0:52 offset1:53
	ds_read2st64_b32 v[84:85], v206 offset0:54 offset1:55
	ds_read2st64_b32 v[74:75], v206 offset0:56 offset1:57
	ds_read2st64_b32 v[80:81], v206 offset0:58 offset1:59
	ds_read2st64_b32 v[64:65], v206 offset0:60 offset1:61
	s_waitcnt lgkmcnt(14)
	v_pk_mul_f32 v[82:83], v[186:187], v[82:83]
	s_lshl_b32 s4, s27, 1
	v_pk_fma_f32 v[82:83], v[50:51], v[70:71], v[82:83] op_sel_hi:[1,0,1] neg_lo:[0,0,1] neg_hi:[0,0,1]
	v_pk_mul_f32 v[50:51], v[186:187], v[78:79]
	s_waitcnt lgkmcnt(0)
	v_pk_mul_f32 v[64:65], v[186:187], v[64:65]
	v_pk_fma_f32 v[92:93], v[48:49], v[70:71], v[50:51] op_sel_hi:[1,0,1] neg_lo:[0,0,1] neg_hi:[0,0,1]
	v_pk_mul_f32 v[48:49], v[186:187], v[86:87]
	v_pk_fma_f32 v[64:65], v[12:13], v[70:71], v[64:65] op_sel_hi:[1,0,1] neg_lo:[0,0,1] neg_hi:[0,0,1]
	v_pk_fma_f32 v[86:87], v[54:55], v[70:71], v[48:49] op_sel_hi:[1,0,1] neg_lo:[0,0,1] neg_hi:[0,0,1]
	v_pk_mul_f32 v[48:49], v[186:187], v[96:97]
	ds_read_b32 v12, v206 offset:15872
	ds_read_b32 v13, v210
	v_pk_fma_f32 v[96:97], v[52:53], v[70:71], v[48:49] op_sel_hi:[1,0,1] neg_lo:[0,0,1] neg_hi:[0,0,1]
	v_pk_mul_f32 v[48:49], v[186:187], v[118:119]
	v_pk_mul_f32 v[140:141], v[92:93], v[92:93]
	v_pk_fma_f32 v[78:79], v[58:59], v[70:71], v[48:49] op_sel_hi:[1,0,1] neg_lo:[0,0,1] neg_hi:[0,0,1]
	v_pk_mul_f32 v[48:49], v[186:187], v[100:101]
	s_waitcnt lgkmcnt(0)
	v_pk_mul_f32 v[12:13], v[186:187], v[12:13]
	v_pk_fma_f32 v[100:101], v[56:57], v[70:71], v[48:49] op_sel_hi:[1,0,1] neg_lo:[0,0,1] neg_hi:[0,0,1]
	v_pk_mul_f32 v[48:49], v[186:187], v[122:123]
	v_pk_fma_f32 v[68:69], v[14:15], v[70:71], v[12:13] op_sel_hi:[1,0,1] neg_lo:[0,0,1] neg_hi:[0,0,1]
	v_pk_fma_f32 v[56:57], v[62:63], v[70:71], v[48:49] op_sel_hi:[1,0,1] neg_lo:[0,0,1] neg_hi:[0,0,1]
	v_pk_mul_f32 v[48:49], v[186:187], v[120:121]
	v_lshl_add_u64 v[12:13], s[20:21], 0, v[160:161]
	v_pk_fma_f32 v[60:61], v[60:61], v[70:71], v[48:49] op_sel_hi:[1,0,1] neg_lo:[0,0,1] neg_hi:[0,0,1]
	v_pk_mul_f32 v[48:49], v[186:187], v[126:127]
	v_lshl_add_u64 v[12:13], v[12:13], 0, s[4:5]
	v_pk_fma_f32 v[52:53], v[34:35], v[70:71], v[48:49] op_sel_hi:[1,0,1] neg_lo:[0,0,1] neg_hi:[0,0,1]
	v_pk_mul_f32 v[34:35], v[186:187], v[124:125]
	v_lshlrev_b32_e32 v160, 1, v180
	v_pk_fma_f32 v[58:59], v[32:33], v[70:71], v[34:35] op_sel_hi:[1,0,1] neg_lo:[0,0,1] neg_hi:[0,0,1]
	v_pk_mul_f32 v[32:33], v[186:187], v[130:131]
	v_lshl_add_u64 v[66:67], v[12:13], 0, v[160:161]
	v_pk_fma_f32 v[48:49], v[38:39], v[70:71], v[32:33] op_sel_hi:[1,0,1] neg_lo:[0,0,1] neg_hi:[0,0,1]
	v_pk_mul_f32 v[32:33], v[186:187], v[128:129]
	global_load_dwordx4 v[12:15], v[184:185], off
	v_pk_fma_f32 v[54:55], v[36:37], v[70:71], v[32:33] op_sel_hi:[1,0,1] neg_lo:[0,0,1] neg_hi:[0,0,1]
	v_pk_mul_f32 v[32:33], v[186:187], v[134:135]
	v_pk_mul_f32 v[138:139], v[82:83], v[82:83]
	v_pk_fma_f32 v[42:43], v[42:43], v[70:71], v[32:33] op_sel_hi:[1,0,1] neg_lo:[0,0,1] neg_hi:[0,0,1]
	v_pk_mul_f32 v[32:33], v[186:187], v[132:133]
	v_pk_mul_f32 v[144:145], v[96:97], v[96:97]
	v_pk_fma_f32 v[50:51], v[40:41], v[70:71], v[32:33] op_sel_hi:[1,0,1] neg_lo:[0,0,1] neg_hi:[0,0,1]
	v_pk_mul_f32 v[32:33], v[186:187], v[136:137]
	v_pk_mul_f32 v[142:143], v[86:87], v[86:87]
	v_pk_fma_f32 v[38:39], v[46:47], v[70:71], v[32:33] op_sel_hi:[1,0,1] neg_lo:[0,0,1] neg_hi:[0,0,1]
	v_pk_mul_f32 v[32:33], v[186:187], v[114:115]
	v_pk_mul_f32 v[146:147], v[100:101], v[100:101]
	v_pk_fma_f32 v[44:45], v[44:45], v[70:71], v[32:33] op_sel_hi:[1,0,1] neg_lo:[0,0,1] neg_hi:[0,0,1]
	v_pk_mul_f32 v[32:33], v[186:187], v[116:117]
	v_pk_mul_f32 v[118:119], v[78:79], v[78:79]
	v_pk_fma_f32 v[34:35], v[18:19], v[70:71], v[32:33] op_sel_hi:[1,0,1] neg_lo:[0,0,1] neg_hi:[0,0,1]
	v_pk_mul_f32 v[18:19], v[186:187], v[110:111]
	v_pk_mul_f32 v[120:121], v[60:61], v[60:61]
	v_pk_fma_f32 v[40:41], v[16:17], v[70:71], v[18:19] op_sel_hi:[1,0,1] neg_lo:[0,0,1] neg_hi:[0,0,1]
	v_pk_mul_f32 v[16:17], v[186:187], v[112:113]
	v_pk_mul_f32 v[62:63], v[56:57], v[56:57]
	v_pk_fma_f32 v[32:33], v[22:23], v[70:71], v[16:17] op_sel_hi:[1,0,1] neg_lo:[0,0,1] neg_hi:[0,0,1]
	v_pk_mul_f32 v[16:17], v[186:187], v[106:107]
	v_pk_mul_f32 v[124:125], v[58:59], v[58:59]
	v_pk_fma_f32 v[36:37], v[20:21], v[70:71], v[16:17] op_sel_hi:[1,0,1] neg_lo:[0,0,1] neg_hi:[0,0,1]
	v_pk_mul_f32 v[16:17], v[186:187], v[108:109]
	v_pk_mul_f32 v[122:123], v[52:53], v[52:53]
	v_pk_fma_f32 v[22:23], v[26:27], v[70:71], v[16:17] op_sel_hi:[1,0,1] neg_lo:[0,0,1] neg_hi:[0,0,1]
	v_pk_mul_f32 v[16:17], v[186:187], v[102:103]
	v_pk_mul_f32 v[128:129], v[54:55], v[54:55]
	v_pk_fma_f32 v[26:27], v[24:25], v[70:71], v[16:17] op_sel_hi:[1,0,1] neg_lo:[0,0,1] neg_hi:[0,0,1]
	v_pk_mul_f32 v[16:17], v[186:187], v[104:105]
	v_pk_mul_f32 v[126:127], v[48:49], v[48:49]
	v_pk_fma_f32 v[18:19], v[30:31], v[70:71], v[16:17] op_sel_hi:[1,0,1] neg_lo:[0,0,1] neg_hi:[0,0,1]
	v_pk_mul_f32 v[16:17], v[186:187], v[98:99]
	v_pk_mul_f32 v[132:133], v[50:51], v[50:51]
	v_pk_fma_f32 v[24:25], v[28:29], v[70:71], v[16:17] op_sel_hi:[1,0,1] neg_lo:[0,0,1] neg_hi:[0,0,1]
	v_pk_mul_f32 v[16:17], v[186:187], v[94:95]
	v_pk_mul_f32 v[130:131], v[42:43], v[42:43]
	v_pk_fma_f32 v[16:17], v[2:3], v[70:71], v[16:17] op_sel_hi:[1,0,1] neg_lo:[0,0,1] neg_hi:[0,0,1]
	v_pk_mul_f32 v[2:3], v[186:187], v[90:91]
	v_pk_mul_f32 v[114:115], v[44:45], v[44:45]
	v_pk_fma_f32 v[20:21], v[0:1], v[70:71], v[2:3] op_sel_hi:[1,0,1] neg_lo:[0,0,1] neg_hi:[0,0,1]
	v_pk_mul_f32 v[0:1], v[186:187], v[84:85]
	v_pk_mul_f32 v[46:47], v[38:39], v[38:39]
	v_pk_fma_f32 v[2:3], v[6:7], v[70:71], v[0:1] op_sel_hi:[1,0,1] neg_lo:[0,0,1] neg_hi:[0,0,1]
	v_pk_mul_f32 v[0:1], v[186:187], v[76:77]
	v_pk_mul_f32 v[110:111], v[40:41], v[40:41]
	v_pk_fma_f32 v[6:7], v[4:5], v[70:71], v[0:1] op_sel_hi:[1,0,1] neg_lo:[0,0,1] neg_hi:[0,0,1]
	v_pk_mul_f32 v[0:1], v[186:187], v[80:81]
	v_pk_mul_f32 v[4:5], v[186:187], v[74:75]
	v_pk_fma_f32 v[0:1], v[10:11], v[70:71], v[0:1] op_sel_hi:[1,0,1] neg_lo:[0,0,1] neg_hi:[0,0,1]
	v_pk_fma_f32 v[4:5], v[8:9], v[70:71], v[4:5] op_sel_hi:[1,0,1] neg_lo:[0,0,1] neg_hi:[0,0,1]
	v_add_f32_e32 v70, v140, v141
	v_add_f32_e32 v70, v70, v138
	v_add_f32_e32 v70, v70, v139
	v_add_f32_e32 v70, v70, v144
	v_add_f32_e32 v70, v70, v145
	v_add_f32_e32 v70, v70, v142
	v_add_f32_e32 v70, v70, v143
	v_add_f32_e32 v70, v70, v146
	v_add_f32_e32 v70, v70, v147
	v_add_f32_e32 v70, v70, v118
	v_add_f32_e32 v70, v70, v119
	v_add_f32_e32 v70, v70, v120
	v_add_f32_e32 v70, v70, v121
	v_add_f32_e32 v62, v70, v62
	v_add_f32_e32 v62, v62, v63
	v_add_f32_e32 v62, v62, v124
	v_add_f32_e32 v62, v62, v125
	v_add_f32_e32 v62, v62, v122
	v_add_f32_e32 v62, v62, v123
	v_add_f32_e32 v62, v62, v128
	v_add_f32_e32 v62, v62, v129
	v_add_f32_e32 v62, v62, v126
	v_add_f32_e32 v62, v62, v127
	v_add_f32_e32 v62, v62, v132
	v_add_f32_e32 v62, v62, v133
	v_add_f32_e32 v62, v62, v130
	v_add_f32_e32 v62, v62, v131
	v_add_f32_e32 v62, v62, v114
	v_add_f32_e32 v62, v62, v115
	v_add_f32_e32 v46, v62, v46
	v_add_f32_e32 v46, v46, v47
	v_add_f32_e32 v46, v46, v110
	v_pk_mul_f32 v[116:117], v[34:35], v[34:35]
	v_add_f32_e32 v46, v46, v111
	v_add_f32_e32 v46, v46, v116
	v_pk_mul_f32 v[106:107], v[36:37], v[36:37]
	v_add_f32_e32 v46, v46, v117
	v_add_f32_e32 v46, v46, v106
	v_pk_mul_f32 v[112:113], v[32:33], v[32:33]
	v_add_f32_e32 v46, v46, v107
	v_add_f32_e32 v46, v46, v112
	v_pk_mul_f32 v[102:103], v[26:27], v[26:27]
	v_add_f32_e32 v46, v46, v113
	v_add_f32_e32 v46, v46, v102
	v_pk_mul_f32 v[108:109], v[22:23], v[22:23]
	v_add_f32_e32 v46, v46, v103
	v_add_f32_e32 v46, v46, v108
	v_pk_mul_f32 v[28:29], v[24:25], v[24:25]
	v_add_f32_e32 v46, v46, v109
	v_add_f32_e32 v28, v46, v28
	v_pk_mul_f32 v[30:31], v[18:19], v[18:19]
	v_add_f32_e32 v28, v28, v29
	v_add_f32_e32 v28, v28, v30
	v_pk_mul_f32 v[90:91], v[20:21], v[20:21]
	v_add_f32_e32 v28, v28, v31
	v_add_f32_e32 v28, v28, v90
	v_pk_mul_f32 v[94:95], v[16:17], v[16:17]
	v_add_f32_e32 v28, v28, v91
	v_add_f32_e32 v28, v28, v94
	v_pk_mul_f32 v[76:77], v[6:7], v[6:7]
	v_add_f32_e32 v28, v28, v95
	v_add_f32_e32 v28, v28, v76
	v_pk_mul_f32 v[84:85], v[2:3], v[2:3]
	v_add_f32_e32 v28, v28, v77
	v_add_f32_e32 v28, v28, v84
	v_pk_mul_f32 v[8:9], v[4:5], v[4:5]
	v_add_f32_e32 v28, v28, v85
	v_add_f32_e32 v8, v28, v8
	v_pk_mul_f32 v[10:11], v[0:1], v[0:1]
	v_add_f32_e32 v8, v8, v9
	v_add_f32_e32 v8, v8, v10
	v_pk_mul_f32 v[72:73], v[64:65], v[64:65]
	v_add_f32_e32 v8, v8, v11
	v_add_f32_e32 v8, v8, v72
	v_pk_mul_f32 v[88:89], v[68:69], v[68:69]
	v_add_f32_e32 v8, v8, v73
	v_add_f32_e32 v8, v8, v88
	v_add_f32_e32 v8, v8, v89
	ds_bpermute_b32 v9, v173, v8
	s_waitcnt lgkmcnt(0)
	v_add_f32_e32 v8, v8, v9
	v_fmamk_f32 v8, v8, 0x3c000000, v216
	v_cmp_gt_f32_e32 vcc, s29, v8
	v_mul_f32_e32 v9, 0x4b800000, v8
	s_nop 0
	v_cndmask_b32_e32 v8, v8, v9, vcc
	v_rsq_f32_e32 v8, v8
	s_nop 0
	v_mul_f32_e32 v9, 0x45800000, v8
	v_cndmask_b32_e32 v8, v8, v9, vcc
	v_mul_f32_e32 v8, v171, v8
	v_pk_mul_f32 v[10:11], v[92:93], v[8:9] op_sel_hi:[1,0]
	v_pk_mul_f32 v[6:7], v[6:7], v[8:9] op_sel_hi:[1,0]
	s_waitcnt vmcnt(0)
	v_pk_mul_f32 v[10:11], v[12:13], v[10:11]
	v_pk_mul_f32 v[12:13], v[82:83], v[8:9] op_sel_hi:[1,0]
	v_cvt_pk_bf16_f32 v10, v10, v11
	v_pk_mul_f32 v[12:13], v[14:15], v[12:13]
	v_pk_mul_f32 v[14:15], v[96:97], v[8:9] op_sel_hi:[1,0]
	v_cvt_pk_bf16_f32 v11, v12, v13
	global_store_dwordx2 v[66:67], v[10:11], off sc1
	global_load_dwordx4 v[10:13], v[184:185], off offset:32
	v_pk_mul_f32 v[2:3], v[2:3], v[8:9] op_sel_hi:[1,0]
	v_pk_mul_f32 v[0:1], v[0:1], v[8:9] op_sel_hi:[1,0]
	s_waitcnt vmcnt(0)
	v_pk_mul_f32 v[10:11], v[10:11], v[14:15]
	v_pk_mul_f32 v[14:15], v[86:87], v[8:9] op_sel_hi:[1,0]
	v_cvt_pk_bf16_f32 v10, v10, v11
	v_pk_mul_f32 v[12:13], v[12:13], v[14:15]
	v_pk_mul_f32 v[14:15], v[100:101], v[8:9] op_sel_hi:[1,0]
	v_cvt_pk_bf16_f32 v11, v12, v13
	global_store_dwordx2 v[66:67], v[10:11], off offset:16 sc1
	global_load_dwordx4 v[10:13], v[184:185], off offset:64
	s_waitcnt vmcnt(0)
	v_pk_mul_f32 v[10:11], v[10:11], v[14:15]
	v_pk_mul_f32 v[14:15], v[78:79], v[8:9] op_sel_hi:[1,0]
	v_cvt_pk_bf16_f32 v10, v10, v11
	v_pk_mul_f32 v[12:13], v[12:13], v[14:15]
	v_pk_mul_f32 v[14:15], v[60:61], v[8:9] op_sel_hi:[1,0]
	v_cvt_pk_bf16_f32 v11, v12, v13
	global_store_dwordx2 v[66:67], v[10:11], off offset:32 sc1
	global_load_dwordx4 v[10:13], v[184:185], off offset:96
	s_waitcnt vmcnt(0)
	v_pk_mul_f32 v[10:11], v[10:11], v[14:15]
	v_pk_mul_f32 v[14:15], v[56:57], v[8:9] op_sel_hi:[1,0]
	v_cvt_pk_bf16_f32 v10, v10, v11
	v_pk_mul_f32 v[12:13], v[12:13], v[14:15]
	v_pk_mul_f32 v[14:15], v[58:59], v[8:9] op_sel_hi:[1,0]
	v_cvt_pk_bf16_f32 v11, v12, v13
	global_store_dwordx2 v[66:67], v[10:11], off offset:48 sc1
	global_load_dwordx4 v[10:13], v[184:185], off offset:128
	s_waitcnt vmcnt(0)
	v_pk_mul_f32 v[10:11], v[10:11], v[14:15]
	v_pk_mul_f32 v[14:15], v[52:53], v[8:9] op_sel_hi:[1,0]
	v_cvt_pk_bf16_f32 v10, v10, v11
	v_pk_mul_f32 v[12:13], v[12:13], v[14:15]
	v_pk_mul_f32 v[14:15], v[54:55], v[8:9] op_sel_hi:[1,0]
	v_cvt_pk_bf16_f32 v11, v12, v13
	global_store_dwordx2 v[66:67], v[10:11], off offset:64 sc1
	global_load_dwordx4 v[10:13], v[184:185], off offset:160
	s_waitcnt vmcnt(0)
	v_pk_mul_f32 v[10:11], v[10:11], v[14:15]
	v_pk_mul_f32 v[14:15], v[48:49], v[8:9] op_sel_hi:[1,0]
	v_cvt_pk_bf16_f32 v10, v10, v11
	v_pk_mul_f32 v[12:13], v[12:13], v[14:15]
	v_pk_mul_f32 v[14:15], v[50:51], v[8:9] op_sel_hi:[1,0]
	v_cvt_pk_bf16_f32 v11, v12, v13
	global_store_dwordx2 v[66:67], v[10:11], off offset:80 sc1
	global_load_dwordx4 v[10:13], v[184:185], off offset:192
	s_waitcnt vmcnt(0)
	v_pk_mul_f32 v[10:11], v[10:11], v[14:15]
	v_pk_mul_f32 v[14:15], v[42:43], v[8:9] op_sel_hi:[1,0]
	v_cvt_pk_bf16_f32 v10, v10, v11
	v_pk_mul_f32 v[12:13], v[12:13], v[14:15]
	v_pk_mul_f32 v[14:15], v[44:45], v[8:9] op_sel_hi:[1,0]
	v_cvt_pk_bf16_f32 v11, v12, v13
	global_store_dwordx2 v[66:67], v[10:11], off offset:96 sc1
	global_load_dwordx4 v[10:13], v[184:185], off offset:224
	s_waitcnt vmcnt(0)
	v_pk_mul_f32 v[10:11], v[14:15], v[10:11]
	v_pk_mul_f32 v[14:15], v[38:39], v[8:9] op_sel_hi:[1,0]
	v_cvt_pk_bf16_f32 v10, v10, v11
	v_pk_mul_f32 v[12:13], v[14:15], v[12:13]
	v_pk_mul_f32 v[14:15], v[40:41], v[8:9] op_sel_hi:[1,0]
	v_cvt_pk_bf16_f32 v11, v12, v13
	global_store_dwordx2 v[66:67], v[10:11], off offset:112 sc1
	global_load_dwordx4 v[10:13], v[184:185], off offset:256
	s_waitcnt vmcnt(0)
	v_pk_mul_f32 v[10:11], v[14:15], v[10:11]
	v_pk_mul_f32 v[14:15], v[34:35], v[8:9] op_sel_hi:[1,0]
	v_cvt_pk_bf16_f32 v10, v10, v11
	v_pk_mul_f32 v[12:13], v[14:15], v[12:13]
	v_pk_mul_f32 v[14:15], v[36:37], v[8:9] op_sel_hi:[1,0]
	v_cvt_pk_bf16_f32 v11, v12, v13
	global_store_dwordx2 v[66:67], v[10:11], off offset:128 sc1
	global_load_dwordx4 v[10:13], v[184:185], off offset:288
	s_waitcnt vmcnt(0)
	v_pk_mul_f32 v[10:11], v[14:15], v[10:11]
	v_pk_mul_f32 v[14:15], v[32:33], v[8:9] op_sel_hi:[1,0]
	v_cvt_pk_bf16_f32 v10, v10, v11
	v_pk_mul_f32 v[12:13], v[14:15], v[12:13]
	v_pk_mul_f32 v[14:15], v[26:27], v[8:9] op_sel_hi:[1,0]
	v_cvt_pk_bf16_f32 v11, v12, v13
	global_store_dwordx2 v[66:67], v[10:11], off offset:144 sc1
	global_load_dwordx4 v[10:13], v[184:185], off offset:320
	s_waitcnt vmcnt(0)
	v_pk_mul_f32 v[10:11], v[14:15], v[10:11]
	v_pk_mul_f32 v[14:15], v[22:23], v[8:9] op_sel_hi:[1,0]
	v_cvt_pk_bf16_f32 v10, v10, v11
	v_pk_mul_f32 v[12:13], v[14:15], v[12:13]
	v_pk_mul_f32 v[14:15], v[24:25], v[8:9] op_sel_hi:[1,0]
	v_cvt_pk_bf16_f32 v11, v12, v13
	global_store_dwordx2 v[66:67], v[10:11], off offset:160 sc1
	global_load_dwordx4 v[10:13], v[184:185], off offset:352
	s_waitcnt vmcnt(0)
	v_pk_mul_f32 v[10:11], v[14:15], v[10:11]
	v_pk_mul_f32 v[14:15], v[18:19], v[8:9] op_sel_hi:[1,0]
	v_cvt_pk_bf16_f32 v10, v10, v11
	v_pk_mul_f32 v[12:13], v[14:15], v[12:13]
	v_pk_mul_f32 v[14:15], v[20:21], v[8:9] op_sel_hi:[1,0]
	v_cvt_pk_bf16_f32 v11, v12, v13
	global_store_dwordx2 v[66:67], v[10:11], off offset:176 sc1
	global_load_dwordx4 v[10:13], v[184:185], off offset:384
	s_waitcnt vmcnt(0)
	v_pk_mul_f32 v[10:11], v[14:15], v[10:11]
	v_pk_mul_f32 v[14:15], v[16:17], v[8:9] op_sel_hi:[1,0]
	v_cvt_pk_bf16_f32 v10, v10, v11
	v_pk_mul_f32 v[12:13], v[14:15], v[12:13]
	s_nop 0
	v_cvt_pk_bf16_f32 v11, v12, v13
	global_store_dwordx2 v[66:67], v[10:11], off offset:192 sc1
	global_load_dwordx4 v[10:13], v[184:185], off offset:416
	s_waitcnt vmcnt(0)
	v_pk_mul_f32 v[6:7], v[6:7], v[10:11]
	v_pk_mul_f32 v[2:3], v[2:3], v[12:13]
	v_cvt_pk_bf16_f32 v6, v6, v7
	v_cvt_pk_bf16_f32 v7, v2, v3
	global_store_dwordx2 v[66:67], v[6:7], off offset:208 sc1
	global_load_dwordx4 v[10:13], v[184:185], off offset:448
	v_pk_mul_f32 v[2:3], v[4:5], v[8:9] op_sel_hi:[1,0]
	v_pk_mul_f32 v[4:5], v[64:65], v[8:9] op_sel_hi:[1,0]
	s_waitcnt vmcnt(0)
	v_pk_mul_f32 v[2:3], v[2:3], v[10:11]
	v_pk_mul_f32 v[0:1], v[0:1], v[12:13]
	v_cvt_pk_bf16_f32 v2, v2, v3
	v_cvt_pk_bf16_f32 v3, v0, v1
	global_store_dwordx2 v[66:67], v[2:3], off offset:224 sc1
	global_load_dwordx4 v[0:3], v[184:185], off offset:480
	s_waitcnt vmcnt(0)
	v_pk_mul_f32 v[0:1], v[4:5], v[0:1]
	v_pk_mul_f32 v[4:5], v[68:69], v[8:9] op_sel_hi:[1,0]
	v_cvt_pk_bf16_f32 v0, v0, v1
	v_pk_mul_f32 v[2:3], v[4:5], v[2:3]
	s_nop 0
	v_cvt_pk_bf16_f32 v1, v2, v3
	global_store_dwordx2 v[66:67], v[0:1], off offset:240 sc1
	s_branch .LBB0_195

.LBB0_230:
	s_or_b64 exec, exec, s[6:7]
	v_mov_b32_e32 v0, s97
	s_waitcnt lgkmcnt(0)
	s_barrier
	ds_read_b32 v0, v0
	s_movk_i32 s4, 0xff
	s_mov_b64 s[6:7], -1
	s_waitcnt lgkmcnt(0)
	s_barrier
	v_cmp_lt_u32_e32 vcc, s4, v0
	v_readfirstlane_b32 s8, v0
	s_cbranch_vccnz .LBB0_225
	s_lshr_b32 s6, s8, 6
	s_lshl_b32 s4, s6, 20
	s_add_u32 s7, s12, s4
	s_addc_u32 s9, s13, 0
	s_lshl_b32 s4, s8, 3
	s_and_b32 s4, s4, 0x180
	s_add_u32 s10, s7, s4
	s_addc_u32 s11, s9, 0
	v_lshl_add_u64 v[4:5], s[10:11], 0, v[160:161]
	v_lshl_add_u64 v[6:7], v[4:5], 0, v[140:141]
	global_load_dwordx4 v[0:3], v[6:7], off offset:512
	v_lshl_add_u64 v[8:9], v[4:5], 0, v[142:143]
	v_lshl_add_u64 v[10:11], v[4:5], 0, v[144:145]
	v_lshl_add_u64 v[4:5], v[4:5], 0, v[146:147]
	s_lshl_b32 s7, s8, 8
	s_lshl_b32 s6, s6, 12
	s_and_b32 s7, s7, 0xf00
	s_or_b32 s6, s6, s7
	v_mov_b32_e32 v149, v161
	v_add_u32_e32 v56, v170, v169
	s_waitcnt vmcnt(0)
	ds_write_b16 v154, v0
	ds_write_b16_d16_hi v154, v0 offset:520
	ds_write_b16 v154, v1 offset:1040
	ds_write_b16_d16_hi v154, v1 offset:1560
	ds_write_b16 v154, v2 offset:2080
	ds_write_b16_d16_hi v154, v2 offset:2600
	ds_write_b16 v154, v3 offset:3120
	ds_write_b16_d16_hi v154, v3 offset:3640
	global_load_dwordx4 v[0:3], v[8:9], off offset:512
	s_waitcnt vmcnt(0)
	ds_write_b16 v155, v0
	ds_write_b16_d16_hi v155, v0 offset:520
	ds_write_b16 v155, v1 offset:1040
	ds_write_b16_d16_hi v155, v1 offset:1560
	ds_write_b16 v155, v2 offset:2080
	ds_write_b16_d16_hi v155, v2 offset:2600
	ds_write_b16 v155, v3 offset:3120
	ds_write_b16_d16_hi v155, v3 offset:3640
	global_load_dwordx4 v[0:3], v[10:11], off offset:512
	s_waitcnt vmcnt(0)
	ds_write_b16 v156, v0
	ds_write_b16_d16_hi v156, v0 offset:520
	ds_write_b16 v156, v1 offset:1040
	ds_write_b16_d16_hi v156, v1 offset:1560
	ds_write_b16 v156, v2 offset:2080
	ds_write_b16_d16_hi v156, v2 offset:2600
	ds_write_b16 v156, v3 offset:3120
	ds_write_b16_d16_hi v156, v3 offset:3640
	global_load_dwordx4 v[0:3], v[4:5], off offset:512
	s_waitcnt vmcnt(0)
	ds_write_b16 v157, v0
	ds_write_b16_d16_hi v157, v0 offset:520
	ds_write_b16 v157, v1 offset:1040
	ds_write_b16_d16_hi v157, v1 offset:1560
	ds_write_b16 v157, v2 offset:2080
	ds_write_b16_d16_hi v157, v2 offset:2600
	ds_write_b16 v157, v3 offset:3120
	ds_write_b16_d16_hi v157, v3 offset:3640
	global_load_dwordx4 v[0:3], v[6:7], off
	v_add_u32_e32 v6, v158, v167
	s_waitcnt vmcnt(0)
	ds_write_b128 v6, v[0:3] offset:33280
	global_load_dwordx4 v[0:3], v[8:9], off
	s_waitcnt vmcnt(0)
	ds_write_b128 v174, v[0:3] offset:33280
	global_load_dwordx4 v[0:3], v[10:11], off
	s_waitcnt vmcnt(0)
	ds_write_b128 v175, v[0:3] offset:33280
	global_load_dwordx4 v[0:3], v[4:5], off
	s_waitcnt vmcnt(0)
	ds_write_b128 v176, v[0:3] offset:33280
	v_add_u32_e32 v0, s6, v159
	v_ashrrev_i32_e32 v1, 31, v0
	v_lshlrev_b64 v[152:153], 11, v[0:1]
	v_lshl_add_u64 v[0:1], s[64:65], 0, v[152:153]
	v_lshl_add_u64 v[0:1], v[0:1], 0, s[4:5]
	v_lshl_add_u64 v[0:1], v[0:1], 0, v[148:149]
	s_waitcnt lgkmcnt(0)
	s_barrier
	global_load_dwordx4 v[48:51], v[0:1], off offset:1536
	global_load_dwordx4 v[136:139], v[0:1], off offset:1568
	global_load_dwordx4 v[132:135], v[0:1], off offset:1600
	global_load_dwordx4 v[128:131], v[0:1], off offset:1632
	ds_read_b128 v[0:3], v56 offset:33280
	ds_read_b128 v[4:7], v56 offset:33312
	s_waitcnt vmcnt(3) lgkmcnt(1)
	v_mfma_f32_32x32x16_bf16 v[112:127], v[0:3], v[48:51], 0
	ds_read_b128 v[0:3], v56 offset:33344
	ds_read_b128 v[32:35], v56 offset:56352
	ds_read_b128 v[52:55], v56 offset:60960
	s_waitcnt vmcnt(2) lgkmcnt(3)
	v_mfma_f32_32x32x16_bf16 v[112:127], v[4:7], v[136:139], v[112:127]
	s_waitcnt vmcnt(1) lgkmcnt(2)
	v_mfma_f32_32x32x16_bf16 v[112:127], v[0:3], v[132:135], v[112:127]
	ds_read_b128 v[0:3], v56 offset:33376
	s_waitcnt vmcnt(0) lgkmcnt(0)
	v_mfma_f32_32x32x16_bf16 v[112:127], v[0:3], v[128:131], v[112:127]
	ds_read_b128 v[0:3], v56 offset:37888
	s_waitcnt lgkmcnt(0)
	v_mfma_f32_32x32x16_bf16 v[96:111], v[0:3], v[48:51], 0
	ds_read_b128 v[0:3], v56 offset:37920
	s_waitcnt lgkmcnt(0)
	v_mfma_f32_32x32x16_bf16 v[96:111], v[0:3], v[136:139], v[96:111]
	ds_read_b128 v[0:3], v56 offset:37952
	s_waitcnt lgkmcnt(0)
	v_mfma_f32_32x32x16_bf16 v[96:111], v[0:3], v[132:135], v[96:111]
	ds_read_b128 v[0:3], v56 offset:37984
	s_waitcnt lgkmcnt(0)
	v_mfma_f32_32x32x16_bf16 v[96:111], v[0:3], v[128:131], v[96:111]
	ds_read_b128 v[0:3], v56 offset:42496
	s_waitcnt lgkmcnt(0)
	v_mfma_f32_32x32x16_bf16 v[80:95], v[0:3], v[48:51], 0
	ds_read_b128 v[0:3], v56 offset:42528
	s_waitcnt lgkmcnt(0)
	v_mfma_f32_32x32x16_bf16 v[80:95], v[0:3], v[136:139], v[80:95]
	ds_read_b128 v[0:3], v56 offset:42560
	s_waitcnt lgkmcnt(0)
	v_mfma_f32_32x32x16_bf16 v[80:95], v[0:3], v[132:135], v[80:95]
	ds_read_b128 v[0:3], v56 offset:42592
	s_waitcnt lgkmcnt(0)
	v_mfma_f32_32x32x16_bf16 v[80:95], v[0:3], v[128:131], v[80:95]
	ds_read_b128 v[0:3], v56 offset:47104
	s_waitcnt lgkmcnt(0)
	v_mfma_f32_32x32x16_bf16 v[64:79], v[0:3], v[48:51], 0
	ds_read_b128 v[0:3], v56 offset:47136
	s_waitcnt lgkmcnt(0)
	v_mfma_f32_32x32x16_bf16 v[64:79], v[0:3], v[136:139], v[64:79]
	ds_read_b128 v[0:3], v56 offset:47168
	s_waitcnt lgkmcnt(0)
	v_mfma_f32_32x32x16_bf16 v[64:79], v[0:3], v[132:135], v[64:79]
	ds_read_b128 v[0:3], v56 offset:47200
	s_waitcnt lgkmcnt(0)
	v_mfma_f32_32x32x16_bf16 v[64:79], v[0:3], v[128:131], v[64:79]
	ds_read_b128 v[0:3], v56 offset:51712
	s_waitcnt lgkmcnt(0)
	v_mfma_f32_32x32x16_bf16 v[16:31], v[0:3], v[48:51], 0
	ds_read_b128 v[0:3], v56 offset:51744
	s_waitcnt lgkmcnt(0)
	v_mfma_f32_32x32x16_bf16 v[16:31], v[0:3], v[136:139], v[16:31]
	ds_read_b128 v[0:3], v56 offset:51776
	s_waitcnt lgkmcnt(0)
	v_mfma_f32_32x32x16_bf16 v[16:31], v[0:3], v[132:135], v[16:31]
	ds_read_b128 v[0:3], v56 offset:51808
	s_waitcnt lgkmcnt(0)
	v_mfma_f32_32x32x16_bf16 v[16:31], v[0:3], v[128:131], v[16:31]
	ds_read_b128 v[0:3], v56 offset:56320
	s_waitcnt lgkmcnt(0)
	v_mfma_f32_32x32x16_bf16 v[0:15], v[0:3], v[48:51], 0
	v_mfma_f32_32x32x16_bf16 v[0:15], v[32:35], v[136:139], v[0:15]
	ds_read_b128 v[32:35], v56 offset:56384
	s_waitcnt lgkmcnt(0)
	v_mfma_f32_32x32x16_bf16 v[0:15], v[32:35], v[132:135], v[0:15]
	ds_read_b128 v[32:35], v56 offset:56416
	s_waitcnt lgkmcnt(0)
	v_mfma_f32_32x32x16_bf16 v[0:15], v[32:35], v[128:131], v[0:15]
	ds_read_b128 v[32:35], v56 offset:60928
	s_waitcnt lgkmcnt(0)
	v_mfma_f32_32x32x16_bf16 v[32:47], v[32:35], v[48:51], 0
	v_mfma_f32_32x32x16_bf16 v[32:47], v[52:55], v[136:139], v[32:47]
	ds_read_b128 v[52:55], v56 offset:60992
	s_waitcnt lgkmcnt(0)
	v_mfma_f32_32x32x16_bf16 v[32:47], v[52:55], v[132:135], v[32:47]
	ds_read_b128 v[52:55], v56 offset:61024
	s_waitcnt lgkmcnt(0)
	v_mfma_f32_32x32x16_bf16 v[32:47], v[52:55], v[128:131], v[32:47]
	ds_read_b128 v[52:55], v171 offset:32256
	ds_read_b128 v[178:181], v171 offset:32288
	s_waitcnt lgkmcnt(1)
	v_mfma_f32_32x32x16_bf16 v[48:63], v[52:55], v[48:51], 0
	s_waitcnt lgkmcnt(0)
	v_mfma_f32_32x32x16_bf16 v[48:63], v[178:181], v[136:139], v[48:63]
	ds_read_b128 v[136:139], v171 offset:32320
	s_waitcnt lgkmcnt(0)
	v_mfma_f32_32x32x16_bf16 v[48:63], v[136:139], v[132:135], v[48:63]
	ds_read_b128 v[132:135], v171 offset:32352
	s_waitcnt lgkmcnt(0)
	v_mfma_f32_32x32x16_bf16 v[48:63], v[132:135], v[128:131], v[48:63]
	v_max3_f32 v128, v112, s96, v113
	v_max3_f32 v128, v128, v114, v115
	v_max3_f32 v128, v128, v116, v117
	v_max3_f32 v128, v128, v118, v119
	v_max3_f32 v128, v128, v120, v121
	v_max3_f32 v128, v128, v122, v123
	v_max3_f32 v128, v128, v124, v125
	v_max3_f32 v128, v128, v126, v127
	v_max3_f32 v128, v128, v96, v97
	v_max3_f32 v128, v128, v98, v99
	v_max3_f32 v128, v128, v100, v101
	v_max3_f32 v128, v128, v102, v103
	v_max3_f32 v128, v128, v104, v105
	v_max3_f32 v128, v128, v106, v107
	v_max3_f32 v128, v128, v108, v109
	v_max3_f32 v128, v128, v110, v111
	v_max3_f32 v128, v128, v80, v81
	v_max3_f32 v128, v128, v82, v83
	v_max3_f32 v128, v128, v84, v85
	v_max3_f32 v128, v128, v86, v87
	v_max3_f32 v128, v128, v88, v89
	v_max3_f32 v128, v128, v90, v91
	v_max3_f32 v128, v128, v92, v93
	v_max3_f32 v128, v128, v94, v95
	v_max3_f32 v128, v128, v64, v65
	v_max3_f32 v128, v128, v66, v67
	v_max3_f32 v128, v128, v68, v69
	v_max3_f32 v128, v128, v70, v71
	v_max3_f32 v128, v128, v72, v73
	v_max3_f32 v128, v128, v74, v75
	v_max3_f32 v128, v128, v76, v77
	v_max3_f32 v128, v128, v78, v79
	v_max3_f32 v128, v128, v16, v17
	v_max3_f32 v128, v128, v18, v19
	v_max3_f32 v128, v128, v20, v21
	v_max3_f32 v128, v128, v22, v23
	v_max3_f32 v128, v128, v24, v25
	v_max3_f32 v128, v128, v26, v27
	v_max3_f32 v128, v128, v28, v29
	v_max3_f32 v128, v128, v30, v31
	v_max3_f32 v128, v128, v0, v1
	v_max3_f32 v128, v128, v2, v3
	v_max3_f32 v128, v128, v4, v5
	v_max3_f32 v128, v128, v6, v7
	v_max3_f32 v128, v128, v8, v9
	v_max3_f32 v128, v128, v10, v11
	v_max3_f32 v128, v128, v12, v13
	v_max3_f32 v128, v128, v14, v15
	v_max3_f32 v128, v128, v32, v33
	v_max3_f32 v128, v128, v34, v35
	v_max3_f32 v128, v128, v36, v37
	v_max3_f32 v128, v128, v38, v39
	v_max3_f32 v128, v128, v40, v41
	v_max3_f32 v128, v128, v42, v43
	v_max3_f32 v128, v128, v44, v45
	v_max3_f32 v128, v128, v46, v47
	v_max3_f32 v128, v128, v48, v49
	v_max3_f32 v128, v128, v50, v51
	v_max3_f32 v128, v128, v52, v53
	v_max3_f32 v128, v128, v54, v55
	v_max3_f32 v128, v128, v56, v57
	v_max3_f32 v128, v128, v58, v59
	v_max3_f32 v128, v128, v60, v61
	v_max3_f32 v128, v128, v62, v63
	ds_bpermute_b32 v129, v173, v128
	s_waitcnt lgkmcnt(0)
	v_max_f32_e32 v129, v129, v129
	v_max_f32_e32 v204, v128, v129
	v_sub_f32_e32 v112, v112, v204
	v_exp_f32_e32 v203, v112
	v_sub_f32_e32 v113, v113, v204
	v_exp_f32_e32 v205, v113
	v_sub_f32_e32 v113, v114, v204
	v_exp_f32_e32 v206, v113
	v_sub_f32_e32 v113, v115, v204
	v_exp_f32_e32 v207, v113
	v_sub_f32_e32 v113, v116, v204
	v_add_f32_e32 v112, 0, v203
	v_exp_f32_e32 v208, v113
	v_sub_f32_e32 v113, v117, v204
	v_add_f32_e32 v112, v205, v112
	v_exp_f32_e32 v209, v113
	v_sub_f32_e32 v113, v118, v204
	v_add_f32_e32 v112, v206, v112
	v_exp_f32_e32 v210, v113
	v_sub_f32_e32 v113, v119, v204
	v_add_f32_e32 v112, v207, v112
	v_exp_f32_e32 v211, v113
	v_add_f32_e32 v112, v208, v112
	v_add_f32_e32 v112, v209, v112
	v_add_f32_e32 v112, v210, v112
	v_add_f32_e32 v113, v211, v112
	v_sub_f32_e32 v112, v120, v204
	v_exp_f32_e32 v112, v112
	v_sub_f32_e32 v120, v127, v204
	v_exp_f32_e32 v120, v120
	v_sub_f32_e32 v96, v96, v204
	v_add_f32_e32 v114, v112, v113
	v_sub_f32_e32 v113, v121, v204
	v_exp_f32_e32 v113, v113
	v_sub_f32_e32 v97, v97, v204
	v_sub_f32_e32 v80, v80, v204
	v_exp_f32_e32 v80, v80
	v_add_f32_e32 v115, v113, v114
	v_sub_f32_e32 v114, v122, v204
	v_exp_f32_e32 v114, v114
	v_sub_f32_e32 v81, v81, v204
	v_exp_f32_e32 v81, v81
	v_sub_f32_e32 v82, v82, v204
	v_add_f32_e32 v116, v114, v115
	v_sub_f32_e32 v115, v123, v204
	v_exp_f32_e32 v115, v115
	v_exp_f32_e32 v195, v82
	v_sub_f32_e32 v83, v83, v204
	v_exp_f32_e32 v197, v83
	v_add_f32_e32 v117, v115, v116
	v_sub_f32_e32 v116, v124, v204
	v_exp_f32_e32 v116, v116
	v_sub_f32_e32 v83, v84, v204
	v_exp_f32_e32 v199, v83
	v_sub_f32_e32 v83, v85, v204
	v_add_f32_e32 v118, v116, v117
	v_sub_f32_e32 v117, v125, v204
	v_exp_f32_e32 v117, v117
	v_exp_f32_e32 v200, v83
	v_sub_f32_e32 v83, v86, v204
	v_exp_f32_e32 v201, v83
	v_add_f32_e32 v119, v117, v118
	v_sub_f32_e32 v118, v126, v204
	v_exp_f32_e32 v118, v118
	v_sub_f32_e32 v83, v87, v204
	v_exp_f32_e32 v202, v83
	v_sub_f32_e32 v83, v88, v204
	v_add_f32_e32 v119, v118, v119
	v_add_f32_e32 v121, v120, v119
	v_exp_f32_e32 v119, v96
	v_exp_f32_e32 v185, v83
	v_sub_f32_e32 v83, v89, v204
	v_exp_f32_e32 v187, v83
	v_add_f32_e32 v96, v119, v121
	v_exp_f32_e32 v121, v97
	v_sub_f32_e32 v97, v98, v204
	v_exp_f32_e32 v122, v97
	v_sub_f32_e32 v97, v99, v204
	v_exp_f32_e32 v123, v97
	v_sub_f32_e32 v97, v100, v204
	v_exp_f32_e32 v124, v97
	v_sub_f32_e32 v97, v101, v204
	v_add_f32_e32 v96, v121, v96
	v_exp_f32_e32 v125, v97
	v_sub_f32_e32 v97, v102, v204
	v_add_f32_e32 v96, v122, v96
	v_exp_f32_e32 v126, v97
	v_sub_f32_e32 v97, v103, v204
	v_add_f32_e32 v96, v123, v96
	v_exp_f32_e32 v127, v97
	v_add_f32_e32 v96, v124, v96
	v_add_f32_e32 v96, v125, v96
	v_add_f32_e32 v96, v126, v96
	v_add_f32_e32 v97, v127, v96
	v_sub_f32_e32 v96, v104, v204
	v_exp_f32_e32 v96, v96
	v_sub_f32_e32 v83, v90, v204
	v_exp_f32_e32 v189, v83
	v_sub_f32_e32 v83, v91, v204
	v_add_f32_e32 v98, v96, v97
	v_sub_f32_e32 v97, v105, v204
	v_exp_f32_e32 v97, v97
	v_exp_f32_e32 v191, v83
	v_sub_f32_e32 v83, v92, v204
	v_exp_f32_e32 v193, v83
	v_add_f32_e32 v99, v97, v98
	v_sub_f32_e32 v98, v106, v204
	v_exp_f32_e32 v98, v98
	v_sub_f32_e32 v83, v93, v204
	v_exp_f32_e32 v194, v83
	v_sub_f32_e32 v83, v94, v204
	v_add_f32_e32 v100, v98, v99
	v_sub_f32_e32 v99, v107, v204
	v_exp_f32_e32 v99, v99
	v_exp_f32_e32 v196, v83
	v_sub_f32_e32 v83, v95, v204
	v_exp_f32_e32 v198, v83
	v_add_f32_e32 v101, v99, v100
	v_sub_f32_e32 v100, v108, v204
	v_exp_f32_e32 v100, v100
	v_sub_f32_e32 v64, v64, v204
	v_exp_f32_e32 v177, v64
	v_sub_f32_e32 v65, v65, v204
	v_add_f32_e32 v102, v100, v101
	v_sub_f32_e32 v101, v109, v204
	v_exp_f32_e32 v101, v101
	v_exp_f32_e32 v179, v65
	v_sub_f32_e32 v65, v66, v204
	v_exp_f32_e32 v181, v65
	v_add_f32_e32 v103, v101, v102
	v_sub_f32_e32 v102, v110, v204
	v_exp_f32_e32 v102, v102
	v_sub_f32_e32 v65, v67, v204
	v_exp_f32_e32 v183, v65
	v_sub_f32_e32 v65, v68, v204
	v_add_f32_e32 v104, v102, v103
	v_sub_f32_e32 v103, v111, v204
	v_exp_f32_e32 v103, v103
	v_exp_f32_e32 v186, v65
	v_sub_f32_e32 v65, v69, v204
	v_exp_f32_e32 v188, v65
	v_add_f32_e32 v104, v103, v104
	v_add_f32_e32 v104, v80, v104
	v_add_f32_e32 v104, v81, v104
	v_add_f32_e32 v82, v195, v104
	v_add_f32_e32 v82, v197, v82
	v_add_f32_e32 v82, v199, v82
	v_add_f32_e32 v82, v200, v82
	v_add_f32_e32 v82, v201, v82
	v_add_f32_e32 v82, v202, v82
	v_add_f32_e32 v82, v185, v82
	v_add_f32_e32 v82, v187, v82
	v_add_f32_e32 v82, v189, v82
	v_add_f32_e32 v82, v191, v82
	v_add_f32_e32 v82, v193, v82
	v_add_f32_e32 v82, v194, v82
	v_add_f32_e32 v82, v196, v82
	v_add_f32_e32 v82, v198, v82
	v_add_f32_e32 v64, v177, v82
	v_add_f32_e32 v64, v179, v64
	v_sub_f32_e32 v65, v70, v204
	v_add_f32_e32 v64, v181, v64
	v_exp_f32_e32 v190, v65
	v_sub_f32_e32 v65, v71, v204
	v_add_f32_e32 v64, v183, v64
	v_exp_f32_e32 v192, v65
	v_sub_f32_e32 v65, v72, v204
	v_add_f32_e32 v64, v186, v64
	v_exp_f32_e32 v134, v65
	v_sub_f32_e32 v65, v73, v204
	v_add_f32_e32 v64, v188, v64
	v_exp_f32_e32 v136, v65
	v_sub_f32_e32 v65, v74, v204
	v_add_f32_e32 v64, v190, v64
	v_exp_f32_e32 v138, v65
	v_sub_f32_e32 v65, v75, v204
	v_add_f32_e32 v64, v192, v64
	v_exp_f32_e32 v149, v65
	v_sub_f32_e32 v65, v76, v204
	v_add_f32_e32 v64, v134, v64
	v_exp_f32_e32 v178, v65
	v_sub_f32_e32 v65, v77, v204
	v_add_f32_e32 v64, v136, v64
	v_exp_f32_e32 v180, v65
	v_sub_f32_e32 v65, v78, v204
	v_add_f32_e32 v64, v138, v64
	v_exp_f32_e32 v182, v65
	v_sub_f32_e32 v65, v79, v204
	v_add_f32_e32 v64, v149, v64
	v_exp_f32_e32 v184, v65
	v_sub_f32_e32 v16, v16, v204
	v_add_f32_e32 v64, v178, v64
	v_exp_f32_e32 v110, v16
	v_sub_f32_e32 v17, v17, v204
	v_add_f32_e32 v64, v180, v64
	v_exp_f32_e32 v128, v17
	v_sub_f32_e32 v17, v18, v204
	v_add_f32_e32 v64, v182, v64
	v_exp_f32_e32 v130, v17
	v_sub_f32_e32 v17, v19, v204
	v_add_f32_e32 v64, v184, v64
	v_exp_f32_e32 v132, v17
	v_sub_f32_e32 v17, v20, v204
	v_add_f32_e32 v16, v110, v64
	v_exp_f32_e32 v135, v17
	v_sub_f32_e32 v17, v21, v204
	v_add_f32_e32 v16, v128, v16
	v_exp_f32_e32 v137, v17
	v_sub_f32_e32 v17, v22, v204
	v_add_f32_e32 v16, v130, v16
	v_exp_f32_e32 v139, v17
	v_sub_f32_e32 v17, v23, v204
	v_add_f32_e32 v16, v132, v16
	v_exp_f32_e32 v151, v17
	v_sub_f32_e32 v17, v24, v204
	v_add_f32_e32 v16, v135, v16
	v_exp_f32_e32 v94, v17
	v_sub_f32_e32 v17, v25, v204
	v_add_f32_e32 v16, v137, v16
	v_exp_f32_e32 v104, v17
	v_sub_f32_e32 v17, v26, v204
	v_add_f32_e32 v16, v139, v16
	v_exp_f32_e32 v106, v17
	v_sub_f32_e32 v17, v27, v204
	v_add_f32_e32 v16, v151, v16
	v_exp_f32_e32 v108, v17
	v_sub_f32_e32 v17, v28, v204
	v_add_f32_e32 v16, v94, v16
	v_exp_f32_e32 v111, v17
	v_sub_f32_e32 v17, v29, v204
	v_add_f32_e32 v16, v104, v16
	v_exp_f32_e32 v129, v17
	v_sub_f32_e32 v17, v30, v204
	v_add_f32_e32 v16, v106, v16
	v_exp_f32_e32 v131, v17
	v_sub_f32_e32 v17, v31, v204
	v_add_f32_e32 v16, v108, v16
	v_exp_f32_e32 v133, v17
	v_sub_f32_e32 v0, v0, v204
	v_add_f32_e32 v16, v111, v16
	v_exp_f32_e32 v90, v0
	v_sub_f32_e32 v1, v1, v204
	v_add_f32_e32 v16, v129, v16
	v_exp_f32_e32 v91, v1
	v_sub_f32_e32 v1, v2, v204
	v_add_f32_e32 v16, v131, v16
	v_exp_f32_e32 v92, v1
	v_sub_f32_e32 v1, v3, v204
	v_add_f32_e32 v16, v133, v16
	v_exp_f32_e32 v93, v1
	v_sub_f32_e32 v1, v4, v204
	v_add_f32_e32 v0, v90, v16
	v_exp_f32_e32 v95, v1
	v_sub_f32_e32 v1, v5, v204
	v_add_f32_e32 v0, v91, v0
	v_exp_f32_e32 v105, v1
	v_sub_f32_e32 v1, v6, v204
	v_add_f32_e32 v0, v92, v0
	v_exp_f32_e32 v107, v1
	v_sub_f32_e32 v1, v7, v204
	v_add_f32_e32 v0, v93, v0
	v_exp_f32_e32 v109, v1
	v_sub_f32_e32 v1, v8, v204
	v_add_f32_e32 v0, v95, v0
	v_exp_f32_e32 v82, v1
	v_sub_f32_e32 v1, v9, v204
	v_add_f32_e32 v0, v105, v0
	v_exp_f32_e32 v83, v1
	v_sub_f32_e32 v1, v10, v204
	v_add_f32_e32 v0, v107, v0
	v_exp_f32_e32 v84, v1
	v_sub_f32_e32 v1, v11, v204
	v_add_f32_e32 v0, v109, v0
	v_exp_f32_e32 v85, v1
	v_sub_f32_e32 v1, v12, v204
	v_add_f32_e32 v0, v82, v0
	v_exp_f32_e32 v86, v1
	v_sub_f32_e32 v1, v13, v204
	v_add_f32_e32 v0, v83, v0
	v_exp_f32_e32 v87, v1
	v_sub_f32_e32 v1, v14, v204
	v_add_f32_e32 v0, v84, v0
	v_exp_f32_e32 v88, v1
	v_sub_f32_e32 v1, v15, v204
	v_add_f32_e32 v0, v85, v0
	v_exp_f32_e32 v89, v1
	v_sub_f32_e32 v1, v32, v204
	v_add_f32_e32 v0, v86, v0
	v_exp_f32_e32 v72, v1
	v_sub_f32_e32 v1, v33, v204
	v_add_f32_e32 v0, v87, v0
	v_exp_f32_e32 v73, v1
	v_sub_f32_e32 v1, v34, v204
	v_add_f32_e32 v0, v88, v0
	v_exp_f32_e32 v74, v1
	v_sub_f32_e32 v1, v35, v204
	v_add_f32_e32 v0, v89, v0
	v_exp_f32_e32 v75, v1
	v_sub_f32_e32 v1, v36, v204
	v_add_f32_e32 v0, v72, v0
	v_exp_f32_e32 v76, v1
	v_sub_f32_e32 v1, v37, v204
	v_add_f32_e32 v0, v73, v0
	v_exp_f32_e32 v77, v1
	v_sub_f32_e32 v1, v38, v204
	v_add_f32_e32 v0, v74, v0
	v_exp_f32_e32 v78, v1
	v_sub_f32_e32 v1, v39, v204
	v_add_f32_e32 v0, v75, v0
	v_exp_f32_e32 v79, v1
	v_sub_f32_e32 v1, v40, v204
	v_add_f32_e32 v0, v76, v0
	v_exp_f32_e32 v64, v1
	v_sub_f32_e32 v1, v41, v204
	v_add_f32_e32 v0, v77, v0
	v_exp_f32_e32 v65, v1
	v_sub_f32_e32 v1, v42, v204
	v_add_f32_e32 v0, v78, v0
	v_exp_f32_e32 v66, v1
	v_sub_f32_e32 v1, v43, v204
	v_add_f32_e32 v0, v79, v0
	v_exp_f32_e32 v67, v1
	v_sub_f32_e32 v1, v44, v204
	v_add_f32_e32 v0, v64, v0
	v_exp_f32_e32 v68, v1
	v_sub_f32_e32 v1, v45, v204
	v_add_f32_e32 v0, v65, v0
	v_exp_f32_e32 v69, v1
	v_sub_f32_e32 v1, v46, v204
	v_add_f32_e32 v0, v66, v0
	v_exp_f32_e32 v70, v1
	v_sub_f32_e32 v1, v47, v204
	v_add_f32_e32 v0, v67, v0
	v_exp_f32_e32 v71, v1
	v_sub_f32_e32 v1, v48, v204
	v_add_f32_e32 v0, v68, v0
	v_exp_f32_e32 v42, v1
	v_sub_f32_e32 v1, v49, v204
	v_add_f32_e32 v0, v69, v0
	v_exp_f32_e32 v43, v1
	v_sub_f32_e32 v1, v50, v204
	v_add_f32_e32 v0, v70, v0
	v_exp_f32_e32 v44, v1
	v_sub_f32_e32 v1, v51, v204
	v_add_f32_e32 v0, v71, v0
	v_exp_f32_e32 v45, v1
	v_sub_f32_e32 v1, v52, v204
	v_add_f32_e32 v0, v42, v0
	v_exp_f32_e32 v46, v1
	v_sub_f32_e32 v1, v53, v204
	v_add_f32_e32 v0, v43, v0
	v_exp_f32_e32 v47, v1
	v_sub_f32_e32 v1, v54, v204
	v_add_f32_e32 v0, v44, v0
	v_exp_f32_e32 v48, v1
	v_sub_f32_e32 v1, v55, v204
	v_add_f32_e32 v0, v45, v0
	v_exp_f32_e32 v49, v1
	v_sub_f32_e32 v1, v56, v204
	v_add_f32_e32 v0, v46, v0
	v_exp_f32_e32 v34, v1
	v_sub_f32_e32 v1, v57, v204
	v_add_f32_e32 v0, v47, v0
	v_exp_f32_e32 v35, v1
	v_sub_f32_e32 v1, v58, v204
	v_add_f32_e32 v0, v48, v0
	v_exp_f32_e32 v36, v1
	v_sub_f32_e32 v1, v59, v204
	v_add_f32_e32 v0, v49, v0
	v_exp_f32_e32 v37, v1
	v_sub_f32_e32 v1, v60, v204
	v_add_f32_e32 v0, v34, v0
	v_exp_f32_e32 v38, v1
	v_sub_f32_e32 v1, v61, v204
	v_add_f32_e32 v0, v35, v0
	v_exp_f32_e32 v39, v1
	v_sub_f32_e32 v1, v62, v204
	v_add_f32_e32 v0, v36, v0
	v_exp_f32_e32 v40, v1
	v_sub_f32_e32 v1, v63, v204
	v_add_f32_e32 v0, v37, v0
	v_exp_f32_e32 v41, v1
	v_add_f32_e32 v0, v38, v0
	v_add_f32_e32 v0, v39, v0
	v_add_f32_e32 v0, v40, v0
	v_add_f32_e32 v32, v41, v0
	ds_read2_b64 v[0:3], v172 offset1:2
	ds_read2_b64 v[52:55], v172 offset0:4 offset1:6
	v_cvt_pk_bf16_f32 v16, v203, v205
	v_cvt_pk_bf16_f32 v17, v206, v207
	v_cvt_pk_bf16_f32 v18, v208, v209
	v_cvt_pk_bf16_f32 v19, v210, v211
	v_add_u32_e32 v50, 0x4000, v172
	ds_read2_b64 v[20:23], v50 offset0:32 offset1:34
	s_waitcnt lgkmcnt(2)
	v_mfma_f32_32x32x16_bf16 v[0:15], v[0:3], v[16:19], 0
	v_cvt_pk_bf16_f32 v56, v112, v113
	v_cvt_pk_bf16_f32 v57, v114, v115
	v_cvt_pk_bf16_f32 v58, v116, v117
	v_cvt_pk_bf16_f32 v59, v118, v120
	v_cvt_pk_bf16_f32 v42, v42, v43
	v_cvt_pk_bf16_f32 v43, v44, v45
	v_cvt_pk_bf16_f32 v44, v46, v47
	s_waitcnt lgkmcnt(1)
	v_mfma_f32_32x32x16_bf16 v[0:15], v[52:55], v[56:59], v[0:15]
	ds_read2_b64 v[52:55], v50 offset0:36 offset1:38
	v_cvt_pk_bf16_f32 v45, v48, v49
	ds_read2_b64 v[46:49], v172 offset0:56 offset1:58
	v_cvt_pk_bf16_f32 v34, v34, v35
	v_cvt_pk_bf16_f32 v35, v36, v37
	v_cvt_pk_bf16_f32 v36, v38, v39
	v_cvt_pk_bf16_f32 v37, v40, v41
	s_waitcnt lgkmcnt(2)
	v_mfma_f32_32x32x16_bf16 v[16:31], v[20:23], v[16:19], 0
	ds_read2_b64 v[38:41], v172 offset0:60 offset1:62
	ds_bpermute_b32 v33, v173, v32
	s_waitcnt lgkmcnt(0)
	v_add_f32_e32 v32, v32, v33
	v_mfma_f32_32x32x16_bf16 v[16:31], v[52:55], v[56:59], v[16:31]
	ds_read2_b64 v[56:59], v172 offset0:8 offset1:10
	v_cvt_pk_bf16_f32 v52, v119, v121
	v_cvt_pk_bf16_f32 v53, v122, v123
	v_cvt_pk_bf16_f32 v54, v124, v125
	v_cvt_pk_bf16_f32 v55, v126, v127
	v_div_scale_f32 v33, s[6:7], v32, v32, 1.0
	s_waitcnt lgkmcnt(0)
	v_mfma_f32_32x32x16_bf16 v[0:15], v[56:59], v[52:55], v[0:15]
	ds_read2_b64 v[56:59], v50 offset0:40 offset1:42
	s_mov_b64 s[6:7], 0
	s_waitcnt lgkmcnt(0)
	v_mfma_f32_32x32x16_bf16 v[16:31], v[56:59], v[52:55], v[16:31]
	ds_read2_b64 v[56:59], v172 offset0:12 offset1:14
	v_cvt_pk_bf16_f32 v52, v96, v97
	v_cvt_pk_bf16_f32 v53, v98, v99
	v_cvt_pk_bf16_f32 v54, v100, v101
	v_cvt_pk_bf16_f32 v55, v102, v103
	s_waitcnt lgkmcnt(0)
	s_nop 0
	v_mfma_f32_32x32x16_bf16 v[0:15], v[56:59], v[52:55], v[0:15]
	ds_read2_b64 v[56:59], v50 offset0:44 offset1:46
	s_waitcnt lgkmcnt(0)
	v_mfma_f32_32x32x16_bf16 v[16:31], v[56:59], v[52:55], v[16:31]
	ds_read2_b64 v[56:59], v172 offset0:16 offset1:18
	v_cvt_pk_bf16_f32 v52, v80, v81
	v_cvt_pk_bf16_f32 v53, v195, v197
	v_cvt_pk_bf16_f32 v54, v199, v200
	v_cvt_pk_bf16_f32 v55, v201, v202
	s_waitcnt lgkmcnt(0)
	s_nop 0
	v_mfma_f32_32x32x16_bf16 v[0:15], v[56:59], v[52:55], v[0:15]
	ds_read2_b64 v[56:59], v50 offset0:48 offset1:50
	s_waitcnt lgkmcnt(0)
	v_mfma_f32_32x32x16_bf16 v[16:31], v[56:59], v[52:55], v[16:31]
	ds_read2_b64 v[56:59], v172 offset0:20 offset1:22
	v_cvt_pk_bf16_f32 v52, v185, v187
	v_cvt_pk_bf16_f32 v53, v189, v191
	v_cvt_pk_bf16_f32 v54, v193, v194
	v_cvt_pk_bf16_f32 v55, v196, v198
	s_waitcnt lgkmcnt(0)
	s_nop 0
	v_mfma_f32_32x32x16_bf16 v[0:15], v[56:59], v[52:55], v[0:15]
	ds_read2_b64 v[56:59], v50 offset0:52 offset1:54
	s_waitcnt lgkmcnt(0)
	v_mfma_f32_32x32x16_bf16 v[16:31], v[56:59], v[52:55], v[16:31]
	ds_read2_b64 v[56:59], v172 offset0:24 offset1:26
	v_cvt_pk_bf16_f32 v52, v177, v179
	v_cvt_pk_bf16_f32 v53, v181, v183
	v_cvt_pk_bf16_f32 v54, v186, v188
	v_cvt_pk_bf16_f32 v55, v190, v192
	s_waitcnt lgkmcnt(0)
	s_nop 0
	v_mfma_f32_32x32x16_bf16 v[0:15], v[56:59], v[52:55], v[0:15]
	ds_read2_b64 v[56:59], v50 offset0:56 offset1:58
	s_waitcnt lgkmcnt(0)
	v_mfma_f32_32x32x16_bf16 v[16:31], v[56:59], v[52:55], v[16:31]
	ds_read2_b64 v[56:59], v172 offset0:28 offset1:30
	v_cvt_pk_bf16_f32 v52, v134, v136
	v_cvt_pk_bf16_f32 v53, v138, v149
	v_cvt_pk_bf16_f32 v54, v178, v180
	v_cvt_pk_bf16_f32 v55, v182, v184
	s_waitcnt lgkmcnt(0)
	s_nop 0
	v_mfma_f32_32x32x16_bf16 v[0:15], v[56:59], v[52:55], v[0:15]
	ds_read2_b64 v[56:59], v50 offset0:60 offset1:62
	s_waitcnt lgkmcnt(0)
	v_mfma_f32_32x32x16_bf16 v[16:31], v[56:59], v[52:55], v[16:31]
	ds_read2_b64 v[56:59], v172 offset0:32 offset1:34
	v_cvt_pk_bf16_f32 v52, v110, v128
	v_cvt_pk_bf16_f32 v53, v130, v132
	v_cvt_pk_bf16_f32 v54, v135, v137
	v_cvt_pk_bf16_f32 v55, v139, v151
	v_mov_b32_e32 v151, v161
	s_waitcnt lgkmcnt(0)
	v_mfma_f32_32x32x16_bf16 v[0:15], v[56:59], v[52:55], v[0:15]
	ds_read2_b64 v[56:59], v50 offset0:64 offset1:66
	s_waitcnt lgkmcnt(0)
	v_mfma_f32_32x32x16_bf16 v[16:31], v[56:59], v[52:55], v[16:31]
	ds_read2_b64 v[56:59], v172 offset0:36 offset1:38
	v_cvt_pk_bf16_f32 v52, v94, v104
	v_cvt_pk_bf16_f32 v53, v106, v108
	v_cvt_pk_bf16_f32 v54, v111, v129
	v_cvt_pk_bf16_f32 v55, v131, v133
	s_waitcnt lgkmcnt(0)
	s_nop 0
	v_mfma_f32_32x32x16_bf16 v[0:15], v[56:59], v[52:55], v[0:15]
	ds_read2_b64 v[56:59], v50 offset0:68 offset1:70
	s_waitcnt lgkmcnt(0)
	v_mfma_f32_32x32x16_bf16 v[16:31], v[56:59], v[52:55], v[16:31]
	ds_read2_b64 v[56:59], v172 offset0:40 offset1:42
	v_cvt_pk_bf16_f32 v52, v90, v91
	v_cvt_pk_bf16_f32 v53, v92, v93
	v_cvt_pk_bf16_f32 v54, v95, v105
	v_cvt_pk_bf16_f32 v55, v107, v109
	s_waitcnt lgkmcnt(0)
	s_nop 0
	v_mfma_f32_32x32x16_bf16 v[0:15], v[56:59], v[52:55], v[0:15]
	ds_read2_b64 v[56:59], v50 offset0:72 offset1:74
	s_waitcnt lgkmcnt(0)
	v_mfma_f32_32x32x16_bf16 v[16:31], v[56:59], v[52:55], v[16:31]
	ds_read2_b64 v[56:59], v172 offset0:44 offset1:46
	v_cvt_pk_bf16_f32 v52, v82, v83
	v_cvt_pk_bf16_f32 v53, v84, v85
	v_cvt_pk_bf16_f32 v54, v86, v87
	v_cvt_pk_bf16_f32 v55, v88, v89
	s_waitcnt lgkmcnt(0)
	s_nop 0
	v_mfma_f32_32x32x16_bf16 v[0:15], v[56:59], v[52:55], v[0:15]
	ds_read2_b64 v[56:59], v50 offset0:76 offset1:78
	s_waitcnt lgkmcnt(0)
	v_mfma_f32_32x32x16_bf16 v[16:31], v[56:59], v[52:55], v[16:31]
	ds_read2_b64 v[56:59], v172 offset0:48 offset1:50
	v_cvt_pk_bf16_f32 v52, v72, v73
	v_cvt_pk_bf16_f32 v53, v74, v75
	v_cvt_pk_bf16_f32 v54, v76, v77
	v_cvt_pk_bf16_f32 v55, v78, v79
	s_waitcnt lgkmcnt(0)
	s_nop 0
	v_mfma_f32_32x32x16_bf16 v[0:15], v[56:59], v[52:55], v[0:15]
	ds_read2_b64 v[56:59], v50 offset0:80 offset1:82
	s_waitcnt lgkmcnt(0)
	v_mfma_f32_32x32x16_bf16 v[16:31], v[56:59], v[52:55], v[16:31]
	ds_read2_b64 v[56:59], v172 offset0:52 offset1:54
	v_cvt_pk_bf16_f32 v52, v64, v65
	v_cvt_pk_bf16_f32 v53, v66, v67
	v_cvt_pk_bf16_f32 v54, v68, v69
	v_cvt_pk_bf16_f32 v55, v70, v71
	s_waitcnt lgkmcnt(0)
	s_nop 0
	v_mfma_f32_32x32x16_bf16 v[0:15], v[56:59], v[52:55], v[0:15]
	ds_read2_b64 v[56:59], v50 offset0:84 offset1:86
	v_mfma_f32_32x32x16_bf16 v[0:15], v[46:49], v[42:45], v[0:15]
	ds_read2_b64 v[46:49], v50 offset0:88 offset1:90
	s_waitcnt lgkmcnt(1)
	v_mfma_f32_32x32x16_bf16 v[16:31], v[56:59], v[52:55], v[16:31]
	v_mfma_f32_32x32x16_bf16 v[0:15], v[38:41], v[34:37], v[0:15]
	ds_read2_b64 v[38:41], v50 offset0:92 offset1:94
	s_waitcnt lgkmcnt(1)
	v_mfma_f32_32x32x16_bf16 v[16:31], v[46:49], v[42:45], v[16:31]
	s_waitcnt lgkmcnt(0)
	v_mfma_f32_32x32x16_bf16 v[16:31], v[38:41], v[34:37], v[16:31]
	v_rcp_f32_e32 v34, v33
	s_nop 0
	v_fma_f32 v35, -v33, v34, 1.0
	v_fmac_f32_e32 v34, v35, v34
	v_div_scale_f32 v35, vcc, 1.0, v32, 1.0
	v_mul_f32_e32 v36, v35, v34
	v_fma_f32 v37, -v33, v36, v35
	v_fmac_f32_e32 v36, v37, v34
	v_fma_f32 v33, -v33, v36, v35
	v_div_fmas_f32 v33, v33, v34, v36
	v_div_fixup_f32 v32, v33, v32, 1.0
	v_lshl_add_u64 v[34:35], s[20:21], 0, v[152:153]
	v_lshl_add_u64 v[34:35], v[34:35], 0, s[4:5]
	v_pk_mul_f32 v[0:1], v[0:1], v[32:33] op_sel_hi:[1,0]
	v_pk_mul_f32 v[2:3], v[2:3], v[32:33] op_sel_hi:[1,0]
	v_lshl_add_u64 v[34:35], v[34:35], 0, v[150:151]
	v_cvt_pk_bf16_f32 v0, v0, v1
	v_cvt_pk_bf16_f32 v1, v2, v3
	global_store_dwordx2 v[34:35], v[0:1], off offset:1536 sc1
	v_pk_mul_f32 v[0:1], v[4:5], v[32:33] op_sel_hi:[1,0]
	v_pk_mul_f32 v[2:3], v[6:7], v[32:33] op_sel_hi:[1,0]
	v_cvt_pk_bf16_f32 v0, v0, v1
	v_cvt_pk_bf16_f32 v1, v2, v3
	global_store_dwordx2 v[34:35], v[0:1], off offset:1552 sc1
	v_pk_mul_f32 v[0:1], v[8:9], v[32:33] op_sel_hi:[1,0]
	v_pk_mul_f32 v[2:3], v[10:11], v[32:33] op_sel_hi:[1,0]
	v_cvt_pk_bf16_f32 v0, v0, v1
	v_cvt_pk_bf16_f32 v1, v2, v3
	global_store_dwordx2 v[34:35], v[0:1], off offset:1568 sc1
	v_pk_mul_f32 v[0:1], v[12:13], v[32:33] op_sel_hi:[1,0]
	v_pk_mul_f32 v[2:3], v[14:15], v[32:33] op_sel_hi:[1,0]
	v_cvt_pk_bf16_f32 v0, v0, v1
	v_cvt_pk_bf16_f32 v1, v2, v3
	global_store_dwordx2 v[34:35], v[0:1], off offset:1584 sc1
	v_pk_mul_f32 v[0:1], v[16:17], v[32:33] op_sel_hi:[1,0]
	v_pk_mul_f32 v[2:3], v[18:19], v[32:33] op_sel_hi:[1,0]
	v_cvt_pk_bf16_f32 v0, v0, v1
	v_cvt_pk_bf16_f32 v1, v2, v3
	global_store_dwordx2 v[34:35], v[0:1], off offset:1600 sc1
	v_pk_mul_f32 v[0:1], v[20:21], v[32:33] op_sel_hi:[1,0]
	v_pk_mul_f32 v[2:3], v[22:23], v[32:33] op_sel_hi:[1,0]
	v_cvt_pk_bf16_f32 v0, v0, v1
	v_cvt_pk_bf16_f32 v1, v2, v3
	global_store_dwordx2 v[34:35], v[0:1], off offset:1616 sc1
	v_pk_mul_f32 v[0:1], v[24:25], v[32:33] op_sel_hi:[1,0]
	v_pk_mul_f32 v[2:3], v[26:27], v[32:33] op_sel_hi:[1,0]
	v_cvt_pk_bf16_f32 v0, v0, v1
	v_cvt_pk_bf16_f32 v1, v2, v3
	global_store_dwordx2 v[34:35], v[0:1], off offset:1632 sc1
	v_pk_mul_f32 v[0:1], v[28:29], v[32:33] op_sel_hi:[1,0]
	v_pk_mul_f32 v[2:3], v[30:31], v[32:33] op_sel_hi:[1,0]
	v_cvt_pk_bf16_f32 v0, v0, v1
	v_cvt_pk_bf16_f32 v1, v2, v3
	global_store_dwordx2 v[34:35], v[0:1], off offset:1648 sc1
	s_barrier
	s_branch .LBB0_225

.LBB0_260:
	s_lshl_b32 s10, s10, 8
	s_waitcnt lgkmcnt(0)
	v_lshlrev_b64 v[154:155], 11, v[148:149]
	s_ashr_i32 s11, s10, 31
	v_cvt_pk_bf16_f32 v124, v124, v125
	v_cvt_pk_bf16_f32 v125, v126, v127
	v_cvt_pk_bf16_f32 v126, v120, v121
	v_lshl_add_u64 v[120:121], s[64:65], 0, v[154:155]
	v_lshl_add_u64 v[120:121], s[10:11], 1, v[120:121]
	s_lshl_b32 s4, s89, 1
	v_mov_b32_e32 v153, v152
	v_cvt_pk_bf16_f32 v127, v122, v123
	v_lshl_add_u64 v[120:121], v[120:121], 0, s[4:5]
	v_lshlrev_b32_e32 v160, 1, v136
	v_mov_b32_e32 v122, v152
	v_mov_b32_e32 v123, v152
	s_mov_b32 s28, 0x3fb8aa3b
	s_brev_b32 s50, 18
	s_mov_b32 s51, 0xfe5163ab
	v_lshl_add_u64 v[120:121], v[120:121], 0, v[160:161]
	v_pk_mul_f32 v[118:119], v[118:119], v[122:123]
	v_pk_mul_f32 v[116:117], v[116:117], v[152:153]
	v_pk_mul_f32 v[114:115], v[114:115], v[122:123]
	s_and_b64 vcc, exec, s[40:41]
	v_pk_mul_f32 v[112:113], v[112:113], v[152:153]
	global_store_dwordx4 v[120:121], v[124:127], off sc1
	s_cbranch_vccnz .LBB0_264
	ds_bpermute_b32 v152, v169, v116
	ds_bpermute_b32 v124, v169, v112
	ds_bpermute_b32 v153, v169, v117
	ds_bpermute_b32 v125, v169, v113
	ds_bpermute_b32 v126, v169, v118
	ds_bpermute_b32 v122, v169, v114
	ds_bpermute_b32 v127, v169, v119
	ds_bpermute_b32 v123, v169, v115
	s_and_saveexec_b64 s[42:43], s[36:37]
	s_cbranch_execz .LBB0_263
	v_lshl_add_u64 v[150:151], s[20:21], 0, v[150:151]
	global_load_dwordx4 v[154:157], v[150:151], off
	global_load_dwordx4 v[176:179], v[150:151], off offset:32
	global_load_dwordx4 v[180:183], v[150:151], off offset:16
	global_load_dwordx4 v[184:187], v[150:151], off offset:48
	s_waitcnt vmcnt(3)
	v_pk_mul_f32 v[118:119], v[118:119], v[156:157]
	v_pk_mul_f32 v[116:117], v[116:117], v[154:155]
	s_waitcnt vmcnt(2) lgkmcnt(5)
	v_pk_mul_f32 v[150:151], v[176:177], v[152:153]
	s_waitcnt lgkmcnt(1)
	v_pk_mul_f32 v[126:127], v[178:179], v[126:127]
	s_waitcnt vmcnt(1)
	v_pk_mul_f32 v[114:115], v[114:115], v[182:183]
	v_pk_mul_f32 v[112:113], v[112:113], v[180:181]
	s_waitcnt vmcnt(0)
	v_pk_mul_f32 v[124:125], v[184:185], v[124:125]
	s_waitcnt lgkmcnt(0)
	v_pk_mul_f32 v[122:123], v[186:187], v[122:123]
	v_pk_fma_f32 v[118:119], v[140:141], v[126:127], v[118:119]
	v_pk_fma_f32 v[116:117], v[138:139], v[150:151], v[116:117]
	v_pk_fma_f32 v[114:115], v[140:141], v[122:123], v[114:115]
	v_pk_fma_f32 v[112:113], v[138:139], v[124:125], v[112:113]

.LBB0_264:
	v_cvt_pk_bf16_f32 v116, v116, v117
	v_cvt_pk_bf16_f32 v117, v118, v119
	v_cvt_pk_bf16_f32 v119, v114, v115
	v_or_b32_e32 v114, 16, v148
	v_ashrrev_i32_e32 v115, 31, v114
	v_cvt_pk_bf16_f32 v118, v112, v113
	v_lshlrev_b64 v[112:113], 6, v[114:115]
	global_store_dwordx4 v[120:121], v[116:119], off offset:256 sc1
	s_and_b64 vcc, exec, s[40:41]
	s_nop 0
	v_lshl_add_u64 v[116:117], v[142:143], 0, v[112:113]
	global_load_dwordx4 v[116:119], v[116:117], off
	s_waitcnt vmcnt(0)
	v_mov_b32_e32 v120, v117
	v_mov_b32_e32 v121, v118
	v_mov_b32_e32 v117, v119
	v_pk_add_f32 v[116:117], v[120:121], v[116:117]
	s_nop 0
	v_add_f32_e32 v116, v116, v117
	ds_bpermute_b32 v117, v169, v116
	s_waitcnt lgkmcnt(0)
	v_add_f32_e32 v116, v116, v117
	ds_bpermute_b32 v117, v172, v116
	s_waitcnt lgkmcnt(0)
	v_add_f32_e32 v116, v116, v117
	v_fmamk_f32 v116, v116, 0x3a800000, v216
	v_mul_f32_e32 v117, 0x4b800000, v116
	v_cmp_gt_f32_e64 s[42:43], s29, v116
	s_nop 1
	v_cndmask_b32_e64 v116, v116, v117, s[42:43]
	v_rsq_f32_e32 v116, v116
	s_nop 0
	v_mul_f32_e32 v117, 0x45800000, v116
	v_cndmask_b32_e64 v116, v116, v117, s[42:43]
	v_mul_f32_e32 v116, v174, v116
	v_pk_mul_f32 v[110:111], v[110:111], v[116:117] op_sel_hi:[1,0]
	v_pk_mul_f32 v[108:109], v[108:109], v[116:117] op_sel_hi:[1,0]
	v_pk_mul_f32 v[106:107], v[106:107], v[116:117] op_sel_hi:[1,0]
	v_pk_mul_f32 v[104:105], v[104:105], v[116:117] op_sel_hi:[1,0]
	s_cbranch_vccnz .LBB0_268
	ds_bpermute_b32 v124, v169, v108
	ds_bpermute_b32 v120, v169, v104
	ds_bpermute_b32 v125, v169, v109
	ds_bpermute_b32 v121, v169, v105
	ds_bpermute_b32 v122, v169, v110
	ds_bpermute_b32 v118, v169, v106
	ds_bpermute_b32 v123, v169, v111
	ds_bpermute_b32 v119, v169, v107
	s_and_saveexec_b64 s[42:43], s[36:37]
	s_cbranch_execz .LBB0_267
	v_lshl_add_u64 v[126:127], s[20:21], 0, v[112:113]
	global_load_dwordx4 v[150:153], v[126:127], off
	global_load_dwordx4 v[154:157], v[126:127], off offset:32
	global_load_dwordx4 v[176:179], v[126:127], off offset:16
	global_load_dwordx4 v[180:183], v[126:127], off offset:48
	s_waitcnt vmcnt(3)
	v_pk_mul_f32 v[110:111], v[110:111], v[152:153]
	v_pk_mul_f32 v[108:109], v[108:109], v[150:151]
	s_waitcnt vmcnt(2) lgkmcnt(5)
	v_pk_mul_f32 v[124:125], v[154:155], v[124:125]
	s_waitcnt lgkmcnt(1)
	v_pk_mul_f32 v[122:123], v[156:157], v[122:123]
	s_waitcnt vmcnt(1)
	v_pk_mul_f32 v[106:107], v[106:107], v[178:179]
	v_pk_mul_f32 v[104:105], v[104:105], v[176:177]
	s_waitcnt vmcnt(0)
	v_pk_mul_f32 v[120:121], v[180:181], v[120:121]
	s_waitcnt lgkmcnt(0)
	v_pk_mul_f32 v[118:119], v[182:183], v[118:119]
	v_pk_fma_f32 v[110:111], v[140:141], v[122:123], v[110:111]
	v_pk_fma_f32 v[108:109], v[138:139], v[124:125], v[108:109]
	v_pk_fma_f32 v[106:107], v[140:141], v[118:119], v[106:107]
	v_pk_fma_f32 v[104:105], v[138:139], v[120:121], v[104:105]

.LBB0_268:
	v_lshlrev_b64 v[114:115], 11, v[114:115]
	v_cvt_pk_bf16_f32 v108, v108, v109
	v_cvt_pk_bf16_f32 v109, v110, v111
	v_cvt_pk_bf16_f32 v110, v104, v105
	v_lshl_add_u64 v[104:105], s[64:65], 0, v[114:115]
	v_lshl_add_u64 v[104:105], s[10:11], 1, v[104:105]
	v_mov_b32_e32 v117, v116
	v_cvt_pk_bf16_f32 v111, v106, v107
	v_lshl_add_u64 v[104:105], v[104:105], 0, s[4:5]
	v_mov_b32_e32 v106, v116
	v_mov_b32_e32 v107, v116
	v_lshl_add_u64 v[104:105], v[104:105], 0, v[160:161]
	v_pk_mul_f32 v[102:103], v[102:103], v[106:107]
	v_pk_mul_f32 v[100:101], v[100:101], v[116:117]
	v_pk_mul_f32 v[98:99], v[98:99], v[106:107]
	s_and_b64 vcc, exec, s[40:41]
	v_pk_mul_f32 v[96:97], v[96:97], v[116:117]
	global_store_dwordx4 v[104:105], v[108:111], off sc1
	s_cbranch_vccnz .LBB0_272
	ds_bpermute_b32 v114, v169, v100
	ds_bpermute_b32 v108, v169, v96
	ds_bpermute_b32 v115, v169, v101
	ds_bpermute_b32 v109, v169, v97
	ds_bpermute_b32 v110, v169, v102
	ds_bpermute_b32 v106, v169, v98
	ds_bpermute_b32 v111, v169, v103
	ds_bpermute_b32 v107, v169, v99
	s_and_saveexec_b64 s[42:43], s[36:37]
	s_cbranch_execz .LBB0_271
	v_lshl_add_u64 v[112:113], s[20:21], 0, v[112:113]
	s_waitcnt lgkmcnt(8)
	global_load_dwordx4 v[116:119], v[112:113], off
	global_load_dwordx4 v[120:123], v[112:113], off offset:32
	global_load_dwordx4 v[124:127], v[112:113], off offset:16
	global_load_dwordx4 v[150:153], v[112:113], off offset:48
	s_waitcnt vmcnt(3)
	v_pk_mul_f32 v[102:103], v[102:103], v[118:119]
	v_pk_mul_f32 v[100:101], v[100:101], v[116:117]
	s_waitcnt vmcnt(2) lgkmcnt(5)
	v_pk_mul_f32 v[112:113], v[120:121], v[114:115]
	s_waitcnt lgkmcnt(1)
	v_pk_mul_f32 v[110:111], v[122:123], v[110:111]
	s_waitcnt vmcnt(1)
	v_pk_mul_f32 v[98:99], v[98:99], v[126:127]
	v_pk_mul_f32 v[96:97], v[96:97], v[124:125]
	s_waitcnt vmcnt(0)
	v_pk_mul_f32 v[108:109], v[150:151], v[108:109]
	s_waitcnt lgkmcnt(0)
	v_pk_mul_f32 v[106:107], v[152:153], v[106:107]
	v_pk_fma_f32 v[102:103], v[140:141], v[110:111], v[102:103]
	v_pk_fma_f32 v[100:101], v[138:139], v[112:113], v[100:101]
	v_pk_fma_f32 v[98:99], v[140:141], v[106:107], v[98:99]
	v_pk_fma_f32 v[96:97], v[138:139], v[108:109], v[96:97]

.LBB0_272:
	v_cvt_pk_bf16_f32 v100, v100, v101
	v_cvt_pk_bf16_f32 v101, v102, v103
	v_cvt_pk_bf16_f32 v103, v98, v99
	v_or_b32_e32 v98, 32, v148
	v_ashrrev_i32_e32 v99, 31, v98
	v_cvt_pk_bf16_f32 v102, v96, v97
	v_lshlrev_b64 v[96:97], 6, v[98:99]
	global_store_dwordx4 v[104:105], v[100:103], off offset:256 sc1
	s_and_b64 vcc, exec, s[40:41]
	s_nop 0
	v_lshl_add_u64 v[100:101], v[142:143], 0, v[96:97]
	global_load_dwordx4 v[100:103], v[100:101], off
	s_waitcnt vmcnt(0)
	v_mov_b32_e32 v104, v101
	v_mov_b32_e32 v105, v102
	v_mov_b32_e32 v101, v103
	v_pk_add_f32 v[100:101], v[104:105], v[100:101]
	s_nop 0
	v_add_f32_e32 v100, v100, v101
	ds_bpermute_b32 v101, v169, v100
	s_waitcnt lgkmcnt(0)
	v_add_f32_e32 v100, v100, v101
	ds_bpermute_b32 v101, v172, v100
	s_waitcnt lgkmcnt(0)
	v_add_f32_e32 v100, v100, v101
	v_fmamk_f32 v100, v100, 0x3a800000, v216
	v_mul_f32_e32 v101, 0x4b800000, v100
	v_cmp_gt_f32_e64 s[42:43], s29, v100
	s_nop 1
	v_cndmask_b32_e64 v100, v100, v101, s[42:43]
	v_rsq_f32_e32 v100, v100
	s_nop 0
	v_mul_f32_e32 v101, 0x45800000, v100
	v_cndmask_b32_e64 v100, v100, v101, s[42:43]
	v_mul_f32_e32 v100, v174, v100
	v_pk_mul_f32 v[94:95], v[94:95], v[100:101] op_sel_hi:[1,0]
	v_pk_mul_f32 v[92:93], v[92:93], v[100:101] op_sel_hi:[1,0]
	v_pk_mul_f32 v[90:91], v[90:91], v[100:101] op_sel_hi:[1,0]
	v_pk_mul_f32 v[88:89], v[88:89], v[100:101] op_sel_hi:[1,0]
	s_cbranch_vccnz .LBB0_276
	ds_bpermute_b32 v108, v169, v92
	ds_bpermute_b32 v104, v169, v88
	ds_bpermute_b32 v109, v169, v93
	ds_bpermute_b32 v105, v169, v89
	ds_bpermute_b32 v106, v169, v94
	ds_bpermute_b32 v102, v169, v90
	ds_bpermute_b32 v107, v169, v95
	ds_bpermute_b32 v103, v169, v91
	s_and_saveexec_b64 s[42:43], s[36:37]
	s_cbranch_execz .LBB0_275
	v_lshl_add_u64 v[122:123], s[20:21], 0, v[96:97]
	global_load_dwordx4 v[110:113], v[122:123], off
	global_load_dwordx4 v[114:117], v[122:123], off offset:32
	global_load_dwordx4 v[118:121], v[122:123], off offset:16
	s_nop 0
	global_load_dwordx4 v[122:125], v[122:123], off offset:48
	s_waitcnt vmcnt(3)
	v_pk_mul_f32 v[94:95], v[94:95], v[112:113]
	v_pk_mul_f32 v[92:93], v[92:93], v[110:111]
	s_waitcnt vmcnt(2) lgkmcnt(5)
	v_pk_mul_f32 v[108:109], v[114:115], v[108:109]
	s_waitcnt lgkmcnt(1)
	v_pk_mul_f32 v[106:107], v[116:117], v[106:107]
	s_waitcnt vmcnt(1)
	v_pk_mul_f32 v[90:91], v[90:91], v[120:121]
	v_pk_mul_f32 v[88:89], v[88:89], v[118:119]
	s_waitcnt vmcnt(0)
	v_pk_mul_f32 v[104:105], v[122:123], v[104:105]
	s_waitcnt lgkmcnt(0)
	v_pk_mul_f32 v[102:103], v[124:125], v[102:103]
	v_pk_fma_f32 v[94:95], v[140:141], v[106:107], v[94:95]
	v_pk_fma_f32 v[92:93], v[138:139], v[108:109], v[92:93]
	v_pk_fma_f32 v[90:91], v[140:141], v[102:103], v[90:91]
	v_pk_fma_f32 v[88:89], v[138:139], v[104:105], v[88:89]

.LBB0_276:
	v_lshlrev_b64 v[98:99], 11, v[98:99]
	v_cvt_pk_bf16_f32 v92, v92, v93
	v_cvt_pk_bf16_f32 v93, v94, v95
	v_cvt_pk_bf16_f32 v94, v88, v89
	v_lshl_add_u64 v[88:89], s[64:65], 0, v[98:99]
	v_lshl_add_u64 v[88:89], s[10:11], 1, v[88:89]
	v_mov_b32_e32 v101, v100
	v_cvt_pk_bf16_f32 v95, v90, v91
	v_lshl_add_u64 v[88:89], v[88:89], 0, s[4:5]
	v_mov_b32_e32 v90, v100
	v_mov_b32_e32 v91, v100
	v_lshl_add_u64 v[88:89], v[88:89], 0, v[160:161]
	v_pk_mul_f32 v[86:87], v[86:87], v[90:91]
	v_pk_mul_f32 v[84:85], v[84:85], v[100:101]
	v_pk_mul_f32 v[82:83], v[82:83], v[90:91]
	s_and_b64 vcc, exec, s[40:41]
	v_pk_mul_f32 v[80:81], v[80:81], v[100:101]
	global_store_dwordx4 v[88:89], v[92:95], off sc1
	s_cbranch_vccnz .LBB0_280
	ds_bpermute_b32 v98, v169, v84
	ds_bpermute_b32 v92, v169, v80
	ds_bpermute_b32 v99, v169, v85
	ds_bpermute_b32 v93, v169, v81
	ds_bpermute_b32 v94, v169, v86
	ds_bpermute_b32 v90, v169, v82
	ds_bpermute_b32 v95, v169, v87
	ds_bpermute_b32 v91, v169, v83
	s_and_saveexec_b64 s[42:43], s[36:37]
	s_cbranch_execz .LBB0_279
	v_lshl_add_u64 v[96:97], s[20:21], 0, v[96:97]
	s_waitcnt lgkmcnt(8)
	global_load_dwordx4 v[100:103], v[96:97], off
	global_load_dwordx4 v[104:107], v[96:97], off offset:32
	global_load_dwordx4 v[108:111], v[96:97], off offset:16
	global_load_dwordx4 v[112:115], v[96:97], off offset:48
	s_waitcnt vmcnt(3)
	v_pk_mul_f32 v[86:87], v[86:87], v[102:103]
	v_pk_mul_f32 v[84:85], v[84:85], v[100:101]
	s_waitcnt vmcnt(2) lgkmcnt(5)
	v_pk_mul_f32 v[96:97], v[104:105], v[98:99]
	s_waitcnt lgkmcnt(1)
	v_pk_mul_f32 v[94:95], v[106:107], v[94:95]
	s_waitcnt vmcnt(1)
	v_pk_mul_f32 v[82:83], v[82:83], v[110:111]
	v_pk_mul_f32 v[80:81], v[80:81], v[108:109]
	s_waitcnt vmcnt(0)
	v_pk_mul_f32 v[92:93], v[112:113], v[92:93]
	s_waitcnt lgkmcnt(0)
	v_pk_mul_f32 v[90:91], v[114:115], v[90:91]
	v_pk_fma_f32 v[86:87], v[140:141], v[94:95], v[86:87]
	v_pk_fma_f32 v[84:85], v[138:139], v[96:97], v[84:85]
	v_pk_fma_f32 v[82:83], v[140:141], v[90:91], v[82:83]
	v_pk_fma_f32 v[80:81], v[138:139], v[92:93], v[80:81]

.LBB0_280:
	v_cvt_pk_bf16_f32 v84, v84, v85
	v_cvt_pk_bf16_f32 v85, v86, v87
	v_cvt_pk_bf16_f32 v87, v82, v83
	v_or_b32_e32 v82, 48, v148
	v_ashrrev_i32_e32 v83, 31, v82
	v_cvt_pk_bf16_f32 v86, v80, v81
	v_lshlrev_b64 v[80:81], 6, v[82:83]
	global_store_dwordx4 v[88:89], v[84:87], off offset:256 sc1
	s_and_b64 vcc, exec, s[40:41]
	s_nop 0
	v_lshl_add_u64 v[84:85], v[142:143], 0, v[80:81]
	global_load_dwordx4 v[84:87], v[84:85], off
	s_waitcnt vmcnt(0)
	v_mov_b32_e32 v88, v85
	v_mov_b32_e32 v89, v86
	v_mov_b32_e32 v85, v87
	v_pk_add_f32 v[84:85], v[88:89], v[84:85]
	s_nop 0
	v_add_f32_e32 v84, v84, v85
	ds_bpermute_b32 v85, v169, v84
	s_waitcnt lgkmcnt(0)
	v_add_f32_e32 v84, v84, v85
	ds_bpermute_b32 v85, v172, v84
	s_waitcnt lgkmcnt(0)
	v_add_f32_e32 v84, v84, v85
	v_fmamk_f32 v84, v84, 0x3a800000, v216
	v_mul_f32_e32 v85, 0x4b800000, v84
	v_cmp_gt_f32_e64 s[42:43], s29, v84
	s_nop 1
	v_cndmask_b32_e64 v84, v84, v85, s[42:43]
	v_rsq_f32_e32 v84, v84
	s_nop 0
	v_mul_f32_e32 v85, 0x45800000, v84
	v_cndmask_b32_e64 v84, v84, v85, s[42:43]
	v_mul_f32_e32 v84, v174, v84
	v_pk_mul_f32 v[78:79], v[78:79], v[84:85] op_sel_hi:[1,0]
	v_pk_mul_f32 v[76:77], v[76:77], v[84:85] op_sel_hi:[1,0]
	v_pk_mul_f32 v[74:75], v[74:75], v[84:85] op_sel_hi:[1,0]
	v_pk_mul_f32 v[72:73], v[72:73], v[84:85] op_sel_hi:[1,0]
	s_cbranch_vccnz .LBB0_284
	ds_bpermute_b32 v92, v169, v76
	ds_bpermute_b32 v88, v169, v72
	ds_bpermute_b32 v93, v169, v77
	ds_bpermute_b32 v89, v169, v73
	ds_bpermute_b32 v90, v169, v78
	ds_bpermute_b32 v86, v169, v74
	ds_bpermute_b32 v91, v169, v79
	ds_bpermute_b32 v87, v169, v75
	s_and_saveexec_b64 s[42:43], s[36:37]
	s_cbranch_execz .LBB0_283
	v_lshl_add_u64 v[106:107], s[20:21], 0, v[80:81]
	global_load_dwordx4 v[94:97], v[106:107], off
	global_load_dwordx4 v[98:101], v[106:107], off offset:32
	global_load_dwordx4 v[102:105], v[106:107], off offset:16
	s_nop 0
	global_load_dwordx4 v[106:109], v[106:107], off offset:48
	s_waitcnt vmcnt(3)
	v_pk_mul_f32 v[78:79], v[78:79], v[96:97]
	v_pk_mul_f32 v[76:77], v[76:77], v[94:95]
	s_waitcnt vmcnt(2) lgkmcnt(5)
	v_pk_mul_f32 v[92:93], v[98:99], v[92:93]
	s_waitcnt lgkmcnt(1)
	v_pk_mul_f32 v[90:91], v[100:101], v[90:91]
	s_waitcnt vmcnt(1)
	v_pk_mul_f32 v[74:75], v[74:75], v[104:105]
	v_pk_mul_f32 v[72:73], v[72:73], v[102:103]
	s_waitcnt vmcnt(0)
	v_pk_mul_f32 v[88:89], v[106:107], v[88:89]
	s_waitcnt lgkmcnt(0)
	v_pk_mul_f32 v[86:87], v[108:109], v[86:87]
	v_pk_fma_f32 v[78:79], v[140:141], v[90:91], v[78:79]
	v_pk_fma_f32 v[76:77], v[138:139], v[92:93], v[76:77]
	v_pk_fma_f32 v[74:75], v[140:141], v[86:87], v[74:75]
	v_pk_fma_f32 v[72:73], v[138:139], v[88:89], v[72:73]

.LBB0_284:
	v_lshlrev_b64 v[82:83], 11, v[82:83]
	v_cvt_pk_bf16_f32 v76, v76, v77
	v_cvt_pk_bf16_f32 v77, v78, v79
	v_cvt_pk_bf16_f32 v78, v72, v73
	v_lshl_add_u64 v[72:73], s[64:65], 0, v[82:83]
	v_lshl_add_u64 v[72:73], s[10:11], 1, v[72:73]
	v_mov_b32_e32 v85, v84
	v_cvt_pk_bf16_f32 v79, v74, v75
	v_lshl_add_u64 v[72:73], v[72:73], 0, s[4:5]
	v_mov_b32_e32 v74, v84
	v_mov_b32_e32 v75, v84
	v_lshl_add_u64 v[72:73], v[72:73], 0, v[160:161]
	v_pk_mul_f32 v[70:71], v[70:71], v[74:75]
	v_pk_mul_f32 v[68:69], v[68:69], v[84:85]
	v_pk_mul_f32 v[66:67], v[66:67], v[74:75]
	s_and_b64 vcc, exec, s[40:41]
	v_pk_mul_f32 v[64:65], v[64:65], v[84:85]
	global_store_dwordx4 v[72:73], v[76:79], off sc1
	s_cbranch_vccnz .LBB0_288
	ds_bpermute_b32 v82, v169, v68
	ds_bpermute_b32 v76, v169, v64
	ds_bpermute_b32 v83, v169, v69
	ds_bpermute_b32 v77, v169, v65
	ds_bpermute_b32 v78, v169, v70
	ds_bpermute_b32 v74, v169, v66
	ds_bpermute_b32 v79, v169, v71
	ds_bpermute_b32 v75, v169, v67
	s_and_saveexec_b64 s[42:43], s[36:37]
	s_cbranch_execz .LBB0_287
	v_lshl_add_u64 v[80:81], s[20:21], 0, v[80:81]
	s_waitcnt lgkmcnt(8)
	global_load_dwordx4 v[84:87], v[80:81], off
	global_load_dwordx4 v[88:91], v[80:81], off offset:32
	global_load_dwordx4 v[92:95], v[80:81], off offset:16
	global_load_dwordx4 v[96:99], v[80:81], off offset:48
	s_waitcnt vmcnt(3)
	v_pk_mul_f32 v[70:71], v[70:71], v[86:87]
	v_pk_mul_f32 v[68:69], v[68:69], v[84:85]
	s_waitcnt vmcnt(2) lgkmcnt(5)
	v_pk_mul_f32 v[80:81], v[88:89], v[82:83]
	s_waitcnt lgkmcnt(1)
	v_pk_mul_f32 v[78:79], v[90:91], v[78:79]
	s_waitcnt vmcnt(1)
	v_pk_mul_f32 v[66:67], v[66:67], v[94:95]
	v_pk_mul_f32 v[64:65], v[64:65], v[92:93]
	s_waitcnt vmcnt(0)
	v_pk_mul_f32 v[76:77], v[96:97], v[76:77]
	s_waitcnt lgkmcnt(0)
	v_pk_mul_f32 v[74:75], v[98:99], v[74:75]
	v_pk_fma_f32 v[70:71], v[140:141], v[78:79], v[70:71]
	v_pk_fma_f32 v[68:69], v[138:139], v[80:81], v[68:69]
	v_pk_fma_f32 v[66:67], v[140:141], v[74:75], v[66:67]
	v_pk_fma_f32 v[64:65], v[138:139], v[76:77], v[64:65]

.LBB0_288:
	v_cvt_pk_bf16_f32 v68, v68, v69
	v_cvt_pk_bf16_f32 v69, v70, v71
	v_cvt_pk_bf16_f32 v71, v66, v67
	v_add_u32_e32 v66, 0x80, v148
	v_ashrrev_i32_e32 v67, 31, v66
	v_cvt_pk_bf16_f32 v70, v64, v65
	v_lshlrev_b64 v[64:65], 6, v[66:67]
	global_store_dwordx4 v[72:73], v[68:71], off offset:256 sc1
	s_and_b64 vcc, exec, s[40:41]
	s_nop 0
	v_lshl_add_u64 v[68:69], v[142:143], 0, v[64:65]
	global_load_dwordx4 v[68:71], v[68:69], off
	s_waitcnt vmcnt(0)
	v_mov_b32_e32 v72, v69
	v_mov_b32_e32 v73, v70
	v_mov_b32_e32 v69, v71
	v_pk_add_f32 v[68:69], v[72:73], v[68:69]
	s_nop 0
	v_add_f32_e32 v68, v68, v69
	ds_bpermute_b32 v69, v169, v68
	s_waitcnt lgkmcnt(0)
	v_add_f32_e32 v68, v68, v69
	ds_bpermute_b32 v69, v172, v68
	s_waitcnt lgkmcnt(0)
	v_add_f32_e32 v68, v68, v69
	v_fmamk_f32 v68, v68, 0x3a800000, v216
	v_mul_f32_e32 v69, 0x4b800000, v68
	v_cmp_gt_f32_e64 s[42:43], s29, v68
	s_nop 1
	v_cndmask_b32_e64 v68, v68, v69, s[42:43]
	v_rsq_f32_e32 v68, v68
	s_nop 0
	v_mul_f32_e32 v69, 0x45800000, v68
	v_cndmask_b32_e64 v68, v68, v69, s[42:43]
	v_mul_f32_e32 v68, v174, v68
	v_pk_mul_f32 v[62:63], v[62:63], v[68:69] op_sel_hi:[1,0]
	v_pk_mul_f32 v[60:61], v[60:61], v[68:69] op_sel_hi:[1,0]
	v_pk_mul_f32 v[58:59], v[58:59], v[68:69] op_sel_hi:[1,0]
	v_pk_mul_f32 v[56:57], v[56:57], v[68:69] op_sel_hi:[1,0]
	s_cbranch_vccnz .LBB0_292
	ds_bpermute_b32 v76, v169, v60
	ds_bpermute_b32 v72, v169, v56
	ds_bpermute_b32 v77, v169, v61
	ds_bpermute_b32 v73, v169, v57
	ds_bpermute_b32 v74, v169, v62
	ds_bpermute_b32 v70, v169, v58
	ds_bpermute_b32 v75, v169, v63
	ds_bpermute_b32 v71, v169, v59
	s_and_saveexec_b64 s[42:43], s[36:37]
	s_cbranch_execz .LBB0_291
	v_lshl_add_u64 v[90:91], s[20:21], 0, v[64:65]
	global_load_dwordx4 v[78:81], v[90:91], off
	global_load_dwordx4 v[82:85], v[90:91], off offset:32
	global_load_dwordx4 v[86:89], v[90:91], off offset:16
	s_nop 0
	global_load_dwordx4 v[90:93], v[90:91], off offset:48
	s_waitcnt vmcnt(3)
	v_pk_mul_f32 v[62:63], v[62:63], v[80:81]
	v_pk_mul_f32 v[60:61], v[60:61], v[78:79]
	s_waitcnt vmcnt(2) lgkmcnt(5)
	v_pk_mul_f32 v[76:77], v[82:83], v[76:77]
	s_waitcnt lgkmcnt(1)
	v_pk_mul_f32 v[74:75], v[84:85], v[74:75]
	s_waitcnt vmcnt(1)
	v_pk_mul_f32 v[58:59], v[58:59], v[88:89]
	v_pk_mul_f32 v[56:57], v[56:57], v[86:87]
	s_waitcnt vmcnt(0)
	v_pk_mul_f32 v[72:73], v[90:91], v[72:73]
	s_waitcnt lgkmcnt(0)
	v_pk_mul_f32 v[70:71], v[92:93], v[70:71]
	v_pk_fma_f32 v[62:63], v[140:141], v[74:75], v[62:63]
	v_pk_fma_f32 v[60:61], v[138:139], v[76:77], v[60:61]
	v_pk_fma_f32 v[58:59], v[140:141], v[70:71], v[58:59]
	v_pk_fma_f32 v[56:57], v[138:139], v[72:73], v[56:57]

.LBB0_292:
	v_lshlrev_b64 v[66:67], 11, v[66:67]
	v_cvt_pk_bf16_f32 v60, v60, v61
	v_cvt_pk_bf16_f32 v61, v62, v63
	v_cvt_pk_bf16_f32 v62, v56, v57
	v_lshl_add_u64 v[56:57], s[64:65], 0, v[66:67]
	v_lshl_add_u64 v[56:57], s[10:11], 1, v[56:57]
	v_mov_b32_e32 v69, v68
	v_cvt_pk_bf16_f32 v63, v58, v59
	v_lshl_add_u64 v[56:57], v[56:57], 0, s[4:5]
	v_mov_b32_e32 v58, v68
	v_mov_b32_e32 v59, v68
	v_lshl_add_u64 v[56:57], v[56:57], 0, v[160:161]
	v_pk_mul_f32 v[54:55], v[54:55], v[58:59]
	v_pk_mul_f32 v[52:53], v[52:53], v[68:69]
	v_pk_mul_f32 v[50:51], v[50:51], v[58:59]
	s_and_b64 vcc, exec, s[40:41]
	v_pk_mul_f32 v[48:49], v[48:49], v[68:69]
	global_store_dwordx4 v[56:57], v[60:63], off sc1
	s_cbranch_vccnz .LBB0_296
	ds_bpermute_b32 v66, v169, v52
	ds_bpermute_b32 v60, v169, v48
	ds_bpermute_b32 v67, v169, v53
	ds_bpermute_b32 v61, v169, v49
	ds_bpermute_b32 v62, v169, v54
	ds_bpermute_b32 v58, v169, v50
	ds_bpermute_b32 v63, v169, v55
	ds_bpermute_b32 v59, v169, v51
	s_and_saveexec_b64 s[42:43], s[36:37]
	s_cbranch_execz .LBB0_295
	v_lshl_add_u64 v[64:65], s[20:21], 0, v[64:65]
	s_waitcnt lgkmcnt(8)
	global_load_dwordx4 v[68:71], v[64:65], off
	global_load_dwordx4 v[72:75], v[64:65], off offset:32
	global_load_dwordx4 v[76:79], v[64:65], off offset:16
	global_load_dwordx4 v[80:83], v[64:65], off offset:48
	s_waitcnt vmcnt(3)
	v_pk_mul_f32 v[54:55], v[54:55], v[70:71]
	v_pk_mul_f32 v[52:53], v[52:53], v[68:69]
	s_waitcnt vmcnt(2) lgkmcnt(5)
	v_pk_mul_f32 v[64:65], v[72:73], v[66:67]
	s_waitcnt lgkmcnt(1)
	v_pk_mul_f32 v[62:63], v[74:75], v[62:63]
	s_waitcnt vmcnt(1)
	v_pk_mul_f32 v[50:51], v[50:51], v[78:79]
	v_pk_mul_f32 v[48:49], v[48:49], v[76:77]
	s_waitcnt vmcnt(0)
	v_pk_mul_f32 v[60:61], v[80:81], v[60:61]
	s_waitcnt lgkmcnt(0)
	v_pk_mul_f32 v[58:59], v[82:83], v[58:59]
	v_pk_fma_f32 v[54:55], v[140:141], v[62:63], v[54:55]
	v_pk_fma_f32 v[52:53], v[138:139], v[64:65], v[52:53]
	v_pk_fma_f32 v[50:51], v[140:141], v[58:59], v[50:51]
	v_pk_fma_f32 v[48:49], v[138:139], v[60:61], v[48:49]

.LBB0_296:
	v_cvt_pk_bf16_f32 v52, v52, v53
	v_cvt_pk_bf16_f32 v53, v54, v55
	v_cvt_pk_bf16_f32 v55, v50, v51
	v_add_u32_e32 v50, 0x90, v148
	v_ashrrev_i32_e32 v51, 31, v50
	v_cvt_pk_bf16_f32 v54, v48, v49
	v_lshlrev_b64 v[48:49], 6, v[50:51]
	global_store_dwordx4 v[56:57], v[52:55], off offset:256 sc1
	s_and_b64 vcc, exec, s[40:41]
	s_nop 0
	v_lshl_add_u64 v[52:53], v[142:143], 0, v[48:49]
	global_load_dwordx4 v[52:55], v[52:53], off
	s_waitcnt vmcnt(0)
	v_mov_b32_e32 v56, v53
	v_mov_b32_e32 v57, v54
	v_mov_b32_e32 v53, v55
	v_pk_add_f32 v[52:53], v[56:57], v[52:53]
	s_nop 0
	v_add_f32_e32 v52, v52, v53
	ds_bpermute_b32 v53, v169, v52
	s_waitcnt lgkmcnt(0)
	v_add_f32_e32 v52, v52, v53
	ds_bpermute_b32 v53, v172, v52
	s_waitcnt lgkmcnt(0)
	v_add_f32_e32 v52, v52, v53
	v_fmamk_f32 v52, v52, 0x3a800000, v216
	v_mul_f32_e32 v53, 0x4b800000, v52
	v_cmp_gt_f32_e64 s[42:43], s29, v52
	s_nop 1
	v_cndmask_b32_e64 v52, v52, v53, s[42:43]
	v_rsq_f32_e32 v52, v52
	s_nop 0
	v_mul_f32_e32 v53, 0x45800000, v52
	v_cndmask_b32_e64 v52, v52, v53, s[42:43]
	v_mul_f32_e32 v52, v174, v52
	v_pk_mul_f32 v[46:47], v[46:47], v[52:53] op_sel_hi:[1,0]
	v_pk_mul_f32 v[44:45], v[44:45], v[52:53] op_sel_hi:[1,0]
	v_pk_mul_f32 v[42:43], v[42:43], v[52:53] op_sel_hi:[1,0]
	v_pk_mul_f32 v[40:41], v[40:41], v[52:53] op_sel_hi:[1,0]
	s_cbranch_vccnz .LBB0_300
	ds_bpermute_b32 v60, v169, v44
	ds_bpermute_b32 v56, v169, v40
	ds_bpermute_b32 v61, v169, v45
	ds_bpermute_b32 v57, v169, v41
	ds_bpermute_b32 v58, v169, v46
	ds_bpermute_b32 v54, v169, v42
	ds_bpermute_b32 v59, v169, v47
	ds_bpermute_b32 v55, v169, v43
	s_and_saveexec_b64 s[42:43], s[36:37]
	s_cbranch_execz .LBB0_299
	v_lshl_add_u64 v[74:75], s[20:21], 0, v[48:49]
	global_load_dwordx4 v[62:65], v[74:75], off
	global_load_dwordx4 v[66:69], v[74:75], off offset:32
	global_load_dwordx4 v[70:73], v[74:75], off offset:16
	s_nop 0
	global_load_dwordx4 v[74:77], v[74:75], off offset:48
	s_waitcnt vmcnt(3)
	v_pk_mul_f32 v[46:47], v[46:47], v[64:65]
	v_pk_mul_f32 v[44:45], v[44:45], v[62:63]
	s_waitcnt vmcnt(2) lgkmcnt(5)
	v_pk_mul_f32 v[60:61], v[66:67], v[60:61]
	s_waitcnt lgkmcnt(1)
	v_pk_mul_f32 v[58:59], v[68:69], v[58:59]
	s_waitcnt vmcnt(1)
	v_pk_mul_f32 v[42:43], v[42:43], v[72:73]
	v_pk_mul_f32 v[40:41], v[40:41], v[70:71]
	s_waitcnt vmcnt(0)
	v_pk_mul_f32 v[56:57], v[74:75], v[56:57]
	s_waitcnt lgkmcnt(0)
	v_pk_mul_f32 v[54:55], v[76:77], v[54:55]
	v_pk_fma_f32 v[46:47], v[140:141], v[58:59], v[46:47]
	v_pk_fma_f32 v[44:45], v[138:139], v[60:61], v[44:45]
	v_pk_fma_f32 v[42:43], v[140:141], v[54:55], v[42:43]
	v_pk_fma_f32 v[40:41], v[138:139], v[56:57], v[40:41]

.LBB0_300:
	v_lshlrev_b64 v[50:51], 11, v[50:51]
	v_cvt_pk_bf16_f32 v44, v44, v45
	v_cvt_pk_bf16_f32 v45, v46, v47
	v_cvt_pk_bf16_f32 v46, v40, v41
	v_lshl_add_u64 v[40:41], s[64:65], 0, v[50:51]
	v_lshl_add_u64 v[40:41], s[10:11], 1, v[40:41]
	v_mov_b32_e32 v53, v52
	v_cvt_pk_bf16_f32 v47, v42, v43
	v_lshl_add_u64 v[40:41], v[40:41], 0, s[4:5]
	v_mov_b32_e32 v42, v52
	v_mov_b32_e32 v43, v52
	v_lshl_add_u64 v[40:41], v[40:41], 0, v[160:161]
	v_pk_mul_f32 v[38:39], v[38:39], v[42:43]
	v_pk_mul_f32 v[36:37], v[36:37], v[52:53]
	v_pk_mul_f32 v[34:35], v[34:35], v[42:43]
	s_and_b64 vcc, exec, s[40:41]
	v_pk_mul_f32 v[32:33], v[32:33], v[52:53]
	global_store_dwordx4 v[40:41], v[44:47], off sc1
	s_cbranch_vccnz .LBB0_304
	ds_bpermute_b32 v50, v169, v36
	ds_bpermute_b32 v44, v169, v32
	ds_bpermute_b32 v51, v169, v37
	ds_bpermute_b32 v45, v169, v33
	ds_bpermute_b32 v46, v169, v38
	ds_bpermute_b32 v42, v169, v34
	ds_bpermute_b32 v47, v169, v39
	ds_bpermute_b32 v43, v169, v35
	s_and_saveexec_b64 s[42:43], s[36:37]
	s_cbranch_execz .LBB0_303
	v_lshl_add_u64 v[48:49], s[20:21], 0, v[48:49]
	s_waitcnt lgkmcnt(8)
	global_load_dwordx4 v[52:55], v[48:49], off
	global_load_dwordx4 v[56:59], v[48:49], off offset:32
	global_load_dwordx4 v[60:63], v[48:49], off offset:16
	global_load_dwordx4 v[64:67], v[48:49], off offset:48
	s_waitcnt vmcnt(3)
	v_pk_mul_f32 v[38:39], v[38:39], v[54:55]
	v_pk_mul_f32 v[36:37], v[36:37], v[52:53]
	s_waitcnt vmcnt(2) lgkmcnt(5)
	v_pk_mul_f32 v[48:49], v[56:57], v[50:51]
	s_waitcnt lgkmcnt(1)
	v_pk_mul_f32 v[46:47], v[58:59], v[46:47]
	s_waitcnt vmcnt(1)
	v_pk_mul_f32 v[34:35], v[34:35], v[62:63]
	v_pk_mul_f32 v[32:33], v[32:33], v[60:61]
	s_waitcnt vmcnt(0)
	v_pk_mul_f32 v[44:45], v[64:65], v[44:45]
	s_waitcnt lgkmcnt(0)
	v_pk_mul_f32 v[42:43], v[66:67], v[42:43]
	v_pk_fma_f32 v[38:39], v[140:141], v[46:47], v[38:39]
	v_pk_fma_f32 v[36:37], v[138:139], v[48:49], v[36:37]
	v_pk_fma_f32 v[34:35], v[140:141], v[42:43], v[34:35]
	v_pk_fma_f32 v[32:33], v[138:139], v[44:45], v[32:33]

.LBB0_304:
	v_cvt_pk_bf16_f32 v36, v36, v37
	v_cvt_pk_bf16_f32 v37, v38, v39
	v_cvt_pk_bf16_f32 v39, v34, v35
	v_add_u32_e32 v34, 0xa0, v148
	v_ashrrev_i32_e32 v35, 31, v34
	v_cvt_pk_bf16_f32 v38, v32, v33
	v_lshlrev_b64 v[32:33], 6, v[34:35]
	global_store_dwordx4 v[40:41], v[36:39], off offset:256 sc1
	s_and_b64 vcc, exec, s[40:41]
	s_nop 0
	v_lshl_add_u64 v[36:37], v[142:143], 0, v[32:33]
	global_load_dwordx4 v[36:39], v[36:37], off
	s_waitcnt vmcnt(0)
	v_mov_b32_e32 v40, v37
	v_mov_b32_e32 v41, v38
	v_mov_b32_e32 v37, v39
	v_pk_add_f32 v[36:37], v[40:41], v[36:37]
	s_nop 0
	v_add_f32_e32 v36, v36, v37
	ds_bpermute_b32 v37, v169, v36
	s_waitcnt lgkmcnt(0)
	v_add_f32_e32 v36, v36, v37
	ds_bpermute_b32 v37, v172, v36
	s_waitcnt lgkmcnt(0)
	v_add_f32_e32 v36, v36, v37
	v_fmamk_f32 v36, v36, 0x3a800000, v216
	v_mul_f32_e32 v37, 0x4b800000, v36
	v_cmp_gt_f32_e64 s[42:43], s29, v36
	s_nop 1
	v_cndmask_b32_e64 v36, v36, v37, s[42:43]
	v_rsq_f32_e32 v36, v36
	s_nop 0
	v_mul_f32_e32 v37, 0x45800000, v36
	v_cndmask_b32_e64 v36, v36, v37, s[42:43]
	v_mul_f32_e32 v36, v174, v36
	v_pk_mul_f32 v[30:31], v[30:31], v[36:37] op_sel_hi:[1,0]
	v_pk_mul_f32 v[28:29], v[28:29], v[36:37] op_sel_hi:[1,0]
	v_pk_mul_f32 v[26:27], v[26:27], v[36:37] op_sel_hi:[1,0]
	v_pk_mul_f32 v[24:25], v[24:25], v[36:37] op_sel_hi:[1,0]
	s_cbranch_vccnz .LBB0_308
	ds_bpermute_b32 v44, v169, v28
	ds_bpermute_b32 v40, v169, v24
	ds_bpermute_b32 v45, v169, v29
	ds_bpermute_b32 v41, v169, v25
	ds_bpermute_b32 v42, v169, v30
	ds_bpermute_b32 v38, v169, v26
	ds_bpermute_b32 v43, v169, v31
	ds_bpermute_b32 v39, v169, v27
	s_and_saveexec_b64 s[42:43], s[36:37]
	s_cbranch_execz .LBB0_307
	v_lshl_add_u64 v[58:59], s[20:21], 0, v[32:33]
	global_load_dwordx4 v[46:49], v[58:59], off
	global_load_dwordx4 v[50:53], v[58:59], off offset:32
	global_load_dwordx4 v[54:57], v[58:59], off offset:16
	s_nop 0
	global_load_dwordx4 v[58:61], v[58:59], off offset:48
	s_waitcnt vmcnt(3)
	v_pk_mul_f32 v[30:31], v[30:31], v[48:49]
	v_pk_mul_f32 v[28:29], v[28:29], v[46:47]
	s_waitcnt vmcnt(2) lgkmcnt(5)
	v_pk_mul_f32 v[44:45], v[50:51], v[44:45]
	s_waitcnt lgkmcnt(1)
	v_pk_mul_f32 v[42:43], v[52:53], v[42:43]
	s_waitcnt vmcnt(1)
	v_pk_mul_f32 v[26:27], v[26:27], v[56:57]
	v_pk_mul_f32 v[24:25], v[24:25], v[54:55]
	s_waitcnt vmcnt(0)
	v_pk_mul_f32 v[40:41], v[58:59], v[40:41]
	s_waitcnt lgkmcnt(0)
	v_pk_mul_f32 v[38:39], v[60:61], v[38:39]
	v_pk_fma_f32 v[30:31], v[140:141], v[42:43], v[30:31]
	v_pk_fma_f32 v[28:29], v[138:139], v[44:45], v[28:29]
	v_pk_fma_f32 v[26:27], v[140:141], v[38:39], v[26:27]
	v_pk_fma_f32 v[24:25], v[138:139], v[40:41], v[24:25]

.LBB0_308:
	v_lshlrev_b64 v[34:35], 11, v[34:35]
	v_cvt_pk_bf16_f32 v28, v28, v29
	v_cvt_pk_bf16_f32 v29, v30, v31
	v_cvt_pk_bf16_f32 v30, v24, v25
	v_lshl_add_u64 v[24:25], s[64:65], 0, v[34:35]
	v_lshl_add_u64 v[24:25], s[10:11], 1, v[24:25]
	v_mov_b32_e32 v37, v36
	v_cvt_pk_bf16_f32 v31, v26, v27
	v_lshl_add_u64 v[24:25], v[24:25], 0, s[4:5]
	v_mov_b32_e32 v26, v36
	v_mov_b32_e32 v27, v36
	v_lshl_add_u64 v[24:25], v[24:25], 0, v[160:161]
	v_pk_mul_f32 v[22:23], v[22:23], v[26:27]
	v_pk_mul_f32 v[20:21], v[20:21], v[36:37]
	v_pk_mul_f32 v[18:19], v[18:19], v[26:27]
	s_and_b64 vcc, exec, s[40:41]
	v_pk_mul_f32 v[16:17], v[16:17], v[36:37]
	global_store_dwordx4 v[24:25], v[28:31], off sc1
	s_cbranch_vccnz .LBB0_312
	ds_bpermute_b32 v34, v169, v20
	ds_bpermute_b32 v28, v169, v16
	ds_bpermute_b32 v35, v169, v21
	ds_bpermute_b32 v29, v169, v17
	ds_bpermute_b32 v30, v169, v22
	ds_bpermute_b32 v26, v169, v18
	ds_bpermute_b32 v31, v169, v23
	ds_bpermute_b32 v27, v169, v19
	s_and_saveexec_b64 s[42:43], s[36:37]
	s_cbranch_execz .LBB0_311
	v_lshl_add_u64 v[32:33], s[20:21], 0, v[32:33]
	s_waitcnt lgkmcnt(8)
	global_load_dwordx4 v[36:39], v[32:33], off
	global_load_dwordx4 v[40:43], v[32:33], off offset:32
	global_load_dwordx4 v[44:47], v[32:33], off offset:16
	global_load_dwordx4 v[48:51], v[32:33], off offset:48
	s_waitcnt vmcnt(3)
	v_pk_mul_f32 v[22:23], v[22:23], v[38:39]
	v_pk_mul_f32 v[20:21], v[20:21], v[36:37]
	s_waitcnt vmcnt(2) lgkmcnt(5)
	v_pk_mul_f32 v[32:33], v[40:41], v[34:35]
	s_waitcnt lgkmcnt(1)
	v_pk_mul_f32 v[30:31], v[42:43], v[30:31]
	s_waitcnt vmcnt(1)
	v_pk_mul_f32 v[18:19], v[18:19], v[46:47]
	v_pk_mul_f32 v[16:17], v[16:17], v[44:45]
	s_waitcnt vmcnt(0)
	v_pk_mul_f32 v[28:29], v[48:49], v[28:29]
	s_waitcnt lgkmcnt(0)
	v_pk_mul_f32 v[26:27], v[50:51], v[26:27]
	v_pk_fma_f32 v[22:23], v[140:141], v[30:31], v[22:23]
	v_pk_fma_f32 v[20:21], v[138:139], v[32:33], v[20:21]
	v_pk_fma_f32 v[18:19], v[140:141], v[26:27], v[18:19]
	v_pk_fma_f32 v[16:17], v[138:139], v[28:29], v[16:17]

.LBB0_312:
	v_cvt_pk_bf16_f32 v20, v20, v21
	v_cvt_pk_bf16_f32 v21, v22, v23
	v_cvt_pk_bf16_f32 v23, v18, v19
	v_add_u32_e32 v18, 0xb0, v148
	v_ashrrev_i32_e32 v19, 31, v18
	v_cvt_pk_bf16_f32 v22, v16, v17
	v_lshlrev_b64 v[16:17], 6, v[18:19]
	global_store_dwordx4 v[24:25], v[20:23], off offset:256 sc1
	s_and_b64 vcc, exec, s[40:41]
	s_nop 0
	v_lshl_add_u64 v[20:21], v[142:143], 0, v[16:17]
	global_load_dwordx4 v[20:23], v[20:21], off
	s_waitcnt vmcnt(0)
	v_mov_b32_e32 v24, v21
	v_mov_b32_e32 v25, v22
	v_mov_b32_e32 v21, v23
	v_pk_add_f32 v[20:21], v[24:25], v[20:21]
	s_nop 0
	v_add_f32_e32 v20, v20, v21
	ds_bpermute_b32 v21, v169, v20
	s_waitcnt lgkmcnt(0)
	v_add_f32_e32 v20, v20, v21
	ds_bpermute_b32 v21, v172, v20
	s_waitcnt lgkmcnt(0)
	v_add_f32_e32 v20, v20, v21
	v_fmamk_f32 v20, v20, 0x3a800000, v216
	v_mul_f32_e32 v21, 0x4b800000, v20
	v_cmp_gt_f32_e64 s[42:43], s29, v20
	s_nop 1
	v_cndmask_b32_e64 v20, v20, v21, s[42:43]
	v_rsq_f32_e32 v20, v20
	s_nop 0
	v_mul_f32_e32 v21, 0x45800000, v20
	v_cndmask_b32_e64 v20, v20, v21, s[42:43]
	v_mul_f32_e32 v20, v174, v20
	v_pk_mul_f32 v[14:15], v[14:15], v[20:21] op_sel_hi:[1,0]
	v_pk_mul_f32 v[12:13], v[12:13], v[20:21] op_sel_hi:[1,0]
	v_pk_mul_f32 v[10:11], v[10:11], v[20:21] op_sel_hi:[1,0]
	v_pk_mul_f32 v[8:9], v[8:9], v[20:21] op_sel_hi:[1,0]
	s_cbranch_vccnz .LBB0_316
	ds_bpermute_b32 v28, v169, v12
	ds_bpermute_b32 v24, v169, v8
	ds_bpermute_b32 v29, v169, v13
	ds_bpermute_b32 v25, v169, v9
	ds_bpermute_b32 v26, v169, v14
	ds_bpermute_b32 v22, v169, v10
	ds_bpermute_b32 v27, v169, v15
	ds_bpermute_b32 v23, v169, v11
	s_and_saveexec_b64 s[42:43], s[36:37]
	s_cbranch_execz .LBB0_315
	v_lshl_add_u64 v[42:43], s[20:21], 0, v[16:17]
	global_load_dwordx4 v[30:33], v[42:43], off
	global_load_dwordx4 v[34:37], v[42:43], off offset:32
	global_load_dwordx4 v[38:41], v[42:43], off offset:16
	s_nop 0
	global_load_dwordx4 v[42:45], v[42:43], off offset:48
	s_waitcnt vmcnt(3)
	v_pk_mul_f32 v[14:15], v[14:15], v[32:33]
	v_pk_mul_f32 v[12:13], v[12:13], v[30:31]
	s_waitcnt vmcnt(2) lgkmcnt(5)
	v_pk_mul_f32 v[28:29], v[34:35], v[28:29]
	s_waitcnt lgkmcnt(1)
	v_pk_mul_f32 v[26:27], v[36:37], v[26:27]
	s_waitcnt vmcnt(1)
	v_pk_mul_f32 v[10:11], v[10:11], v[40:41]
	v_pk_mul_f32 v[8:9], v[8:9], v[38:39]
	s_waitcnt vmcnt(0)
	v_pk_mul_f32 v[24:25], v[42:43], v[24:25]
	s_waitcnt lgkmcnt(0)
	v_pk_mul_f32 v[22:23], v[44:45], v[22:23]
	v_pk_fma_f32 v[14:15], v[140:141], v[26:27], v[14:15]
	v_pk_fma_f32 v[12:13], v[138:139], v[28:29], v[12:13]
	v_pk_fma_f32 v[10:11], v[140:141], v[22:23], v[10:11]
	v_pk_fma_f32 v[8:9], v[138:139], v[24:25], v[8:9]

.LBB0_316:
	v_lshlrev_b64 v[18:19], 11, v[18:19]
	v_cvt_pk_bf16_f32 v12, v12, v13
	v_cvt_pk_bf16_f32 v13, v14, v15
	v_cvt_pk_bf16_f32 v14, v8, v9
	v_lshl_add_u64 v[8:9], s[64:65], 0, v[18:19]
	v_lshl_add_u64 v[8:9], s[10:11], 1, v[8:9]
	v_mov_b32_e32 v21, v20
	v_cvt_pk_bf16_f32 v15, v10, v11
	v_lshl_add_u64 v[8:9], v[8:9], 0, s[4:5]
	v_mov_b32_e32 v10, v20
	v_mov_b32_e32 v11, v20
	v_lshl_add_u64 v[8:9], v[8:9], 0, v[160:161]
	v_pk_mul_f32 v[6:7], v[6:7], v[10:11]
	v_pk_mul_f32 v[4:5], v[4:5], v[20:21]
	v_pk_mul_f32 v[2:3], v[2:3], v[10:11]
	s_and_b64 vcc, exec, s[40:41]
	v_pk_mul_f32 v[0:1], v[0:1], v[20:21]
	global_store_dwordx4 v[8:9], v[12:15], off sc1
	s_cbranch_vccnz .LBB0_320
	ds_bpermute_b32 v18, v169, v4
	ds_bpermute_b32 v12, v169, v0
	ds_bpermute_b32 v19, v169, v5
	ds_bpermute_b32 v13, v169, v1
	ds_bpermute_b32 v14, v169, v6
	ds_bpermute_b32 v10, v169, v2
	ds_bpermute_b32 v15, v169, v7
	ds_bpermute_b32 v11, v169, v3
	s_and_saveexec_b64 s[10:11], s[36:37]
	s_cbranch_execz .LBB0_319
	v_lshl_add_u64 v[16:17], s[20:21], 0, v[16:17]
	s_waitcnt lgkmcnt(8)
	global_load_dwordx4 v[20:23], v[16:17], off
	global_load_dwordx4 v[24:27], v[16:17], off offset:32
	global_load_dwordx4 v[28:31], v[16:17], off offset:16
	global_load_dwordx4 v[32:35], v[16:17], off offset:48
	s_waitcnt vmcnt(3)
	v_pk_mul_f32 v[6:7], v[6:7], v[22:23]
	v_pk_mul_f32 v[4:5], v[4:5], v[20:21]
	s_waitcnt vmcnt(2) lgkmcnt(5)
	v_pk_mul_f32 v[16:17], v[24:25], v[18:19]
	s_waitcnt lgkmcnt(1)
	v_pk_mul_f32 v[14:15], v[26:27], v[14:15]
	s_waitcnt vmcnt(1)
	v_pk_mul_f32 v[2:3], v[2:3], v[30:31]
	v_pk_mul_f32 v[0:1], v[0:1], v[28:29]
	s_waitcnt vmcnt(0)
	v_pk_mul_f32 v[12:13], v[32:33], v[12:13]
	s_waitcnt lgkmcnt(0)
	v_pk_mul_f32 v[10:11], v[34:35], v[10:11]
	v_pk_fma_f32 v[6:7], v[140:141], v[14:15], v[6:7]
	v_pk_fma_f32 v[4:5], v[138:139], v[16:17], v[4:5]
	v_pk_fma_f32 v[2:3], v[140:141], v[10:11], v[2:3]
	v_pk_fma_f32 v[0:1], v[138:139], v[12:13], v[0:1]

.LBB0_320:
	v_cvt_pk_bf16_f32 v4, v4, v5
	v_cvt_pk_bf16_f32 v5, v6, v7
	v_cvt_pk_bf16_f32 v6, v0, v1
	v_cvt_pk_bf16_f32 v7, v2, v3
	s_andn2_b64 vcc, exec, s[38:39]
	s_mov_b64 s[10:11], -1
	global_store_dwordx4 v[8:9], v[4:7], off offset:256 sc1
	s_cbranch_vccnz .LBB0_245
	s_andn2_b64 vcc, exec, s[68:69]
	s_cbranch_vccnz .LBB0_244
	s_barrier
	s_branch .LBB0_244

.LBB0_381:
	v_lshl_add_u32 v184, s25, 8, v167
	v_lshl_or_b32 v180, s24, 8, v202
	v_ashrrev_i32_e32 v181, 31, v180
	v_ashrrev_i32_e32 v185, 31, v184
	v_or_b32_e32 v194, 16, v184
	v_lshl_add_u64 v[182:183], v[180:181], 1, s[0:1]
	v_lshlrev_b64 v[198:199], 11, v[184:185]
	v_ashrrev_i32_e32 v195, 31, v194
	v_or_b32_e32 v190, 32, v184
	v_lshl_add_u64 v[128:129], v[182:183], 0, v[198:199]
	v_lshlrev_b64 v[196:197], 11, v[194:195]
	v_ashrrev_i32_e32 v191, 31, v190
	v_or_b32_e32 v186, 48, v184
	global_load_dwordx4 v[206:209], v[128:129], off
	global_load_dwordx4 v[152:155], v[128:129], off offset:256
	v_lshl_add_u64 v[128:129], v[182:183], 0, v[196:197]
	v_lshlrev_b64 v[192:193], 11, v[190:191]
	v_ashrrev_i32_e32 v187, 31, v186
	global_load_dwordx4 v[148:151], v[128:129], off
	global_load_dwordx4 v[144:147], v[128:129], off offset:256
	v_lshl_add_u64 v[128:129], v[182:183], 0, v[192:193]
	v_lshlrev_b64 v[188:189], 11, v[186:187]
	global_load_dwordx4 v[140:143], v[128:129], off
	global_load_dwordx4 v[136:139], v[128:129], off offset:256
	v_lshl_add_u64 v[128:129], v[182:183], 0, v[188:189]
	global_load_dwordx4 v[132:135], v[128:129], off
	s_nop 0
	global_load_dwordx4 v[128:131], v[128:129], off offset:256
	v_cndmask_b32_e64 v162, 0, 1, s[16:17]
	v_cmp_ne_u32_e64 s[40:41], 1, v162
	v_lshlrev_b64 v[162:163], 12, v[184:185]
	v_mov_b32_e32 v173, v172
	v_lshl_add_u64 v[162:163], s[12:13], 0, v[162:163]
	s_andn2_b64 vcc, exec, s[16:17]
	s_waitcnt vmcnt(0)
	v_lshlrev_b32_e32 v164, 16, v206
	v_and_b32_e32 v165, 0xffff0000, v206
	v_lshlrev_b32_e32 v200, 16, v207
	v_and_b32_e32 v201, 0xffff0000, v207
	v_lshlrev_b32_e32 v206, 16, v208
	v_and_b32_e32 v207, 0xffff0000, v208
	v_lshlrev_b32_e32 v208, 16, v209
	v_and_b32_e32 v209, 0xffff0000, v209
	v_pk_fma_f32 v[126:127], v[172:173], v[126:127], v[200:201]
	v_pk_fma_f32 v[124:125], v[174:175], v[124:125], v[164:165]
	v_pk_fma_f32 v[122:123], v[172:173], v[122:123], v[208:209]
	v_pk_fma_f32 v[120:121], v[174:175], v[120:121], v[206:207]
	v_lshl_add_u64 v[200:201], v[180:181], 2, v[162:163]
	s_cbranch_vccnz .LBB0_383
	s_mov_b64 s[82:83], 0
	global_store_dwordx4 v[200:201], v[124:127], off sc1
	global_store_dwordx4 v[200:201], v[120:123], off offset:16 sc1
	s_branch .LBB0_384

.LBB0_384:
	v_lshl_add_u64 v[162:163], s[0:1], 0, v[198:199]
	s_andn2_b64 vcc, exec, s[82:83]
	v_lshl_add_u64 v[198:199], v[180:181], 1, v[162:163]
	s_mov_b32 s28, 0x3fb8aa3b
	s_cbranch_vccnz .LBB0_386
	v_cvt_pk_bf16_f32 v206, v124, v125
	v_cvt_pk_bf16_f32 v207, v126, v127
	v_cvt_pk_bf16_f32 v208, v120, v121
	v_cvt_pk_bf16_f32 v209, v122, v123
	global_store_dwordx4 v[198:199], v[206:209], off sc1
.LBB0_386:
	v_lshlrev_b32_e32 v162, 16, v152
	v_and_b32_e32 v163, 0xffff0000, v152
	v_lshlrev_b32_e32 v152, 16, v153
	v_and_b32_e32 v153, 0xffff0000, v153
	v_lshlrev_b32_e32 v164, 16, v154
	v_and_b32_e32 v165, 0xffff0000, v154
	v_lshlrev_b32_e32 v154, 16, v155
	v_and_b32_e32 v155, 0xffff0000, v155
	v_mov_b32_e32 v173, v172
	v_pk_fma_f32 v[118:119], v[172:173], v[118:119], v[152:153]
	v_pk_fma_f32 v[116:117], v[174:175], v[116:117], v[162:163]
	v_pk_fma_f32 v[114:115], v[172:173], v[114:115], v[154:155]
	s_and_b64 vcc, exec, s[40:41]
	v_pk_fma_f32 v[112:113], v[174:175], v[112:113], v[164:165]
	s_cbranch_vccnz .LBB0_450
	global_store_dwordx4 v[200:201], v[116:119], off offset:512 sc1
	global_store_dwordx4 v[200:201], v[112:115], off offset:528 sc1
	s_cbranch_execnz .LBB0_389
.LBB0_388:
	v_cvt_pk_bf16_f32 v152, v116, v117
	v_cvt_pk_bf16_f32 v153, v118, v119
	v_cvt_pk_bf16_f32 v154, v112, v113
	v_cvt_pk_bf16_f32 v155, v114, v115
	global_store_dwordx4 v[198:199], v[152:155], off offset:256 sc1

.LBB0_391:
	s_or_b64 exec, exec, s[82:83]
	s_waitcnt lgkmcnt(0)
	v_lshlrev_b64 v[112:113], 12, v[194:195]
	v_lshlrev_b32_e32 v114, 16, v148
	v_and_b32_e32 v115, 0xffff0000, v148
	v_lshlrev_b32_e32 v116, 16, v149
	v_and_b32_e32 v117, 0xffff0000, v149
	v_lshlrev_b32_e32 v118, 16, v150
	v_and_b32_e32 v119, 0xffff0000, v150
	v_lshlrev_b32_e32 v120, 16, v151
	v_and_b32_e32 v121, 0xffff0000, v151
	v_mov_b32_e32 v173, v172
	v_lshl_add_u64 v[112:113], s[12:13], 0, v[112:113]
	v_pk_fma_f32 v[110:111], v[172:173], v[110:111], v[116:117]
	v_pk_fma_f32 v[108:109], v[174:175], v[108:109], v[114:115]
	v_pk_fma_f32 v[106:107], v[172:173], v[106:107], v[120:121]
	v_pk_fma_f32 v[104:105], v[174:175], v[104:105], v[118:119]
	s_and_b64 vcc, exec, s[40:41]
	v_lshl_add_u64 v[114:115], v[180:181], 2, v[112:113]
	s_cbranch_vccnz .LBB0_451
	global_store_dwordx4 v[114:115], v[108:111], off sc1
	global_store_dwordx4 v[114:115], v[104:107], off offset:16 sc1
	v_lshl_add_u64 v[112:113], s[0:1], 0, v[196:197]
	v_lshl_add_u64 v[112:113], v[180:181], 1, v[112:113]
	s_cbranch_execnz .LBB0_394
.LBB0_393:
	v_cvt_pk_bf16_f32 v116, v108, v109
	v_cvt_pk_bf16_f32 v117, v110, v111
	v_cvt_pk_bf16_f32 v118, v104, v105
	v_cvt_pk_bf16_f32 v119, v106, v107
	global_store_dwordx4 v[112:113], v[116:119], off sc1
.LBB0_394:
	s_nop 1
	v_lshlrev_b32_e32 v116, 16, v144
	v_and_b32_e32 v117, 0xffff0000, v144
	v_lshlrev_b32_e32 v118, 16, v145
	v_and_b32_e32 v119, 0xffff0000, v145
	v_lshlrev_b32_e32 v120, 16, v146
	v_and_b32_e32 v121, 0xffff0000, v146
	v_lshlrev_b32_e32 v122, 16, v147
	v_and_b32_e32 v123, 0xffff0000, v147
	v_mov_b32_e32 v173, v172
	v_pk_fma_f32 v[102:103], v[172:173], v[102:103], v[118:119]
	v_pk_fma_f32 v[100:101], v[174:175], v[100:101], v[116:117]
	v_pk_fma_f32 v[98:99], v[172:173], v[98:99], v[122:123]
	s_and_b64 vcc, exec, s[40:41]
	v_pk_fma_f32 v[96:97], v[174:175], v[96:97], v[120:121]
	s_cbranch_vccnz .LBB0_452
	global_store_dwordx4 v[114:115], v[100:103], off offset:512 sc1
	global_store_dwordx4 v[114:115], v[96:99], off offset:528 sc1
	s_cbranch_execnz .LBB0_397
.LBB0_396:
	v_cvt_pk_bf16_f32 v114, v100, v101
	v_cvt_pk_bf16_f32 v115, v102, v103
	v_cvt_pk_bf16_f32 v116, v96, v97
	v_cvt_pk_bf16_f32 v117, v98, v99
	global_store_dwordx4 v[112:113], v[114:117], off offset:256 sc1

.LBB0_399:
	s_or_b64 exec, exec, s[82:83]
	s_waitcnt lgkmcnt(0)
	v_lshlrev_b64 v[96:97], 12, v[190:191]
	v_lshlrev_b32_e32 v98, 16, v140
	v_and_b32_e32 v99, 0xffff0000, v140
	v_lshlrev_b32_e32 v100, 16, v141
	v_and_b32_e32 v101, 0xffff0000, v141
	v_lshlrev_b32_e32 v102, 16, v142
	v_and_b32_e32 v103, 0xffff0000, v142
	v_lshlrev_b32_e32 v104, 16, v143
	v_and_b32_e32 v105, 0xffff0000, v143
	v_mov_b32_e32 v173, v172
	v_lshl_add_u64 v[96:97], s[12:13], 0, v[96:97]
	v_pk_fma_f32 v[94:95], v[172:173], v[94:95], v[100:101]
	v_pk_fma_f32 v[92:93], v[174:175], v[92:93], v[98:99]
	v_pk_fma_f32 v[90:91], v[172:173], v[90:91], v[104:105]
	v_pk_fma_f32 v[88:89], v[174:175], v[88:89], v[102:103]
	s_and_b64 vcc, exec, s[40:41]
	v_lshl_add_u64 v[98:99], v[180:181], 2, v[96:97]
	s_cbranch_vccnz .LBB0_453
	global_store_dwordx4 v[98:99], v[92:95], off sc1
	global_store_dwordx4 v[98:99], v[88:91], off offset:16 sc1
	v_lshl_add_u64 v[96:97], s[0:1], 0, v[192:193]
	v_lshl_add_u64 v[96:97], v[180:181], 1, v[96:97]
	s_cbranch_execnz .LBB0_402
.LBB0_401:
	v_cvt_pk_bf16_f32 v100, v92, v93
	v_cvt_pk_bf16_f32 v101, v94, v95
	v_cvt_pk_bf16_f32 v102, v88, v89
	v_cvt_pk_bf16_f32 v103, v90, v91
	global_store_dwordx4 v[96:97], v[100:103], off sc1
.LBB0_402:
	s_nop 1
	v_lshlrev_b32_e32 v100, 16, v136
	v_and_b32_e32 v101, 0xffff0000, v136
	v_lshlrev_b32_e32 v102, 16, v137
	v_and_b32_e32 v103, 0xffff0000, v137
	v_lshlrev_b32_e32 v104, 16, v138
	v_and_b32_e32 v105, 0xffff0000, v138
	v_lshlrev_b32_e32 v106, 16, v139
	v_and_b32_e32 v107, 0xffff0000, v139
	v_mov_b32_e32 v173, v172
	v_pk_fma_f32 v[86:87], v[172:173], v[86:87], v[102:103]
	v_pk_fma_f32 v[84:85], v[174:175], v[84:85], v[100:101]
	v_pk_fma_f32 v[82:83], v[172:173], v[82:83], v[106:107]
	s_and_b64 vcc, exec, s[40:41]
	v_pk_fma_f32 v[80:81], v[174:175], v[80:81], v[104:105]
	s_cbranch_vccnz .LBB0_454
	global_store_dwordx4 v[98:99], v[84:87], off offset:512 sc1
	global_store_dwordx4 v[98:99], v[80:83], off offset:528 sc1
	s_cbranch_execnz .LBB0_405
.LBB0_404:
	v_cvt_pk_bf16_f32 v98, v84, v85
	v_cvt_pk_bf16_f32 v99, v86, v87
	v_cvt_pk_bf16_f32 v100, v80, v81
	v_cvt_pk_bf16_f32 v101, v82, v83
	global_store_dwordx4 v[96:97], v[98:101], off offset:256 sc1

.LBB0_407:
	s_or_b64 exec, exec, s[82:83]
	s_waitcnt lgkmcnt(0)
	v_lshlrev_b64 v[80:81], 12, v[186:187]
	v_lshlrev_b32_e32 v82, 16, v132
	v_and_b32_e32 v83, 0xffff0000, v132
	v_lshlrev_b32_e32 v84, 16, v133
	v_and_b32_e32 v85, 0xffff0000, v133
	v_lshlrev_b32_e32 v86, 16, v134
	v_and_b32_e32 v87, 0xffff0000, v134
	v_lshlrev_b32_e32 v88, 16, v135
	v_and_b32_e32 v89, 0xffff0000, v135
	v_mov_b32_e32 v173, v172
	v_lshl_add_u64 v[80:81], s[12:13], 0, v[80:81]
	v_pk_fma_f32 v[78:79], v[172:173], v[78:79], v[84:85]
	v_pk_fma_f32 v[76:77], v[174:175], v[76:77], v[82:83]
	v_pk_fma_f32 v[74:75], v[172:173], v[74:75], v[88:89]
	v_pk_fma_f32 v[72:73], v[174:175], v[72:73], v[86:87]
	s_and_b64 vcc, exec, s[40:41]
	v_lshl_add_u64 v[82:83], v[180:181], 2, v[80:81]
	s_cbranch_vccnz .LBB0_455
	global_store_dwordx4 v[82:83], v[76:79], off sc1
	global_store_dwordx4 v[82:83], v[72:75], off offset:16 sc1
	v_lshl_add_u64 v[80:81], s[0:1], 0, v[188:189]
	v_lshl_add_u64 v[80:81], v[180:181], 1, v[80:81]
	s_cbranch_execnz .LBB0_410
.LBB0_409:
	v_cvt_pk_bf16_f32 v84, v76, v77
	v_cvt_pk_bf16_f32 v85, v78, v79
	v_cvt_pk_bf16_f32 v86, v72, v73
	v_cvt_pk_bf16_f32 v87, v74, v75
	global_store_dwordx4 v[80:81], v[84:87], off sc1
.LBB0_410:
	s_nop 1
	v_lshlrev_b32_e32 v84, 16, v128
	v_and_b32_e32 v85, 0xffff0000, v128
	v_lshlrev_b32_e32 v86, 16, v129
	v_and_b32_e32 v87, 0xffff0000, v129
	v_lshlrev_b32_e32 v88, 16, v130
	v_and_b32_e32 v89, 0xffff0000, v130
	v_lshlrev_b32_e32 v90, 16, v131
	v_and_b32_e32 v91, 0xffff0000, v131
	v_mov_b32_e32 v173, v172
	v_pk_fma_f32 v[70:71], v[172:173], v[70:71], v[86:87]
	v_pk_fma_f32 v[68:69], v[174:175], v[68:69], v[84:85]
	v_pk_fma_f32 v[66:67], v[172:173], v[66:67], v[90:91]
	s_and_b64 vcc, exec, s[40:41]
	v_pk_fma_f32 v[64:65], v[174:175], v[64:65], v[88:89]
	s_cbranch_vccnz .LBB0_456
	global_store_dwordx4 v[82:83], v[68:71], off offset:512 sc1
	global_store_dwordx4 v[82:83], v[64:67], off offset:528 sc1
	s_cbranch_execnz .LBB0_413
.LBB0_412:
	v_cvt_pk_bf16_f32 v82, v68, v69
	v_cvt_pk_bf16_f32 v83, v70, v71
	v_cvt_pk_bf16_f32 v84, v64, v65
	v_cvt_pk_bf16_f32 v85, v66, v67
	global_store_dwordx4 v[80:81], v[82:85], off offset:256 sc1

.LBB0_415:
	s_or_b64 exec, exec, s[82:83]
	v_add_u32_e32 v104, 0x80, v184
	v_ashrrev_i32_e32 v105, 31, v104
	v_add_u32_e32 v100, 0x90, v184
	v_lshlrev_b64 v[106:107], 11, v[104:105]
	v_ashrrev_i32_e32 v101, 31, v100
	v_add_u32_e32 v96, 0xa0, v184
	s_waitcnt lgkmcnt(0)
	v_lshl_add_u64 v[64:65], v[182:183], 0, v[106:107]
	v_lshlrev_b64 v[102:103], 11, v[100:101]
	v_ashrrev_i32_e32 v97, 31, v96
	v_add_u32_e32 v92, 0xb0, v184
	global_load_dwordx4 v[108:111], v[64:65], off
	global_load_dwordx4 v[88:91], v[64:65], off offset:256
	v_lshl_add_u64 v[64:65], v[182:183], 0, v[102:103]
	v_lshlrev_b64 v[98:99], 11, v[96:97]
	v_ashrrev_i32_e32 v93, 31, v92
	global_load_dwordx4 v[84:87], v[64:65], off
	global_load_dwordx4 v[80:83], v[64:65], off offset:256
	v_lshl_add_u64 v[64:65], v[182:183], 0, v[98:99]
	v_lshlrev_b64 v[94:95], 11, v[92:93]
	global_load_dwordx4 v[76:79], v[64:65], off
	global_load_dwordx4 v[72:75], v[64:65], off offset:256
	v_lshl_add_u64 v[64:65], v[182:183], 0, v[94:95]
	global_load_dwordx4 v[68:71], v[64:65], off
	s_nop 0
	global_load_dwordx4 v[64:67], v[64:65], off offset:256
	v_lshlrev_b64 v[112:113], 12, v[104:105]
	v_mov_b32_e32 v173, v172
	v_lshl_add_u64 v[112:113], s[12:13], 0, v[112:113]
	s_and_b64 vcc, exec, s[40:41]
	s_waitcnt vmcnt(7)
	v_lshlrev_b32_e32 v114, 16, v108
	v_and_b32_e32 v115, 0xffff0000, v108
	v_lshlrev_b32_e32 v108, 16, v109
	v_and_b32_e32 v109, 0xffff0000, v109
	v_lshlrev_b32_e32 v116, 16, v110
	v_and_b32_e32 v117, 0xffff0000, v110
	v_lshlrev_b32_e32 v110, 16, v111
	v_and_b32_e32 v111, 0xffff0000, v111
	v_pk_fma_f32 v[62:63], v[172:173], v[62:63], v[108:109]
	v_pk_fma_f32 v[60:61], v[174:175], v[60:61], v[114:115]
	v_pk_fma_f32 v[58:59], v[172:173], v[58:59], v[110:111]
	v_pk_fma_f32 v[56:57], v[174:175], v[56:57], v[116:117]
	v_lshl_add_u64 v[108:109], v[180:181], 2, v[112:113]
	s_cbranch_vccnz .LBB0_457
	global_store_dwordx4 v[108:109], v[60:63], off sc1
	global_store_dwordx4 v[108:109], v[56:59], off offset:16 sc1
	v_lshl_add_u64 v[106:107], s[0:1], 0, v[106:107]
	v_lshl_add_u64 v[106:107], v[180:181], 1, v[106:107]
	s_cbranch_execnz .LBB0_418
.LBB0_417:
	v_cvt_pk_bf16_f32 v110, v60, v61
	v_cvt_pk_bf16_f32 v111, v62, v63
	v_cvt_pk_bf16_f32 v112, v56, v57
	v_cvt_pk_bf16_f32 v113, v58, v59
	global_store_dwordx4 v[106:107], v[110:113], off sc1
.LBB0_418:
	s_waitcnt vmcnt(6)
	s_nop 0
	v_lshlrev_b32_e32 v110, 16, v88
	v_and_b32_e32 v111, 0xffff0000, v88
	v_lshlrev_b32_e32 v88, 16, v89
	v_and_b32_e32 v89, 0xffff0000, v89
	v_lshlrev_b32_e32 v112, 16, v90
	v_and_b32_e32 v113, 0xffff0000, v90
	v_lshlrev_b32_e32 v90, 16, v91
	v_and_b32_e32 v91, 0xffff0000, v91
	v_mov_b32_e32 v173, v172
	v_pk_fma_f32 v[54:55], v[172:173], v[54:55], v[88:89]
	v_pk_fma_f32 v[52:53], v[174:175], v[52:53], v[110:111]
	v_pk_fma_f32 v[50:51], v[172:173], v[50:51], v[90:91]
	s_and_b64 vcc, exec, s[40:41]
	v_pk_fma_f32 v[48:49], v[174:175], v[48:49], v[112:113]
	s_cbranch_vccnz .LBB0_458
	global_store_dwordx4 v[108:109], v[52:55], off offset:512 sc1
	global_store_dwordx4 v[108:109], v[48:51], off offset:528 sc1
	s_cbranch_execnz .LBB0_421
.LBB0_420:
	v_cvt_pk_bf16_f32 v88, v52, v53
	v_cvt_pk_bf16_f32 v89, v54, v55
	v_cvt_pk_bf16_f32 v90, v48, v49
	v_cvt_pk_bf16_f32 v91, v50, v51
	global_store_dwordx4 v[106:107], v[88:91], off offset:256 sc1

.LBB0_423:
	s_or_b64 exec, exec, s[82:83]
	s_waitcnt lgkmcnt(0)
	v_lshlrev_b64 v[48:49], 12, v[100:101]
	s_waitcnt vmcnt(5)
	v_lshlrev_b32_e32 v50, 16, v84
	v_and_b32_e32 v51, 0xffff0000, v84
	v_lshlrev_b32_e32 v52, 16, v85
	v_and_b32_e32 v53, 0xffff0000, v85
	v_lshlrev_b32_e32 v54, 16, v86
	v_and_b32_e32 v55, 0xffff0000, v86
	v_lshlrev_b32_e32 v56, 16, v87
	v_and_b32_e32 v57, 0xffff0000, v87
	v_mov_b32_e32 v173, v172
	v_lshl_add_u64 v[48:49], s[12:13], 0, v[48:49]
	v_pk_fma_f32 v[46:47], v[172:173], v[46:47], v[52:53]
	v_pk_fma_f32 v[44:45], v[174:175], v[44:45], v[50:51]
	v_pk_fma_f32 v[42:43], v[172:173], v[42:43], v[56:57]
	v_pk_fma_f32 v[40:41], v[174:175], v[40:41], v[54:55]
	s_and_b64 vcc, exec, s[40:41]
	v_lshl_add_u64 v[50:51], v[180:181], 2, v[48:49]
	s_cbranch_vccnz .LBB0_459
	global_store_dwordx4 v[50:51], v[44:47], off sc1
	global_store_dwordx4 v[50:51], v[40:43], off offset:16 sc1
	v_lshl_add_u64 v[48:49], s[0:1], 0, v[102:103]
	v_lshl_add_u64 v[48:49], v[180:181], 1, v[48:49]
	s_cbranch_execnz .LBB0_426
.LBB0_425:
	v_cvt_pk_bf16_f32 v52, v44, v45
	v_cvt_pk_bf16_f32 v53, v46, v47
	v_cvt_pk_bf16_f32 v54, v40, v41
	v_cvt_pk_bf16_f32 v55, v42, v43
	global_store_dwordx4 v[48:49], v[52:55], off sc1
.LBB0_426:
	s_waitcnt vmcnt(4)
	s_nop 0
	v_lshlrev_b32_e32 v52, 16, v80
	v_and_b32_e32 v53, 0xffff0000, v80
	v_lshlrev_b32_e32 v54, 16, v81
	v_and_b32_e32 v55, 0xffff0000, v81
	v_lshlrev_b32_e32 v56, 16, v82
	v_and_b32_e32 v57, 0xffff0000, v82
	v_lshlrev_b32_e32 v58, 16, v83
	v_and_b32_e32 v59, 0xffff0000, v83
	v_mov_b32_e32 v173, v172
	v_pk_fma_f32 v[38:39], v[172:173], v[38:39], v[54:55]
	v_pk_fma_f32 v[36:37], v[174:175], v[36:37], v[52:53]
	v_pk_fma_f32 v[34:35], v[172:173], v[34:35], v[58:59]
	s_and_b64 vcc, exec, s[40:41]
	v_pk_fma_f32 v[32:33], v[174:175], v[32:33], v[56:57]
	s_cbranch_vccnz .LBB0_460
	global_store_dwordx4 v[50:51], v[36:39], off offset:512 sc1
	global_store_dwordx4 v[50:51], v[32:35], off offset:528 sc1
	s_cbranch_execnz .LBB0_429
.LBB0_428:
	v_cvt_pk_bf16_f32 v50, v36, v37
	v_cvt_pk_bf16_f32 v51, v38, v39
	v_cvt_pk_bf16_f32 v52, v32, v33
	v_cvt_pk_bf16_f32 v53, v34, v35
	global_store_dwordx4 v[48:49], v[50:53], off offset:256 sc1

.LBB0_431:
	s_or_b64 exec, exec, s[82:83]
	s_waitcnt lgkmcnt(0)
	v_lshlrev_b64 v[32:33], 12, v[96:97]
	s_waitcnt vmcnt(3)
	v_lshlrev_b32_e32 v34, 16, v76
	v_and_b32_e32 v35, 0xffff0000, v76
	v_lshlrev_b32_e32 v36, 16, v77
	v_and_b32_e32 v37, 0xffff0000, v77
	v_lshlrev_b32_e32 v38, 16, v78
	v_and_b32_e32 v39, 0xffff0000, v78
	v_lshlrev_b32_e32 v40, 16, v79
	v_and_b32_e32 v41, 0xffff0000, v79
	v_mov_b32_e32 v173, v172
	v_lshl_add_u64 v[32:33], s[12:13], 0, v[32:33]
	v_pk_fma_f32 v[30:31], v[172:173], v[30:31], v[36:37]
	v_pk_fma_f32 v[28:29], v[174:175], v[28:29], v[34:35]
	v_pk_fma_f32 v[26:27], v[172:173], v[26:27], v[40:41]
	v_pk_fma_f32 v[24:25], v[174:175], v[24:25], v[38:39]
	s_and_b64 vcc, exec, s[40:41]
	v_lshl_add_u64 v[34:35], v[180:181], 2, v[32:33]
	s_cbranch_vccnz .LBB0_461
	global_store_dwordx4 v[34:35], v[28:31], off sc1
	global_store_dwordx4 v[34:35], v[24:27], off offset:16 sc1
	v_lshl_add_u64 v[32:33], s[0:1], 0, v[98:99]
	v_lshl_add_u64 v[32:33], v[180:181], 1, v[32:33]
	s_cbranch_execnz .LBB0_434
.LBB0_433:
	v_cvt_pk_bf16_f32 v36, v28, v29
	v_cvt_pk_bf16_f32 v37, v30, v31
	v_cvt_pk_bf16_f32 v38, v24, v25
	v_cvt_pk_bf16_f32 v39, v26, v27
	global_store_dwordx4 v[32:33], v[36:39], off sc1
.LBB0_434:
	s_waitcnt vmcnt(2)
	s_nop 0
	v_lshlrev_b32_e32 v36, 16, v72
	v_and_b32_e32 v37, 0xffff0000, v72
	v_lshlrev_b32_e32 v38, 16, v73
	v_and_b32_e32 v39, 0xffff0000, v73
	v_lshlrev_b32_e32 v40, 16, v74
	v_and_b32_e32 v41, 0xffff0000, v74
	v_lshlrev_b32_e32 v42, 16, v75
	v_and_b32_e32 v43, 0xffff0000, v75
	v_mov_b32_e32 v173, v172
	v_pk_fma_f32 v[22:23], v[172:173], v[22:23], v[38:39]
	v_pk_fma_f32 v[20:21], v[174:175], v[20:21], v[36:37]
	v_pk_fma_f32 v[18:19], v[172:173], v[18:19], v[42:43]
	s_and_b64 vcc, exec, s[40:41]
	v_pk_fma_f32 v[16:17], v[174:175], v[16:17], v[40:41]
	s_cbranch_vccnz .LBB0_462
	global_store_dwordx4 v[34:35], v[20:23], off offset:512 sc1
	global_store_dwordx4 v[34:35], v[16:19], off offset:528 sc1
	s_cbranch_execnz .LBB0_437
.LBB0_436:
	v_cvt_pk_bf16_f32 v34, v20, v21
	v_cvt_pk_bf16_f32 v35, v22, v23
	v_cvt_pk_bf16_f32 v36, v16, v17
	v_cvt_pk_bf16_f32 v37, v18, v19
	global_store_dwordx4 v[32:33], v[34:37], off offset:256 sc1

.LBB0_439:
	s_or_b64 exec, exec, s[82:83]
	s_waitcnt lgkmcnt(0)
	v_lshlrev_b64 v[16:17], 12, v[92:93]
	s_waitcnt vmcnt(1)
	v_lshlrev_b32_e32 v18, 16, v68
	v_and_b32_e32 v19, 0xffff0000, v68
	v_lshlrev_b32_e32 v20, 16, v69
	v_and_b32_e32 v21, 0xffff0000, v69
	v_lshlrev_b32_e32 v22, 16, v70
	v_and_b32_e32 v23, 0xffff0000, v70
	v_lshlrev_b32_e32 v24, 16, v71
	v_and_b32_e32 v25, 0xffff0000, v71
	v_mov_b32_e32 v173, v172
	v_lshl_add_u64 v[16:17], s[12:13], 0, v[16:17]
	v_pk_fma_f32 v[14:15], v[172:173], v[14:15], v[20:21]
	v_pk_fma_f32 v[12:13], v[174:175], v[12:13], v[18:19]
	v_pk_fma_f32 v[10:11], v[172:173], v[10:11], v[24:25]
	v_pk_fma_f32 v[8:9], v[174:175], v[8:9], v[22:23]
	s_and_b64 vcc, exec, s[40:41]
	v_lshl_add_u64 v[18:19], v[180:181], 2, v[16:17]
	s_cbranch_vccnz .LBB0_463
	global_store_dwordx4 v[18:19], v[12:15], off sc1
	global_store_dwordx4 v[18:19], v[8:11], off offset:16 sc1
	v_lshl_add_u64 v[16:17], s[0:1], 0, v[94:95]
	v_lshl_add_u64 v[16:17], v[180:181], 1, v[16:17]
	s_cbranch_execnz .LBB0_442
.LBB0_441:
	v_cvt_pk_bf16_f32 v20, v12, v13
	v_cvt_pk_bf16_f32 v21, v14, v15
	v_cvt_pk_bf16_f32 v22, v8, v9
	v_cvt_pk_bf16_f32 v23, v10, v11
	global_store_dwordx4 v[16:17], v[20:23], off sc1
.LBB0_442:
	s_waitcnt vmcnt(0)
	s_nop 0
	v_lshlrev_b32_e32 v20, 16, v64
	v_and_b32_e32 v21, 0xffff0000, v64
	v_lshlrev_b32_e32 v22, 16, v65
	v_and_b32_e32 v23, 0xffff0000, v65
	v_lshlrev_b32_e32 v24, 16, v66
	v_and_b32_e32 v25, 0xffff0000, v66
	v_lshlrev_b32_e32 v26, 16, v67
	v_and_b32_e32 v27, 0xffff0000, v67
	v_mov_b32_e32 v173, v172
	v_pk_fma_f32 v[6:7], v[172:173], v[6:7], v[22:23]
	v_pk_fma_f32 v[4:5], v[174:175], v[4:5], v[20:21]
	v_pk_fma_f32 v[2:3], v[172:173], v[2:3], v[26:27]
	s_and_b64 vcc, exec, s[40:41]
	v_pk_fma_f32 v[0:1], v[174:175], v[0:1], v[24:25]
	s_cbranch_vccnz .LBB0_464
	global_store_dwordx4 v[18:19], v[4:7], off offset:512 sc1
	global_store_dwordx4 v[18:19], v[0:3], off offset:528 sc1
	s_cbranch_execnz .LBB0_445
.LBB0_444:
	v_cvt_pk_bf16_f32 v18, v4, v5
	v_cvt_pk_bf16_f32 v19, v6, v7
	v_cvt_pk_bf16_f32 v20, v0, v1
	v_cvt_pk_bf16_f32 v21, v2, v3
	global_store_dwordx4 v[16:17], v[18:21], off offset:256 sc1

.LBB0_481:
	s_lshl_b32 s4, s8, 8
	s_add_i32 s4, s4, s90
	v_or_b32_e32 v150, s4, v195
	s_mov_b64 s[8:9], -1
	s_cmp_lt_i32 s14, 22
	v_ashrrev_i32_e32 v151, 31, v150
	s_brev_b32 s50, 18
	s_mov_b32 s51, 0xfe5163ab
	s_cbranch_scc1 .LBB0_612
	v_lshlrev_b64 v[152:153], 6, v[150:151]
	v_lshl_add_u64 v[154:155], v[142:143], 0, v[152:153]
	global_load_dwordx4 v[154:157], v[154:155], off
	s_cmp_gt_u32 s14, 24
	s_cselect_b64 s[12:13], -1, 0
	s_lshl_b32 s8, s14, 1
	s_ashr_i32 s4, s4, 12
	s_sub_i32 s17, s8, 50
	s_mul_i32 s4, s4, 6
	s_add_i32 s8, s4, s17
	s_mov_b64 s[40:41], -1
	s_waitcnt vmcnt(0)
	v_mov_b32_e32 v158, v155
	v_mov_b32_e32 v159, v156
	v_mov_b32_e32 v155, v157
	v_pk_add_f32 v[154:155], v[158:159], v[154:155]
	s_nop 0
	v_add_f32_e32 v154, v154, v155
	ds_bpermute_b32 v155, v197, v154
	s_waitcnt lgkmcnt(0)
	v_add_f32_e32 v154, v154, v155
	ds_bpermute_b32 v155, v198, v154
	s_waitcnt lgkmcnt(0)
	v_add_f32_e32 v154, v154, v155
	v_fmamk_f32 v154, v154, 0x3a800000, v216
	v_cmp_gt_f32_e32 vcc, s29, v154
	v_mul_f32_e32 v155, 0x4b800000, v154
	s_nop 0
	v_cndmask_b32_e32 v154, v154, v155, vcc
	v_rsq_f32_e32 v154, v154
	s_nop 0
	v_mul_f32_e32 v155, 0x45800000, v154
	v_cndmask_b32_e32 v154, v154, v155, vcc
	v_and_b32_e32 v155, 0xfcf, v150
	v_pk_mul_f32 v[174:175], v[126:127], v[154:155] op_sel_hi:[1,0]
	v_pk_mul_f32 v[176:177], v[124:125], v[154:155] op_sel_hi:[1,0]
	v_pk_mul_f32 v[170:171], v[122:123], v[154:155] op_sel_hi:[1,0]
	v_pk_mul_f32 v[172:173], v[120:121], v[154:155] op_sel_hi:[1,0]
	s_and_b64 vcc, exec, s[12:13]
	v_lshlrev_b32_e32 v158, 1, v155
	s_cbranch_vccz .LBB0_484
	s_ashr_i32 s9, s8, 31
	s_lshl_b64 s[24:25], s[8:9], 20
	v_lshl_add_u64 v[156:157], v[144:145], 0, s[24:25]
	v_mov_b32_e32 v159, v161
	v_lshl_add_u64 v[156:157], v[156:157], 0, v[158:159]
	v_add_co_u32_e32 v162, vcc, s68, v156
	v_cvt_pk_bf16_f32 v155, v176, v177
	s_nop 0
	v_addc_co_u32_e32 v163, vcc, 0, v157, vcc
	global_store_short_d16_hi v[162:163], v155, off
	v_add_co_u32_e32 v162, vcc, s69, v156
	v_cvt_pk_bf16_f32 v159, v174, v175
	s_nop 0
	v_addc_co_u32_e32 v163, vcc, 0, v157, vcc
	global_store_short v[162:163], v159, off sc1
	v_add_co_u32_e32 v162, vcc, s70, v156
	v_cvt_pk_bf16_f32 v160, v172, v173
	s_nop 0
	v_addc_co_u32_e32 v163, vcc, 0, v157, vcc
	global_store_short_d16_hi v[162:163], v159, off
	v_add_co_u32_e32 v162, vcc, s71, v156
	global_store_short v[156:157], v155, off sc1
	s_nop 0
	v_addc_co_u32_e32 v163, vcc, 0, v157, vcc
	global_store_short v[162:163], v160, off sc1
	v_add_co_u32_e32 v162, vcc, 0xa000, v156
	v_cvt_pk_bf16_f32 v164, v170, v171
	s_nop 0
	v_addc_co_u32_e32 v163, vcc, 0, v157, vcc
	global_store_short_d16_hi v[162:163], v160, off
	v_add_co_u32_e32 v162, vcc, 0xc000, v156
	s_mov_b64 s[40:41], 0
	s_nop 0
	v_addc_co_u32_e32 v163, vcc, 0, v157, vcc
	v_add_co_u32_e32 v156, vcc, 0xe000, v156
	global_store_short v[162:163], v164, off sc1
	s_nop 0
	v_addc_co_u32_e32 v157, vcc, 0, v157, vcc
	global_store_short_d16_hi v[156:157], v164, off

.LBB0_489:
	v_lshl_add_u64 v[162:163], s[30:31], 0, v[156:157]
	v_lshl_add_u64 v[162:163], s[4:5], 1, v[162:163]
	s_lshl_b32 s24, s91, 1
	s_mov_b32 s25, s5
	v_lshl_add_u64 v[162:163], v[162:163], 0, s[24:25]
	v_lshlrev_b32_e32 v160, 1, v136
	v_cvt_pk_bf16_f32 v176, v176, v177
	v_cvt_pk_bf16_f32 v177, v174, v175
	s_waitcnt lgkmcnt(2)
	v_cvt_pk_bf16_f32 v178, v172, v173
	s_waitcnt lgkmcnt(0)
	v_cvt_pk_bf16_f32 v179, v170, v171
	v_lshl_add_u64 v[162:163], v[162:163], 0, v[160:161]
	global_store_dwordx4 v[162:163], v[176:179], off sc1
.LBB0_490:
	v_mov_b32_e32 v155, v154
	v_mov_b32_e32 v162, v154
	v_mov_b32_e32 v163, v154
	v_cndmask_b32_e64 v159, 0, 1, s[12:13]
	v_pk_mul_f32 v[172:173], v[118:119], v[162:163]
	v_pk_mul_f32 v[174:175], v[116:117], v[154:155]
	v_pk_mul_f32 v[170:171], v[114:115], v[162:163]
	v_pk_mul_f32 v[154:155], v[112:113], v[154:155]
	v_cmp_ne_u32_e64 s[42:43], 1, v159
	s_andn2_b64 vcc, exec, s[12:13]
	s_mov_b64 s[12:13], -1
	s_cbranch_vccnz .LBB0_492
	s_or_b32 s12, s8, 1
	s_ashr_i32 s13, s12, 31
	s_lshl_b64 s[12:13], s[12:13], 20
	v_lshl_add_u64 v[162:163], v[144:145], 0, s[12:13]
	v_mov_b32_e32 v159, v161
	v_lshl_add_u64 v[158:159], v[162:163], 0, v[158:159]
	v_add_co_u32_e32 v162, vcc, s68, v158
	v_cvt_pk_bf16_f32 v160, v174, v175
	s_nop 0
	v_addc_co_u32_e32 v163, vcc, 0, v159, vcc
	global_store_short_d16_hi v[162:163], v160, off
	v_add_co_u32_e32 v162, vcc, s69, v158
	v_cvt_pk_bf16_f32 v164, v172, v173
	s_nop 0
	v_addc_co_u32_e32 v163, vcc, 0, v159, vcc
	global_store_short v[162:163], v164, off sc1
	v_add_co_u32_e32 v162, vcc, s70, v158
	v_cvt_pk_bf16_f32 v165, v154, v155
	s_nop 0
	v_addc_co_u32_e32 v163, vcc, 0, v159, vcc
	global_store_short_d16_hi v[162:163], v164, off
	v_add_co_u32_e32 v162, vcc, s71, v158
	global_store_short v[158:159], v160, off sc1
	s_nop 0
	v_addc_co_u32_e32 v163, vcc, 0, v159, vcc
	global_store_short v[162:163], v165, off sc1
	v_add_co_u32_e32 v162, vcc, 0xa000, v158
	v_cvt_pk_bf16_f32 v176, v170, v171
	s_nop 0
	v_addc_co_u32_e32 v163, vcc, 0, v159, vcc
	global_store_short_d16_hi v[162:163], v165, off
	v_add_co_u32_e32 v162, vcc, 0xc000, v158
	s_mov_b64 s[12:13], 0
	s_nop 0
	v_addc_co_u32_e32 v163, vcc, 0, v159, vcc
	v_add_co_u32_e32 v158, vcc, 0xe000, v158
	global_store_short v[162:163], v176, off sc1
	s_nop 0
	v_addc_co_u32_e32 v159, vcc, 0, v159, vcc
	global_store_short_d16_hi v[158:159], v176, off

.LBB0_497:
	v_lshl_add_u64 v[156:157], s[30:31], 0, v[156:157]
	v_lshl_add_u64 v[156:157], s[4:5], 1, v[156:157]
	s_lshl_b32 s12, s91, 1
	s_mov_b32 s13, s5
	v_lshl_add_u64 v[156:157], v[156:157], 0, s[12:13]
	v_lshlrev_b32_e32 v160, 1, v136
	v_cvt_pk_bf16_f32 v152, v174, v175
	v_cvt_pk_bf16_f32 v153, v172, v173
	v_cvt_pk_bf16_f32 v154, v154, v155
	v_cvt_pk_bf16_f32 v155, v170, v171
	v_lshl_add_u64 v[156:157], v[156:157], 0, v[160:161]
	global_store_dwordx4 v[156:157], v[152:155], off offset:256 sc1
.LBB0_498:
	s_nop 1
	v_or_b32_e32 v154, 16, v150
	v_ashrrev_i32_e32 v155, 31, v154
	v_lshlrev_b64 v[152:153], 6, v[154:155]
	v_lshl_add_u64 v[156:157], v[142:143], 0, v[152:153]
	s_waitcnt lgkmcnt(0)
	global_load_dwordx4 v[156:159], v[156:157], off
	s_movk_i32 s9, 0xfdf
	s_mov_b64 s[12:13], -1
	s_waitcnt vmcnt(0)
	v_mov_b32_e32 v162, v157
	v_mov_b32_e32 v163, v158
	v_mov_b32_e32 v157, v159
	v_pk_add_f32 v[156:157], v[162:163], v[156:157]
	s_nop 0
	v_add_f32_e32 v155, v156, v157
	ds_bpermute_b32 v156, v197, v155
	s_waitcnt lgkmcnt(0)
	v_add_f32_e32 v155, v155, v156
	ds_bpermute_b32 v156, v198, v155
	s_waitcnt lgkmcnt(0)
	v_add_f32_e32 v155, v155, v156
	v_fmamk_f32 v155, v155, 0x3a800000, v216
	v_cmp_gt_f32_e32 vcc, s29, v155
	v_mul_f32_e32 v156, 0x4b800000, v155
	s_nop 0
	v_cndmask_b32_e32 v155, v155, v156, vcc
	v_rsq_f32_e32 v155, v155
	s_nop 0
	v_mul_f32_e32 v156, 0x45800000, v155
	v_cndmask_b32_e32 v156, v155, v156, vcc
	v_bitop3_b32 v155, v150, s9, 16 bitop3:0xc8
	v_pk_mul_f32 v[174:175], v[110:111], v[156:157] op_sel_hi:[1,0]
	v_pk_mul_f32 v[176:177], v[108:109], v[156:157] op_sel_hi:[1,0]
	v_pk_mul_f32 v[158:159], v[106:107], v[156:157] op_sel_hi:[1,0]
	v_pk_mul_f32 v[170:171], v[104:105], v[156:157] op_sel_hi:[1,0]
	s_and_b64 vcc, exec, s[42:43]
	v_lshlrev_b32_e32 v172, 1, v155
	s_cbranch_vccnz .LBB0_500
	s_ashr_i32 s9, s8, 31
	s_lshl_b64 s[12:13], s[8:9], 20
	v_lshl_add_u64 v[162:163], v[144:145], 0, s[12:13]
	v_mov_b32_e32 v173, v161
	v_lshl_add_u64 v[162:163], v[162:163], 0, v[172:173]
	v_add_co_u32_e32 v164, vcc, s68, v162
	v_cvt_pk_bf16_f32 v155, v176, v177
	s_nop 0
	v_addc_co_u32_e32 v165, vcc, 0, v163, vcc
	global_store_short_d16_hi v[164:165], v155, off
	v_add_co_u32_e32 v164, vcc, s69, v162
	v_cvt_pk_bf16_f32 v157, v174, v175
	s_nop 0
	v_addc_co_u32_e32 v165, vcc, 0, v163, vcc
	global_store_short v[164:165], v157, off sc1
	v_add_co_u32_e32 v164, vcc, s70, v162
	v_cvt_pk_bf16_f32 v160, v170, v171
	s_nop 0
	v_addc_co_u32_e32 v165, vcc, 0, v163, vcc
	global_store_short_d16_hi v[164:165], v157, off
	v_add_co_u32_e32 v164, vcc, s71, v162
	global_store_short v[162:163], v155, off sc1
	s_nop 0
	v_addc_co_u32_e32 v165, vcc, 0, v163, vcc
	global_store_short v[164:165], v160, off sc1
	v_add_co_u32_e32 v164, vcc, 0xa000, v162
	v_cvt_pk_bf16_f32 v173, v158, v159
	s_nop 0
	v_addc_co_u32_e32 v165, vcc, 0, v163, vcc
	global_store_short_d16_hi v[164:165], v160, off
	v_add_co_u32_e32 v164, vcc, 0xc000, v162
	s_mov_b64 s[12:13], 0
	s_nop 0
	v_addc_co_u32_e32 v165, vcc, 0, v163, vcc
	v_add_co_u32_e32 v162, vcc, 0xe000, v162
	global_store_short v[164:165], v173, off sc1
	s_nop 0
	v_addc_co_u32_e32 v163, vcc, 0, v163, vcc
	global_store_short_d16_hi v[162:163], v173, off

.LBB0_505:
	s_waitcnt lgkmcnt(0)
	v_cvt_pk_bf16_f32 v179, v158, v159
	v_lshl_add_u64 v[158:159], s[30:31], 0, v[154:155]
	v_lshl_add_u64 v[158:159], s[4:5], 1, v[158:159]
	s_lshl_b32 s12, s91, 1
	s_mov_b32 s13, s5
	v_lshl_add_u64 v[158:159], v[158:159], 0, s[12:13]
	v_lshlrev_b32_e32 v160, 1, v136
	v_cvt_pk_bf16_f32 v176, v176, v177
	v_cvt_pk_bf16_f32 v177, v174, v175
	v_cvt_pk_bf16_f32 v178, v170, v171
	v_lshl_add_u64 v[158:159], v[158:159], 0, v[160:161]
	global_store_dwordx4 v[158:159], v[176:179], off sc1
.LBB0_506:
	v_mov_b32_e32 v157, v156
	v_mov_b32_e32 v158, v156
	v_mov_b32_e32 v159, v156
	v_pk_mul_f32 v[170:171], v[102:103], v[158:159]
	v_pk_mul_f32 v[174:175], v[100:101], v[156:157]
	v_pk_mul_f32 v[158:159], v[98:99], v[158:159]
	v_pk_mul_f32 v[156:157], v[96:97], v[156:157]
	s_and_b64 vcc, exec, s[42:43]
	s_mov_b64 s[12:13], -1
	s_cbranch_vccnz .LBB0_508
	s_or_b32 s12, s8, 1
	s_ashr_i32 s13, s12, 31
	s_lshl_b64 s[12:13], s[12:13], 20
	v_lshl_add_u64 v[162:163], v[144:145], 0, s[12:13]
	v_mov_b32_e32 v173, v161
	v_lshl_add_u64 v[162:163], v[162:163], 0, v[172:173]
	v_add_co_u32_e32 v164, vcc, s68, v162
	v_cvt_pk_bf16_f32 v160, v174, v175
	s_nop 0
	v_addc_co_u32_e32 v165, vcc, 0, v163, vcc
	global_store_short_d16_hi v[164:165], v160, off
	v_add_co_u32_e32 v164, vcc, s69, v162
	v_cvt_pk_bf16_f32 v172, v170, v171
	s_nop 0
	v_addc_co_u32_e32 v165, vcc, 0, v163, vcc
	global_store_short v[164:165], v172, off sc1
	v_add_co_u32_e32 v164, vcc, s70, v162
	v_cvt_pk_bf16_f32 v173, v156, v157
	s_nop 0
	v_addc_co_u32_e32 v165, vcc, 0, v163, vcc
	global_store_short_d16_hi v[164:165], v172, off
	v_add_co_u32_e32 v164, vcc, s71, v162
	global_store_short v[162:163], v160, off sc1
	s_nop 0
	v_addc_co_u32_e32 v165, vcc, 0, v163, vcc
	global_store_short v[164:165], v173, off sc1
	v_add_co_u32_e32 v164, vcc, 0xa000, v162
	v_cvt_pk_bf16_f32 v176, v158, v159
	s_nop 0
	v_addc_co_u32_e32 v165, vcc, 0, v163, vcc
	global_store_short_d16_hi v[164:165], v173, off
	v_add_co_u32_e32 v164, vcc, 0xc000, v162
	s_mov_b64 s[12:13], 0
	s_nop 0
	v_addc_co_u32_e32 v165, vcc, 0, v163, vcc
	v_add_co_u32_e32 v162, vcc, 0xe000, v162
	global_store_short v[164:165], v176, off sc1
	s_nop 0
	v_addc_co_u32_e32 v163, vcc, 0, v163, vcc
	global_store_short_d16_hi v[162:163], v176, off

.LBB0_513:
	v_lshl_add_u64 v[152:153], s[30:31], 0, v[154:155]
	v_lshl_add_u64 v[152:153], s[4:5], 1, v[152:153]
	s_lshl_b32 s12, s91, 1
	s_mov_b32 s13, s5
	v_lshl_add_u64 v[152:153], v[152:153], 0, s[12:13]
	v_lshlrev_b32_e32 v160, 1, v136
	s_waitcnt lgkmcnt(2)
	v_cvt_pk_bf16_f32 v172, v174, v175
	s_waitcnt lgkmcnt(0)
	v_cvt_pk_bf16_f32 v173, v170, v171
	v_cvt_pk_bf16_f32 v174, v156, v157
	v_cvt_pk_bf16_f32 v175, v158, v159
	v_lshl_add_u64 v[152:153], v[152:153], 0, v[160:161]
	global_store_dwordx4 v[152:153], v[172:175], off offset:256 sc1
.LBB0_514:
	v_or_b32_e32 v154, 32, v150
	v_ashrrev_i32_e32 v155, 31, v154
	v_lshlrev_b64 v[152:153], 6, v[154:155]
	v_lshl_add_u64 v[156:157], v[142:143], 0, v[152:153]
	global_load_dwordx4 v[156:159], v[156:157], off
	s_movk_i32 s9, 0xfef
	s_mov_b64 s[12:13], -1
	s_waitcnt vmcnt(0)
	v_mov_b32_e32 v162, v157
	v_mov_b32_e32 v163, v158
	v_mov_b32_e32 v157, v159
	v_pk_add_f32 v[156:157], v[162:163], v[156:157]
	s_nop 0
	v_add_f32_e32 v155, v156, v157
	ds_bpermute_b32 v156, v197, v155
	s_waitcnt lgkmcnt(0)
	v_add_f32_e32 v155, v155, v156
	ds_bpermute_b32 v156, v198, v155
	s_waitcnt lgkmcnt(0)
	v_add_f32_e32 v155, v155, v156
	v_fmamk_f32 v155, v155, 0x3a800000, v216
	v_cmp_gt_f32_e32 vcc, s29, v155
	v_mul_f32_e32 v156, 0x4b800000, v155
	s_nop 0
	v_cndmask_b32_e32 v155, v155, v156, vcc
	v_rsq_f32_e32 v155, v155
	s_nop 0
	v_mul_f32_e32 v156, 0x45800000, v155
	v_cndmask_b32_e32 v156, v155, v156, vcc
	v_bitop3_b32 v155, v150, s9, 32 bitop3:0xc8
	v_pk_mul_f32 v[174:175], v[94:95], v[156:157] op_sel_hi:[1,0]
	v_pk_mul_f32 v[176:177], v[92:93], v[156:157] op_sel_hi:[1,0]
	v_pk_mul_f32 v[158:159], v[90:91], v[156:157] op_sel_hi:[1,0]
	v_pk_mul_f32 v[170:171], v[88:89], v[156:157] op_sel_hi:[1,0]
	s_and_b64 vcc, exec, s[42:43]
	v_lshlrev_b32_e32 v172, 1, v155
	s_cbranch_vccnz .LBB0_516
	s_ashr_i32 s9, s8, 31
	s_lshl_b64 s[12:13], s[8:9], 20
	v_lshl_add_u64 v[162:163], v[144:145], 0, s[12:13]
	v_mov_b32_e32 v173, v161
	v_lshl_add_u64 v[162:163], v[162:163], 0, v[172:173]
	v_add_co_u32_e32 v164, vcc, s68, v162
	v_cvt_pk_bf16_f32 v155, v176, v177
	s_nop 0
	v_addc_co_u32_e32 v165, vcc, 0, v163, vcc
	global_store_short_d16_hi v[164:165], v155, off
	v_add_co_u32_e32 v164, vcc, s69, v162
	v_cvt_pk_bf16_f32 v157, v174, v175
	s_nop 0
	v_addc_co_u32_e32 v165, vcc, 0, v163, vcc
	global_store_short v[164:165], v157, off sc1
	v_add_co_u32_e32 v164, vcc, s70, v162
	v_cvt_pk_bf16_f32 v160, v170, v171
	s_nop 0
	v_addc_co_u32_e32 v165, vcc, 0, v163, vcc
	global_store_short_d16_hi v[164:165], v157, off
	v_add_co_u32_e32 v164, vcc, s71, v162
	global_store_short v[162:163], v155, off sc1
	s_nop 0
	v_addc_co_u32_e32 v165, vcc, 0, v163, vcc
	global_store_short v[164:165], v160, off sc1
	v_add_co_u32_e32 v164, vcc, 0xa000, v162
	v_cvt_pk_bf16_f32 v173, v158, v159
	s_nop 0
	v_addc_co_u32_e32 v165, vcc, 0, v163, vcc
	global_store_short_d16_hi v[164:165], v160, off
	v_add_co_u32_e32 v164, vcc, 0xc000, v162
	s_mov_b64 s[12:13], 0
	s_nop 0
	v_addc_co_u32_e32 v165, vcc, 0, v163, vcc
	v_add_co_u32_e32 v162, vcc, 0xe000, v162
	global_store_short v[164:165], v173, off sc1
	s_nop 0
	v_addc_co_u32_e32 v163, vcc, 0, v163, vcc
	global_store_short_d16_hi v[162:163], v173, off

.LBB0_522:
	v_mov_b32_e32 v157, v156
	v_mov_b32_e32 v158, v156
	v_mov_b32_e32 v159, v156
	v_pk_mul_f32 v[170:171], v[86:87], v[158:159]
	v_pk_mul_f32 v[174:175], v[84:85], v[156:157]
	v_pk_mul_f32 v[158:159], v[82:83], v[158:159]
	v_pk_mul_f32 v[156:157], v[80:81], v[156:157]
	s_and_b64 vcc, exec, s[42:43]
	s_mov_b64 s[12:13], -1
	s_cbranch_vccnz .LBB0_524
	s_or_b32 s12, s8, 1
	s_ashr_i32 s13, s12, 31
	s_lshl_b64 s[12:13], s[12:13], 20
	v_lshl_add_u64 v[162:163], v[144:145], 0, s[12:13]
	v_mov_b32_e32 v173, v161
	v_lshl_add_u64 v[162:163], v[162:163], 0, v[172:173]
	v_add_co_u32_e32 v164, vcc, s68, v162
	v_cvt_pk_bf16_f32 v160, v174, v175
	s_nop 0
	v_addc_co_u32_e32 v165, vcc, 0, v163, vcc
	global_store_short_d16_hi v[164:165], v160, off
	v_add_co_u32_e32 v164, vcc, s69, v162
	v_cvt_pk_bf16_f32 v172, v170, v171
	s_nop 0
	v_addc_co_u32_e32 v165, vcc, 0, v163, vcc
	global_store_short v[164:165], v172, off sc1
	v_add_co_u32_e32 v164, vcc, s70, v162
	v_cvt_pk_bf16_f32 v173, v156, v157
	s_nop 0
	v_addc_co_u32_e32 v165, vcc, 0, v163, vcc
	global_store_short_d16_hi v[164:165], v172, off
	v_add_co_u32_e32 v164, vcc, s71, v162
	global_store_short v[162:163], v160, off sc1
	s_nop 0
	v_addc_co_u32_e32 v165, vcc, 0, v163, vcc
	global_store_short v[164:165], v173, off sc1
	v_add_co_u32_e32 v164, vcc, 0xa000, v162
	v_cvt_pk_bf16_f32 v176, v158, v159
	s_nop 0
	v_addc_co_u32_e32 v165, vcc, 0, v163, vcc
	global_store_short_d16_hi v[164:165], v173, off
	v_add_co_u32_e32 v164, vcc, 0xc000, v162
	s_mov_b64 s[12:13], 0
	s_nop 0
	v_addc_co_u32_e32 v165, vcc, 0, v163, vcc
	v_add_co_u32_e32 v162, vcc, 0xe000, v162
	global_store_short v[164:165], v176, off sc1
	s_nop 0
	v_addc_co_u32_e32 v163, vcc, 0, v163, vcc
	global_store_short_d16_hi v[162:163], v176, off

.LBB0_530:
	v_or_b32_e32 v154, 48, v150
	v_ashrrev_i32_e32 v155, 31, v154
	v_lshlrev_b64 v[152:153], 6, v[154:155]
	v_lshl_add_u64 v[156:157], v[142:143], 0, v[152:153]
	global_load_dwordx4 v[156:159], v[156:157], off
	s_movk_i32 s9, 0xfff
	s_mov_b64 s[12:13], -1
	s_waitcnt vmcnt(0)
	v_mov_b32_e32 v162, v157
	v_mov_b32_e32 v163, v158
	v_mov_b32_e32 v157, v159
	v_pk_add_f32 v[156:157], v[162:163], v[156:157]
	s_nop 0
	v_add_f32_e32 v155, v156, v157
	ds_bpermute_b32 v156, v197, v155
	s_waitcnt lgkmcnt(0)
	v_add_f32_e32 v155, v155, v156
	ds_bpermute_b32 v156, v198, v155
	s_waitcnt lgkmcnt(0)
	v_add_f32_e32 v155, v155, v156
	v_fmamk_f32 v155, v155, 0x3a800000, v216
	v_cmp_gt_f32_e32 vcc, s29, v155
	v_mul_f32_e32 v156, 0x4b800000, v155
	s_nop 0
	v_cndmask_b32_e32 v155, v155, v156, vcc
	v_rsq_f32_e32 v155, v155
	s_nop 0
	v_mul_f32_e32 v156, 0x45800000, v155
	v_cndmask_b32_e32 v156, v155, v156, vcc
	v_bitop3_b32 v155, v150, s9, 48 bitop3:0xc8
	v_pk_mul_f32 v[174:175], v[78:79], v[156:157] op_sel_hi:[1,0]
	v_pk_mul_f32 v[176:177], v[76:77], v[156:157] op_sel_hi:[1,0]
	v_pk_mul_f32 v[158:159], v[74:75], v[156:157] op_sel_hi:[1,0]
	v_pk_mul_f32 v[170:171], v[72:73], v[156:157] op_sel_hi:[1,0]
	s_and_b64 vcc, exec, s[42:43]
	v_lshlrev_b32_e32 v172, 1, v155
	s_cbranch_vccnz .LBB0_532
	s_ashr_i32 s9, s8, 31
	s_lshl_b64 s[12:13], s[8:9], 20
	v_lshl_add_u64 v[162:163], v[144:145], 0, s[12:13]
	v_mov_b32_e32 v173, v161
	v_lshl_add_u64 v[162:163], v[162:163], 0, v[172:173]
	v_add_co_u32_e32 v164, vcc, s68, v162
	v_cvt_pk_bf16_f32 v155, v176, v177
	s_nop 0
	v_addc_co_u32_e32 v165, vcc, 0, v163, vcc
	global_store_short_d16_hi v[164:165], v155, off
	v_add_co_u32_e32 v164, vcc, s69, v162
	v_cvt_pk_bf16_f32 v157, v174, v175
	s_nop 0
	v_addc_co_u32_e32 v165, vcc, 0, v163, vcc
	global_store_short v[164:165], v157, off sc1
	v_add_co_u32_e32 v164, vcc, s70, v162
	v_cvt_pk_bf16_f32 v160, v170, v171
	s_nop 0
	v_addc_co_u32_e32 v165, vcc, 0, v163, vcc
	global_store_short_d16_hi v[164:165], v157, off
	v_add_co_u32_e32 v164, vcc, s71, v162
	global_store_short v[162:163], v155, off sc1
	s_nop 0
	v_addc_co_u32_e32 v165, vcc, 0, v163, vcc
	global_store_short v[164:165], v160, off sc1
	v_add_co_u32_e32 v164, vcc, 0xa000, v162
	v_cvt_pk_bf16_f32 v173, v158, v159
	s_nop 0
	v_addc_co_u32_e32 v165, vcc, 0, v163, vcc
	global_store_short_d16_hi v[164:165], v160, off
	v_add_co_u32_e32 v164, vcc, 0xc000, v162
	s_mov_b64 s[12:13], 0
	s_nop 0
	v_addc_co_u32_e32 v165, vcc, 0, v163, vcc
	v_add_co_u32_e32 v162, vcc, 0xe000, v162
	global_store_short v[164:165], v173, off sc1
	s_nop 0
	v_addc_co_u32_e32 v163, vcc, 0, v163, vcc
	global_store_short_d16_hi v[162:163], v173, off

.LBB0_538:
	v_mov_b32_e32 v157, v156
	v_mov_b32_e32 v158, v156
	v_mov_b32_e32 v159, v156
	v_pk_mul_f32 v[170:171], v[70:71], v[158:159]
	v_pk_mul_f32 v[174:175], v[68:69], v[156:157]
	v_pk_mul_f32 v[158:159], v[66:67], v[158:159]
	v_pk_mul_f32 v[156:157], v[64:65], v[156:157]
	s_and_b64 vcc, exec, s[42:43]
	s_mov_b64 s[12:13], -1
	s_cbranch_vccnz .LBB0_540
	s_or_b32 s8, s8, 1
	s_ashr_i32 s9, s8, 31
	s_lshl_b64 s[8:9], s[8:9], 20
	v_lshl_add_u64 v[162:163], v[144:145], 0, s[8:9]
	v_mov_b32_e32 v173, v161
	v_lshl_add_u64 v[162:163], v[162:163], 0, v[172:173]
	v_add_co_u32_e32 v164, vcc, s68, v162
	v_cvt_pk_bf16_f32 v160, v174, v175
	s_nop 0
	v_addc_co_u32_e32 v165, vcc, 0, v163, vcc
	global_store_short_d16_hi v[164:165], v160, off
	v_add_co_u32_e32 v164, vcc, s69, v162
	v_cvt_pk_bf16_f32 v172, v170, v171
	s_nop 0
	v_addc_co_u32_e32 v165, vcc, 0, v163, vcc
	global_store_short v[164:165], v172, off sc1
	v_add_co_u32_e32 v164, vcc, s70, v162
	v_cvt_pk_bf16_f32 v173, v156, v157
	s_nop 0
	v_addc_co_u32_e32 v165, vcc, 0, v163, vcc
	global_store_short_d16_hi v[164:165], v172, off
	v_add_co_u32_e32 v164, vcc, s71, v162
	global_store_short v[162:163], v160, off sc1
	s_nop 0
	v_addc_co_u32_e32 v165, vcc, 0, v163, vcc
	global_store_short v[164:165], v173, off sc1
	v_add_co_u32_e32 v164, vcc, 0xa000, v162
	v_cvt_pk_bf16_f32 v176, v158, v159
	s_nop 0
	v_addc_co_u32_e32 v165, vcc, 0, v163, vcc
	global_store_short_d16_hi v[164:165], v173, off
	v_add_co_u32_e32 v164, vcc, 0xc000, v162
	s_mov_b64 s[12:13], 0
	s_nop 0
	v_addc_co_u32_e32 v165, vcc, 0, v163, vcc
	v_add_co_u32_e32 v162, vcc, 0xe000, v162
	global_store_short v[164:165], v176, off sc1
	s_nop 0
	v_addc_co_u32_e32 v163, vcc, 0, v163, vcc
	global_store_short_d16_hi v[162:163], v176, off

.LBB0_545:
	v_lshl_add_u64 v[152:153], s[30:31], 0, v[154:155]
	v_lshl_add_u64 v[152:153], s[4:5], 1, v[152:153]
	s_lshl_b32 s8, s91, 1
	s_mov_b32 s9, s5
	v_lshl_add_u64 v[152:153], v[152:153], 0, s[8:9]
	v_lshlrev_b32_e32 v160, 1, v136
	s_waitcnt lgkmcnt(2)
	v_cvt_pk_bf16_f32 v172, v174, v175
	s_waitcnt lgkmcnt(0)
	v_cvt_pk_bf16_f32 v173, v170, v171
	v_cvt_pk_bf16_f32 v174, v156, v157
	v_cvt_pk_bf16_f32 v175, v158, v159
	v_lshl_add_u64 v[152:153], v[152:153], 0, v[160:161]
	global_store_dwordx4 v[152:153], v[172:175], off offset:256 sc1
.LBB0_546:
	v_add_u32_e32 v158, 0x80, v150
	v_ashrrev_i32_e32 v159, 31, v158
	v_lshlrev_b64 v[156:157], 6, v[158:159]
	v_lshl_add_u64 v[154:155], v[142:143], 0, v[156:157]
	global_load_dwordx4 v[170:173], v[154:155], off
	v_ashrrev_i32_e32 v152, 12, v158
	v_mad_i32_i24 v152, v152, 6, s17
	s_mov_b64 s[8:9], -1
	s_waitcnt vmcnt(0)
	v_mov_b32_e32 v154, v171
	v_mov_b32_e32 v155, v172
	v_mov_b32_e32 v171, v173
	v_pk_add_f32 v[154:155], v[154:155], v[170:171]
	s_nop 0
	v_add_f32_e32 v153, v154, v155
	ds_bpermute_b32 v154, v197, v153
	v_and_b32_e32 v155, 0xfcf, v158
	v_lshlrev_b32_e32 v178, 1, v155
	s_waitcnt lgkmcnt(0)
	v_add_f32_e32 v153, v153, v154
	ds_bpermute_b32 v154, v198, v153
	s_waitcnt lgkmcnt(0)
	v_add_f32_e32 v153, v153, v154
	v_fmamk_f32 v153, v153, 0x3a800000, v216
	v_cmp_gt_f32_e32 vcc, s29, v153
	v_mul_f32_e32 v154, 0x4b800000, v153
	s_nop 0
	v_cndmask_b32_e32 v153, v153, v154, vcc
	v_rsq_f32_e32 v153, v153
	s_nop 0
	v_mul_f32_e32 v154, 0x45800000, v153
	v_cndmask_b32_e32 v154, v153, v154, vcc
	v_pk_mul_f32 v[174:175], v[62:63], v[154:155] op_sel_hi:[1,0]
	v_pk_mul_f32 v[176:177], v[60:61], v[154:155] op_sel_hi:[1,0]
	v_pk_mul_f32 v[170:171], v[58:59], v[154:155] op_sel_hi:[1,0]
	v_pk_mul_f32 v[172:173], v[56:57], v[154:155] op_sel_hi:[1,0]
	s_and_b64 vcc, exec, s[42:43]
	v_ashrrev_i32_e32 v153, 31, v152
	s_cbranch_vccnz .LBB0_548
	v_lshlrev_b64 v[162:163], 20, v[152:153]
	v_lshl_add_u64 v[162:163], v[144:145], 0, v[162:163]
	v_mov_b32_e32 v179, v161
	v_lshl_add_u64 v[162:163], v[162:163], 0, v[178:179]
	v_add_co_u32_e32 v164, vcc, s68, v162
	v_cvt_pk_bf16_f32 v155, v176, v177
	s_nop 0
	v_addc_co_u32_e32 v165, vcc, 0, v163, vcc
	global_store_short_d16_hi v[164:165], v155, off
	v_add_co_u32_e32 v164, vcc, s69, v162
	v_cvt_pk_bf16_f32 v159, v174, v175
	s_nop 0
	v_addc_co_u32_e32 v165, vcc, 0, v163, vcc
	global_store_short v[164:165], v159, off sc1
	v_add_co_u32_e32 v164, vcc, s70, v162
	v_cvt_pk_bf16_f32 v160, v172, v173
	s_nop 0
	v_addc_co_u32_e32 v165, vcc, 0, v163, vcc
	global_store_short_d16_hi v[164:165], v159, off
	v_add_co_u32_e32 v164, vcc, s71, v162
	global_store_short v[162:163], v155, off sc1
	s_nop 0
	v_addc_co_u32_e32 v165, vcc, 0, v163, vcc
	global_store_short v[164:165], v160, off sc1
	v_add_co_u32_e32 v164, vcc, 0xa000, v162
	v_cvt_pk_bf16_f32 v179, v170, v171
	s_nop 0
	v_addc_co_u32_e32 v165, vcc, 0, v163, vcc
	global_store_short_d16_hi v[164:165], v160, off
	v_add_co_u32_e32 v164, vcc, 0xc000, v162
	s_mov_b64 s[8:9], 0
	s_nop 0
	v_addc_co_u32_e32 v165, vcc, 0, v163, vcc
	v_add_co_u32_e32 v162, vcc, 0xe000, v162
	global_store_short v[164:165], v179, off sc1
	s_nop 0
	v_addc_co_u32_e32 v163, vcc, 0, v163, vcc
	global_store_short_d16_hi v[162:163], v179, off

.LBB0_553:
	v_lshl_add_u64 v[162:163], s[30:31], 0, v[158:159]
	v_lshl_add_u64 v[162:163], s[4:5], 1, v[162:163]
	s_lshl_b32 s8, s91, 1
	s_mov_b32 s9, s5
	v_lshl_add_u64 v[162:163], v[162:163], 0, s[8:9]
	v_lshlrev_b32_e32 v160, 1, v136
	s_waitcnt lgkmcnt(2)
	v_cvt_pk_bf16_f32 v180, v176, v177
	s_waitcnt lgkmcnt(0)
	v_cvt_pk_bf16_f32 v181, v174, v175
	v_cvt_pk_bf16_f32 v182, v172, v173
	v_cvt_pk_bf16_f32 v183, v170, v171
	v_lshl_add_u64 v[162:163], v[162:163], 0, v[160:161]
	global_store_dwordx4 v[162:163], v[180:183], off sc1
.LBB0_554:
	v_mov_b32_e32 v155, v154
	v_mov_b32_e32 v162, v154
	v_mov_b32_e32 v163, v154
	v_pk_mul_f32 v[176:177], v[52:53], v[154:155]
	v_pk_mul_f32 v[172:173], v[48:49], v[154:155]
	v_or_b32_e32 v154, 1, v152
	v_pk_mul_f32 v[174:175], v[54:55], v[162:163]
	v_pk_mul_f32 v[170:171], v[50:51], v[162:163]
	s_mov_b64 s[8:9], -1
	s_and_b64 vcc, exec, s[42:43]
	v_ashrrev_i32_e32 v155, 31, v154
	s_cbranch_vccnz .LBB0_556
	v_lshlrev_b64 v[162:163], 20, v[154:155]
	v_lshl_add_u64 v[162:163], v[144:145], 0, v[162:163]
	v_mov_b32_e32 v179, v161
	v_lshl_add_u64 v[162:163], v[162:163], 0, v[178:179]
	v_add_co_u32_e32 v164, vcc, s68, v162
	v_cvt_pk_bf16_f32 v160, v176, v177
	s_nop 0
	v_addc_co_u32_e32 v165, vcc, 0, v163, vcc
	global_store_short_d16_hi v[164:165], v160, off
	v_add_co_u32_e32 v164, vcc, s69, v162
	v_cvt_pk_bf16_f32 v178, v174, v175
	s_nop 0
	v_addc_co_u32_e32 v165, vcc, 0, v163, vcc
	global_store_short v[164:165], v178, off sc1
	v_add_co_u32_e32 v164, vcc, s70, v162
	v_cvt_pk_bf16_f32 v179, v172, v173
	s_nop 0
	v_addc_co_u32_e32 v165, vcc, 0, v163, vcc
	global_store_short_d16_hi v[164:165], v178, off
	v_add_co_u32_e32 v164, vcc, s71, v162
	global_store_short v[162:163], v160, off sc1
	s_nop 0
	v_addc_co_u32_e32 v165, vcc, 0, v163, vcc
	global_store_short v[164:165], v179, off sc1
	v_add_co_u32_e32 v164, vcc, 0xa000, v162
	v_cvt_pk_bf16_f32 v180, v170, v171
	s_nop 0
	v_addc_co_u32_e32 v165, vcc, 0, v163, vcc
	global_store_short_d16_hi v[164:165], v179, off
	v_add_co_u32_e32 v164, vcc, 0xc000, v162
	s_mov_b64 s[8:9], 0
	s_nop 0
	v_addc_co_u32_e32 v165, vcc, 0, v163, vcc
	v_add_co_u32_e32 v162, vcc, 0xe000, v162
	global_store_short v[164:165], v180, off sc1
	s_nop 0
	v_addc_co_u32_e32 v163, vcc, 0, v163, vcc
	global_store_short_d16_hi v[162:163], v180, off

.LBB0_561:
	v_lshl_add_u64 v[156:157], s[30:31], 0, v[158:159]
	v_lshl_add_u64 v[156:157], s[4:5], 1, v[156:157]
	s_lshl_b32 s8, s91, 1
	s_mov_b32 s9, s5
	v_lshl_add_u64 v[156:157], v[156:157], 0, s[8:9]
	v_lshlrev_b32_e32 v160, 1, v136
	v_cvt_pk_bf16_f32 v176, v176, v177
	v_cvt_pk_bf16_f32 v177, v174, v175
	s_waitcnt lgkmcnt(2)
	v_cvt_pk_bf16_f32 v178, v172, v173
	s_waitcnt lgkmcnt(0)
	v_cvt_pk_bf16_f32 v179, v170, v171
	v_lshl_add_u64 v[156:157], v[156:157], 0, v[160:161]
	global_store_dwordx4 v[156:157], v[176:179], off offset:256 sc1
.LBB0_562:
	v_add_u32_e32 v158, 0x90, v150
	v_ashrrev_i32_e32 v159, 31, v158
	v_lshlrev_b64 v[156:157], 6, v[158:159]
	v_lshl_add_u64 v[162:163], v[142:143], 0, v[156:157]
	global_load_dwordx4 v[170:173], v[162:163], off
	s_mov_b64 s[8:9], -1
	s_waitcnt vmcnt(0)
	v_mov_b32_e32 v162, v171
	v_mov_b32_e32 v163, v172
	v_mov_b32_e32 v171, v173
	v_pk_add_f32 v[162:163], v[162:163], v[170:171]
	s_nop 0
	v_add_f32_e32 v159, v162, v163
	ds_bpermute_b32 v160, v197, v159
	s_waitcnt lgkmcnt(0)
	v_add_f32_e32 v159, v159, v160
	ds_bpermute_b32 v160, v198, v159
	s_waitcnt lgkmcnt(0)
	v_add_f32_e32 v159, v159, v160
	v_fmamk_f32 v159, v159, 0x3a800000, v216
	v_cmp_gt_f32_e32 vcc, s29, v159
	v_mul_f32_e32 v160, 0x4b800000, v159
	s_nop 0
	v_cndmask_b32_e32 v159, v159, v160, vcc
	v_rsq_f32_e32 v159, v159
	s_nop 0
	v_mul_f32_e32 v160, 0x45800000, v159
	v_cndmask_b32_e32 v170, v159, v160, vcc
	v_and_b32_e32 v159, 0xfdf, v158
	v_pk_mul_f32 v[178:179], v[46:47], v[170:171] op_sel_hi:[1,0]
	v_pk_mul_f32 v[180:181], v[44:45], v[170:171] op_sel_hi:[1,0]
	v_pk_mul_f32 v[172:173], v[42:43], v[170:171] op_sel_hi:[1,0]
	v_pk_mul_f32 v[174:175], v[40:41], v[170:171] op_sel_hi:[1,0]
	s_and_b64 vcc, exec, s[42:43]
	v_lshlrev_b32_e32 v176, 1, v159
	s_cbranch_vccnz .LBB0_564
	v_lshlrev_b64 v[162:163], 20, v[152:153]
	v_lshl_add_u64 v[162:163], v[144:145], 0, v[162:163]
	v_mov_b32_e32 v177, v161
	v_lshl_add_u64 v[162:163], v[162:163], 0, v[176:177]
	v_add_co_u32_e32 v164, vcc, s68, v162
	v_cvt_pk_bf16_f32 v159, v180, v181
	s_nop 0
	v_addc_co_u32_e32 v165, vcc, 0, v163, vcc
	global_store_short_d16_hi v[164:165], v159, off
	v_add_co_u32_e32 v164, vcc, s69, v162
	v_cvt_pk_bf16_f32 v160, v178, v179
	s_nop 0
	v_addc_co_u32_e32 v165, vcc, 0, v163, vcc
	global_store_short v[164:165], v160, off sc1
	v_add_co_u32_e32 v164, vcc, s70, v162
	v_cvt_pk_bf16_f32 v171, v174, v175
	s_nop 0
	v_addc_co_u32_e32 v165, vcc, 0, v163, vcc
	global_store_short_d16_hi v[164:165], v160, off
	v_add_co_u32_e32 v164, vcc, s71, v162
	global_store_short v[162:163], v159, off sc1
	s_nop 0
	v_addc_co_u32_e32 v165, vcc, 0, v163, vcc
	global_store_short v[164:165], v171, off sc1
	v_add_co_u32_e32 v164, vcc, 0xa000, v162
	v_cvt_pk_bf16_f32 v177, v172, v173
	s_nop 0
	v_addc_co_u32_e32 v165, vcc, 0, v163, vcc
	global_store_short_d16_hi v[164:165], v171, off
	v_add_co_u32_e32 v164, vcc, 0xc000, v162
	s_mov_b64 s[8:9], 0
	s_nop 0
	v_addc_co_u32_e32 v165, vcc, 0, v163, vcc
	v_add_co_u32_e32 v162, vcc, 0xe000, v162
	global_store_short v[164:165], v177, off sc1
	s_nop 0
	v_addc_co_u32_e32 v163, vcc, 0, v163, vcc
	global_store_short_d16_hi v[162:163], v177, off

.LBB0_569:
	v_lshl_add_u64 v[162:163], s[30:31], 0, v[158:159]
	v_lshl_add_u64 v[162:163], s[4:5], 1, v[162:163]
	s_lshl_b32 s8, s91, 1
	s_mov_b32 s9, s5
	v_lshl_add_u64 v[162:163], v[162:163], 0, s[8:9]
	v_lshlrev_b32_e32 v160, 1, v136
	v_cvt_pk_bf16_f32 v180, v180, v181
	v_cvt_pk_bf16_f32 v181, v178, v179
	s_waitcnt lgkmcnt(2)
	v_cvt_pk_bf16_f32 v182, v174, v175
	s_waitcnt lgkmcnt(0)
	v_cvt_pk_bf16_f32 v183, v172, v173
	v_lshl_add_u64 v[162:163], v[162:163], 0, v[160:161]
	global_store_dwordx4 v[162:163], v[180:183], off sc1
.LBB0_570:
	v_mov_b32_e32 v171, v170
	v_mov_b32_e32 v162, v170
	v_mov_b32_e32 v163, v170
	v_pk_mul_f32 v[174:175], v[38:39], v[162:163]
	v_pk_mul_f32 v[178:179], v[36:37], v[170:171]
	v_pk_mul_f32 v[172:173], v[34:35], v[162:163]
	v_pk_mul_f32 v[170:171], v[32:33], v[170:171]
	s_and_b64 vcc, exec, s[42:43]
	s_mov_b64 s[8:9], -1
	s_cbranch_vccnz .LBB0_572
	v_lshlrev_b64 v[162:163], 20, v[154:155]
	v_lshl_add_u64 v[162:163], v[144:145], 0, v[162:163]
	v_mov_b32_e32 v177, v161
	v_lshl_add_u64 v[162:163], v[162:163], 0, v[176:177]
	v_add_co_u32_e32 v164, vcc, s68, v162
	v_cvt_pk_bf16_f32 v160, v178, v179
	s_nop 0
	v_addc_co_u32_e32 v165, vcc, 0, v163, vcc
	global_store_short_d16_hi v[164:165], v160, off
	v_add_co_u32_e32 v164, vcc, s69, v162
	v_cvt_pk_bf16_f32 v176, v174, v175
	s_nop 0
	v_addc_co_u32_e32 v165, vcc, 0, v163, vcc
	global_store_short v[164:165], v176, off sc1
	v_add_co_u32_e32 v164, vcc, s70, v162
	v_cvt_pk_bf16_f32 v177, v170, v171
	s_nop 0
	v_addc_co_u32_e32 v165, vcc, 0, v163, vcc
	global_store_short_d16_hi v[164:165], v176, off
	v_add_co_u32_e32 v164, vcc, s71, v162
	global_store_short v[162:163], v160, off sc1
	s_nop 0
	v_addc_co_u32_e32 v165, vcc, 0, v163, vcc
	global_store_short v[164:165], v177, off sc1
	v_add_co_u32_e32 v164, vcc, 0xa000, v162
	v_cvt_pk_bf16_f32 v180, v172, v173
	s_nop 0
	v_addc_co_u32_e32 v165, vcc, 0, v163, vcc
	global_store_short_d16_hi v[164:165], v177, off
	v_add_co_u32_e32 v164, vcc, 0xc000, v162
	s_mov_b64 s[8:9], 0
	s_nop 0
	v_addc_co_u32_e32 v165, vcc, 0, v163, vcc
	v_add_co_u32_e32 v162, vcc, 0xe000, v162
	global_store_short v[164:165], v180, off sc1
	s_nop 0
	v_addc_co_u32_e32 v163, vcc, 0, v163, vcc
	global_store_short_d16_hi v[162:163], v180, off

.LBB0_577:
	v_lshl_add_u64 v[156:157], s[30:31], 0, v[158:159]
	v_lshl_add_u64 v[156:157], s[4:5], 1, v[156:157]
	s_lshl_b32 s8, s91, 1
	s_mov_b32 s9, s5
	v_lshl_add_u64 v[156:157], v[156:157], 0, s[8:9]
	v_lshlrev_b32_e32 v160, 1, v136
	s_waitcnt lgkmcnt(2)
	v_cvt_pk_bf16_f32 v176, v178, v179
	s_waitcnt lgkmcnt(0)
	v_cvt_pk_bf16_f32 v177, v174, v175
	v_cvt_pk_bf16_f32 v178, v170, v171
	v_cvt_pk_bf16_f32 v179, v172, v173
	v_lshl_add_u64 v[156:157], v[156:157], 0, v[160:161]
	global_store_dwordx4 v[156:157], v[176:179], off offset:256 sc1
.LBB0_578:
	v_add_u32_e32 v158, 0xa0, v150
	v_ashrrev_i32_e32 v159, 31, v158
	v_lshlrev_b64 v[156:157], 6, v[158:159]
	v_lshl_add_u64 v[162:163], v[142:143], 0, v[156:157]
	global_load_dwordx4 v[170:173], v[162:163], off
	s_mov_b64 s[8:9], -1
	s_waitcnt vmcnt(0)
	v_mov_b32_e32 v162, v171
	v_mov_b32_e32 v163, v172
	v_mov_b32_e32 v171, v173
	v_pk_add_f32 v[162:163], v[162:163], v[170:171]
	s_nop 0
	v_add_f32_e32 v159, v162, v163
	ds_bpermute_b32 v160, v197, v159
	s_waitcnt lgkmcnt(0)
	v_add_f32_e32 v159, v159, v160
	ds_bpermute_b32 v160, v198, v159
	s_waitcnt lgkmcnt(0)
	v_add_f32_e32 v159, v159, v160
	v_fmamk_f32 v159, v159, 0x3a800000, v216
	v_cmp_gt_f32_e32 vcc, s29, v159
	v_mul_f32_e32 v160, 0x4b800000, v159
	s_nop 0
	v_cndmask_b32_e32 v159, v159, v160, vcc
	v_rsq_f32_e32 v159, v159
	s_nop 0
	v_mul_f32_e32 v160, 0x45800000, v159
	v_cndmask_b32_e32 v170, v159, v160, vcc
	v_and_b32_e32 v159, 0xfef, v158
	v_pk_mul_f32 v[178:179], v[30:31], v[170:171] op_sel_hi:[1,0]
	v_pk_mul_f32 v[180:181], v[28:29], v[170:171] op_sel_hi:[1,0]
	v_pk_mul_f32 v[172:173], v[26:27], v[170:171] op_sel_hi:[1,0]
	v_pk_mul_f32 v[174:175], v[24:25], v[170:171] op_sel_hi:[1,0]
	s_and_b64 vcc, exec, s[42:43]
	v_lshlrev_b32_e32 v176, 1, v159
	s_cbranch_vccnz .LBB0_580
	v_lshlrev_b64 v[162:163], 20, v[152:153]
	v_lshl_add_u64 v[162:163], v[144:145], 0, v[162:163]
	v_mov_b32_e32 v177, v161
	v_lshl_add_u64 v[162:163], v[162:163], 0, v[176:177]
	v_add_co_u32_e32 v164, vcc, s68, v162
	v_cvt_pk_bf16_f32 v159, v180, v181
	s_nop 0
	v_addc_co_u32_e32 v165, vcc, 0, v163, vcc
	global_store_short_d16_hi v[164:165], v159, off
	v_add_co_u32_e32 v164, vcc, s69, v162
	v_cvt_pk_bf16_f32 v160, v178, v179
	s_nop 0
	v_addc_co_u32_e32 v165, vcc, 0, v163, vcc
	global_store_short v[164:165], v160, off sc1
	v_add_co_u32_e32 v164, vcc, s70, v162
	v_cvt_pk_bf16_f32 v171, v174, v175
	s_nop 0
	v_addc_co_u32_e32 v165, vcc, 0, v163, vcc
	global_store_short_d16_hi v[164:165], v160, off
	v_add_co_u32_e32 v164, vcc, s71, v162
	global_store_short v[162:163], v159, off sc1
	s_nop 0
	v_addc_co_u32_e32 v165, vcc, 0, v163, vcc
	global_store_short v[164:165], v171, off sc1
	v_add_co_u32_e32 v164, vcc, 0xa000, v162
	v_cvt_pk_bf16_f32 v177, v172, v173
	s_nop 0
	v_addc_co_u32_e32 v165, vcc, 0, v163, vcc
	global_store_short_d16_hi v[164:165], v171, off
	v_add_co_u32_e32 v164, vcc, 0xc000, v162
	s_mov_b64 s[8:9], 0
	s_nop 0
	v_addc_co_u32_e32 v165, vcc, 0, v163, vcc
	v_add_co_u32_e32 v162, vcc, 0xe000, v162
	global_store_short v[164:165], v177, off sc1
	s_nop 0
	v_addc_co_u32_e32 v163, vcc, 0, v163, vcc
	global_store_short_d16_hi v[162:163], v177, off

.LBB0_586:
	v_mov_b32_e32 v171, v170
	v_mov_b32_e32 v162, v170
	v_mov_b32_e32 v163, v170
	v_pk_mul_f32 v[174:175], v[22:23], v[162:163]
	v_pk_mul_f32 v[178:179], v[20:21], v[170:171]
	v_pk_mul_f32 v[172:173], v[18:19], v[162:163]
	v_pk_mul_f32 v[170:171], v[16:17], v[170:171]
	s_and_b64 vcc, exec, s[42:43]
	s_mov_b64 s[8:9], -1
	s_cbranch_vccnz .LBB0_588
	v_lshlrev_b64 v[162:163], 20, v[154:155]
	v_lshl_add_u64 v[162:163], v[144:145], 0, v[162:163]
	v_mov_b32_e32 v177, v161
	v_lshl_add_u64 v[162:163], v[162:163], 0, v[176:177]
	v_add_co_u32_e32 v164, vcc, s68, v162
	v_cvt_pk_bf16_f32 v160, v178, v179
	s_nop 0
	v_addc_co_u32_e32 v165, vcc, 0, v163, vcc
	global_store_short_d16_hi v[164:165], v160, off
	v_add_co_u32_e32 v164, vcc, s69, v162
	v_cvt_pk_bf16_f32 v176, v174, v175
	s_nop 0
	v_addc_co_u32_e32 v165, vcc, 0, v163, vcc
	global_store_short v[164:165], v176, off sc1
	v_add_co_u32_e32 v164, vcc, s70, v162
	v_cvt_pk_bf16_f32 v177, v170, v171
	s_nop 0
	v_addc_co_u32_e32 v165, vcc, 0, v163, vcc
	global_store_short_d16_hi v[164:165], v176, off
	v_add_co_u32_e32 v164, vcc, s71, v162
	global_store_short v[162:163], v160, off sc1
	s_nop 0
	v_addc_co_u32_e32 v165, vcc, 0, v163, vcc
	global_store_short v[164:165], v177, off sc1
	v_add_co_u32_e32 v164, vcc, 0xa000, v162
	v_cvt_pk_bf16_f32 v180, v172, v173
	s_nop 0
	v_addc_co_u32_e32 v165, vcc, 0, v163, vcc
	global_store_short_d16_hi v[164:165], v177, off
	v_add_co_u32_e32 v164, vcc, 0xc000, v162
	s_mov_b64 s[8:9], 0
	s_nop 0
	v_addc_co_u32_e32 v165, vcc, 0, v163, vcc
	v_add_co_u32_e32 v162, vcc, 0xe000, v162
	global_store_short v[164:165], v180, off sc1
	s_nop 0
	v_addc_co_u32_e32 v163, vcc, 0, v163, vcc
	global_store_short_d16_hi v[162:163], v180, off

.LBB0_594:
	v_add_u32_e32 v180, 0xb0, v150
	v_ashrrev_i32_e32 v181, 31, v180
	v_lshlrev_b64 v[156:157], 6, v[180:181]
	v_lshl_add_u64 v[158:159], v[142:143], 0, v[156:157]
	global_load_dwordx4 v[170:173], v[158:159], off
	s_mov_b64 s[8:9], -1
	s_waitcnt vmcnt(0)
	v_mov_b32_e32 v158, v171
	v_mov_b32_e32 v159, v172
	v_mov_b32_e32 v171, v173
	v_pk_add_f32 v[158:159], v[158:159], v[170:171]
	s_nop 0
	v_add_f32_e32 v158, v158, v159
	ds_bpermute_b32 v159, v197, v158
	s_waitcnt lgkmcnt(0)
	v_add_f32_e32 v158, v158, v159
	ds_bpermute_b32 v159, v198, v158
	s_waitcnt lgkmcnt(0)
	v_add_f32_e32 v158, v158, v159
	v_fmamk_f32 v158, v158, 0x3a800000, v216
	v_cmp_gt_f32_e32 vcc, s29, v158
	v_mul_f32_e32 v159, 0x4b800000, v158
	s_nop 0
	v_cndmask_b32_e32 v158, v158, v159, vcc
	v_rsq_f32_e32 v158, v158
	s_nop 0
	v_mul_f32_e32 v159, 0x45800000, v158
	v_cndmask_b32_e32 v158, v158, v159, vcc
	v_and_b32_e32 v159, 0xfff, v180
	v_pk_mul_f32 v[176:177], v[14:15], v[158:159] op_sel_hi:[1,0]
	v_pk_mul_f32 v[178:179], v[12:13], v[158:159] op_sel_hi:[1,0]
	v_pk_mul_f32 v[170:171], v[10:11], v[158:159] op_sel_hi:[1,0]
	v_pk_mul_f32 v[172:173], v[8:9], v[158:159] op_sel_hi:[1,0]
	s_and_b64 vcc, exec, s[42:43]
	v_lshlrev_b32_e32 v174, 1, v159
	s_cbranch_vccnz .LBB0_596
	v_lshlrev_b64 v[152:153], 20, v[152:153]
	v_lshl_add_u64 v[152:153], v[144:145], 0, v[152:153]
	v_mov_b32_e32 v175, v161
	v_lshl_add_u64 v[152:153], v[152:153], 0, v[174:175]
	v_add_co_u32_e32 v162, vcc, s68, v152
	v_cvt_pk_bf16_f32 v159, v178, v179
	s_nop 0
	v_addc_co_u32_e32 v163, vcc, 0, v153, vcc
	global_store_short_d16_hi v[162:163], v159, off
	v_add_co_u32_e32 v162, vcc, s69, v152
	v_cvt_pk_bf16_f32 v160, v176, v177
	s_nop 0
	v_addc_co_u32_e32 v163, vcc, 0, v153, vcc
	global_store_short v[162:163], v160, off sc1
	v_add_co_u32_e32 v162, vcc, s70, v152
	v_cvt_pk_bf16_f32 v164, v172, v173
	s_nop 0
	v_addc_co_u32_e32 v163, vcc, 0, v153, vcc
	global_store_short_d16_hi v[162:163], v160, off
	v_add_co_u32_e32 v162, vcc, s71, v152
	global_store_short v[152:153], v159, off sc1
	s_nop 0
	v_addc_co_u32_e32 v163, vcc, 0, v153, vcc
	global_store_short v[162:163], v164, off sc1
	v_add_co_u32_e32 v162, vcc, 0xa000, v152
	v_cvt_pk_bf16_f32 v165, v170, v171
	s_nop 0
	v_addc_co_u32_e32 v163, vcc, 0, v153, vcc
	global_store_short_d16_hi v[162:163], v164, off
	v_add_co_u32_e32 v162, vcc, 0xc000, v152
	s_mov_b64 s[8:9], 0
	s_nop 0
	v_addc_co_u32_e32 v163, vcc, 0, v153, vcc
	v_add_co_u32_e32 v152, vcc, 0xe000, v152
	global_store_short v[162:163], v165, off sc1
	s_nop 0
	v_addc_co_u32_e32 v153, vcc, 0, v153, vcc
	global_store_short_d16_hi v[152:153], v165, off

.LBB0_601:
	v_lshl_add_u64 v[162:163], s[30:31], 0, v[152:153]
	v_lshl_add_u64 v[162:163], s[4:5], 1, v[162:163]
	s_lshl_b32 s8, s91, 1
	s_mov_b32 s9, s5
	v_lshl_add_u64 v[162:163], v[162:163], 0, s[8:9]
	v_lshlrev_b32_e32 v160, 1, v136
	v_cvt_pk_bf16_f32 v178, v178, v179
	v_cvt_pk_bf16_f32 v179, v176, v177
	s_waitcnt lgkmcnt(2)
	v_cvt_pk_bf16_f32 v180, v172, v173
	s_waitcnt lgkmcnt(0)
	v_cvt_pk_bf16_f32 v181, v170, v171
	v_lshl_add_u64 v[162:163], v[162:163], 0, v[160:161]
	global_store_dwordx4 v[162:163], v[178:181], off sc1
.LBB0_602:
	v_mov_b32_e32 v159, v158
	v_mov_b32_e32 v162, v158
	v_mov_b32_e32 v163, v158
	v_pk_mul_f32 v[172:173], v[6:7], v[162:163]
	v_pk_mul_f32 v[176:177], v[4:5], v[158:159]
	v_pk_mul_f32 v[170:171], v[2:3], v[162:163]
	v_pk_mul_f32 v[158:159], v[0:1], v[158:159]
	s_and_b64 vcc, exec, s[42:43]
	s_mov_b64 s[8:9], -1
	s_cbranch_vccnz .LBB0_604
	v_lshlrev_b64 v[154:155], 20, v[154:155]
	v_lshl_add_u64 v[154:155], v[144:145], 0, v[154:155]
	v_mov_b32_e32 v175, v161
	v_lshl_add_u64 v[154:155], v[154:155], 0, v[174:175]
	v_add_co_u32_e32 v162, vcc, s68, v154
	v_cvt_pk_bf16_f32 v160, v176, v177
	s_nop 0
	v_addc_co_u32_e32 v163, vcc, 0, v155, vcc
	global_store_short_d16_hi v[162:163], v160, off
	v_add_co_u32_e32 v162, vcc, s69, v154
	v_cvt_pk_bf16_f32 v164, v172, v173
	s_nop 0
	v_addc_co_u32_e32 v163, vcc, 0, v155, vcc
	global_store_short v[162:163], v164, off sc1
	v_add_co_u32_e32 v162, vcc, s70, v154
	v_cvt_pk_bf16_f32 v165, v158, v159
	s_nop 0
	v_addc_co_u32_e32 v163, vcc, 0, v155, vcc
	global_store_short_d16_hi v[162:163], v164, off
	v_add_co_u32_e32 v162, vcc, s71, v154
	global_store_short v[154:155], v160, off sc1
	s_nop 0
	v_addc_co_u32_e32 v163, vcc, 0, v155, vcc
	global_store_short v[162:163], v165, off sc1
	v_add_co_u32_e32 v162, vcc, 0xa000, v154
	v_cvt_pk_bf16_f32 v174, v170, v171
	s_nop 0
	v_addc_co_u32_e32 v163, vcc, 0, v155, vcc
	global_store_short_d16_hi v[162:163], v165, off
	v_add_co_u32_e32 v162, vcc, 0xc000, v154
	s_mov_b64 s[8:9], 0
	s_nop 0
	v_addc_co_u32_e32 v163, vcc, 0, v155, vcc
	v_add_co_u32_e32 v154, vcc, 0xe000, v154
	global_store_short v[162:163], v174, off sc1
	s_nop 0
	v_addc_co_u32_e32 v155, vcc, 0, v155, vcc
	global_store_short_d16_hi v[154:155], v174, off

.LBB0_609:
	v_lshl_add_u64 v[152:153], s[30:31], 0, v[152:153]
	v_lshl_add_u64 v[152:153], s[4:5], 1, v[152:153]
	s_lshl_b32 s4, s91, 1
	v_lshl_add_u64 v[152:153], v[152:153], 0, s[4:5]
	v_lshlrev_b32_e32 v160, 1, v136
	s_waitcnt lgkmcnt(2)
	v_cvt_pk_bf16_f32 v154, v176, v177
	s_waitcnt lgkmcnt(0)
	v_cvt_pk_bf16_f32 v155, v172, v173
	v_cvt_pk_bf16_f32 v156, v158, v159
	v_cvt_pk_bf16_f32 v157, v170, v171
	v_lshl_add_u64 v[152:153], v[152:153], 0, v[160:161]
	global_store_dwordx4 v[152:153], v[154:157], off offset:256 sc1

.LBB0_612:
	s_and_b64 vcc, exec, s[8:9]
	s_cbranch_vccz .LBB0_611
	v_lshlrev_b64 v[154:155], 6, v[150:151]
	v_lshl_add_u64 v[154:155], v[142:143], 0, v[154:155]
	v_add_co_u32_e32 v156, vcc, 0x2000, v154
	s_nop 1
	v_addc_co_u32_e32 v157, vcc, 0, v155, vcc
	global_load_dwordx4 v[170:173], v[154:155], off
	global_load_dwordx4 v[174:177], v[154:155], off offset:1024
	global_load_dwordx4 v[178:181], v[154:155], off offset:2048
	global_load_dwordx4 v[182:185], v[154:155], off offset:3072
	global_load_dwordx4 v[186:189], v[156:157], off
	global_load_dwordx4 v[200:203], v[156:157], off offset:1024
	global_load_dwordx4 v[204:207], v[156:157], off offset:2048
	global_load_dwordx4 v[208:211], v[156:157], off offset:3072
	v_or_b32_e32 v152, s91, v136
	v_lshl_or_b32 v152, s14, 7, v152
	v_ashrrev_i32_e32 v153, 31, v152
	s_waitcnt vmcnt(0)
	v_add_f32_e32 v170, v171, v170
	v_add_f32_e32 v172, v172, v173
	v_add_f32_e32 v174, v175, v174
	v_add_f32_e32 v176, v176, v177
	v_add_f32_e32 v178, v179, v178
	v_add_f32_e32 v180, v180, v181
	v_add_f32_e32 v182, v183, v182
	v_add_f32_e32 v184, v184, v185
	v_add_f32_e32 v186, v187, v186
	v_add_f32_e32 v188, v188, v189
	v_add_f32_e32 v200, v201, v200
	v_add_f32_e32 v202, v202, v203
	v_add_f32_e32 v204, v205, v204
	v_add_f32_e32 v206, v206, v207
	v_add_f32_e32 v208, v209, v208
	v_add_f32_e32 v210, v210, v211
	v_add_f32_e32 v170, v170, v172
	v_add_f32_e32 v174, v174, v176
	v_add_f32_e32 v178, v178, v180
	v_add_f32_e32 v182, v182, v184
	v_add_f32_e32 v186, v186, v188
	v_add_f32_e32 v200, v200, v202
	v_add_f32_e32 v204, v204, v206
	v_add_f32_e32 v208, v208, v210
	ds_bpermute_b32 v171, v197, v170
	ds_bpermute_b32 v175, v197, v174
	ds_bpermute_b32 v179, v197, v178
	ds_bpermute_b32 v183, v197, v182
	ds_bpermute_b32 v187, v197, v186
	ds_bpermute_b32 v201, v197, v200
	ds_bpermute_b32 v205, v197, v204
	ds_bpermute_b32 v209, v197, v208
	s_waitcnt lgkmcnt(0)
	v_add_f32_e32 v170, v170, v171
	v_add_f32_e32 v174, v174, v175
	v_add_f32_e32 v178, v178, v179
	v_add_f32_e32 v182, v182, v183
	v_add_f32_e32 v186, v186, v187
	v_add_f32_e32 v200, v200, v201
	v_add_f32_e32 v204, v204, v205
	v_add_f32_e32 v208, v208, v209
	ds_bpermute_b32 v171, v198, v170
	ds_bpermute_b32 v175, v198, v174
	ds_bpermute_b32 v179, v198, v178
	ds_bpermute_b32 v183, v198, v182
	ds_bpermute_b32 v187, v198, v186
	ds_bpermute_b32 v201, v198, v200
	ds_bpermute_b32 v205, v198, v204
	ds_bpermute_b32 v209, v198, v208
	s_waitcnt lgkmcnt(0)
	v_add_f32_e32 v170, v170, v171
	v_add_f32_e32 v174, v174, v175
	v_add_f32_e32 v178, v178, v179
	v_add_f32_e32 v182, v182, v183
	v_add_f32_e32 v186, v186, v187
	v_add_f32_e32 v200, v200, v201
	v_add_f32_e32 v204, v204, v205
	v_add_f32_e32 v208, v208, v209
	v_fmamk_f32 v170, v170, 0x3a800000, v216
	v_fmamk_f32 v174, v174, 0x3a800000, v216
	v_fmamk_f32 v178, v178, 0x3a800000, v216
	v_fmamk_f32 v182, v182, 0x3a800000, v216
	v_fmamk_f32 v186, v186, 0x3a800000, v216
	v_fmamk_f32 v200, v200, 0x3a800000, v216
	v_fmamk_f32 v204, v204, 0x3a800000, v216
	v_fmamk_f32 v208, v208, 0x3a800000, v216
	v_cmp_gt_f32_e32 vcc, s29, v170
	v_mul_f32_e32 v171, 0x4b800000, v170
	s_nop 0
	v_cndmask_b32_e32 v170, v170, v171, vcc
	v_rsq_f32_e32 v170, v170
	s_nop 0
	v_mul_f32_e32 v171, 0x45800000, v170
	v_cndmask_b32_e32 v170, v170, v171, vcc
	v_cmp_gt_f32_e32 vcc, s29, v174
	v_mul_f32_e32 v175, 0x4b800000, v174
	s_nop 0
	v_cndmask_b32_e32 v174, v174, v175, vcc
	v_rsq_f32_e32 v174, v174
	s_nop 0
	v_mul_f32_e32 v175, 0x45800000, v174
	v_cndmask_b32_e32 v174, v174, v175, vcc
	v_cmp_gt_f32_e32 vcc, s29, v178
	v_mul_f32_e32 v179, 0x4b800000, v178
	s_nop 0
	v_cndmask_b32_e32 v178, v178, v179, vcc
	v_rsq_f32_e32 v178, v178
	s_nop 0
	v_mul_f32_e32 v179, 0x45800000, v178
	v_cndmask_b32_e32 v178, v178, v179, vcc
	v_cmp_gt_f32_e32 vcc, s29, v182
	v_mul_f32_e32 v183, 0x4b800000, v182
	s_nop 0
	v_cndmask_b32_e32 v182, v182, v183, vcc
	v_rsq_f32_e32 v182, v182
	s_nop 0
	v_mul_f32_e32 v183, 0x45800000, v182
	v_cndmask_b32_e32 v182, v182, v183, vcc
	v_cmp_gt_f32_e32 vcc, s29, v186
	v_mul_f32_e32 v187, 0x4b800000, v186
	s_nop 0
	v_cndmask_b32_e32 v186, v186, v187, vcc
	v_rsq_f32_e32 v186, v186
	s_nop 0
	v_mul_f32_e32 v187, 0x45800000, v186
	v_cndmask_b32_e32 v186, v186, v187, vcc
	v_cmp_gt_f32_e32 vcc, s29, v200
	v_mul_f32_e32 v201, 0x4b800000, v200
	s_nop 0
	v_cndmask_b32_e32 v200, v200, v201, vcc
	v_rsq_f32_e32 v200, v200
	s_nop 0
	v_mul_f32_e32 v201, 0x45800000, v200
	v_cndmask_b32_e32 v200, v200, v201, vcc
	v_cmp_gt_f32_e32 vcc, s29, v204
	v_mul_f32_e32 v205, 0x4b800000, v204
	s_nop 0
	v_cndmask_b32_e32 v204, v204, v205, vcc
	v_rsq_f32_e32 v204, v204
	s_nop 0
	v_mul_f32_e32 v205, 0x45800000, v204
	v_cndmask_b32_e32 v204, v204, v205, vcc
	v_cmp_gt_f32_e32 vcc, s29, v208
	v_mul_f32_e32 v209, 0x4b800000, v208
	s_nop 0
	v_cndmask_b32_e32 v208, v208, v209, vcc
	v_rsq_f32_e32 v208, v208
	s_nop 0
	v_mul_f32_e32 v209, 0x45800000, v208
	v_cndmask_b32_e32 v208, v208, v209, vcc
	v_mov_b32_e32 v154, v170
	v_pk_mul_f32 v[124:125], v[124:125], v[154:155] op_sel_hi:[1,0]
	v_pk_mul_f32 v[116:117], v[116:117], v[154:155] op_sel_hi:[1,0]
	v_mul_f32_e32 v151, 0xbfb8aa3b, v124
	v_pk_mul_f32 v[116:117], v[124:125], v[116:117]
	v_mul_f32_e32 v124, 0xbfb8aa3b, v125
	v_exp_f32_e32 v124, v124
	v_pk_mul_f32 v[118:119], v[118:119], v[154:155] op_sel_hi:[1,0]
	v_pk_mul_f32 v[120:121], v[120:121], v[154:155] op_sel_hi:[1,0]
	v_pk_mul_f32 v[112:113], v[112:113], v[154:155] op_sel_hi:[1,0]
	v_add_f32_e32 v124, 1.0, v124
	v_rcp_f32_e32 v157, v124
	v_pk_mul_f32 v[124:125], v[126:127], v[154:155] op_sel_hi:[1,0]
	v_pk_mul_f32 v[112:113], v[120:121], v[112:113]
	v_mul_f32_e32 v126, 0xbfb8aa3b, v124
	v_pk_mul_f32 v[118:119], v[124:125], v[118:119]
	v_mul_f32_e32 v124, 0xbfb8aa3b, v125
	v_exp_f32_e32 v124, v124
	v_exp_f32_e32 v126, v126
	v_pk_mul_f32 v[114:115], v[114:115], v[154:155] op_sel_hi:[1,0]
	v_exp_f32_e32 v151, v151
	v_add_f32_e32 v124, 1.0, v124
	v_rcp_f32_e32 v127, v124
	v_mul_f32_e32 v124, 0xbfb8aa3b, v120
	v_mul_f32_e32 v120, 0xbfb8aa3b, v121
	v_exp_f32_e32 v124, v124
	v_exp_f32_e32 v120, v120
	v_add_f32_e32 v126, 1.0, v126
	v_add_f32_e32 v151, 1.0, v151
	v_add_f32_e32 v124, 1.0, v124
	v_add_f32_e32 v120, 1.0, v120
	v_rcp_f32_e32 v124, v124
	v_rcp_f32_e32 v125, v120
	v_rcp_f32_e32 v126, v126
	v_rcp_f32_e32 v156, v151
	v_pk_mul_f32 v[120:121], v[112:113], v[124:125]
	v_pk_mul_f32 v[112:113], v[122:123], v[154:155] op_sel_hi:[1,0]
	v_pk_mul_f32 v[118:119], v[118:119], v[126:127]
	v_mul_f32_e32 v122, 0xbfb8aa3b, v112
	v_pk_mul_f32 v[114:115], v[112:113], v[114:115]
	v_mul_f32_e32 v112, 0xbfb8aa3b, v113
	v_exp_f32_e32 v122, v122
	v_exp_f32_e32 v112, v112
	v_pk_mul_f32 v[116:117], v[116:117], v[156:157]
	v_cvt_pk_bf16_f32 v113, v118, v119
	v_add_f32_e32 v122, 1.0, v122
	v_add_f32_e32 v112, 1.0, v112
	v_rcp_f32_e32 v122, v122
	v_rcp_f32_e32 v123, v112
	v_mov_b64_e32 v[118:119], s[64:65]
	v_cvt_pk_bf16_f32 v112, v116, v117
	v_lshlrev_b64 v[116:117], 1, v[152:153]
	v_pk_mul_f32 v[122:123], v[114:115], v[122:123]
	v_cvt_pk_bf16_f32 v114, v120, v121
	v_mad_i64_i32 v[120:121], s[8:9], v150, s72, v[118:119]
	v_cvt_pk_bf16_f32 v115, v122, v123
	v_lshl_add_u64 v[120:121], v[120:121], 0, v[116:117]
	global_store_dwordx4 v[120:121], v[112:115], off sc1
	s_nop 1
	v_or_b32_e32 v112, 16, v150
	v_mov_b32_e32 v114, v174
	v_pk_mul_f32 v[108:109], v[108:109], v[114:115] op_sel_hi:[1,0]
	v_pk_mul_f32 v[100:101], v[100:101], v[114:115] op_sel_hi:[1,0]
	v_mul_f32_e32 v113, 0xbfb8aa3b, v108
	v_pk_mul_f32 v[100:101], v[108:109], v[100:101]
	v_mul_f32_e32 v108, 0xbfb8aa3b, v109
	v_exp_f32_e32 v108, v108
	v_pk_mul_f32 v[102:103], v[102:103], v[114:115] op_sel_hi:[1,0]
	v_pk_mul_f32 v[104:105], v[104:105], v[114:115] op_sel_hi:[1,0]
	v_pk_mul_f32 v[96:97], v[96:97], v[114:115] op_sel_hi:[1,0]
	v_add_f32_e32 v108, 1.0, v108
	v_rcp_f32_e32 v121, v108
	v_pk_mul_f32 v[108:109], v[110:111], v[114:115] op_sel_hi:[1,0]
	v_pk_mul_f32 v[96:97], v[104:105], v[96:97]
	v_mul_f32_e32 v110, 0xbfb8aa3b, v108
	v_pk_mul_f32 v[102:103], v[108:109], v[102:103]
	v_mul_f32_e32 v108, 0xbfb8aa3b, v109
	v_exp_f32_e32 v108, v108
	v_pk_mul_f32 v[98:99], v[98:99], v[114:115] op_sel_hi:[1,0]
	v_exp_f32_e32 v113, v113
	v_exp_f32_e32 v110, v110
	v_add_f32_e32 v108, 1.0, v108
	v_rcp_f32_e32 v111, v108
	v_mul_f32_e32 v108, 0xbfb8aa3b, v104
	v_mul_f32_e32 v104, 0xbfb8aa3b, v105
	v_exp_f32_e32 v108, v108
	v_exp_f32_e32 v104, v104
	v_add_f32_e32 v113, 1.0, v113
	v_rcp_f32_e32 v120, v113
	v_add_f32_e32 v108, 1.0, v108
	v_add_f32_e32 v104, 1.0, v104
	v_rcp_f32_e32 v108, v108
	v_rcp_f32_e32 v109, v104
	v_add_f32_e32 v110, 1.0, v110
	v_rcp_f32_e32 v110, v110
	v_pk_mul_f32 v[100:101], v[100:101], v[120:121]
	v_pk_mul_f32 v[104:105], v[96:97], v[108:109]
	v_pk_mul_f32 v[96:97], v[106:107], v[114:115] op_sel_hi:[1,0]
	v_pk_mul_f32 v[102:103], v[102:103], v[110:111]
	v_mul_f32_e32 v106, 0xbfb8aa3b, v96
	v_pk_mul_f32 v[98:99], v[96:97], v[98:99]
	v_mul_f32_e32 v96, 0xbfb8aa3b, v97
	v_exp_f32_e32 v106, v106
	v_exp_f32_e32 v96, v96
	v_cvt_pk_bf16_f32 v97, v102, v103
	v_add_f32_e32 v106, 1.0, v106
	v_add_f32_e32 v96, 1.0, v96
	v_rcp_f32_e32 v106, v106
	v_rcp_f32_e32 v107, v96
	v_cvt_pk_bf16_f32 v96, v100, v101
	v_mad_i64_i32 v[100:101], s[8:9], v112, s72, v[118:119]
	v_pk_mul_f32 v[106:107], v[98:99], v[106:107]
	v_cvt_pk_bf16_f32 v98, v104, v105
	v_cvt_pk_bf16_f32 v99, v106, v107
	v_lshl_add_u64 v[100:101], v[100:101], 0, v[116:117]
	global_store_dwordx4 v[100:101], v[96:99], off sc1
	s_nop 1
	v_or_b32_e32 v96, 32, v150
	v_mov_b32_e32 v98, v178
	v_pk_mul_f32 v[92:93], v[92:93], v[98:99] op_sel_hi:[1,0]
	v_pk_mul_f32 v[84:85], v[84:85], v[98:99] op_sel_hi:[1,0]
	v_mul_f32_e32 v97, 0xbfb8aa3b, v92
	v_pk_mul_f32 v[84:85], v[92:93], v[84:85]
	v_mul_f32_e32 v92, 0xbfb8aa3b, v93
	v_exp_f32_e32 v92, v92
	v_pk_mul_f32 v[86:87], v[86:87], v[98:99] op_sel_hi:[1,0]
	v_pk_mul_f32 v[88:89], v[88:89], v[98:99] op_sel_hi:[1,0]
	v_pk_mul_f32 v[80:81], v[80:81], v[98:99] op_sel_hi:[1,0]
	v_add_f32_e32 v92, 1.0, v92
	v_rcp_f32_e32 v101, v92
	v_pk_mul_f32 v[92:93], v[94:95], v[98:99] op_sel_hi:[1,0]
	v_pk_mul_f32 v[80:81], v[88:89], v[80:81]
	v_mul_f32_e32 v94, 0xbfb8aa3b, v92
	v_pk_mul_f32 v[86:87], v[92:93], v[86:87]
	v_mul_f32_e32 v92, 0xbfb8aa3b, v93
	v_exp_f32_e32 v92, v92
	v_pk_mul_f32 v[82:83], v[82:83], v[98:99] op_sel_hi:[1,0]
	v_exp_f32_e32 v97, v97
	v_exp_f32_e32 v94, v94
	v_add_f32_e32 v92, 1.0, v92
	v_rcp_f32_e32 v95, v92
	v_mul_f32_e32 v92, 0xbfb8aa3b, v88
	v_mul_f32_e32 v88, 0xbfb8aa3b, v89
	v_exp_f32_e32 v92, v92
	v_exp_f32_e32 v88, v88
	v_add_f32_e32 v97, 1.0, v97
	v_rcp_f32_e32 v100, v97
	v_add_f32_e32 v92, 1.0, v92
	v_add_f32_e32 v88, 1.0, v88
	v_rcp_f32_e32 v92, v92
	v_rcp_f32_e32 v93, v88
	v_add_f32_e32 v94, 1.0, v94
	v_rcp_f32_e32 v94, v94
	v_pk_mul_f32 v[84:85], v[84:85], v[100:101]
	v_pk_mul_f32 v[88:89], v[80:81], v[92:93]
	v_pk_mul_f32 v[80:81], v[90:91], v[98:99] op_sel_hi:[1,0]
	v_pk_mul_f32 v[86:87], v[86:87], v[94:95]
	v_mul_f32_e32 v90, 0xbfb8aa3b, v80
	v_pk_mul_f32 v[82:83], v[80:81], v[82:83]
	v_mul_f32_e32 v80, 0xbfb8aa3b, v81
	v_exp_f32_e32 v90, v90
	v_exp_f32_e32 v80, v80
	v_cvt_pk_bf16_f32 v81, v86, v87
	v_add_f32_e32 v90, 1.0, v90
	v_add_f32_e32 v80, 1.0, v80
	v_rcp_f32_e32 v90, v90
	v_rcp_f32_e32 v91, v80
	v_cvt_pk_bf16_f32 v80, v84, v85
	v_mad_i64_i32 v[84:85], s[8:9], v96, s72, v[118:119]
	v_pk_mul_f32 v[90:91], v[82:83], v[90:91]
	v_cvt_pk_bf16_f32 v82, v88, v89
	v_cvt_pk_bf16_f32 v83, v90, v91
	v_lshl_add_u64 v[84:85], v[84:85], 0, v[116:117]
	global_store_dwordx4 v[84:85], v[80:83], off sc1
	s_nop 1
	v_or_b32_e32 v80, 48, v150
	v_mov_b32_e32 v82, v182
	v_pk_mul_f32 v[76:77], v[76:77], v[82:83] op_sel_hi:[1,0]
	v_pk_mul_f32 v[68:69], v[68:69], v[82:83] op_sel_hi:[1,0]
	v_mul_f32_e32 v81, 0xbfb8aa3b, v76
	v_pk_mul_f32 v[68:69], v[76:77], v[68:69]
	v_mul_f32_e32 v76, 0xbfb8aa3b, v77
	v_exp_f32_e32 v76, v76
	v_pk_mul_f32 v[70:71], v[70:71], v[82:83] op_sel_hi:[1,0]
	v_pk_mul_f32 v[72:73], v[72:73], v[82:83] op_sel_hi:[1,0]
	v_pk_mul_f32 v[64:65], v[64:65], v[82:83] op_sel_hi:[1,0]
	v_add_f32_e32 v76, 1.0, v76
	v_rcp_f32_e32 v85, v76
	v_pk_mul_f32 v[76:77], v[78:79], v[82:83] op_sel_hi:[1,0]
	v_pk_mul_f32 v[64:65], v[72:73], v[64:65]
	v_mul_f32_e32 v78, 0xbfb8aa3b, v76
	v_pk_mul_f32 v[70:71], v[76:77], v[70:71]
	v_mul_f32_e32 v76, 0xbfb8aa3b, v77
	v_exp_f32_e32 v76, v76
	v_pk_mul_f32 v[66:67], v[66:67], v[82:83] op_sel_hi:[1,0]
	v_exp_f32_e32 v81, v81
	v_exp_f32_e32 v78, v78
	v_add_f32_e32 v76, 1.0, v76
	v_rcp_f32_e32 v79, v76
	v_mul_f32_e32 v76, 0xbfb8aa3b, v72
	v_mul_f32_e32 v72, 0xbfb8aa3b, v73
	v_exp_f32_e32 v76, v76
	v_exp_f32_e32 v72, v72
	v_add_f32_e32 v81, 1.0, v81
	v_rcp_f32_e32 v84, v81
	v_add_f32_e32 v76, 1.0, v76
	v_add_f32_e32 v72, 1.0, v72
	v_rcp_f32_e32 v76, v76
	v_rcp_f32_e32 v77, v72
	v_add_f32_e32 v78, 1.0, v78
	v_rcp_f32_e32 v78, v78
	v_pk_mul_f32 v[68:69], v[68:69], v[84:85]
	v_pk_mul_f32 v[72:73], v[64:65], v[76:77]
	v_pk_mul_f32 v[64:65], v[74:75], v[82:83] op_sel_hi:[1,0]
	v_pk_mul_f32 v[70:71], v[70:71], v[78:79]
	v_mul_f32_e32 v74, 0xbfb8aa3b, v64
	v_pk_mul_f32 v[66:67], v[64:65], v[66:67]
	v_mul_f32_e32 v64, 0xbfb8aa3b, v65
	v_exp_f32_e32 v74, v74
	v_exp_f32_e32 v64, v64
	v_cvt_pk_bf16_f32 v65, v70, v71
	v_add_f32_e32 v74, 1.0, v74
	v_add_f32_e32 v64, 1.0, v64
	v_rcp_f32_e32 v74, v74
	v_rcp_f32_e32 v75, v64
	v_cvt_pk_bf16_f32 v64, v68, v69
	v_mad_i64_i32 v[68:69], s[8:9], v80, s72, v[118:119]
	v_pk_mul_f32 v[74:75], v[66:67], v[74:75]
	v_cvt_pk_bf16_f32 v66, v72, v73
	v_cvt_pk_bf16_f32 v67, v74, v75
	v_lshl_add_u64 v[68:69], v[68:69], 0, v[116:117]
	global_store_dwordx4 v[68:69], v[64:67], off sc1
	s_nop 1
	v_add_u32_e32 v64, 0x80, v150
	v_mov_b32_e32 v66, v186
	v_pk_mul_f32 v[60:61], v[60:61], v[66:67] op_sel_hi:[1,0]
	v_pk_mul_f32 v[52:53], v[52:53], v[66:67] op_sel_hi:[1,0]
	v_mul_f32_e32 v65, 0xbfb8aa3b, v60
	v_pk_mul_f32 v[52:53], v[60:61], v[52:53]
	v_mul_f32_e32 v60, 0xbfb8aa3b, v61
	v_exp_f32_e32 v60, v60
	v_pk_mul_f32 v[54:55], v[54:55], v[66:67] op_sel_hi:[1,0]
	v_pk_mul_f32 v[56:57], v[56:57], v[66:67] op_sel_hi:[1,0]
	v_pk_mul_f32 v[48:49], v[48:49], v[66:67] op_sel_hi:[1,0]
	v_add_f32_e32 v60, 1.0, v60
	v_rcp_f32_e32 v69, v60
	v_pk_mul_f32 v[60:61], v[62:63], v[66:67] op_sel_hi:[1,0]
	v_pk_mul_f32 v[48:49], v[56:57], v[48:49]
	v_mul_f32_e32 v62, 0xbfb8aa3b, v60
	v_pk_mul_f32 v[54:55], v[60:61], v[54:55]
	v_mul_f32_e32 v60, 0xbfb8aa3b, v61
	v_exp_f32_e32 v60, v60
	v_pk_mul_f32 v[50:51], v[50:51], v[66:67] op_sel_hi:[1,0]
	v_exp_f32_e32 v65, v65
	v_exp_f32_e32 v62, v62
	v_add_f32_e32 v60, 1.0, v60
	v_rcp_f32_e32 v63, v60
	v_mul_f32_e32 v60, 0xbfb8aa3b, v56
	v_mul_f32_e32 v56, 0xbfb8aa3b, v57
	v_exp_f32_e32 v60, v60
	v_exp_f32_e32 v56, v56
	v_add_f32_e32 v65, 1.0, v65
	v_rcp_f32_e32 v68, v65
	v_add_f32_e32 v60, 1.0, v60
	v_add_f32_e32 v56, 1.0, v56
	v_rcp_f32_e32 v60, v60
	v_rcp_f32_e32 v61, v56
	v_add_f32_e32 v62, 1.0, v62
	v_rcp_f32_e32 v62, v62
	v_pk_mul_f32 v[52:53], v[52:53], v[68:69]
	v_pk_mul_f32 v[56:57], v[48:49], v[60:61]
	v_pk_mul_f32 v[48:49], v[58:59], v[66:67] op_sel_hi:[1,0]
	v_pk_mul_f32 v[54:55], v[54:55], v[62:63]
	v_mul_f32_e32 v58, 0xbfb8aa3b, v48
	v_pk_mul_f32 v[50:51], v[48:49], v[50:51]
	v_mul_f32_e32 v48, 0xbfb8aa3b, v49
	v_exp_f32_e32 v58, v58
	v_exp_f32_e32 v48, v48
	v_cvt_pk_bf16_f32 v49, v54, v55
	v_add_f32_e32 v58, 1.0, v58
	v_add_f32_e32 v48, 1.0, v48
	v_rcp_f32_e32 v58, v58
	v_rcp_f32_e32 v59, v48
	v_cvt_pk_bf16_f32 v48, v52, v53
	v_mad_i64_i32 v[52:53], s[8:9], v64, s72, v[118:119]
	v_pk_mul_f32 v[58:59], v[50:51], v[58:59]
	v_cvt_pk_bf16_f32 v50, v56, v57
	v_cvt_pk_bf16_f32 v51, v58, v59
	v_lshl_add_u64 v[52:53], v[52:53], 0, v[116:117]
	global_store_dwordx4 v[52:53], v[48:51], off sc1
	s_nop 1
	v_add_u32_e32 v48, 0x90, v150
	v_mov_b32_e32 v50, v200
	v_pk_mul_f32 v[44:45], v[44:45], v[50:51] op_sel_hi:[1,0]
	v_pk_mul_f32 v[36:37], v[36:37], v[50:51] op_sel_hi:[1,0]
	v_mul_f32_e32 v49, 0xbfb8aa3b, v44
	v_pk_mul_f32 v[36:37], v[44:45], v[36:37]
	v_mul_f32_e32 v44, 0xbfb8aa3b, v45
	v_exp_f32_e32 v44, v44
	v_pk_mul_f32 v[38:39], v[38:39], v[50:51] op_sel_hi:[1,0]
	v_pk_mul_f32 v[40:41], v[40:41], v[50:51] op_sel_hi:[1,0]
	v_pk_mul_f32 v[32:33], v[32:33], v[50:51] op_sel_hi:[1,0]
	v_add_f32_e32 v44, 1.0, v44
	v_rcp_f32_e32 v53, v44
	v_pk_mul_f32 v[44:45], v[46:47], v[50:51] op_sel_hi:[1,0]
	v_pk_mul_f32 v[32:33], v[40:41], v[32:33]
	v_mul_f32_e32 v46, 0xbfb8aa3b, v44
	v_pk_mul_f32 v[38:39], v[44:45], v[38:39]
	v_mul_f32_e32 v44, 0xbfb8aa3b, v45
	v_exp_f32_e32 v44, v44
	v_pk_mul_f32 v[34:35], v[34:35], v[50:51] op_sel_hi:[1,0]
	v_exp_f32_e32 v49, v49
	v_exp_f32_e32 v46, v46
	v_add_f32_e32 v44, 1.0, v44
	v_rcp_f32_e32 v47, v44
	v_mul_f32_e32 v44, 0xbfb8aa3b, v40
	v_mul_f32_e32 v40, 0xbfb8aa3b, v41
	v_exp_f32_e32 v44, v44
	v_exp_f32_e32 v40, v40
	v_add_f32_e32 v49, 1.0, v49
	v_rcp_f32_e32 v52, v49
	v_add_f32_e32 v44, 1.0, v44
	v_add_f32_e32 v40, 1.0, v40
	v_rcp_f32_e32 v44, v44
	v_rcp_f32_e32 v45, v40
	v_add_f32_e32 v46, 1.0, v46
	v_rcp_f32_e32 v46, v46
	v_pk_mul_f32 v[36:37], v[36:37], v[52:53]
	v_pk_mul_f32 v[40:41], v[32:33], v[44:45]
	v_pk_mul_f32 v[32:33], v[42:43], v[50:51] op_sel_hi:[1,0]
	v_pk_mul_f32 v[38:39], v[38:39], v[46:47]
	v_mul_f32_e32 v42, 0xbfb8aa3b, v32
	v_pk_mul_f32 v[34:35], v[32:33], v[34:35]
	v_mul_f32_e32 v32, 0xbfb8aa3b, v33
	v_exp_f32_e32 v42, v42
	v_exp_f32_e32 v32, v32
	v_cvt_pk_bf16_f32 v33, v38, v39
	v_add_f32_e32 v42, 1.0, v42
	v_add_f32_e32 v32, 1.0, v32
	v_rcp_f32_e32 v42, v42
	v_rcp_f32_e32 v43, v32
	v_cvt_pk_bf16_f32 v32, v36, v37
	v_mad_i64_i32 v[36:37], s[8:9], v48, s72, v[118:119]
	v_pk_mul_f32 v[42:43], v[34:35], v[42:43]
	v_cvt_pk_bf16_f32 v34, v40, v41
	v_cvt_pk_bf16_f32 v35, v42, v43
	v_lshl_add_u64 v[36:37], v[36:37], 0, v[116:117]
	global_store_dwordx4 v[36:37], v[32:35], off sc1
	s_nop 1
	v_add_u32_e32 v32, 0xa0, v150
	v_mov_b32_e32 v34, v204
	v_pk_mul_f32 v[28:29], v[28:29], v[34:35] op_sel_hi:[1,0]
	v_pk_mul_f32 v[20:21], v[20:21], v[34:35] op_sel_hi:[1,0]
	v_mul_f32_e32 v33, 0xbfb8aa3b, v28
	v_pk_mul_f32 v[20:21], v[28:29], v[20:21]
	v_mul_f32_e32 v28, 0xbfb8aa3b, v29
	v_exp_f32_e32 v28, v28
	v_pk_mul_f32 v[22:23], v[22:23], v[34:35] op_sel_hi:[1,0]
	v_pk_mul_f32 v[24:25], v[24:25], v[34:35] op_sel_hi:[1,0]
	v_pk_mul_f32 v[16:17], v[16:17], v[34:35] op_sel_hi:[1,0]
	v_add_f32_e32 v28, 1.0, v28
	v_rcp_f32_e32 v37, v28
	v_pk_mul_f32 v[28:29], v[30:31], v[34:35] op_sel_hi:[1,0]
	v_pk_mul_f32 v[16:17], v[24:25], v[16:17]
	v_mul_f32_e32 v30, 0xbfb8aa3b, v28
	v_pk_mul_f32 v[22:23], v[28:29], v[22:23]
	v_mul_f32_e32 v28, 0xbfb8aa3b, v29
	v_exp_f32_e32 v28, v28
	v_pk_mul_f32 v[18:19], v[18:19], v[34:35] op_sel_hi:[1,0]
	v_exp_f32_e32 v33, v33
	v_exp_f32_e32 v30, v30
	v_add_f32_e32 v28, 1.0, v28
	v_rcp_f32_e32 v31, v28
	v_mul_f32_e32 v28, 0xbfb8aa3b, v24
	v_mul_f32_e32 v24, 0xbfb8aa3b, v25
	v_exp_f32_e32 v28, v28
	v_exp_f32_e32 v24, v24
	v_add_f32_e32 v33, 1.0, v33
	v_rcp_f32_e32 v36, v33
	v_add_f32_e32 v28, 1.0, v28
	v_add_f32_e32 v24, 1.0, v24
	v_rcp_f32_e32 v28, v28
	v_rcp_f32_e32 v29, v24
	v_add_f32_e32 v30, 1.0, v30
	v_rcp_f32_e32 v30, v30
	v_pk_mul_f32 v[20:21], v[20:21], v[36:37]
	v_pk_mul_f32 v[24:25], v[16:17], v[28:29]
	v_pk_mul_f32 v[16:17], v[26:27], v[34:35] op_sel_hi:[1,0]
	v_pk_mul_f32 v[22:23], v[22:23], v[30:31]
	v_mul_f32_e32 v26, 0xbfb8aa3b, v16
	v_pk_mul_f32 v[18:19], v[16:17], v[18:19]
	v_mul_f32_e32 v16, 0xbfb8aa3b, v17
	v_exp_f32_e32 v26, v26
	v_exp_f32_e32 v16, v16
	v_cvt_pk_bf16_f32 v17, v22, v23
	v_add_f32_e32 v26, 1.0, v26
	v_add_f32_e32 v16, 1.0, v16
	v_rcp_f32_e32 v26, v26
	v_rcp_f32_e32 v27, v16
	v_cvt_pk_bf16_f32 v16, v20, v21
	v_mad_i64_i32 v[20:21], s[8:9], v32, s72, v[118:119]
	v_pk_mul_f32 v[26:27], v[18:19], v[26:27]
	v_cvt_pk_bf16_f32 v18, v24, v25
	v_cvt_pk_bf16_f32 v19, v26, v27
	v_lshl_add_u64 v[20:21], v[20:21], 0, v[116:117]
	global_store_dwordx4 v[20:21], v[16:19], off sc1
	s_nop 1
	v_add_u32_e32 v16, 0xb0, v150
	v_mov_b32_e32 v18, v208
	v_pk_mul_f32 v[12:13], v[12:13], v[18:19] op_sel_hi:[1,0]
	v_pk_mul_f32 v[4:5], v[4:5], v[18:19] op_sel_hi:[1,0]
	v_mul_f32_e32 v17, 0xbfb8aa3b, v12
	v_pk_mul_f32 v[4:5], v[12:13], v[4:5]
	v_mul_f32_e32 v12, 0xbfb8aa3b, v13
	v_exp_f32_e32 v12, v12
	v_pk_mul_f32 v[6:7], v[6:7], v[18:19] op_sel_hi:[1,0]
	v_pk_mul_f32 v[8:9], v[8:9], v[18:19] op_sel_hi:[1,0]
	v_pk_mul_f32 v[0:1], v[0:1], v[18:19] op_sel_hi:[1,0]
	v_add_f32_e32 v12, 1.0, v12
	v_rcp_f32_e32 v21, v12
	v_pk_mul_f32 v[12:13], v[14:15], v[18:19] op_sel_hi:[1,0]
	v_pk_mul_f32 v[0:1], v[8:9], v[0:1]
	v_mul_f32_e32 v14, 0xbfb8aa3b, v12
	v_pk_mul_f32 v[6:7], v[12:13], v[6:7]
	v_mul_f32_e32 v12, 0xbfb8aa3b, v13
	v_exp_f32_e32 v12, v12
	v_pk_mul_f32 v[2:3], v[2:3], v[18:19] op_sel_hi:[1,0]
	v_exp_f32_e32 v17, v17
	v_exp_f32_e32 v14, v14
	v_add_f32_e32 v12, 1.0, v12
	v_rcp_f32_e32 v15, v12
	v_mul_f32_e32 v12, 0xbfb8aa3b, v8
	v_mul_f32_e32 v8, 0xbfb8aa3b, v9
	v_exp_f32_e32 v12, v12
	v_exp_f32_e32 v8, v8
	v_add_f32_e32 v17, 1.0, v17
	v_rcp_f32_e32 v20, v17
	v_add_f32_e32 v12, 1.0, v12
	v_add_f32_e32 v8, 1.0, v8
	v_rcp_f32_e32 v12, v12
	v_rcp_f32_e32 v13, v8
	v_add_f32_e32 v14, 1.0, v14
	v_rcp_f32_e32 v14, v14
	v_pk_mul_f32 v[4:5], v[4:5], v[20:21]
	v_pk_mul_f32 v[8:9], v[0:1], v[12:13]
	v_pk_mul_f32 v[0:1], v[10:11], v[18:19] op_sel_hi:[1,0]
	v_pk_mul_f32 v[6:7], v[6:7], v[14:15]
	v_mul_f32_e32 v10, 0xbfb8aa3b, v0
	v_pk_mul_f32 v[2:3], v[0:1], v[2:3]
	v_mul_f32_e32 v0, 0xbfb8aa3b, v1
	v_exp_f32_e32 v10, v10
	v_exp_f32_e32 v0, v0
	v_cvt_pk_bf16_f32 v1, v6, v7
	v_add_f32_e32 v10, 1.0, v10
	v_add_f32_e32 v0, 1.0, v0
	v_rcp_f32_e32 v10, v10
	v_rcp_f32_e32 v11, v0
	v_cvt_pk_bf16_f32 v0, v4, v5
	v_mad_i64_i32 v[4:5], s[8:9], v16, s72, v[118:119]
	v_pk_mul_f32 v[10:11], v[2:3], v[10:11]
	v_cvt_pk_bf16_f32 v2, v8, v9
	v_cvt_pk_bf16_f32 v3, v10, v11
	v_lshl_add_u64 v[4:5], v[4:5], 0, v[116:117]
	global_store_dwordx4 v[4:5], v[0:3], off sc1
	s_andn2_b64 vcc, exec, s[38:39]
	s_mov_b64 s[8:9], -1
	s_cbranch_vccnz .LBB0_474

.LBB0_658:
	v_lshl_add_u32 v144, s10, 8, v140
	s_lshl_b32 s10, s11, 8
	v_ashrrev_i32_e32 v145, 31, v144
	s_ashr_i32 s11, s10, 31
	v_cvt_pk_bf16_f32 v124, v124, v125
	v_cvt_pk_bf16_f32 v125, v126, v127
	v_cvt_pk_bf16_f32 v126, v120, v121
	v_lshlrev_b64 v[120:121], 12, v[144:145]
	v_lshl_add_u64 v[120:121], s[22:23], 0, v[120:121]
	s_lshl_b64 s[10:11], s[10:11], 1
	v_lshl_add_u64 v[120:121], v[120:121], 0, s[10:11]
	v_lshl_add_u64 v[120:121], v[120:121], 0, s[4:5]
	v_lshl_add_u64 v[120:121], v[120:121], 0, v[160:161]
	v_cvt_pk_bf16_f32 v108, v108, v109
	v_cvt_pk_bf16_f32 v109, v110, v111
	v_cvt_pk_bf16_f32 v110, v104, v105
	v_cvt_pk_bf16_f32 v111, v106, v107
	global_store_dwordx4 v[120:121], v[108:111], off offset:256 sc1
	v_cvt_pk_bf16_f32 v92, v92, v93
	v_cvt_pk_bf16_f32 v93, v94, v95
	v_or_b32_e32 v108, 16, v144
	v_ashrrev_i32_e32 v109, 31, v108
	v_lshlrev_b64 v[108:109], 12, v[108:109]
	v_lshl_add_u64 v[108:109], s[22:23], 0, v[108:109]
	v_lshl_add_u64 v[108:109], v[108:109], 0, s[10:11]
	v_lshl_add_u64 v[108:109], v[108:109], 0, s[4:5]
	v_lshl_add_u64 v[108:109], v[108:109], 0, v[160:161]
	v_cvt_pk_bf16_f32 v94, v88, v89
	v_cvt_pk_bf16_f32 v95, v90, v91
	global_store_dwordx4 v[108:109], v[92:95], off offset:256 sc1
	v_cvt_pk_bf16_f32 v76, v76, v77
	v_cvt_pk_bf16_f32 v77, v78, v79
	v_or_b32_e32 v92, 32, v144
	v_ashrrev_i32_e32 v93, 31, v92
	v_lshlrev_b64 v[92:93], 12, v[92:93]
	v_lshl_add_u64 v[92:93], s[22:23], 0, v[92:93]
	v_lshl_add_u64 v[92:93], v[92:93], 0, s[10:11]
	v_lshl_add_u64 v[92:93], v[92:93], 0, s[4:5]
	v_lshl_add_u64 v[92:93], v[92:93], 0, v[160:161]
	v_cvt_pk_bf16_f32 v78, v72, v73
	v_cvt_pk_bf16_f32 v79, v74, v75
	global_store_dwordx4 v[92:93], v[76:79], off offset:256 sc1
	v_cvt_pk_bf16_f32 v60, v60, v61
	v_cvt_pk_bf16_f32 v61, v62, v63
	v_or_b32_e32 v76, 48, v144
	v_ashrrev_i32_e32 v77, 31, v76
	v_lshlrev_b64 v[76:77], 12, v[76:77]
	v_lshl_add_u64 v[76:77], s[22:23], 0, v[76:77]
	v_lshl_add_u64 v[76:77], v[76:77], 0, s[10:11]
	s_mov_b64 s[10:11], 0x80000
	v_cvt_pk_bf16_f32 v62, v56, v57
	v_lshl_add_u64 v[56:57], v[120:121], 0, s[10:11]
	s_mov_b32 s10, 0x80000
	v_cvt_pk_bf16_f32 v63, v58, v59
	v_add_co_u32_e32 v58, vcc, s10, v120
	v_cvt_pk_bf16_f32 v44, v44, v45
	v_cvt_pk_bf16_f32 v45, v46, v47
	v_cvt_pk_bf16_f32 v46, v40, v41
	v_cvt_pk_bf16_f32 v47, v42, v43
	s_mov_b64 s[10:11], 0x90000
	v_addc_co_u32_e32 v59, vcc, 0, v121, vcc
	global_store_dwordx4 v[56:57], v[44:47], off offset:256 sc1
	v_cvt_pk_bf16_f32 v28, v28, v29
	v_cvt_pk_bf16_f32 v29, v30, v31
	v_lshl_add_u64 v[44:45], v[120:121], 0, s[10:11]
	s_mov_b32 s10, 0x90000
	v_add_co_u32_e32 v46, vcc, s10, v120
	v_cvt_pk_bf16_f32 v30, v24, v25
	v_cvt_pk_bf16_f32 v31, v26, v27
	s_mov_b64 s[10:11], 0xa0000
	v_addc_co_u32_e32 v47, vcc, 0, v121, vcc
	global_store_dwordx4 v[44:45], v[28:31], off offset:256 sc1
	v_cvt_pk_bf16_f32 v12, v12, v13
	v_cvt_pk_bf16_f32 v13, v14, v15
	v_lshl_add_u64 v[28:29], v[120:121], 0, s[10:11]
	s_mov_b32 s10, 0xa0000
	v_add_co_u32_e32 v30, vcc, s10, v120
	v_cvt_pk_bf16_f32 v14, v8, v9
	v_cvt_pk_bf16_f32 v15, v10, v11
	s_mov_b64 s[10:11], 0xb0000
	v_addc_co_u32_e32 v31, vcc, 0, v121, vcc
	global_store_dwordx4 v[28:29], v[12:15], off offset:256 sc1
	v_lshl_add_u64 v[76:77], v[76:77], 0, s[4:5]
	v_cvt_pk_bf16_f32 v127, v122, v123
	v_lshl_add_u64 v[12:13], v[120:121], 0, s[10:11]
	s_mov_b32 s10, 0xb0000
	v_add_co_u32_e32 v14, vcc, s10, v120
	v_cvt_pk_bf16_f32 v104, v116, v117
	s_nop 0
	v_addc_co_u32_e32 v15, vcc, 0, v121, vcc
	v_cvt_pk_bf16_f32 v105, v118, v119
	v_cvt_pk_bf16_f32 v106, v112, v113
	v_cvt_pk_bf16_f32 v107, v114, v115
	v_cvt_pk_bf16_f32 v88, v100, v101
	v_cvt_pk_bf16_f32 v89, v102, v103
	v_cvt_pk_bf16_f32 v90, v96, v97
	v_cvt_pk_bf16_f32 v91, v98, v99
	v_cvt_pk_bf16_f32 v72, v84, v85
	v_cvt_pk_bf16_f32 v73, v86, v87
	v_cvt_pk_bf16_f32 v74, v80, v81
	v_cvt_pk_bf16_f32 v75, v82, v83
	v_lshl_add_u64 v[76:77], v[76:77], 0, v[160:161]
	v_cvt_pk_bf16_f32 v68, v68, v69
	v_cvt_pk_bf16_f32 v69, v70, v71
	v_cvt_pk_bf16_f32 v70, v64, v65
	v_cvt_pk_bf16_f32 v71, v66, v67
	v_cvt_pk_bf16_f32 v40, v52, v53
	v_cvt_pk_bf16_f32 v41, v54, v55
	v_cvt_pk_bf16_f32 v42, v48, v49
	v_cvt_pk_bf16_f32 v43, v50, v51
	v_cvt_pk_bf16_f32 v24, v36, v37
	v_cvt_pk_bf16_f32 v25, v38, v39
	v_cvt_pk_bf16_f32 v26, v32, v33
	v_cvt_pk_bf16_f32 v27, v34, v35
	v_cvt_pk_bf16_f32 v8, v20, v21
	v_cvt_pk_bf16_f32 v9, v22, v23
	v_cvt_pk_bf16_f32 v10, v16, v17
	v_cvt_pk_bf16_f32 v11, v18, v19
	v_cvt_pk_bf16_f32 v4, v4, v5
	v_cvt_pk_bf16_f32 v5, v6, v7
	v_cvt_pk_bf16_f32 v6, v0, v1
	v_cvt_pk_bf16_f32 v7, v2, v3
	s_andn2_b64 vcc, exec, s[12:13]
	s_mov_b64 s[10:11], -1
	v_readlane_b32 s90, v255, 19
	v_readlane_b32 s92, v255, 28
	global_store_dwordx4 v[120:121], v[124:127], off sc1
	global_store_dwordx4 v[108:109], v[104:107], off sc1
	global_store_dwordx4 v[92:93], v[88:91], off sc1
	global_store_dwordx4 v[76:77], v[72:75], off sc1
	global_store_dwordx4 v[76:77], v[68:71], off offset:256 sc1
	global_store_dwordx4 v[58:59], v[60:63], off sc1
	global_store_dwordx4 v[46:47], v[40:43], off sc1
	global_store_dwordx4 v[30:31], v[24:27], off sc1
	global_store_dwordx4 v[14:15], v[8:11], off sc1
	global_store_dwordx4 v[12:13], v[4:7], off offset:256 sc1
	v_readlane_b32 s91, v255, 20
	s_cbranch_vccnz .LBB0_647
	s_andn2_b64 vcc, exec, s[6:7]
	s_cbranch_vccnz .LBB0_646
	s_barrier
	s_branch .LBB0_646

.LBB0_671:
	s_ashr_i32 s17, s16, 31
	ds_read2_b32 v[8:9], v40 offset0:33 offset1:41
	ds_read2_b32 v[10:11], v40 offset1:8
	s_lshl_b64 s[10:11], s[16:17], 1
	s_add_u32 s8, s8, s10
	s_addc_u32 s9, s9, s11
	v_mov_b32_e32 v1, v161
	ds_read2_b32 v[12:13], v40 offset0:66 offset1:74
	ds_read2_b32 v[14:15], v40 offset0:99 offset1:107
	ds_read2_b32 v[16:17], v40 offset0:132 offset1:140
	ds_read2_b32 v[18:19], v40 offset0:165 offset1:173
	ds_read2_b32 v[20:21], v40 offset0:198 offset1:206
	ds_read2_b32 v[22:23], v40 offset0:231 offset1:239
	v_lshl_add_u64 v[6:7], s[8:9], 0, v[0:1]
	v_add_u32_e32 v1, s14, v39
	s_waitcnt lgkmcnt(6)
	v_cvt_pk_bf16_f32 v2, v10, v8
	v_ashrrev_i32_e32 v8, 31, v1
	v_mul_lo_u32 v8, s6, v8
	v_mul_lo_u32 v10, s7, v1
	v_mad_u64_u32 v[24:25], s[8:9], s6, v1, 0
	v_add3_u32 v25, v25, v8, v10
	s_waitcnt lgkmcnt(4)
	v_cvt_pk_bf16_f32 v3, v12, v14
	s_waitcnt lgkmcnt(2)
	v_cvt_pk_bf16_f32 v4, v16, v18
	s_waitcnt lgkmcnt(0)
	v_cvt_pk_bf16_f32 v5, v20, v22
	v_lshl_add_u64 v[24:25], v[24:25], 1, v[6:7]
	v_add_u32_e32 v8, 8, v1
	global_store_dwordx4 v[24:25], v[2:5], off sc1
	v_readlane_b32 s4, v253, 7
	s_add_i32 s25, s25, s4
	v_cvt_pk_bf16_f32 v2, v11, v9
	v_ashrrev_i32_e32 v9, 31, v8
	v_mul_lo_u32 v10, s6, v9
	v_mul_lo_u32 v11, s7, v8
	v_mad_u64_u32 v[8:9], s[8:9], s6, v8, 0
	v_add3_u32 v9, v9, v10, v11
	v_cvt_pk_bf16_f32 v3, v13, v15
	v_cvt_pk_bf16_f32 v4, v17, v19
	v_cvt_pk_bf16_f32 v5, v21, v23
	v_lshl_add_u64 v[8:9], v[8:9], 1, v[6:7]
	global_store_dwordx4 v[8:9], v[2:5], off sc1
	ds_read2_b32 v[8:9], v40 offset0:49 offset1:57
	ds_read2_b32 v[10:11], v40 offset0:16 offset1:24
	ds_read2_b32 v[12:13], v40 offset0:82 offset1:90
	ds_read2_b32 v[14:15], v40 offset0:115 offset1:123
	ds_read2_b32 v[16:17], v40 offset0:148 offset1:156
	ds_read2_b32 v[18:19], v40 offset0:181 offset1:189
	ds_read2_b32 v[20:21], v40 offset0:214 offset1:222
	ds_read2_b32 v[22:23], v40 offset0:247 offset1:255
	s_cmp_ge_i32 s25, s24
	s_waitcnt lgkmcnt(6)
	v_cvt_pk_bf16_f32 v2, v10, v8
	v_add_u32_e32 v8, 16, v1
	v_ashrrev_i32_e32 v10, 31, v8
	s_waitcnt lgkmcnt(4)
	v_cvt_pk_bf16_f32 v3, v12, v14
	v_mul_lo_u32 v10, s6, v10
	v_mul_lo_u32 v12, s7, v8
	v_mad_u64_u32 v[24:25], s[8:9], s6, v8, 0
	v_add3_u32 v25, v25, v10, v12
	v_add_u32_e32 v1, 24, v1
	s_waitcnt lgkmcnt(2)
	v_cvt_pk_bf16_f32 v4, v16, v18
	s_waitcnt lgkmcnt(0)
	v_cvt_pk_bf16_f32 v5, v20, v22
	v_lshl_add_u64 v[24:25], v[24:25], 1, v[6:7]
	v_ashrrev_i32_e32 v8, 31, v1
	global_store_dwordx4 v[24:25], v[2:5], off sc1
	v_mul_lo_u32 v10, s6, v8
	v_readlane_b32 s4, v255, 30
	v_cvt_pk_bf16_f32 v2, v11, v9
	v_mul_lo_u32 v11, s7, v1
	v_mad_u64_u32 v[8:9], s[6:7], s6, v1, 0
	v_add3_u32 v9, v9, v10, v11
	v_cvt_pk_bf16_f32 v3, v13, v15
	v_cvt_pk_bf16_f32 v4, v17, v19
	v_cvt_pk_bf16_f32 v5, v21, v23
	v_lshl_add_u64 v[6:7], v[8:9], 1, v[6:7]
	global_store_dwordx4 v[6:7], v[2:5], off sc1
	s_waitcnt lgkmcnt(0)
	v_readlane_b32 s26, v255, 31
	s_cbranch_scc1 .LBB0_706
